# v15 + all s_setprio toggles removed from the GEMM K-loops (B, D, Fseq, I, J)
# speedup vs baseline: 1.0019x; 1.0019x over previous
; #define PG8_STAGE(bufoff, gbase, voff) do { _Pragma("unroll") for (int _i = 0; _i < 2; ++_i) \
;         __builtin_amdgcn_global_load_lds((const unsigned*)((const char*)(gbase) + (voff)[_i]), (LAS unsigned*)(lds + (bufoff) + ldsw + _i * 8192), 16, 0, 0); } while (0)
; #define PG8_LDA(dst, b, h) do { _Pragma("unroll") for (int m = 0; m < 4; ++m) _Pragma("unroll") for (int k = 0; k < 2; ++k) dst[m][k] = *(const LAS bf16x8*)(lds + PG8_SA(b, h) + aoff + m * 2048 + k * 1024); } while (0)
; #define PG8_LDB(dst, b, h) do { _Pragma("unroll") for (int n = 0; n < 2; ++n) _Pragma("unroll") for (int k = 0; k < 2; ++k) dst[n][k] = *(const LAS bf16x8*)(lds + PG8_SB(b, h) + boff + n * 2048 + k * 1024); } while (0)
; #define PG8_MMA(ai, bj, At, Bt) do { __builtin_amdgcn_s_setprio(1); _Pragma("unroll") for (int m = 0; m < 4; ++m) _Pragma("unroll") for (int n = 0; n < 2; ++n) _Pragma("unroll") for (int k = 0; k < 2; ++k) \
;         acc[ai][bj][m][n] = __builtin_amdgcn_mfma_f32_16x16x32_bf16(Bt[n][k], At[m][k], acc[ai][bj][m][n], 0, 0, 0); __builtin_amdgcn_s_setprio(0); } while (0)
; #define PG8_WAIT_V(n) asm volatile("s_waitcnt vmcnt(" #n ")" ::: "memory")
; #define PG8_WAIT_L(n) asm volatile("s_waitcnt lgkmcnt(" #n ")" ::: "memory")
; #define PG8_BAR __builtin_amdgcn_s_barrier()
; #define PG8_SCHED __builtin_amdgcn_sched_barrier(0)
; template <class Epi, class Sched, bool ALIGN_EPI = true, bool SP2 = true>
; __device__ __forceinline__ void gemm_phase(LAS unsigned char* lds, const Sched& S, const Epi& E, const int lda, const int ldb) {
;     ...
;             PG8_LDB(B0, 0, 0); PG8_LDB(B1, 0, 1); PG8_SCHED; PG8_LDA(At, 0, 0); PG8_STAGE(PG8_SA(1, 1), a1 + hstepA, voffA);
;             PG8_WAIT_V(8); PG8_WAIT_L(0); PG8_BAR; PG8_MMA(0, 0, At, B0); PG8_MMA(0, 1, At, B1); PG8_BAR; PG8_SCHED;
;             PG8_LDA(At, 0, 1); PG8_STAGE(PG8_SB(0, 0), b2, voffB); PG8_STAGE(PG8_SB(0, 1), b2 + hstepB, voffB); PG8_STAGE(PG8_SA(0, 0), a2, voffA);
;             PG8_WAIT_V(8); PG8_WAIT_L(0); PG8_BAR; PG8_MMA(1, 0, At, B0); PG8_MMA(1, 1, At, B1); PG8_BAR; PG8_SCHED;
.LBB0_291:
	s_add_u32 s8, s6, 0xfff00080
	s_addc_u32 s9, s7, -1
	s_add_i32 s50, 0, 0x10000
	s_cmp_eq_u32 s33, 60
	s_cselect_b32 s27, s23, s9
	s_cselect_b32 s26, s22, s8
	s_cselect_b32 s9, s25, s30
	s_cselect_b32 s8, s24, s28
	s_add_i32 s54, 0, 0x14000
	v_add_u32_e32 v158, s50, v147
	v_add_u32_e32 v174, s54, v147
	ds_read_b128 v[142:145], v158
	ds_read_b128 v[150:153], v158 offset:1024
	ds_read_b128 v[154:157], v158 offset:2048
	ds_read_b128 v[158:161], v158 offset:3072
	ds_read_b128 v[162:165], v174
	ds_read_b128 v[166:169], v174 offset:1024
	ds_read_b128 v[170:173], v174 offset:2048
	ds_read_b128 v[174:177], v174 offset:3072
	v_lshl_add_u64 v[224:225], s[6:7], 0, v[138:139]
	s_add_i32 m0, s51, 0xc000
	ds_read_b128 v[178:181], v149
	ds_read_b128 v[182:185], v149 offset:1024
	ds_read_b128 v[186:189], v149 offset:2048
	ds_read_b128 v[190:193], v149 offset:3072
	ds_read_b128 v[194:197], v149 offset:4096
	ds_read_b128 v[212:215], v149 offset:5120
	ds_read_b128 v[216:219], v149 offset:6144
	ds_read_b128 v[220:223], v149 offset:7168
	global_load_lds_dwordx4 v[224:225], off
	v_lshl_add_u64 v[224:225], s[6:7], 0, v[140:141]
	s_add_i32 m0, s51, 0xe000
	s_nop 0
	global_load_lds_dwordx4 v[224:225], off
	s_waitcnt vmcnt(8)
	s_waitcnt lgkmcnt(0)
	s_barrier
	s_waitcnt lgkmcnt(0)
	v_mfma_f32_16x16x32_bf16 v[128:131], v[142:145], v[178:181], v[128:131]
	v_mfma_f32_16x16x32_bf16 v[124:127], v[154:157], v[178:181], v[124:127]
	v_mfma_f32_16x16x32_bf16 v[110:113], v[142:145], v[186:189], v[110:113]
	v_mfma_f32_16x16x32_bf16 v[106:109], v[154:157], v[186:189], v[106:109]
	v_mfma_f32_16x16x32_bf16 v[94:97], v[142:145], v[194:197], v[94:97]
	v_mfma_f32_16x16x32_bf16 v[90:93], v[154:157], v[194:197], v[90:93]
	v_mfma_f32_16x16x32_bf16 v[78:81], v[142:145], v[216:219], v[78:81]
	v_mfma_f32_16x16x32_bf16 v[74:77], v[154:157], v[216:219], v[74:77]
	v_mfma_f32_16x16x32_bf16 v[128:131], v[150:153], v[182:185], v[128:131]
	v_mfma_f32_16x16x32_bf16 v[124:127], v[158:161], v[182:185], v[124:127]
	v_mfma_f32_16x16x32_bf16 v[110:113], v[150:153], v[190:193], v[110:113]
	v_mfma_f32_16x16x32_bf16 v[106:109], v[158:161], v[190:193], v[106:109]
	v_mfma_f32_16x16x32_bf16 v[94:97], v[150:153], v[212:215], v[94:97]
	v_mfma_f32_16x16x32_bf16 v[90:93], v[158:161], v[212:215], v[90:93]
	v_mfma_f32_16x16x32_bf16 v[78:81], v[150:153], v[220:223], v[78:81]
	v_mfma_f32_16x16x32_bf16 v[74:77], v[158:161], v[220:223], v[74:77]
	v_mfma_f32_16x16x32_bf16 v[120:123], v[162:165], v[178:181], v[120:123]
	v_mfma_f32_16x16x32_bf16 v[116:119], v[170:173], v[178:181], v[116:119]
	v_mfma_f32_16x16x32_bf16 v[102:105], v[162:165], v[186:189], v[102:105]
	v_mfma_f32_16x16x32_bf16 v[98:101], v[170:173], v[186:189], v[98:101]
	v_mfma_f32_16x16x32_bf16 v[86:89], v[162:165], v[194:197], v[86:89]
	v_mfma_f32_16x16x32_bf16 v[82:85], v[170:173], v[194:197], v[82:85]
	v_mfma_f32_16x16x32_bf16 v[70:73], v[162:165], v[216:219], v[70:73]
	v_mfma_f32_16x16x32_bf16 v[66:69], v[170:173], v[216:219], v[66:69]
	v_mfma_f32_16x16x32_bf16 v[120:123], v[166:169], v[182:185], v[120:123]
	v_mfma_f32_16x16x32_bf16 v[116:119], v[174:177], v[182:185], v[116:119]
	v_mfma_f32_16x16x32_bf16 v[102:105], v[166:169], v[190:193], v[102:105]
	v_mfma_f32_16x16x32_bf16 v[98:101], v[174:177], v[190:193], v[98:101]
	v_mfma_f32_16x16x32_bf16 v[86:89], v[166:169], v[212:215], v[86:89]
	v_mfma_f32_16x16x32_bf16 v[82:85], v[174:177], v[212:215], v[82:85]
	v_mfma_f32_16x16x32_bf16 v[70:73], v[166:169], v[220:223], v[70:73]
	v_mfma_f32_16x16x32_bf16 v[66:69], v[174:177], v[220:223], v[66:69]
	s_barrier
	s_add_i32 s50, s50, s49
	v_lshl_add_u64 v[224:225], s[8:9], 0, v[114:115]
	s_mov_b32 m0, s50
	ds_read_b128 v[178:181], v149 offset:16384
	ds_read_b128 v[182:185], v149 offset:17408
	ds_read_b128 v[186:189], v149 offset:18432
	ds_read_b128 v[190:193], v149 offset:19456
	ds_read_b128 v[194:197], v149 offset:20480
	ds_read_b128 v[212:215], v149 offset:21504
	ds_read_b128 v[216:219], v149 offset:22528
	ds_read_b128 v[220:223], v149 offset:23552
	global_load_lds_dwordx4 v[224:225], off
	s_add_i32 m0, s50, 0x2000
	s_add_u32 s74, s8, 0x100000
	v_lshl_add_u64 v[226:227], s[8:9], 0, v[136:137]
	s_addc_u32 s75, s9, 0
	s_add_i32 s50, s54, s49
	global_load_lds_dwordx4 v[226:227], off
	v_lshl_add_u64 v[228:229], s[74:75], 0, v[114:115]
	s_mov_b32 m0, s50
	v_lshl_add_u64 v[230:231], s[26:27], 0, v[134:135]
	global_load_lds_dwordx4 v[228:229], off
	v_lshl_add_u64 v[228:229], s[74:75], 0, v[136:137]
	s_add_i32 m0, s50, 0x2000
	s_nop 0
	global_load_lds_dwordx4 v[228:229], off
	v_lshl_add_u64 v[228:229], s[26:27], 0, v[132:133]
	s_mov_b32 m0, s51
	s_nop 0
	global_load_lds_dwordx4 v[228:229], off
	s_mov_b32 m0, s57
	s_nop 0
	global_load_lds_dwordx4 v[230:231], off
	s_waitcnt vmcnt(8)
	s_waitcnt lgkmcnt(0)
	s_barrier
; #define PG8_STAGE(bufoff, gbase, voff) do { _Pragma("unroll") for (int _i = 0; _i < 2; ++_i) \
;         __builtin_amdgcn_global_load_lds((const unsigned*)((const char*)(gbase) + (voff)[_i]), (LAS unsigned*)(lds + (bufoff) + ldsw + _i * 8192), 16, 0, 0); } while (0)
; #define PG8_LDA(dst, b, h) do { _Pragma("unroll") for (int m = 0; m < 4; ++m) _Pragma("unroll") for (int k = 0; k < 2; ++k) dst[m][k] = *(const LAS bf16x8*)(lds + PG8_SA(b, h) + aoff + m * 2048 + k * 1024); } while (0)
; #define PG8_LDB(dst, b, h) do { _Pragma("unroll") for (int n = 0; n < 2; ++n) _Pragma("unroll") for (int k = 0; k < 2; ++k) dst[n][k] = *(const LAS bf16x8*)(lds + PG8_SB(b, h) + boff + n * 2048 + k * 1024); } while (0)
; #define PG8_MMA(ai, bj, At, Bt) do { __builtin_amdgcn_s_setprio(1); _Pragma("unroll") for (int m = 0; m < 4; ++m) _Pragma("unroll") for (int n = 0; n < 2; ++n) _Pragma("unroll") for (int k = 0; k < 2; ++k) \
;         acc[ai][bj][m][n] = __builtin_amdgcn_mfma_f32_16x16x32_bf16(Bt[n][k], At[m][k], acc[ai][bj][m][n], 0, 0, 0); __builtin_amdgcn_s_setprio(0); } while (0)
; #define PG8_WAIT_V(n) asm volatile("s_waitcnt vmcnt(" #n ")" ::: "memory")
; #define PG8_WAIT_L(n) asm volatile("s_waitcnt lgkmcnt(" #n ")" ::: "memory")
; #define PG8_BAR __builtin_amdgcn_s_barrier()
; #define PG8_SCHED __builtin_amdgcn_sched_barrier(0)
; template <class Epi, class Sched, bool ALIGN_EPI = true, bool SP2 = true>
; __device__ __forceinline__ void gemm_phase(LAS unsigned char* lds, const Sched& S, const Epi& E, const int lda, const int ldb) {
;     ...
;             PG8_WAIT_V(8); PG8_WAIT_L(0); PG8_BAR; PG8_MMA(1, 0, At, B0); PG8_MMA(1, 1, At, B1); PG8_BAR; PG8_SCHED;
;             PG8_LDB(B0, 1, 0); PG8_LDB(B1, 1, 1); PG8_SCHED; PG8_LDA(At, 1, 0); PG8_STAGE(PG8_SA(0, 1), a2 + hstepA, voffA);
;             PG8_WAIT_V(8); PG8_WAIT_L(0); PG8_BAR; PG8_MMA(0, 0, At, B0); PG8_MMA(0, 1, At, B1); PG8_BAR; PG8_SCHED;
	s_waitcnt lgkmcnt(0)
	v_mfma_f32_16x16x32_bf16 v[62:65], v[142:145], v[178:181], v[62:65]
	v_mfma_f32_16x16x32_bf16 v[58:61], v[154:157], v[178:181], v[58:61]
	v_mfma_f32_16x16x32_bf16 v[46:49], v[142:145], v[186:189], v[46:49]
	v_mfma_f32_16x16x32_bf16 v[42:45], v[154:157], v[186:189], v[42:45]
	v_mfma_f32_16x16x32_bf16 v[30:33], v[142:145], v[194:197], v[30:33]
	v_mfma_f32_16x16x32_bf16 v[26:29], v[154:157], v[194:197], v[26:29]
	v_mfma_f32_16x16x32_bf16 v[14:17], v[142:145], v[216:219], v[14:17]
	v_mfma_f32_16x16x32_bf16 v[10:13], v[154:157], v[216:219], v[10:13]
	v_mfma_f32_16x16x32_bf16 v[62:65], v[150:153], v[182:185], v[62:65]
	v_mfma_f32_16x16x32_bf16 v[58:61], v[158:161], v[182:185], v[58:61]
	v_mfma_f32_16x16x32_bf16 v[46:49], v[150:153], v[190:193], v[46:49]
	v_mfma_f32_16x16x32_bf16 v[42:45], v[158:161], v[190:193], v[42:45]
	v_mfma_f32_16x16x32_bf16 v[30:33], v[150:153], v[212:215], v[30:33]
	v_mfma_f32_16x16x32_bf16 v[26:29], v[158:161], v[212:215], v[26:29]
	v_mfma_f32_16x16x32_bf16 v[14:17], v[150:153], v[220:223], v[14:17]
	v_mfma_f32_16x16x32_bf16 v[10:13], v[158:161], v[220:223], v[10:13]
	v_mfma_f32_16x16x32_bf16 v[54:57], v[162:165], v[178:181], v[54:57]
	v_mfma_f32_16x16x32_bf16 v[50:53], v[170:173], v[178:181], v[50:53]
	v_mfma_f32_16x16x32_bf16 v[38:41], v[162:165], v[186:189], v[38:41]
	v_mfma_f32_16x16x32_bf16 v[34:37], v[170:173], v[186:189], v[34:37]
	v_mfma_f32_16x16x32_bf16 v[22:25], v[162:165], v[194:197], v[22:25]
	v_mfma_f32_16x16x32_bf16 v[18:21], v[170:173], v[194:197], v[18:21]
	v_mfma_f32_16x16x32_bf16 v[6:9], v[162:165], v[216:219], v[6:9]
	v_mfma_f32_16x16x32_bf16 v[2:5], v[170:173], v[216:219], v[2:5]
	v_mfma_f32_16x16x32_bf16 v[54:57], v[166:169], v[182:185], v[54:57]
	v_mfma_f32_16x16x32_bf16 v[50:53], v[174:177], v[182:185], v[50:53]
	v_mfma_f32_16x16x32_bf16 v[38:41], v[166:169], v[190:193], v[38:41]
	v_mfma_f32_16x16x32_bf16 v[34:37], v[174:177], v[190:193], v[34:37]
	v_mfma_f32_16x16x32_bf16 v[22:25], v[166:169], v[212:215], v[22:25]
	v_mfma_f32_16x16x32_bf16 v[18:21], v[174:177], v[212:215], v[18:21]
	v_mfma_f32_16x16x32_bf16 v[6:9], v[166:169], v[220:223], v[6:9]
	v_mfma_f32_16x16x32_bf16 v[2:5], v[174:177], v[220:223], v[2:5]
	s_barrier
	s_add_i32 s50, 0, 0x18000
	s_add_i32 s54, 0, 0x1c000
	v_add_u32_e32 v158, s50, v147
	v_add_u32_e32 v174, s54, v147
	ds_read_b128 v[142:145], v158
	ds_read_b128 v[150:153], v158 offset:1024
	ds_read_b128 v[154:157], v158 offset:2048
	ds_read_b128 v[158:161], v158 offset:3072
	ds_read_b128 v[162:165], v174
	ds_read_b128 v[166:169], v174 offset:1024
	ds_read_b128 v[170:173], v174 offset:2048
	ds_read_b128 v[174:177], v174 offset:3072
	s_add_u32 s26, s26, 0x100000
	s_addc_u32 s27, s27, 0
	s_mov_b32 m0, s62
	v_lshl_add_u64 v[232:233], s[26:27], 0, v[132:133]
	ds_read_b128 v[178:181], v149 offset:32768
	ds_read_b128 v[182:185], v149 offset:33792
	ds_read_b128 v[186:189], v149 offset:34816
	ds_read_b128 v[190:193], v149 offset:35840
	ds_read_b128 v[194:197], v149 offset:36864
	ds_read_b128 v[212:215], v149 offset:37888
	ds_read_b128 v[216:219], v149 offset:38912
	ds_read_b128 v[220:223], v149 offset:39936
	global_load_lds_dwordx4 v[232:233], off
	v_lshl_add_u64 v[232:233], s[26:27], 0, v[134:135]
	s_mov_b32 m0, s63
	s_nop 0
	global_load_lds_dwordx4 v[232:233], off
	s_waitcnt vmcnt(8)
	s_waitcnt lgkmcnt(0)
	s_barrier
	s_waitcnt lgkmcnt(0)
	v_mfma_f32_16x16x32_bf16 v[128:131], v[142:145], v[178:181], v[128:131]
	v_mfma_f32_16x16x32_bf16 v[124:127], v[154:157], v[178:181], v[124:127]
	v_mfma_f32_16x16x32_bf16 v[110:113], v[142:145], v[186:189], v[110:113]
	v_mfma_f32_16x16x32_bf16 v[106:109], v[154:157], v[186:189], v[106:109]
	v_mfma_f32_16x16x32_bf16 v[94:97], v[142:145], v[194:197], v[94:97]
	v_mfma_f32_16x16x32_bf16 v[90:93], v[154:157], v[194:197], v[90:93]
	v_mfma_f32_16x16x32_bf16 v[78:81], v[142:145], v[216:219], v[78:81]
	v_mfma_f32_16x16x32_bf16 v[74:77], v[154:157], v[216:219], v[74:77]
	v_mfma_f32_16x16x32_bf16 v[128:131], v[150:153], v[182:185], v[128:131]
	v_mfma_f32_16x16x32_bf16 v[124:127], v[158:161], v[182:185], v[124:127]
	v_mfma_f32_16x16x32_bf16 v[110:113], v[150:153], v[190:193], v[110:113]
	v_mfma_f32_16x16x32_bf16 v[106:109], v[158:161], v[190:193], v[106:109]
	v_mfma_f32_16x16x32_bf16 v[94:97], v[150:153], v[212:215], v[94:97]
	v_mfma_f32_16x16x32_bf16 v[90:93], v[158:161], v[212:215], v[90:93]
	v_mfma_f32_16x16x32_bf16 v[78:81], v[150:153], v[220:223], v[78:81]
	v_mfma_f32_16x16x32_bf16 v[74:77], v[158:161], v[220:223], v[74:77]
	v_mfma_f32_16x16x32_bf16 v[120:123], v[162:165], v[178:181], v[120:123]
	v_mfma_f32_16x16x32_bf16 v[116:119], v[170:173], v[178:181], v[116:119]
	v_mfma_f32_16x16x32_bf16 v[102:105], v[162:165], v[186:189], v[102:105]
	v_mfma_f32_16x16x32_bf16 v[98:101], v[170:173], v[186:189], v[98:101]
	v_mfma_f32_16x16x32_bf16 v[86:89], v[162:165], v[194:197], v[86:89]
	v_mfma_f32_16x16x32_bf16 v[82:85], v[170:173], v[194:197], v[82:85]
	v_mfma_f32_16x16x32_bf16 v[70:73], v[162:165], v[216:219], v[70:73]
	v_mfma_f32_16x16x32_bf16 v[66:69], v[170:173], v[216:219], v[66:69]
	v_mfma_f32_16x16x32_bf16 v[120:123], v[166:169], v[182:185], v[120:123]
	v_mfma_f32_16x16x32_bf16 v[116:119], v[174:177], v[182:185], v[116:119]
	v_mfma_f32_16x16x32_bf16 v[102:105], v[166:169], v[190:193], v[102:105]
	v_mfma_f32_16x16x32_bf16 v[98:101], v[174:177], v[190:193], v[98:101]
	v_mfma_f32_16x16x32_bf16 v[86:89], v[166:169], v[212:215], v[86:89]
	v_mfma_f32_16x16x32_bf16 v[82:85], v[174:177], v[212:215], v[82:85]
	v_mfma_f32_16x16x32_bf16 v[70:73], v[166:169], v[220:223], v[70:73]
	v_mfma_f32_16x16x32_bf16 v[66:69], v[174:177], v[220:223], v[66:69]
	s_barrier
; #define PG8_STAGE(bufoff, gbase, voff) do { _Pragma("unroll") for (int _i = 0; _i < 2; ++_i) \
;         __builtin_amdgcn_global_load_lds((const unsigned*)((const char*)(gbase) + (voff)[_i]), (LAS unsigned*)(lds + (bufoff) + ldsw + _i * 8192), 16, 0, 0); } while (0)
; #define PG8_LDA(dst, b, h) do { _Pragma("unroll") for (int m = 0; m < 4; ++m) _Pragma("unroll") for (int k = 0; k < 2; ++k) dst[m][k] = *(const LAS bf16x8*)(lds + PG8_SA(b, h) + aoff + m * 2048 + k * 1024); } while (0)
; #define PG8_MMA(ai, bj, At, Bt) do { __builtin_amdgcn_s_setprio(1); _Pragma("unroll") for (int m = 0; m < 4; ++m) _Pragma("unroll") for (int n = 0; n < 2; ++n) _Pragma("unroll") for (int k = 0; k < 2; ++k) \
;         acc[ai][bj][m][n] = __builtin_amdgcn_mfma_f32_16x16x32_bf16(Bt[n][k], At[m][k], acc[ai][bj][m][n], 0, 0, 0); __builtin_amdgcn_s_setprio(0); } while (0)
; #define PG8_WAIT_V(n) asm volatile("s_waitcnt vmcnt(" #n ")" ::: "memory")
; #define PG8_WAIT_L(n) asm volatile("s_waitcnt lgkmcnt(" #n ")" ::: "memory")
; #define PG8_BAR __builtin_amdgcn_s_barrier()
; #define PG8_SCHED __builtin_amdgcn_sched_barrier(0)
; template <class Epi, class Sched, bool ALIGN_EPI = true, bool SP2 = true>
; __device__ __forceinline__ void gemm_phase(LAS unsigned char* lds, const Sched& S, const Epi& E, const int lda, const int ldb) {
;     ...
;             PG8_LDA(At, 1, 1); PG8_STAGE(PG8_SB(1, 0), b3, voffB); PG8_STAGE(PG8_SB(1, 1), b3 + hstepB, voffB); PG8_STAGE(PG8_SA(1, 0), a3, voffA);
;             PG8_WAIT_V(8); PG8_WAIT_L(0); PG8_BAR; PG8_MMA(1, 0, At, B0); PG8_MMA(1, 1, At, B1); PG8_BAR; PG8_SCHED;
;     ...
;         if constexpr (ALIGN_EPI) { if (wr == 0) PG8_BAR; }
	s_add_i32 s26, s50, s49
	v_lshl_add_u64 v[224:225], v[224:225], 0, s[70:71]
	s_mov_b32 m0, s26
	ds_read_b128 v[178:181], v149 offset:49152
	ds_read_b128 v[182:185], v149 offset:50176
	ds_read_b128 v[186:189], v149 offset:51200
	ds_read_b128 v[190:193], v149 offset:52224
	ds_read_b128 v[194:197], v149 offset:53248
	ds_read_b128 v[212:215], v149 offset:54272
	ds_read_b128 v[216:219], v149 offset:55296
	ds_read_b128 v[220:223], v149 offset:56320
	global_load_lds_dwordx4 v[224:225], off
	s_add_i32 m0, s26, 0x2000
	s_add_u32 s8, s8, 0x100080
	v_lshl_add_u64 v[224:225], v[226:227], 0, s[70:71]
	s_addc_u32 s9, s9, 0
	s_add_i32 s26, s54, s49
	global_load_lds_dwordx4 v[224:225], off
	v_lshl_add_u64 v[224:225], s[8:9], 0, v[114:115]
	s_mov_b32 m0, s26
	s_nop 0
	global_load_lds_dwordx4 v[224:225], off
	v_lshl_add_u64 v[224:225], s[8:9], 0, v[136:137]
	s_add_i32 m0, s26, 0x2000
	s_nop 0
	global_load_lds_dwordx4 v[224:225], off
	v_lshl_add_u64 v[224:225], v[228:229], 0, s[70:71]
	s_mov_b32 m0, s76
	s_nop 0
	global_load_lds_dwordx4 v[224:225], off
	v_lshl_add_u64 v[224:225], v[230:231], 0, s[70:71]
	s_mov_b32 m0, s77
	s_nop 0
	global_load_lds_dwordx4 v[224:225], off
	s_waitcnt vmcnt(8)
	s_waitcnt lgkmcnt(0)
	s_barrier
	s_waitcnt lgkmcnt(0)
	v_mfma_f32_16x16x32_bf16 v[62:65], v[142:145], v[178:181], v[62:65]
	v_mfma_f32_16x16x32_bf16 v[58:61], v[154:157], v[178:181], v[58:61]
	v_mfma_f32_16x16x32_bf16 v[46:49], v[142:145], v[186:189], v[46:49]
	v_mfma_f32_16x16x32_bf16 v[42:45], v[154:157], v[186:189], v[42:45]
	v_mfma_f32_16x16x32_bf16 v[30:33], v[142:145], v[194:197], v[30:33]
	v_mfma_f32_16x16x32_bf16 v[26:29], v[154:157], v[194:197], v[26:29]
	v_mfma_f32_16x16x32_bf16 v[14:17], v[142:145], v[216:219], v[14:17]
	v_mfma_f32_16x16x32_bf16 v[10:13], v[154:157], v[216:219], v[10:13]
	v_mfma_f32_16x16x32_bf16 v[62:65], v[150:153], v[182:185], v[62:65]
	v_mfma_f32_16x16x32_bf16 v[58:61], v[158:161], v[182:185], v[58:61]
	v_mfma_f32_16x16x32_bf16 v[46:49], v[150:153], v[190:193], v[46:49]
	v_mfma_f32_16x16x32_bf16 v[42:45], v[158:161], v[190:193], v[42:45]
	v_mfma_f32_16x16x32_bf16 v[30:33], v[150:153], v[212:215], v[30:33]
	v_mfma_f32_16x16x32_bf16 v[26:29], v[158:161], v[212:215], v[26:29]
	v_mfma_f32_16x16x32_bf16 v[14:17], v[150:153], v[220:223], v[14:17]
	v_mfma_f32_16x16x32_bf16 v[10:13], v[158:161], v[220:223], v[10:13]
	v_mfma_f32_16x16x32_bf16 v[54:57], v[162:165], v[178:181], v[54:57]
	v_mfma_f32_16x16x32_bf16 v[50:53], v[170:173], v[178:181], v[50:53]
	v_mfma_f32_16x16x32_bf16 v[38:41], v[162:165], v[186:189], v[38:41]
	v_mfma_f32_16x16x32_bf16 v[34:37], v[170:173], v[186:189], v[34:37]
	v_mfma_f32_16x16x32_bf16 v[22:25], v[162:165], v[194:197], v[22:25]
	v_mfma_f32_16x16x32_bf16 v[18:21], v[170:173], v[194:197], v[18:21]
	v_mfma_f32_16x16x32_bf16 v[6:9], v[162:165], v[216:219], v[6:9]
	v_mfma_f32_16x16x32_bf16 v[2:5], v[170:173], v[216:219], v[2:5]
	v_mfma_f32_16x16x32_bf16 v[54:57], v[166:169], v[182:185], v[54:57]
	v_mfma_f32_16x16x32_bf16 v[50:53], v[174:177], v[182:185], v[50:53]
	v_mfma_f32_16x16x32_bf16 v[38:41], v[166:169], v[190:193], v[38:41]
	v_mfma_f32_16x16x32_bf16 v[34:37], v[174:177], v[190:193], v[34:37]
	v_mfma_f32_16x16x32_bf16 v[22:25], v[166:169], v[212:215], v[22:25]
	v_mfma_f32_16x16x32_bf16 v[18:21], v[174:177], v[212:215], v[18:21]
	v_mfma_f32_16x16x32_bf16 v[6:9], v[166:169], v[220:223], v[6:9]
	v_mfma_f32_16x16x32_bf16 v[2:5], v[174:177], v[220:223], v[2:5]
	s_barrier
	s_add_i32 s33, s33, 2
	s_add_u32 s6, s6, 0x100
	s_addc_u32 s7, s7, 0
	s_add_u32 s28, s28, 0x100
	s_addc_u32 s30, s30, 0
	s_cmp_gt_u32 s33, 61
	s_cbranch_scc0 .LBB0_291
	s_and_b64 vcc, exec, s[10:11]
	s_cbranch_vccz .LBB0_294
	s_barrier

; #define PG8_STAGE(bufoff, gbase, voff) do { _Pragma("unroll") for (int _i = 0; _i < 2; ++_i) \
;         __builtin_amdgcn_global_load_lds((const unsigned*)((const char*)(gbase) + (voff)[_i]), (LAS unsigned*)(lds + (bufoff) + ldsw + _i * 8192), 16, 0, 0); } while (0)
; #define PG8_LDA(dst, b, h) do { _Pragma("unroll") for (int m = 0; m < 4; ++m) _Pragma("unroll") for (int k = 0; k < 2; ++k) dst[m][k] = *(const LAS bf16x8*)(lds + PG8_SA(b, h) + aoff + m * 2048 + k * 1024); } while (0)
; #define PG8_LDB(dst, b, h) do { _Pragma("unroll") for (int n = 0; n < 2; ++n) _Pragma("unroll") for (int k = 0; k < 2; ++k) dst[n][k] = *(const LAS bf16x8*)(lds + PG8_SB(b, h) + boff + n * 2048 + k * 1024); } while (0)
; #define PG8_MMA(ai, bj, At, Bt) do { __builtin_amdgcn_s_setprio(1); _Pragma("unroll") for (int m = 0; m < 4; ++m) _Pragma("unroll") for (int n = 0; n < 2; ++n) _Pragma("unroll") for (int k = 0; k < 2; ++k) \
;         acc[ai][bj][m][n] = __builtin_amdgcn_mfma_f32_16x16x32_bf16(Bt[n][k], At[m][k], acc[ai][bj][m][n], 0, 0, 0); __builtin_amdgcn_s_setprio(0); } while (0)
; #define PG8_WAIT_V(n) asm volatile("s_waitcnt vmcnt(" #n ")" ::: "memory")
; #define PG8_WAIT_L(n) asm volatile("s_waitcnt lgkmcnt(" #n ")" ::: "memory")
; #define PG8_BAR __builtin_amdgcn_s_barrier()
; #define PG8_SCHED __builtin_amdgcn_sched_barrier(0)
; template <class Epi, class Sched, bool ALIGN_EPI = true, bool SP2 = true>
; __device__ __forceinline__ void gemm_phase(LAS unsigned char* lds, const Sched& S, const Epi& E, const int lda, const int ldb) {
;     ...
;             PG8_LDB(B0, 0, 0); PG8_LDB(B1, 0, 1); PG8_SCHED; PG8_LDA(At, 0, 0); PG8_STAGE(PG8_SA(1, 1), a1 + hstepA, voffA);
;             PG8_WAIT_V(8); PG8_WAIT_L(0); PG8_BAR; PG8_MMA(0, 0, At, B0); PG8_MMA(0, 1, At, B1); PG8_BAR; PG8_SCHED;
;             PG8_LDA(At, 0, 1); PG8_STAGE(PG8_SB(0, 0), b2, voffB); PG8_STAGE(PG8_SB(0, 1), b2 + hstepB, voffB); PG8_STAGE(PG8_SA(0, 0), a2, voffA);
;             PG8_WAIT_V(8); PG8_WAIT_L(0); PG8_BAR; PG8_MMA(1, 0, At, B0); PG8_MMA(1, 1, At, B1); PG8_BAR; PG8_SCHED;
.LBB0_343:
	s_add_u32 s26, s24, 0xfffc0080
	s_addc_u32 s27, s25, -1
	s_add_i32 s50, 0, 0x10000
	s_cmp_eq_u32 s82, 12
	s_cselect_b32 s37, s11, s27
	s_cselect_b32 s36, s10, s26
	v_add_u32_e32 v142, s50, v145
	s_cselect_b32 s27, s21, s81
	s_cselect_b32 s26, s20, s80
	s_add_i32 s54, 0, 0x14000
	ds_read_b128 v[148:151], v142
	ds_read_b128 v[152:155], v142 offset:1024
	ds_read_b128 v[156:159], v142 offset:2048
	ds_read_b128 v[160:163], v142 offset:3072
	v_add_u32_e32 v142, s54, v145
	ds_read_b128 v[164:167], v142
	ds_read_b128 v[168:171], v142 offset:1024
	ds_read_b128 v[172:175], v142 offset:2048
	ds_read_b128 v[176:179], v142 offset:3072
	v_lshl_add_u64 v[142:143], s[24:25], 0, v[138:139]
	s_add_i32 m0, s63, 0xc000
	ds_read_b128 v[180:183], v147
	ds_read_b128 v[184:187], v147 offset:1024
	ds_read_b128 v[188:191], v147 offset:2048
	ds_read_b128 v[192:195], v147 offset:3072
	ds_read_b128 v[212:215], v147 offset:4096
	ds_read_b128 v[216:219], v147 offset:5120
	ds_read_b128 v[220:223], v147 offset:6144
	ds_read_b128 v[224:227], v147 offset:7168
	global_load_lds_dwordx4 v[142:143], off
	v_lshl_add_u64 v[142:143], s[24:25], 0, v[140:141]
	s_add_i32 m0, s63, 0xe000
	s_nop 0
	global_load_lds_dwordx4 v[142:143], off
	s_waitcnt vmcnt(8)
	s_waitcnt lgkmcnt(0)
	s_barrier
	s_waitcnt lgkmcnt(0)
	v_mfma_f32_16x16x32_bf16 v[128:131], v[148:151], v[180:183], v[128:131]
	v_mfma_f32_16x16x32_bf16 v[124:127], v[156:159], v[180:183], v[124:127]
	v_mfma_f32_16x16x32_bf16 v[120:123], v[148:151], v[188:191], v[120:123]
	v_mfma_f32_16x16x32_bf16 v[110:113], v[156:159], v[188:191], v[110:113]
	v_mfma_f32_16x16x32_bf16 v[102:105], v[148:151], v[212:215], v[102:105]
	v_mfma_f32_16x16x32_bf16 v[94:97], v[156:159], v[212:215], v[94:97]
	v_mfma_f32_16x16x32_bf16 v[86:89], v[148:151], v[220:223], v[86:89]
	v_mfma_f32_16x16x32_bf16 v[78:81], v[156:159], v[220:223], v[78:81]
	v_mfma_f32_16x16x32_bf16 v[128:131], v[152:155], v[184:187], v[128:131]
	v_mfma_f32_16x16x32_bf16 v[124:127], v[160:163], v[184:187], v[124:127]
	v_mfma_f32_16x16x32_bf16 v[120:123], v[152:155], v[192:195], v[120:123]
	v_mfma_f32_16x16x32_bf16 v[110:113], v[160:163], v[192:195], v[110:113]
	v_mfma_f32_16x16x32_bf16 v[102:105], v[152:155], v[216:219], v[102:105]
	v_mfma_f32_16x16x32_bf16 v[94:97], v[160:163], v[216:219], v[94:97]
	v_mfma_f32_16x16x32_bf16 v[86:89], v[152:155], v[224:227], v[86:89]
	v_mfma_f32_16x16x32_bf16 v[78:81], v[160:163], v[224:227], v[78:81]
	v_mfma_f32_16x16x32_bf16 v[116:119], v[164:167], v[180:183], v[116:119]
	v_mfma_f32_16x16x32_bf16 v[106:109], v[172:175], v[180:183], v[106:109]
	v_mfma_f32_16x16x32_bf16 v[98:101], v[164:167], v[188:191], v[98:101]
	v_mfma_f32_16x16x32_bf16 v[90:93], v[172:175], v[188:191], v[90:93]
	v_mfma_f32_16x16x32_bf16 v[82:85], v[164:167], v[212:215], v[82:85]
	v_mfma_f32_16x16x32_bf16 v[74:77], v[172:175], v[212:215], v[74:77]
	v_mfma_f32_16x16x32_bf16 v[70:73], v[164:167], v[220:223], v[70:73]
	v_mfma_f32_16x16x32_bf16 v[66:69], v[172:175], v[220:223], v[66:69]
	v_mfma_f32_16x16x32_bf16 v[116:119], v[168:171], v[184:187], v[116:119]
	v_mfma_f32_16x16x32_bf16 v[106:109], v[176:179], v[184:187], v[106:109]
	v_mfma_f32_16x16x32_bf16 v[98:101], v[168:171], v[192:195], v[98:101]
	v_mfma_f32_16x16x32_bf16 v[90:93], v[176:179], v[192:195], v[90:93]
	v_mfma_f32_16x16x32_bf16 v[82:85], v[168:171], v[216:219], v[82:85]
	v_mfma_f32_16x16x32_bf16 v[74:77], v[176:179], v[216:219], v[74:77]
	v_mfma_f32_16x16x32_bf16 v[70:73], v[168:171], v[224:227], v[70:73]
	v_mfma_f32_16x16x32_bf16 v[66:69], v[176:179], v[224:227], v[66:69]
	s_barrier
	s_add_i32 s50, s50, s51
	v_lshl_add_u64 v[142:143], s[26:27], 0, v[114:115]
	s_mov_b32 m0, s50
	ds_read_b128 v[180:183], v147 offset:16384
	ds_read_b128 v[184:187], v147 offset:17408
	ds_read_b128 v[188:191], v147 offset:18432
	ds_read_b128 v[192:195], v147 offset:19456
	ds_read_b128 v[212:215], v147 offset:20480
	ds_read_b128 v[216:219], v147 offset:21504
	ds_read_b128 v[220:223], v147 offset:22528
	ds_read_b128 v[224:227], v147 offset:23552
	global_load_lds_dwordx4 v[142:143], off
	s_add_i32 m0, s50, 0x2000
	s_add_u32 s86, s26, 0x40000
	v_lshl_add_u64 v[196:197], s[26:27], 0, v[132:133]
	s_addc_u32 s87, s27, 0
	s_add_i32 s50, s54, s51
	global_load_lds_dwordx4 v[196:197], off
	v_lshl_add_u64 v[228:229], s[86:87], 0, v[114:115]
	s_mov_b32 m0, s50
	v_lshl_add_u64 v[230:231], s[36:37], 0, v[134:135]
	global_load_lds_dwordx4 v[228:229], off
	v_lshl_add_u64 v[228:229], s[86:87], 0, v[132:133]
	s_add_i32 m0, s50, 0x2000
	s_nop 0
	global_load_lds_dwordx4 v[228:229], off
	v_lshl_add_u64 v[228:229], s[36:37], 0, v[136:137]
	s_mov_b32 m0, s63
	s_nop 0
	global_load_lds_dwordx4 v[228:229], off
	s_mov_b32 m0, s72
	s_nop 0
	global_load_lds_dwordx4 v[230:231], off
	s_waitcnt vmcnt(8)
	s_waitcnt lgkmcnt(0)
	s_barrier
; #define PG8_STAGE(bufoff, gbase, voff) do { _Pragma("unroll") for (int _i = 0; _i < 2; ++_i) \
;         __builtin_amdgcn_global_load_lds((const unsigned*)((const char*)(gbase) + (voff)[_i]), (LAS unsigned*)(lds + (bufoff) + ldsw + _i * 8192), 16, 0, 0); } while (0)
; #define PG8_LDA(dst, b, h) do { _Pragma("unroll") for (int m = 0; m < 4; ++m) _Pragma("unroll") for (int k = 0; k < 2; ++k) dst[m][k] = *(const LAS bf16x8*)(lds + PG8_SA(b, h) + aoff + m * 2048 + k * 1024); } while (0)
; #define PG8_LDB(dst, b, h) do { _Pragma("unroll") for (int n = 0; n < 2; ++n) _Pragma("unroll") for (int k = 0; k < 2; ++k) dst[n][k] = *(const LAS bf16x8*)(lds + PG8_SB(b, h) + boff + n * 2048 + k * 1024); } while (0)
; #define PG8_MMA(ai, bj, At, Bt) do { __builtin_amdgcn_s_setprio(1); _Pragma("unroll") for (int m = 0; m < 4; ++m) _Pragma("unroll") for (int n = 0; n < 2; ++n) _Pragma("unroll") for (int k = 0; k < 2; ++k) \
;         acc[ai][bj][m][n] = __builtin_amdgcn_mfma_f32_16x16x32_bf16(Bt[n][k], At[m][k], acc[ai][bj][m][n], 0, 0, 0); __builtin_amdgcn_s_setprio(0); } while (0)
; #define PG8_WAIT_V(n) asm volatile("s_waitcnt vmcnt(" #n ")" ::: "memory")
; #define PG8_WAIT_L(n) asm volatile("s_waitcnt lgkmcnt(" #n ")" ::: "memory")
; #define PG8_BAR __builtin_amdgcn_s_barrier()
; #define PG8_SCHED __builtin_amdgcn_sched_barrier(0)
; template <class Epi, class Sched, bool ALIGN_EPI = true, bool SP2 = true>
; __device__ __forceinline__ void gemm_phase(LAS unsigned char* lds, const Sched& S, const Epi& E, const int lda, const int ldb) {
;     ...
;             PG8_WAIT_V(8); PG8_WAIT_L(0); PG8_BAR; PG8_MMA(1, 0, At, B0); PG8_MMA(1, 1, At, B1); PG8_BAR; PG8_SCHED;
;             PG8_LDB(B0, 1, 0); PG8_LDB(B1, 1, 1); PG8_SCHED; PG8_LDA(At, 1, 0); PG8_STAGE(PG8_SA(0, 1), a2 + hstepA, voffA);
;             PG8_WAIT_V(8); PG8_WAIT_L(0); PG8_BAR; PG8_MMA(0, 0, At, B0); PG8_MMA(0, 1, At, B1); PG8_BAR; PG8_SCHED;
	s_waitcnt lgkmcnt(0)
	v_mfma_f32_16x16x32_bf16 v[62:65], v[148:151], v[180:183], v[62:65]
	v_mfma_f32_16x16x32_bf16 v[58:61], v[156:159], v[180:183], v[58:61]
	v_mfma_f32_16x16x32_bf16 v[54:57], v[148:151], v[188:191], v[54:57]
	v_mfma_f32_16x16x32_bf16 v[46:49], v[156:159], v[188:191], v[46:49]
	v_mfma_f32_16x16x32_bf16 v[38:41], v[148:151], v[212:215], v[38:41]
	v_mfma_f32_16x16x32_bf16 v[30:33], v[156:159], v[212:215], v[30:33]
	v_mfma_f32_16x16x32_bf16 v[22:25], v[148:151], v[220:223], v[22:25]
	v_mfma_f32_16x16x32_bf16 v[14:17], v[156:159], v[220:223], v[14:17]
	v_mfma_f32_16x16x32_bf16 v[62:65], v[152:155], v[184:187], v[62:65]
	v_mfma_f32_16x16x32_bf16 v[58:61], v[160:163], v[184:187], v[58:61]
	v_mfma_f32_16x16x32_bf16 v[54:57], v[152:155], v[192:195], v[54:57]
	v_mfma_f32_16x16x32_bf16 v[46:49], v[160:163], v[192:195], v[46:49]
	v_mfma_f32_16x16x32_bf16 v[38:41], v[152:155], v[216:219], v[38:41]
	v_mfma_f32_16x16x32_bf16 v[30:33], v[160:163], v[216:219], v[30:33]
	v_mfma_f32_16x16x32_bf16 v[22:25], v[152:155], v[224:227], v[22:25]
	v_mfma_f32_16x16x32_bf16 v[14:17], v[160:163], v[224:227], v[14:17]
	v_mfma_f32_16x16x32_bf16 v[50:53], v[164:167], v[180:183], v[50:53]
	v_mfma_f32_16x16x32_bf16 v[42:45], v[172:175], v[180:183], v[42:45]
	v_mfma_f32_16x16x32_bf16 v[34:37], v[164:167], v[188:191], v[34:37]
	v_mfma_f32_16x16x32_bf16 v[26:29], v[172:175], v[188:191], v[26:29]
	v_mfma_f32_16x16x32_bf16 v[18:21], v[164:167], v[212:215], v[18:21]
	v_mfma_f32_16x16x32_bf16 v[10:13], v[172:175], v[212:215], v[10:13]
	v_mfma_f32_16x16x32_bf16 v[6:9], v[164:167], v[220:223], v[6:9]
	v_mfma_f32_16x16x32_bf16 v[2:5], v[172:175], v[220:223], v[2:5]
	v_mfma_f32_16x16x32_bf16 v[50:53], v[168:171], v[184:187], v[50:53]
	v_mfma_f32_16x16x32_bf16 v[42:45], v[176:179], v[184:187], v[42:45]
	v_mfma_f32_16x16x32_bf16 v[34:37], v[168:171], v[192:195], v[34:37]
	v_mfma_f32_16x16x32_bf16 v[26:29], v[176:179], v[192:195], v[26:29]
	v_mfma_f32_16x16x32_bf16 v[18:21], v[168:171], v[216:219], v[18:21]
	v_mfma_f32_16x16x32_bf16 v[10:13], v[176:179], v[216:219], v[10:13]
	v_mfma_f32_16x16x32_bf16 v[6:9], v[168:171], v[224:227], v[6:9]
	v_mfma_f32_16x16x32_bf16 v[2:5], v[176:179], v[224:227], v[2:5]
	s_barrier
	s_add_i32 s50, 0, 0x18000
	s_add_i32 s54, 0, 0x1c000
	v_add_u32_e32 v160, s50, v145
	v_add_u32_e32 v176, s54, v145
	ds_read_b128 v[148:151], v160
	ds_read_b128 v[152:155], v160 offset:1024
	ds_read_b128 v[156:159], v160 offset:2048
	ds_read_b128 v[160:163], v160 offset:3072
	ds_read_b128 v[164:167], v176
	ds_read_b128 v[168:171], v176 offset:1024
	ds_read_b128 v[172:175], v176 offset:2048
	ds_read_b128 v[176:179], v176 offset:3072
	s_add_u32 s36, s36, 0x40000
	s_addc_u32 s37, s37, 0
	s_mov_b32 m0, s33
	v_lshl_add_u64 v[232:233], s[36:37], 0, v[136:137]
	ds_read_b128 v[180:183], v147 offset:32768
	ds_read_b128 v[184:187], v147 offset:33792
	ds_read_b128 v[188:191], v147 offset:34816
	ds_read_b128 v[192:195], v147 offset:35840
	ds_read_b128 v[212:215], v147 offset:36864
	ds_read_b128 v[216:219], v147 offset:37888
	ds_read_b128 v[220:223], v147 offset:38912
	ds_read_b128 v[224:227], v147 offset:39936
	global_load_lds_dwordx4 v[232:233], off
	v_lshl_add_u64 v[232:233], s[36:37], 0, v[134:135]
	s_mov_b32 m0, s73
	s_nop 0
	global_load_lds_dwordx4 v[232:233], off
	s_waitcnt vmcnt(8)
	s_waitcnt lgkmcnt(0)
	s_barrier
	s_waitcnt lgkmcnt(0)
	v_mfma_f32_16x16x32_bf16 v[128:131], v[148:151], v[180:183], v[128:131]
	v_mfma_f32_16x16x32_bf16 v[124:127], v[156:159], v[180:183], v[124:127]
	v_mfma_f32_16x16x32_bf16 v[120:123], v[148:151], v[188:191], v[120:123]
	v_mfma_f32_16x16x32_bf16 v[110:113], v[156:159], v[188:191], v[110:113]
	v_mfma_f32_16x16x32_bf16 v[102:105], v[148:151], v[212:215], v[102:105]
	v_mfma_f32_16x16x32_bf16 v[94:97], v[156:159], v[212:215], v[94:97]
	v_mfma_f32_16x16x32_bf16 v[86:89], v[148:151], v[220:223], v[86:89]
	v_mfma_f32_16x16x32_bf16 v[78:81], v[156:159], v[220:223], v[78:81]
	v_mfma_f32_16x16x32_bf16 v[128:131], v[152:155], v[184:187], v[128:131]
	v_mfma_f32_16x16x32_bf16 v[124:127], v[160:163], v[184:187], v[124:127]
	v_mfma_f32_16x16x32_bf16 v[120:123], v[152:155], v[192:195], v[120:123]
	v_mfma_f32_16x16x32_bf16 v[110:113], v[160:163], v[192:195], v[110:113]
	v_mfma_f32_16x16x32_bf16 v[102:105], v[152:155], v[216:219], v[102:105]
	v_mfma_f32_16x16x32_bf16 v[94:97], v[160:163], v[216:219], v[94:97]
	v_mfma_f32_16x16x32_bf16 v[86:89], v[152:155], v[224:227], v[86:89]
	v_mfma_f32_16x16x32_bf16 v[78:81], v[160:163], v[224:227], v[78:81]
	v_mfma_f32_16x16x32_bf16 v[116:119], v[164:167], v[180:183], v[116:119]
	v_mfma_f32_16x16x32_bf16 v[106:109], v[172:175], v[180:183], v[106:109]
	v_mfma_f32_16x16x32_bf16 v[98:101], v[164:167], v[188:191], v[98:101]
	v_mfma_f32_16x16x32_bf16 v[90:93], v[172:175], v[188:191], v[90:93]
	v_mfma_f32_16x16x32_bf16 v[82:85], v[164:167], v[212:215], v[82:85]
	v_mfma_f32_16x16x32_bf16 v[74:77], v[172:175], v[212:215], v[74:77]
	v_mfma_f32_16x16x32_bf16 v[70:73], v[164:167], v[220:223], v[70:73]
	v_mfma_f32_16x16x32_bf16 v[66:69], v[172:175], v[220:223], v[66:69]
	v_mfma_f32_16x16x32_bf16 v[116:119], v[168:171], v[184:187], v[116:119]
	v_mfma_f32_16x16x32_bf16 v[106:109], v[176:179], v[184:187], v[106:109]
	v_mfma_f32_16x16x32_bf16 v[98:101], v[168:171], v[192:195], v[98:101]
	v_mfma_f32_16x16x32_bf16 v[90:93], v[176:179], v[192:195], v[90:93]
	v_mfma_f32_16x16x32_bf16 v[82:85], v[168:171], v[216:219], v[82:85]
	v_mfma_f32_16x16x32_bf16 v[74:77], v[176:179], v[216:219], v[74:77]
	v_mfma_f32_16x16x32_bf16 v[70:73], v[168:171], v[224:227], v[70:73]
	v_mfma_f32_16x16x32_bf16 v[66:69], v[176:179], v[224:227], v[66:69]
	s_barrier
; #define PG8_STAGE(bufoff, gbase, voff) do { _Pragma("unroll") for (int _i = 0; _i < 2; ++_i) \
;         __builtin_amdgcn_global_load_lds((const unsigned*)((const char*)(gbase) + (voff)[_i]), (LAS unsigned*)(lds + (bufoff) + ldsw + _i * 8192), 16, 0, 0); } while (0)
; #define PG8_LDA(dst, b, h) do { _Pragma("unroll") for (int m = 0; m < 4; ++m) _Pragma("unroll") for (int k = 0; k < 2; ++k) dst[m][k] = *(const LAS bf16x8*)(lds + PG8_SA(b, h) + aoff + m * 2048 + k * 1024); } while (0)
; #define PG8_MMA(ai, bj, At, Bt) do { __builtin_amdgcn_s_setprio(1); _Pragma("unroll") for (int m = 0; m < 4; ++m) _Pragma("unroll") for (int n = 0; n < 2; ++n) _Pragma("unroll") for (int k = 0; k < 2; ++k) \
;         acc[ai][bj][m][n] = __builtin_amdgcn_mfma_f32_16x16x32_bf16(Bt[n][k], At[m][k], acc[ai][bj][m][n], 0, 0, 0); __builtin_amdgcn_s_setprio(0); } while (0)
; #define PG8_WAIT_V(n) asm volatile("s_waitcnt vmcnt(" #n ")" ::: "memory")
; #define PG8_WAIT_L(n) asm volatile("s_waitcnt lgkmcnt(" #n ")" ::: "memory")
; #define PG8_BAR __builtin_amdgcn_s_barrier()
; #define PG8_SCHED __builtin_amdgcn_sched_barrier(0)
; template <class Epi, class Sched, bool ALIGN_EPI = true, bool SP2 = true>
; __device__ __forceinline__ void gemm_phase(LAS unsigned char* lds, const Sched& S, const Epi& E, const int lda, const int ldb) {
;     ...
;             PG8_LDA(At, 1, 1); PG8_STAGE(PG8_SB(1, 0), b3, voffB); PG8_STAGE(PG8_SB(1, 1), b3 + hstepB, voffB); PG8_STAGE(PG8_SA(1, 0), a3, voffA);
;             PG8_WAIT_V(8); PG8_WAIT_L(0); PG8_BAR; PG8_MMA(1, 0, At, B0); PG8_MMA(1, 1, At, B1); PG8_BAR; PG8_SCHED;
;     ...
;         if constexpr (ALIGN_EPI) { if (wr == 0) PG8_BAR; }
	s_add_i32 s36, s50, s51
	v_lshl_add_u64 v[142:143], v[142:143], 0, s[70:71]
	s_mov_b32 m0, s36
	ds_read_b128 v[180:183], v147 offset:49152
	ds_read_b128 v[184:187], v147 offset:50176
	ds_read_b128 v[188:191], v147 offset:51200
	ds_read_b128 v[192:195], v147 offset:52224
	ds_read_b128 v[212:215], v147 offset:53248
	ds_read_b128 v[216:219], v147 offset:54272
	ds_read_b128 v[220:223], v147 offset:55296
	ds_read_b128 v[224:227], v147 offset:56320
	global_load_lds_dwordx4 v[142:143], off
	s_add_i32 m0, s36, 0x2000
	s_add_u32 s26, s26, 0x40080
	v_lshl_add_u64 v[142:143], v[196:197], 0, s[70:71]
	s_addc_u32 s27, s27, 0
	s_add_i32 s36, s54, s51
	global_load_lds_dwordx4 v[142:143], off
	v_lshl_add_u64 v[142:143], s[26:27], 0, v[114:115]
	s_mov_b32 m0, s36
	s_nop 0
	global_load_lds_dwordx4 v[142:143], off
	v_lshl_add_u64 v[142:143], s[26:27], 0, v[132:133]
	s_add_i32 m0, s36, 0x2000
	s_nop 0
	global_load_lds_dwordx4 v[142:143], off
	v_lshl_add_u64 v[142:143], v[228:229], 0, s[70:71]
	s_mov_b32 m0, s74
	s_nop 0
	global_load_lds_dwordx4 v[142:143], off
	v_lshl_add_u64 v[142:143], v[230:231], 0, s[70:71]
	s_mov_b32 m0, s75
	s_nop 0
	global_load_lds_dwordx4 v[142:143], off
	s_waitcnt vmcnt(8)
	s_waitcnt lgkmcnt(0)
	s_barrier
	s_waitcnt lgkmcnt(0)
	v_mfma_f32_16x16x32_bf16 v[62:65], v[148:151], v[180:183], v[62:65]
	v_mfma_f32_16x16x32_bf16 v[58:61], v[156:159], v[180:183], v[58:61]
	v_mfma_f32_16x16x32_bf16 v[54:57], v[148:151], v[188:191], v[54:57]
	v_mfma_f32_16x16x32_bf16 v[46:49], v[156:159], v[188:191], v[46:49]
	v_mfma_f32_16x16x32_bf16 v[38:41], v[148:151], v[212:215], v[38:41]
	v_mfma_f32_16x16x32_bf16 v[30:33], v[156:159], v[212:215], v[30:33]
	v_mfma_f32_16x16x32_bf16 v[22:25], v[148:151], v[220:223], v[22:25]
	v_mfma_f32_16x16x32_bf16 v[14:17], v[156:159], v[220:223], v[14:17]
	v_mfma_f32_16x16x32_bf16 v[62:65], v[152:155], v[184:187], v[62:65]
	v_mfma_f32_16x16x32_bf16 v[58:61], v[160:163], v[184:187], v[58:61]
	v_mfma_f32_16x16x32_bf16 v[54:57], v[152:155], v[192:195], v[54:57]
	v_mfma_f32_16x16x32_bf16 v[46:49], v[160:163], v[192:195], v[46:49]
	v_mfma_f32_16x16x32_bf16 v[38:41], v[152:155], v[216:219], v[38:41]
	v_mfma_f32_16x16x32_bf16 v[30:33], v[160:163], v[216:219], v[30:33]
	v_mfma_f32_16x16x32_bf16 v[22:25], v[152:155], v[224:227], v[22:25]
	v_mfma_f32_16x16x32_bf16 v[14:17], v[160:163], v[224:227], v[14:17]
	v_mfma_f32_16x16x32_bf16 v[50:53], v[164:167], v[180:183], v[50:53]
	v_mfma_f32_16x16x32_bf16 v[42:45], v[172:175], v[180:183], v[42:45]
	v_mfma_f32_16x16x32_bf16 v[34:37], v[164:167], v[188:191], v[34:37]
	v_mfma_f32_16x16x32_bf16 v[26:29], v[172:175], v[188:191], v[26:29]
	v_mfma_f32_16x16x32_bf16 v[18:21], v[164:167], v[212:215], v[18:21]
	v_mfma_f32_16x16x32_bf16 v[10:13], v[172:175], v[212:215], v[10:13]
	v_mfma_f32_16x16x32_bf16 v[6:9], v[164:167], v[220:223], v[6:9]
	v_mfma_f32_16x16x32_bf16 v[2:5], v[172:175], v[220:223], v[2:5]
	v_mfma_f32_16x16x32_bf16 v[50:53], v[168:171], v[184:187], v[50:53]
	v_mfma_f32_16x16x32_bf16 v[42:45], v[176:179], v[184:187], v[42:45]
	v_mfma_f32_16x16x32_bf16 v[34:37], v[168:171], v[192:195], v[34:37]
	v_mfma_f32_16x16x32_bf16 v[26:29], v[176:179], v[192:195], v[26:29]
	v_mfma_f32_16x16x32_bf16 v[18:21], v[168:171], v[216:219], v[18:21]
	v_mfma_f32_16x16x32_bf16 v[10:13], v[176:179], v[216:219], v[10:13]
	v_mfma_f32_16x16x32_bf16 v[6:9], v[168:171], v[224:227], v[6:9]
	v_mfma_f32_16x16x32_bf16 v[2:5], v[176:179], v[224:227], v[2:5]
	s_barrier
	s_add_i32 s82, s82, 2
	s_add_u32 s24, s24, 0x100
	s_addc_u32 s25, s25, 0
	s_add_u32 s80, s80, 0x100
	s_addc_u32 s81, s81, 0
	s_cmp_gt_u32 s82, 13
	s_cbranch_scc0 .LBB0_343
	s_and_b64 vcc, exec, s[8:9]
	s_cbranch_vccz .LBB0_346
	s_barrier

; #define PG8_STAGE(bufoff, gbase, voff) do { _Pragma("unroll") for (int _i = 0; _i < 2; ++_i) \
;         __builtin_amdgcn_global_load_lds((const unsigned*)((const char*)(gbase) + (voff)[_i]), (LAS unsigned*)(lds + (bufoff) + ldsw + _i * 8192), 16, 0, 0); } while (0)
; #define PG8_LDA(dst, b, h) do { _Pragma("unroll") for (int m = 0; m < 4; ++m) _Pragma("unroll") for (int k = 0; k < 2; ++k) dst[m][k] = *(const LAS bf16x8*)(lds + PG8_SA(b, h) + aoff + m * 2048 + k * 1024); } while (0)
; #define PG8_LDB(dst, b, h) do { _Pragma("unroll") for (int n = 0; n < 2; ++n) _Pragma("unroll") for (int k = 0; k < 2; ++k) dst[n][k] = *(const LAS bf16x8*)(lds + PG8_SB(b, h) + boff + n * 2048 + k * 1024); } while (0)
; #define PG8_MMA(ai, bj, At, Bt) do { __builtin_amdgcn_s_setprio(1); _Pragma("unroll") for (int m = 0; m < 4; ++m) _Pragma("unroll") for (int n = 0; n < 2; ++n) _Pragma("unroll") for (int k = 0; k < 2; ++k) \
;         acc[ai][bj][m][n] = __builtin_amdgcn_mfma_f32_16x16x32_bf16(Bt[n][k], At[m][k], acc[ai][bj][m][n], 0, 0, 0); __builtin_amdgcn_s_setprio(0); } while (0)
; #define PG8_WAIT_V(n) asm volatile("s_waitcnt vmcnt(" #n ")" ::: "memory")
; #define PG8_WAIT_L(n) asm volatile("s_waitcnt lgkmcnt(" #n ")" ::: "memory")
; #define PG8_BAR __builtin_amdgcn_s_barrier()
; #define PG8_SCHED __builtin_amdgcn_sched_barrier(0)
; template <class Epi, class Sched, bool ALIGN_EPI = true, bool SP2 = true>
; __device__ __forceinline__ void gemm_phase(LAS unsigned char* lds, const Sched& S, const Epi& E, const int lda, const int ldb) {
;     ...
;             PG8_LDB(B0, 0, 0); PG8_LDB(B1, 0, 1); PG8_SCHED; PG8_LDA(At, 0, 0); PG8_STAGE(PG8_SA(1, 1), a1 + hstepA, voffA);
;             PG8_WAIT_V(8); PG8_WAIT_L(0); PG8_BAR; PG8_MMA(0, 0, At, B0); PG8_MMA(0, 1, At, B1); PG8_BAR; PG8_SCHED;
;             PG8_LDA(At, 0, 1); PG8_STAGE(PG8_SB(0, 0), b2, voffB); PG8_STAGE(PG8_SB(0, 1), b2 + hstepB, voffB); PG8_STAGE(PG8_SA(0, 0), a2, voffA);
;             PG8_WAIT_V(8); PG8_WAIT_L(0); PG8_BAR; PG8_MMA(1, 0, At, B0); PG8_MMA(1, 1, At, B1); PG8_BAR; PG8_SCHED;
.LBB0_362:
	s_add_u32 s6, s0, 0xfff00080
	s_addc_u32 s7, s1, -1
	s_add_i32 s50, 0, 0x10000
	s_cmp_eq_u32 s33, 60
	s_cselect_b32 s27, s23, s7
	s_cselect_b32 s26, s22, s6
	s_cselect_b32 s7, s25, s30
	s_cselect_b32 s6, s24, s28
	s_add_i32 s54, 0, 0x14000
	v_add_u32_e32 v158, s50, v147
	v_add_u32_e32 v174, s54, v147
	ds_read_b128 v[142:145], v158
	ds_read_b128 v[150:153], v158 offset:1024
	ds_read_b128 v[154:157], v158 offset:2048
	ds_read_b128 v[158:161], v158 offset:3072
	ds_read_b128 v[162:165], v174
	ds_read_b128 v[166:169], v174 offset:1024
	ds_read_b128 v[170:173], v174 offset:2048
	ds_read_b128 v[174:177], v174 offset:3072
	v_lshl_add_u64 v[224:225], s[0:1], 0, v[138:139]
	s_add_i32 m0, s41, 0xc000
	ds_read_b128 v[178:181], v149
	ds_read_b128 v[182:185], v149 offset:1024
	ds_read_b128 v[186:189], v149 offset:2048
	ds_read_b128 v[190:193], v149 offset:3072
	ds_read_b128 v[194:197], v149 offset:4096
	ds_read_b128 v[212:215], v149 offset:5120
	ds_read_b128 v[216:219], v149 offset:6144
	ds_read_b128 v[220:223], v149 offset:7168
	global_load_lds_dwordx4 v[224:225], off
	v_lshl_add_u64 v[224:225], s[0:1], 0, v[140:141]
	s_add_i32 m0, s41, 0xe000
	s_nop 0
	global_load_lds_dwordx4 v[224:225], off
	s_waitcnt vmcnt(8)
	s_waitcnt lgkmcnt(0)
	s_barrier
	s_waitcnt lgkmcnt(0)
	v_mfma_f32_16x16x32_bf16 v[128:131], v[142:145], v[178:181], v[128:131]
	v_mfma_f32_16x16x32_bf16 v[124:127], v[154:157], v[178:181], v[124:127]
	v_mfma_f32_16x16x32_bf16 v[110:113], v[142:145], v[186:189], v[110:113]
	v_mfma_f32_16x16x32_bf16 v[106:109], v[154:157], v[186:189], v[106:109]
	v_mfma_f32_16x16x32_bf16 v[94:97], v[142:145], v[194:197], v[94:97]
	v_mfma_f32_16x16x32_bf16 v[90:93], v[154:157], v[194:197], v[90:93]
	v_mfma_f32_16x16x32_bf16 v[78:81], v[142:145], v[216:219], v[78:81]
	v_mfma_f32_16x16x32_bf16 v[74:77], v[154:157], v[216:219], v[74:77]
	v_mfma_f32_16x16x32_bf16 v[128:131], v[150:153], v[182:185], v[128:131]
	v_mfma_f32_16x16x32_bf16 v[124:127], v[158:161], v[182:185], v[124:127]
	v_mfma_f32_16x16x32_bf16 v[110:113], v[150:153], v[190:193], v[110:113]
	v_mfma_f32_16x16x32_bf16 v[106:109], v[158:161], v[190:193], v[106:109]
	v_mfma_f32_16x16x32_bf16 v[94:97], v[150:153], v[212:215], v[94:97]
	v_mfma_f32_16x16x32_bf16 v[90:93], v[158:161], v[212:215], v[90:93]
	v_mfma_f32_16x16x32_bf16 v[78:81], v[150:153], v[220:223], v[78:81]
	v_mfma_f32_16x16x32_bf16 v[74:77], v[158:161], v[220:223], v[74:77]
	v_mfma_f32_16x16x32_bf16 v[120:123], v[162:165], v[178:181], v[120:123]
	v_mfma_f32_16x16x32_bf16 v[116:119], v[170:173], v[178:181], v[116:119]
	v_mfma_f32_16x16x32_bf16 v[102:105], v[162:165], v[186:189], v[102:105]
	v_mfma_f32_16x16x32_bf16 v[98:101], v[170:173], v[186:189], v[98:101]
	v_mfma_f32_16x16x32_bf16 v[86:89], v[162:165], v[194:197], v[86:89]
	v_mfma_f32_16x16x32_bf16 v[82:85], v[170:173], v[194:197], v[82:85]
	v_mfma_f32_16x16x32_bf16 v[70:73], v[162:165], v[216:219], v[70:73]
	v_mfma_f32_16x16x32_bf16 v[66:69], v[170:173], v[216:219], v[66:69]
	v_mfma_f32_16x16x32_bf16 v[120:123], v[166:169], v[182:185], v[120:123]
	v_mfma_f32_16x16x32_bf16 v[116:119], v[174:177], v[182:185], v[116:119]
	v_mfma_f32_16x16x32_bf16 v[102:105], v[166:169], v[190:193], v[102:105]
	v_mfma_f32_16x16x32_bf16 v[98:101], v[174:177], v[190:193], v[98:101]
	v_mfma_f32_16x16x32_bf16 v[86:89], v[166:169], v[212:215], v[86:89]
	v_mfma_f32_16x16x32_bf16 v[82:85], v[174:177], v[212:215], v[82:85]
	v_mfma_f32_16x16x32_bf16 v[70:73], v[166:169], v[220:223], v[70:73]
	v_mfma_f32_16x16x32_bf16 v[66:69], v[174:177], v[220:223], v[66:69]
	s_barrier
	s_add_i32 s50, s50, s40
	v_lshl_add_u64 v[224:225], s[6:7], 0, v[114:115]
	s_mov_b32 m0, s50
	ds_read_b128 v[178:181], v149 offset:16384
	ds_read_b128 v[182:185], v149 offset:17408
	ds_read_b128 v[186:189], v149 offset:18432
	ds_read_b128 v[190:193], v149 offset:19456
	ds_read_b128 v[194:197], v149 offset:20480
	ds_read_b128 v[212:215], v149 offset:21504
	ds_read_b128 v[216:219], v149 offset:22528
	ds_read_b128 v[220:223], v149 offset:23552
	global_load_lds_dwordx4 v[224:225], off
	s_add_i32 m0, s50, 0x2000
	s_add_u32 s74, s6, 0x100000
	v_lshl_add_u64 v[226:227], s[6:7], 0, v[136:137]
	s_addc_u32 s75, s7, 0
	s_add_i32 s50, s54, s40
	global_load_lds_dwordx4 v[226:227], off
	v_lshl_add_u64 v[228:229], s[74:75], 0, v[114:115]
	s_mov_b32 m0, s50
	v_lshl_add_u64 v[230:231], s[26:27], 0, v[134:135]
	global_load_lds_dwordx4 v[228:229], off
	v_lshl_add_u64 v[228:229], s[74:75], 0, v[136:137]
	s_add_i32 m0, s50, 0x2000
	s_nop 0
	global_load_lds_dwordx4 v[228:229], off
	v_lshl_add_u64 v[228:229], s[26:27], 0, v[132:133]
	s_mov_b32 m0, s41
	s_nop 0
	global_load_lds_dwordx4 v[228:229], off
	s_mov_b32 m0, s48
	s_nop 0
	global_load_lds_dwordx4 v[230:231], off
	s_waitcnt vmcnt(8)
	s_waitcnt lgkmcnt(0)
	s_barrier
; #define PG8_STAGE(bufoff, gbase, voff) do { _Pragma("unroll") for (int _i = 0; _i < 2; ++_i) \
;         __builtin_amdgcn_global_load_lds((const unsigned*)((const char*)(gbase) + (voff)[_i]), (LAS unsigned*)(lds + (bufoff) + ldsw + _i * 8192), 16, 0, 0); } while (0)
; #define PG8_LDA(dst, b, h) do { _Pragma("unroll") for (int m = 0; m < 4; ++m) _Pragma("unroll") for (int k = 0; k < 2; ++k) dst[m][k] = *(const LAS bf16x8*)(lds + PG8_SA(b, h) + aoff + m * 2048 + k * 1024); } while (0)
; #define PG8_LDB(dst, b, h) do { _Pragma("unroll") for (int n = 0; n < 2; ++n) _Pragma("unroll") for (int k = 0; k < 2; ++k) dst[n][k] = *(const LAS bf16x8*)(lds + PG8_SB(b, h) + boff + n * 2048 + k * 1024); } while (0)
; #define PG8_MMA(ai, bj, At, Bt) do { __builtin_amdgcn_s_setprio(1); _Pragma("unroll") for (int m = 0; m < 4; ++m) _Pragma("unroll") for (int n = 0; n < 2; ++n) _Pragma("unroll") for (int k = 0; k < 2; ++k) \
;         acc[ai][bj][m][n] = __builtin_amdgcn_mfma_f32_16x16x32_bf16(Bt[n][k], At[m][k], acc[ai][bj][m][n], 0, 0, 0); __builtin_amdgcn_s_setprio(0); } while (0)
; #define PG8_WAIT_V(n) asm volatile("s_waitcnt vmcnt(" #n ")" ::: "memory")
; #define PG8_WAIT_L(n) asm volatile("s_waitcnt lgkmcnt(" #n ")" ::: "memory")
; #define PG8_BAR __builtin_amdgcn_s_barrier()
; #define PG8_SCHED __builtin_amdgcn_sched_barrier(0)
; template <class Epi, class Sched, bool ALIGN_EPI = true, bool SP2 = true>
; __device__ __forceinline__ void gemm_phase(LAS unsigned char* lds, const Sched& S, const Epi& E, const int lda, const int ldb) {
;     ...
;             PG8_WAIT_V(8); PG8_WAIT_L(0); PG8_BAR; PG8_MMA(1, 0, At, B0); PG8_MMA(1, 1, At, B1); PG8_BAR; PG8_SCHED;
;             PG8_LDB(B0, 1, 0); PG8_LDB(B1, 1, 1); PG8_SCHED; PG8_LDA(At, 1, 0); PG8_STAGE(PG8_SA(0, 1), a2 + hstepA, voffA);
;             PG8_WAIT_V(8); PG8_WAIT_L(0); PG8_BAR; PG8_MMA(0, 0, At, B0); PG8_MMA(0, 1, At, B1); PG8_BAR; PG8_SCHED;
	s_waitcnt lgkmcnt(0)
	v_mfma_f32_16x16x32_bf16 v[62:65], v[142:145], v[178:181], v[62:65]
	v_mfma_f32_16x16x32_bf16 v[58:61], v[154:157], v[178:181], v[58:61]
	v_mfma_f32_16x16x32_bf16 v[46:49], v[142:145], v[186:189], v[46:49]
	v_mfma_f32_16x16x32_bf16 v[42:45], v[154:157], v[186:189], v[42:45]
	v_mfma_f32_16x16x32_bf16 v[30:33], v[142:145], v[194:197], v[30:33]
	v_mfma_f32_16x16x32_bf16 v[26:29], v[154:157], v[194:197], v[26:29]
	v_mfma_f32_16x16x32_bf16 v[14:17], v[142:145], v[216:219], v[14:17]
	v_mfma_f32_16x16x32_bf16 v[10:13], v[154:157], v[216:219], v[10:13]
	v_mfma_f32_16x16x32_bf16 v[62:65], v[150:153], v[182:185], v[62:65]
	v_mfma_f32_16x16x32_bf16 v[58:61], v[158:161], v[182:185], v[58:61]
	v_mfma_f32_16x16x32_bf16 v[46:49], v[150:153], v[190:193], v[46:49]
	v_mfma_f32_16x16x32_bf16 v[42:45], v[158:161], v[190:193], v[42:45]
	v_mfma_f32_16x16x32_bf16 v[30:33], v[150:153], v[212:215], v[30:33]
	v_mfma_f32_16x16x32_bf16 v[26:29], v[158:161], v[212:215], v[26:29]
	v_mfma_f32_16x16x32_bf16 v[14:17], v[150:153], v[220:223], v[14:17]
	v_mfma_f32_16x16x32_bf16 v[10:13], v[158:161], v[220:223], v[10:13]
	v_mfma_f32_16x16x32_bf16 v[54:57], v[162:165], v[178:181], v[54:57]
	v_mfma_f32_16x16x32_bf16 v[50:53], v[170:173], v[178:181], v[50:53]
	v_mfma_f32_16x16x32_bf16 v[38:41], v[162:165], v[186:189], v[38:41]
	v_mfma_f32_16x16x32_bf16 v[34:37], v[170:173], v[186:189], v[34:37]
	v_mfma_f32_16x16x32_bf16 v[22:25], v[162:165], v[194:197], v[22:25]
	v_mfma_f32_16x16x32_bf16 v[18:21], v[170:173], v[194:197], v[18:21]
	v_mfma_f32_16x16x32_bf16 v[6:9], v[162:165], v[216:219], v[6:9]
	v_mfma_f32_16x16x32_bf16 v[2:5], v[170:173], v[216:219], v[2:5]
	v_mfma_f32_16x16x32_bf16 v[54:57], v[166:169], v[182:185], v[54:57]
	v_mfma_f32_16x16x32_bf16 v[50:53], v[174:177], v[182:185], v[50:53]
	v_mfma_f32_16x16x32_bf16 v[38:41], v[166:169], v[190:193], v[38:41]
	v_mfma_f32_16x16x32_bf16 v[34:37], v[174:177], v[190:193], v[34:37]
	v_mfma_f32_16x16x32_bf16 v[22:25], v[166:169], v[212:215], v[22:25]
	v_mfma_f32_16x16x32_bf16 v[18:21], v[174:177], v[212:215], v[18:21]
	v_mfma_f32_16x16x32_bf16 v[6:9], v[166:169], v[220:223], v[6:9]
	v_mfma_f32_16x16x32_bf16 v[2:5], v[174:177], v[220:223], v[2:5]
	s_barrier
	s_add_i32 s50, 0, 0x18000
	s_add_i32 s54, 0, 0x1c000
	v_add_u32_e32 v158, s50, v147
	v_add_u32_e32 v174, s54, v147
	ds_read_b128 v[142:145], v158
	ds_read_b128 v[150:153], v158 offset:1024
	ds_read_b128 v[154:157], v158 offset:2048
	ds_read_b128 v[158:161], v158 offset:3072
	ds_read_b128 v[162:165], v174
	ds_read_b128 v[166:169], v174 offset:1024
	ds_read_b128 v[170:173], v174 offset:2048
	ds_read_b128 v[174:177], v174 offset:3072
	s_add_u32 s26, s26, 0x100000
	s_addc_u32 s27, s27, 0
	s_mov_b32 m0, s49
	v_lshl_add_u64 v[232:233], s[26:27], 0, v[132:133]
	ds_read_b128 v[178:181], v149 offset:32768
	ds_read_b128 v[182:185], v149 offset:33792
	ds_read_b128 v[186:189], v149 offset:34816
	ds_read_b128 v[190:193], v149 offset:35840
	ds_read_b128 v[194:197], v149 offset:36864
	ds_read_b128 v[212:215], v149 offset:37888
	ds_read_b128 v[216:219], v149 offset:38912
	ds_read_b128 v[220:223], v149 offset:39936
	global_load_lds_dwordx4 v[232:233], off
	v_lshl_add_u64 v[232:233], s[26:27], 0, v[134:135]
	s_mov_b32 m0, s51
	s_nop 0
	global_load_lds_dwordx4 v[232:233], off
	s_waitcnt vmcnt(8)
	s_waitcnt lgkmcnt(0)
	s_barrier
	s_waitcnt lgkmcnt(0)
	v_mfma_f32_16x16x32_bf16 v[128:131], v[142:145], v[178:181], v[128:131]
	v_mfma_f32_16x16x32_bf16 v[124:127], v[154:157], v[178:181], v[124:127]
	v_mfma_f32_16x16x32_bf16 v[110:113], v[142:145], v[186:189], v[110:113]
	v_mfma_f32_16x16x32_bf16 v[106:109], v[154:157], v[186:189], v[106:109]
	v_mfma_f32_16x16x32_bf16 v[94:97], v[142:145], v[194:197], v[94:97]
	v_mfma_f32_16x16x32_bf16 v[90:93], v[154:157], v[194:197], v[90:93]
	v_mfma_f32_16x16x32_bf16 v[78:81], v[142:145], v[216:219], v[78:81]
	v_mfma_f32_16x16x32_bf16 v[74:77], v[154:157], v[216:219], v[74:77]
	v_mfma_f32_16x16x32_bf16 v[128:131], v[150:153], v[182:185], v[128:131]
	v_mfma_f32_16x16x32_bf16 v[124:127], v[158:161], v[182:185], v[124:127]
	v_mfma_f32_16x16x32_bf16 v[110:113], v[150:153], v[190:193], v[110:113]
	v_mfma_f32_16x16x32_bf16 v[106:109], v[158:161], v[190:193], v[106:109]
	v_mfma_f32_16x16x32_bf16 v[94:97], v[150:153], v[212:215], v[94:97]
	v_mfma_f32_16x16x32_bf16 v[90:93], v[158:161], v[212:215], v[90:93]
	v_mfma_f32_16x16x32_bf16 v[78:81], v[150:153], v[220:223], v[78:81]
	v_mfma_f32_16x16x32_bf16 v[74:77], v[158:161], v[220:223], v[74:77]
	v_mfma_f32_16x16x32_bf16 v[120:123], v[162:165], v[178:181], v[120:123]
	v_mfma_f32_16x16x32_bf16 v[116:119], v[170:173], v[178:181], v[116:119]
	v_mfma_f32_16x16x32_bf16 v[102:105], v[162:165], v[186:189], v[102:105]
	v_mfma_f32_16x16x32_bf16 v[98:101], v[170:173], v[186:189], v[98:101]
	v_mfma_f32_16x16x32_bf16 v[86:89], v[162:165], v[194:197], v[86:89]
	v_mfma_f32_16x16x32_bf16 v[82:85], v[170:173], v[194:197], v[82:85]
	v_mfma_f32_16x16x32_bf16 v[70:73], v[162:165], v[216:219], v[70:73]
	v_mfma_f32_16x16x32_bf16 v[66:69], v[170:173], v[216:219], v[66:69]
	v_mfma_f32_16x16x32_bf16 v[120:123], v[166:169], v[182:185], v[120:123]
	v_mfma_f32_16x16x32_bf16 v[116:119], v[174:177], v[182:185], v[116:119]
	v_mfma_f32_16x16x32_bf16 v[102:105], v[166:169], v[190:193], v[102:105]
	v_mfma_f32_16x16x32_bf16 v[98:101], v[174:177], v[190:193], v[98:101]
	v_mfma_f32_16x16x32_bf16 v[86:89], v[166:169], v[212:215], v[86:89]
	v_mfma_f32_16x16x32_bf16 v[82:85], v[174:177], v[212:215], v[82:85]
	v_mfma_f32_16x16x32_bf16 v[70:73], v[166:169], v[220:223], v[70:73]
	v_mfma_f32_16x16x32_bf16 v[66:69], v[174:177], v[220:223], v[66:69]
	s_barrier
; #define PG8_STAGE(bufoff, gbase, voff) do { _Pragma("unroll") for (int _i = 0; _i < 2; ++_i) \
;         __builtin_amdgcn_global_load_lds((const unsigned*)((const char*)(gbase) + (voff)[_i]), (LAS unsigned*)(lds + (bufoff) + ldsw + _i * 8192), 16, 0, 0); } while (0)
; #define PG8_LDA(dst, b, h) do { _Pragma("unroll") for (int m = 0; m < 4; ++m) _Pragma("unroll") for (int k = 0; k < 2; ++k) dst[m][k] = *(const LAS bf16x8*)(lds + PG8_SA(b, h) + aoff + m * 2048 + k * 1024); } while (0)
; #define PG8_MMA(ai, bj, At, Bt) do { __builtin_amdgcn_s_setprio(1); _Pragma("unroll") for (int m = 0; m < 4; ++m) _Pragma("unroll") for (int n = 0; n < 2; ++n) _Pragma("unroll") for (int k = 0; k < 2; ++k) \
;         acc[ai][bj][m][n] = __builtin_amdgcn_mfma_f32_16x16x32_bf16(Bt[n][k], At[m][k], acc[ai][bj][m][n], 0, 0, 0); __builtin_amdgcn_s_setprio(0); } while (0)
; #define PG8_WAIT_V(n) asm volatile("s_waitcnt vmcnt(" #n ")" ::: "memory")
; #define PG8_WAIT_L(n) asm volatile("s_waitcnt lgkmcnt(" #n ")" ::: "memory")
; #define PG8_BAR __builtin_amdgcn_s_barrier()
; #define PG8_SCHED __builtin_amdgcn_sched_barrier(0)
; template <class Epi, class Sched, bool ALIGN_EPI = true, bool SP2 = true>
; __device__ __forceinline__ void gemm_phase(LAS unsigned char* lds, const Sched& S, const Epi& E, const int lda, const int ldb) {
;     ...
;             PG8_LDA(At, 1, 1); PG8_STAGE(PG8_SB(1, 0), b3, voffB); PG8_STAGE(PG8_SB(1, 1), b3 + hstepB, voffB); PG8_STAGE(PG8_SA(1, 0), a3, voffA);
;             PG8_WAIT_V(8); PG8_WAIT_L(0); PG8_BAR; PG8_MMA(1, 0, At, B0); PG8_MMA(1, 1, At, B1); PG8_BAR; PG8_SCHED;
;     ...
;         if constexpr (ALIGN_EPI) { if (wr == 0) PG8_BAR; }
	s_add_i32 s26, s50, s40
	v_lshl_add_u64 v[224:225], v[224:225], 0, s[70:71]
	s_mov_b32 m0, s26
	ds_read_b128 v[178:181], v149 offset:49152
	ds_read_b128 v[182:185], v149 offset:50176
	ds_read_b128 v[186:189], v149 offset:51200
	ds_read_b128 v[190:193], v149 offset:52224
	ds_read_b128 v[194:197], v149 offset:53248
	ds_read_b128 v[212:215], v149 offset:54272
	ds_read_b128 v[216:219], v149 offset:55296
	ds_read_b128 v[220:223], v149 offset:56320
	global_load_lds_dwordx4 v[224:225], off
	s_add_i32 m0, s26, 0x2000
	s_add_u32 s6, s6, 0x100080
	v_lshl_add_u64 v[224:225], v[226:227], 0, s[70:71]
	s_addc_u32 s7, s7, 0
	s_add_i32 s26, s54, s40
	global_load_lds_dwordx4 v[224:225], off
	v_lshl_add_u64 v[224:225], s[6:7], 0, v[114:115]
	s_mov_b32 m0, s26
	s_nop 0
	global_load_lds_dwordx4 v[224:225], off
	v_lshl_add_u64 v[224:225], s[6:7], 0, v[136:137]
	s_add_i32 m0, s26, 0x2000
	s_nop 0
	global_load_lds_dwordx4 v[224:225], off
	v_lshl_add_u64 v[224:225], v[228:229], 0, s[70:71]
	s_mov_b32 m0, s57
	s_nop 0
	global_load_lds_dwordx4 v[224:225], off
	v_lshl_add_u64 v[224:225], v[230:231], 0, s[70:71]
	s_mov_b32 m0, s62
	s_nop 0
	global_load_lds_dwordx4 v[224:225], off
	s_waitcnt vmcnt(8)
	s_waitcnt lgkmcnt(0)
	s_barrier
	s_waitcnt lgkmcnt(0)
	v_mfma_f32_16x16x32_bf16 v[62:65], v[142:145], v[178:181], v[62:65]
	v_mfma_f32_16x16x32_bf16 v[58:61], v[154:157], v[178:181], v[58:61]
	v_mfma_f32_16x16x32_bf16 v[46:49], v[142:145], v[186:189], v[46:49]
	v_mfma_f32_16x16x32_bf16 v[42:45], v[154:157], v[186:189], v[42:45]
	v_mfma_f32_16x16x32_bf16 v[30:33], v[142:145], v[194:197], v[30:33]
	v_mfma_f32_16x16x32_bf16 v[26:29], v[154:157], v[194:197], v[26:29]
	v_mfma_f32_16x16x32_bf16 v[14:17], v[142:145], v[216:219], v[14:17]
	v_mfma_f32_16x16x32_bf16 v[10:13], v[154:157], v[216:219], v[10:13]
	v_mfma_f32_16x16x32_bf16 v[62:65], v[150:153], v[182:185], v[62:65]
	v_mfma_f32_16x16x32_bf16 v[58:61], v[158:161], v[182:185], v[58:61]
	v_mfma_f32_16x16x32_bf16 v[46:49], v[150:153], v[190:193], v[46:49]
	v_mfma_f32_16x16x32_bf16 v[42:45], v[158:161], v[190:193], v[42:45]
	v_mfma_f32_16x16x32_bf16 v[30:33], v[150:153], v[212:215], v[30:33]
	v_mfma_f32_16x16x32_bf16 v[26:29], v[158:161], v[212:215], v[26:29]
	v_mfma_f32_16x16x32_bf16 v[14:17], v[150:153], v[220:223], v[14:17]
	v_mfma_f32_16x16x32_bf16 v[10:13], v[158:161], v[220:223], v[10:13]
	v_mfma_f32_16x16x32_bf16 v[54:57], v[162:165], v[178:181], v[54:57]
	v_mfma_f32_16x16x32_bf16 v[50:53], v[170:173], v[178:181], v[50:53]
	v_mfma_f32_16x16x32_bf16 v[38:41], v[162:165], v[186:189], v[38:41]
	v_mfma_f32_16x16x32_bf16 v[34:37], v[170:173], v[186:189], v[34:37]
	v_mfma_f32_16x16x32_bf16 v[22:25], v[162:165], v[194:197], v[22:25]
	v_mfma_f32_16x16x32_bf16 v[18:21], v[170:173], v[194:197], v[18:21]
	v_mfma_f32_16x16x32_bf16 v[6:9], v[162:165], v[216:219], v[6:9]
	v_mfma_f32_16x16x32_bf16 v[2:5], v[170:173], v[216:219], v[2:5]
	v_mfma_f32_16x16x32_bf16 v[54:57], v[166:169], v[182:185], v[54:57]
	v_mfma_f32_16x16x32_bf16 v[50:53], v[174:177], v[182:185], v[50:53]
	v_mfma_f32_16x16x32_bf16 v[38:41], v[166:169], v[190:193], v[38:41]
	v_mfma_f32_16x16x32_bf16 v[34:37], v[174:177], v[190:193], v[34:37]
	v_mfma_f32_16x16x32_bf16 v[22:25], v[166:169], v[212:215], v[22:25]
	v_mfma_f32_16x16x32_bf16 v[18:21], v[174:177], v[212:215], v[18:21]
	v_mfma_f32_16x16x32_bf16 v[6:9], v[166:169], v[220:223], v[6:9]
	v_mfma_f32_16x16x32_bf16 v[2:5], v[174:177], v[220:223], v[2:5]
	s_barrier
	s_add_i32 s33, s33, 2
	s_add_u32 s0, s0, 0x100
	s_addc_u32 s1, s1, 0
	s_add_u32 s28, s28, 0x100
	s_addc_u32 s30, s30, 0
	s_cmp_gt_u32 s33, 61
	s_cbranch_scc0 .LBB0_362
	s_and_b64 vcc, exec, s[10:11]
	s_cbranch_vccz .LBB0_365
	s_barrier

; #define PG8_STAGE(bufoff, gbase, voff) do { _Pragma("unroll") for (int _i = 0; _i < 2; ++_i) \
;         __builtin_amdgcn_global_load_lds((const unsigned*)((const char*)(gbase) + (voff)[_i]), (LAS unsigned*)(lds + (bufoff) + ldsw + _i * 8192), 16, 0, 0); } while (0)
; #define PG8_LDA(dst, b, h) do { _Pragma("unroll") for (int m = 0; m < 4; ++m) _Pragma("unroll") for (int k = 0; k < 2; ++k) dst[m][k] = *(const LAS bf16x8*)(lds + PG8_SA(b, h) + aoff + m * 2048 + k * 1024); } while (0)
; #define PG8_LDB(dst, b, h) do { _Pragma("unroll") for (int n = 0; n < 2; ++n) _Pragma("unroll") for (int k = 0; k < 2; ++k) dst[n][k] = *(const LAS bf16x8*)(lds + PG8_SB(b, h) + boff + n * 2048 + k * 1024); } while (0)
; #define PG8_MMA(ai, bj, At, Bt) do { __builtin_amdgcn_s_setprio(1); _Pragma("unroll") for (int m = 0; m < 4; ++m) _Pragma("unroll") for (int n = 0; n < 2; ++n) _Pragma("unroll") for (int k = 0; k < 2; ++k) \
;         acc[ai][bj][m][n] = __builtin_amdgcn_mfma_f32_16x16x32_bf16(Bt[n][k], At[m][k], acc[ai][bj][m][n], 0, 0, 0); __builtin_amdgcn_s_setprio(0); } while (0)
; #define PG8_WAIT_V(n) asm volatile("s_waitcnt vmcnt(" #n ")" ::: "memory")
; #define PG8_WAIT_L(n) asm volatile("s_waitcnt lgkmcnt(" #n ")" ::: "memory")
; #define PG8_BAR __builtin_amdgcn_s_barrier()
; #define PG8_SCHED __builtin_amdgcn_sched_barrier(0)
; template <class Epi, class Sched, bool ALIGN_EPI = true, bool SP2 = true>
; __device__ __forceinline__ void gemm_phase(LAS unsigned char* lds, const Sched& S, const Epi& E, const int lda, const int ldb) {
;     ...
;             PG8_LDB(B0, 0, 0); PG8_LDB(B1, 0, 1); PG8_SCHED; PG8_LDA(At, 0, 0); PG8_STAGE(PG8_SA(1, 1), a1 + hstepA, voffA);
;             PG8_WAIT_V(8); PG8_WAIT_L(0); PG8_BAR; PG8_MMA(0, 0, At, B0); PG8_MMA(0, 1, At, B1); PG8_BAR; PG8_SCHED;
;             PG8_LDA(At, 0, 1); PG8_STAGE(PG8_SB(0, 0), b2, voffB); PG8_STAGE(PG8_SB(0, 1), b2 + hstepB, voffB); PG8_STAGE(PG8_SA(0, 0), a2, voffA);
;             PG8_WAIT_V(8); PG8_WAIT_L(0); PG8_BAR; PG8_MMA(1, 0, At, B0); PG8_MMA(1, 1, At, B1); PG8_BAR; PG8_SCHED;
.LBB0_619:
	s_add_u32 s26, s24, 0xfffe0080
	s_addc_u32 s27, s25, -1
	s_add_i32 s50, 0, 0x10000
	s_cmp_eq_u32 s76, 4
	s_cselect_b32 s37, s21, s27
	s_cselect_b32 s36, s20, s26
	v_add_u32_e32 v142, s50, v145
	s_cselect_b32 s27, s23, s75
	s_cselect_b32 s26, s22, s74
	s_add_i32 s54, 0, 0x14000
	ds_read_b128 v[148:151], v142
	ds_read_b128 v[152:155], v142 offset:1024
	ds_read_b128 v[156:159], v142 offset:2048
	ds_read_b128 v[160:163], v142 offset:3072
	v_add_u32_e32 v142, s54, v145
	ds_read_b128 v[164:167], v142
	ds_read_b128 v[168:171], v142 offset:1024
	ds_read_b128 v[172:175], v142 offset:2048
	ds_read_b128 v[176:179], v142 offset:3072
	v_lshl_add_u64 v[142:143], s[24:25], 0, v[138:139]
	s_add_i32 m0, s48, 0xc000
	ds_read_b128 v[180:183], v147
	ds_read_b128 v[184:187], v147 offset:1024
	ds_read_b128 v[188:191], v147 offset:2048
	ds_read_b128 v[192:195], v147 offset:3072
	ds_read_b128 v[212:215], v147 offset:4096
	ds_read_b128 v[216:219], v147 offset:5120
	ds_read_b128 v[220:223], v147 offset:6144
	ds_read_b128 v[224:227], v147 offset:7168
	global_load_lds_dwordx4 v[142:143], off
	v_lshl_add_u64 v[142:143], s[24:25], 0, v[140:141]
	s_add_i32 m0, s48, 0xe000
	s_nop 0
	global_load_lds_dwordx4 v[142:143], off
	s_waitcnt vmcnt(8)
	s_waitcnt lgkmcnt(0)
	s_barrier
	s_waitcnt lgkmcnt(0)
	v_mfma_f32_16x16x32_bf16 v[128:131], v[148:151], v[180:183], v[128:131]
	v_mfma_f32_16x16x32_bf16 v[124:127], v[156:159], v[180:183], v[124:127]
	v_mfma_f32_16x16x32_bf16 v[120:123], v[148:151], v[188:191], v[120:123]
	v_mfma_f32_16x16x32_bf16 v[110:113], v[156:159], v[188:191], v[110:113]
	v_mfma_f32_16x16x32_bf16 v[102:105], v[148:151], v[212:215], v[102:105]
	v_mfma_f32_16x16x32_bf16 v[94:97], v[156:159], v[212:215], v[94:97]
	v_mfma_f32_16x16x32_bf16 v[86:89], v[148:151], v[220:223], v[86:89]
	v_mfma_f32_16x16x32_bf16 v[78:81], v[156:159], v[220:223], v[78:81]
	v_mfma_f32_16x16x32_bf16 v[128:131], v[152:155], v[184:187], v[128:131]
	v_mfma_f32_16x16x32_bf16 v[124:127], v[160:163], v[184:187], v[124:127]
	v_mfma_f32_16x16x32_bf16 v[120:123], v[152:155], v[192:195], v[120:123]
	v_mfma_f32_16x16x32_bf16 v[110:113], v[160:163], v[192:195], v[110:113]
	v_mfma_f32_16x16x32_bf16 v[102:105], v[152:155], v[216:219], v[102:105]
	v_mfma_f32_16x16x32_bf16 v[94:97], v[160:163], v[216:219], v[94:97]
	v_mfma_f32_16x16x32_bf16 v[86:89], v[152:155], v[224:227], v[86:89]
	v_mfma_f32_16x16x32_bf16 v[78:81], v[160:163], v[224:227], v[78:81]
	v_mfma_f32_16x16x32_bf16 v[116:119], v[164:167], v[180:183], v[116:119]
	v_mfma_f32_16x16x32_bf16 v[106:109], v[172:175], v[180:183], v[106:109]
	v_mfma_f32_16x16x32_bf16 v[98:101], v[164:167], v[188:191], v[98:101]
	v_mfma_f32_16x16x32_bf16 v[90:93], v[172:175], v[188:191], v[90:93]
	v_mfma_f32_16x16x32_bf16 v[82:85], v[164:167], v[212:215], v[82:85]
	v_mfma_f32_16x16x32_bf16 v[74:77], v[172:175], v[212:215], v[74:77]
	v_mfma_f32_16x16x32_bf16 v[70:73], v[164:167], v[220:223], v[70:73]
	v_mfma_f32_16x16x32_bf16 v[66:69], v[172:175], v[220:223], v[66:69]
	v_mfma_f32_16x16x32_bf16 v[116:119], v[168:171], v[184:187], v[116:119]
	v_mfma_f32_16x16x32_bf16 v[106:109], v[176:179], v[184:187], v[106:109]
	v_mfma_f32_16x16x32_bf16 v[98:101], v[168:171], v[192:195], v[98:101]
	v_mfma_f32_16x16x32_bf16 v[90:93], v[176:179], v[192:195], v[90:93]
	v_mfma_f32_16x16x32_bf16 v[82:85], v[168:171], v[216:219], v[82:85]
	v_mfma_f32_16x16x32_bf16 v[74:77], v[176:179], v[216:219], v[74:77]
	v_mfma_f32_16x16x32_bf16 v[70:73], v[168:171], v[224:227], v[70:73]
	v_mfma_f32_16x16x32_bf16 v[66:69], v[176:179], v[224:227], v[66:69]
	s_barrier
	s_add_i32 s50, s50, s39
	v_lshl_add_u64 v[142:143], s[26:27], 0, v[114:115]
	s_mov_b32 m0, s50
	ds_read_b128 v[180:183], v147 offset:16384
	ds_read_b128 v[184:187], v147 offset:17408
	ds_read_b128 v[188:191], v147 offset:18432
	ds_read_b128 v[192:195], v147 offset:19456
	ds_read_b128 v[212:215], v147 offset:20480
	ds_read_b128 v[216:219], v147 offset:21504
	ds_read_b128 v[220:223], v147 offset:22528
	ds_read_b128 v[224:227], v147 offset:23552
	global_load_lds_dwordx4 v[142:143], off
	s_add_i32 m0, s50, 0x2000
	s_add_u32 s78, s26, 0x20000
	v_lshl_add_u64 v[196:197], s[26:27], 0, v[132:133]
	s_addc_u32 s79, s27, 0
	s_add_i32 s50, s54, s39
	global_load_lds_dwordx4 v[196:197], off
	v_lshl_add_u64 v[228:229], s[78:79], 0, v[114:115]
	s_mov_b32 m0, s50
	v_lshl_add_u64 v[230:231], s[36:37], 0, v[134:135]
	global_load_lds_dwordx4 v[228:229], off
	v_lshl_add_u64 v[228:229], s[78:79], 0, v[132:133]
	s_add_i32 m0, s50, 0x2000
	s_nop 0
	global_load_lds_dwordx4 v[228:229], off
	v_lshl_add_u64 v[228:229], s[36:37], 0, v[136:137]
	s_mov_b32 m0, s48
	s_nop 0
	global_load_lds_dwordx4 v[228:229], off
	s_mov_b32 m0, s49
	s_nop 0
	global_load_lds_dwordx4 v[230:231], off
	s_waitcnt vmcnt(8)
	s_waitcnt lgkmcnt(0)
	s_barrier
; #define PG8_STAGE(bufoff, gbase, voff) do { _Pragma("unroll") for (int _i = 0; _i < 2; ++_i) \
;         __builtin_amdgcn_global_load_lds((const unsigned*)((const char*)(gbase) + (voff)[_i]), (LAS unsigned*)(lds + (bufoff) + ldsw + _i * 8192), 16, 0, 0); } while (0)
; #define PG8_LDA(dst, b, h) do { _Pragma("unroll") for (int m = 0; m < 4; ++m) _Pragma("unroll") for (int k = 0; k < 2; ++k) dst[m][k] = *(const LAS bf16x8*)(lds + PG8_SA(b, h) + aoff + m * 2048 + k * 1024); } while (0)
; #define PG8_LDB(dst, b, h) do { _Pragma("unroll") for (int n = 0; n < 2; ++n) _Pragma("unroll") for (int k = 0; k < 2; ++k) dst[n][k] = *(const LAS bf16x8*)(lds + PG8_SB(b, h) + boff + n * 2048 + k * 1024); } while (0)
; #define PG8_MMA(ai, bj, At, Bt) do { __builtin_amdgcn_s_setprio(1); _Pragma("unroll") for (int m = 0; m < 4; ++m) _Pragma("unroll") for (int n = 0; n < 2; ++n) _Pragma("unroll") for (int k = 0; k < 2; ++k) \
;         acc[ai][bj][m][n] = __builtin_amdgcn_mfma_f32_16x16x32_bf16(Bt[n][k], At[m][k], acc[ai][bj][m][n], 0, 0, 0); __builtin_amdgcn_s_setprio(0); } while (0)
; #define PG8_WAIT_V(n) asm volatile("s_waitcnt vmcnt(" #n ")" ::: "memory")
; #define PG8_WAIT_L(n) asm volatile("s_waitcnt lgkmcnt(" #n ")" ::: "memory")
; #define PG8_BAR __builtin_amdgcn_s_barrier()
; #define PG8_SCHED __builtin_amdgcn_sched_barrier(0)
; template <class Epi, class Sched, bool ALIGN_EPI = true, bool SP2 = true>
; __device__ __forceinline__ void gemm_phase(LAS unsigned char* lds, const Sched& S, const Epi& E, const int lda, const int ldb) {
;     ...
;             PG8_WAIT_V(8); PG8_WAIT_L(0); PG8_BAR; PG8_MMA(1, 0, At, B0); PG8_MMA(1, 1, At, B1); PG8_BAR; PG8_SCHED;
;             PG8_LDB(B0, 1, 0); PG8_LDB(B1, 1, 1); PG8_SCHED; PG8_LDA(At, 1, 0); PG8_STAGE(PG8_SA(0, 1), a2 + hstepA, voffA);
;             PG8_WAIT_V(8); PG8_WAIT_L(0); PG8_BAR; PG8_MMA(0, 0, At, B0); PG8_MMA(0, 1, At, B1); PG8_BAR; PG8_SCHED;
	s_waitcnt lgkmcnt(0)
	v_mfma_f32_16x16x32_bf16 v[62:65], v[148:151], v[180:183], v[62:65]
	v_mfma_f32_16x16x32_bf16 v[58:61], v[156:159], v[180:183], v[58:61]
	v_mfma_f32_16x16x32_bf16 v[54:57], v[148:151], v[188:191], v[54:57]
	v_mfma_f32_16x16x32_bf16 v[46:49], v[156:159], v[188:191], v[46:49]
	v_mfma_f32_16x16x32_bf16 v[38:41], v[148:151], v[212:215], v[38:41]
	v_mfma_f32_16x16x32_bf16 v[30:33], v[156:159], v[212:215], v[30:33]
	v_mfma_f32_16x16x32_bf16 v[22:25], v[148:151], v[220:223], v[22:25]
	v_mfma_f32_16x16x32_bf16 v[14:17], v[156:159], v[220:223], v[14:17]
	v_mfma_f32_16x16x32_bf16 v[62:65], v[152:155], v[184:187], v[62:65]
	v_mfma_f32_16x16x32_bf16 v[58:61], v[160:163], v[184:187], v[58:61]
	v_mfma_f32_16x16x32_bf16 v[54:57], v[152:155], v[192:195], v[54:57]
	v_mfma_f32_16x16x32_bf16 v[46:49], v[160:163], v[192:195], v[46:49]
	v_mfma_f32_16x16x32_bf16 v[38:41], v[152:155], v[216:219], v[38:41]
	v_mfma_f32_16x16x32_bf16 v[30:33], v[160:163], v[216:219], v[30:33]
	v_mfma_f32_16x16x32_bf16 v[22:25], v[152:155], v[224:227], v[22:25]
	v_mfma_f32_16x16x32_bf16 v[14:17], v[160:163], v[224:227], v[14:17]
	v_mfma_f32_16x16x32_bf16 v[50:53], v[164:167], v[180:183], v[50:53]
	v_mfma_f32_16x16x32_bf16 v[42:45], v[172:175], v[180:183], v[42:45]
	v_mfma_f32_16x16x32_bf16 v[34:37], v[164:167], v[188:191], v[34:37]
	v_mfma_f32_16x16x32_bf16 v[26:29], v[172:175], v[188:191], v[26:29]
	v_mfma_f32_16x16x32_bf16 v[18:21], v[164:167], v[212:215], v[18:21]
	v_mfma_f32_16x16x32_bf16 v[10:13], v[172:175], v[212:215], v[10:13]
	v_mfma_f32_16x16x32_bf16 v[6:9], v[164:167], v[220:223], v[6:9]
	v_mfma_f32_16x16x32_bf16 v[2:5], v[172:175], v[220:223], v[2:5]
	v_mfma_f32_16x16x32_bf16 v[50:53], v[168:171], v[184:187], v[50:53]
	v_mfma_f32_16x16x32_bf16 v[42:45], v[176:179], v[184:187], v[42:45]
	v_mfma_f32_16x16x32_bf16 v[34:37], v[168:171], v[192:195], v[34:37]
	v_mfma_f32_16x16x32_bf16 v[26:29], v[176:179], v[192:195], v[26:29]
	v_mfma_f32_16x16x32_bf16 v[18:21], v[168:171], v[216:219], v[18:21]
	v_mfma_f32_16x16x32_bf16 v[10:13], v[176:179], v[216:219], v[10:13]
	v_mfma_f32_16x16x32_bf16 v[6:9], v[168:171], v[224:227], v[6:9]
	v_mfma_f32_16x16x32_bf16 v[2:5], v[176:179], v[224:227], v[2:5]
	s_barrier
	s_add_i32 s50, 0, 0x18000
	s_add_i32 s54, 0, 0x1c000
	v_add_u32_e32 v160, s50, v145
	v_add_u32_e32 v176, s54, v145
	ds_read_b128 v[148:151], v160
	ds_read_b128 v[152:155], v160 offset:1024
	ds_read_b128 v[156:159], v160 offset:2048
	ds_read_b128 v[160:163], v160 offset:3072
	ds_read_b128 v[164:167], v176
	ds_read_b128 v[168:171], v176 offset:1024
	ds_read_b128 v[172:175], v176 offset:2048
	ds_read_b128 v[176:179], v176 offset:3072
	s_add_u32 s36, s36, 0x20000
	s_addc_u32 s37, s37, 0
	s_mov_b32 m0, s51
	v_lshl_add_u64 v[232:233], s[36:37], 0, v[136:137]
	ds_read_b128 v[180:183], v147 offset:32768
	ds_read_b128 v[184:187], v147 offset:33792
	ds_read_b128 v[188:191], v147 offset:34816
	ds_read_b128 v[192:195], v147 offset:35840
	ds_read_b128 v[212:215], v147 offset:36864
	ds_read_b128 v[216:219], v147 offset:37888
	ds_read_b128 v[220:223], v147 offset:38912
	ds_read_b128 v[224:227], v147 offset:39936
	global_load_lds_dwordx4 v[232:233], off
	v_lshl_add_u64 v[232:233], s[36:37], 0, v[134:135]
	s_mov_b32 m0, s52
	s_nop 0
	global_load_lds_dwordx4 v[232:233], off
	s_waitcnt vmcnt(8)
	s_waitcnt lgkmcnt(0)
	s_barrier
	s_waitcnt lgkmcnt(0)
	v_mfma_f32_16x16x32_bf16 v[128:131], v[148:151], v[180:183], v[128:131]
	v_mfma_f32_16x16x32_bf16 v[124:127], v[156:159], v[180:183], v[124:127]
	v_mfma_f32_16x16x32_bf16 v[120:123], v[148:151], v[188:191], v[120:123]
	v_mfma_f32_16x16x32_bf16 v[110:113], v[156:159], v[188:191], v[110:113]
	v_mfma_f32_16x16x32_bf16 v[102:105], v[148:151], v[212:215], v[102:105]
	v_mfma_f32_16x16x32_bf16 v[94:97], v[156:159], v[212:215], v[94:97]
	v_mfma_f32_16x16x32_bf16 v[86:89], v[148:151], v[220:223], v[86:89]
	v_mfma_f32_16x16x32_bf16 v[78:81], v[156:159], v[220:223], v[78:81]
	v_mfma_f32_16x16x32_bf16 v[128:131], v[152:155], v[184:187], v[128:131]
	v_mfma_f32_16x16x32_bf16 v[124:127], v[160:163], v[184:187], v[124:127]
	v_mfma_f32_16x16x32_bf16 v[120:123], v[152:155], v[192:195], v[120:123]
	v_mfma_f32_16x16x32_bf16 v[110:113], v[160:163], v[192:195], v[110:113]
	v_mfma_f32_16x16x32_bf16 v[102:105], v[152:155], v[216:219], v[102:105]
	v_mfma_f32_16x16x32_bf16 v[94:97], v[160:163], v[216:219], v[94:97]
	v_mfma_f32_16x16x32_bf16 v[86:89], v[152:155], v[224:227], v[86:89]
	v_mfma_f32_16x16x32_bf16 v[78:81], v[160:163], v[224:227], v[78:81]
	v_mfma_f32_16x16x32_bf16 v[116:119], v[164:167], v[180:183], v[116:119]
	v_mfma_f32_16x16x32_bf16 v[106:109], v[172:175], v[180:183], v[106:109]
	v_mfma_f32_16x16x32_bf16 v[98:101], v[164:167], v[188:191], v[98:101]
	v_mfma_f32_16x16x32_bf16 v[90:93], v[172:175], v[188:191], v[90:93]
	v_mfma_f32_16x16x32_bf16 v[82:85], v[164:167], v[212:215], v[82:85]
	v_mfma_f32_16x16x32_bf16 v[74:77], v[172:175], v[212:215], v[74:77]
	v_mfma_f32_16x16x32_bf16 v[70:73], v[164:167], v[220:223], v[70:73]
	v_mfma_f32_16x16x32_bf16 v[66:69], v[172:175], v[220:223], v[66:69]
	v_mfma_f32_16x16x32_bf16 v[116:119], v[168:171], v[184:187], v[116:119]
	v_mfma_f32_16x16x32_bf16 v[106:109], v[176:179], v[184:187], v[106:109]
	v_mfma_f32_16x16x32_bf16 v[98:101], v[168:171], v[192:195], v[98:101]
	v_mfma_f32_16x16x32_bf16 v[90:93], v[176:179], v[192:195], v[90:93]
	v_mfma_f32_16x16x32_bf16 v[82:85], v[168:171], v[216:219], v[82:85]
	v_mfma_f32_16x16x32_bf16 v[74:77], v[176:179], v[216:219], v[74:77]
	v_mfma_f32_16x16x32_bf16 v[70:73], v[168:171], v[224:227], v[70:73]
	v_mfma_f32_16x16x32_bf16 v[66:69], v[176:179], v[224:227], v[66:69]
	s_barrier
; #define PG8_STAGE(bufoff, gbase, voff) do { _Pragma("unroll") for (int _i = 0; _i < 2; ++_i) \
;         __builtin_amdgcn_global_load_lds((const unsigned*)((const char*)(gbase) + (voff)[_i]), (LAS unsigned*)(lds + (bufoff) + ldsw + _i * 8192), 16, 0, 0); } while (0)
; #define PG8_LDA(dst, b, h) do { _Pragma("unroll") for (int m = 0; m < 4; ++m) _Pragma("unroll") for (int k = 0; k < 2; ++k) dst[m][k] = *(const LAS bf16x8*)(lds + PG8_SA(b, h) + aoff + m * 2048 + k * 1024); } while (0)
; #define PG8_MMA(ai, bj, At, Bt) do { __builtin_amdgcn_s_setprio(1); _Pragma("unroll") for (int m = 0; m < 4; ++m) _Pragma("unroll") for (int n = 0; n < 2; ++n) _Pragma("unroll") for (int k = 0; k < 2; ++k) \
;         acc[ai][bj][m][n] = __builtin_amdgcn_mfma_f32_16x16x32_bf16(Bt[n][k], At[m][k], acc[ai][bj][m][n], 0, 0, 0); __builtin_amdgcn_s_setprio(0); } while (0)
; #define PG8_WAIT_V(n) asm volatile("s_waitcnt vmcnt(" #n ")" ::: "memory")
; #define PG8_WAIT_L(n) asm volatile("s_waitcnt lgkmcnt(" #n ")" ::: "memory")
; #define PG8_BAR __builtin_amdgcn_s_barrier()
; #define PG8_SCHED __builtin_amdgcn_sched_barrier(0)
; template <class Epi, class Sched, bool ALIGN_EPI = true, bool SP2 = true>
; __device__ __forceinline__ void gemm_phase(LAS unsigned char* lds, const Sched& S, const Epi& E, const int lda, const int ldb) {
;     ...
;             PG8_LDA(At, 1, 1); PG8_STAGE(PG8_SB(1, 0), b3, voffB); PG8_STAGE(PG8_SB(1, 1), b3 + hstepB, voffB); PG8_STAGE(PG8_SA(1, 0), a3, voffA);
;             PG8_WAIT_V(8); PG8_WAIT_L(0); PG8_BAR; PG8_MMA(1, 0, At, B0); PG8_MMA(1, 1, At, B1); PG8_BAR; PG8_SCHED;
;     ...
;         if constexpr (ALIGN_EPI) { if (wr == 0) PG8_BAR; }
	s_add_i32 s36, s50, s39
	v_lshl_add_u64 v[142:143], v[142:143], 0, s[70:71]
	s_mov_b32 m0, s36
	ds_read_b128 v[180:183], v147 offset:49152
	ds_read_b128 v[184:187], v147 offset:50176
	ds_read_b128 v[188:191], v147 offset:51200
	ds_read_b128 v[192:195], v147 offset:52224
	ds_read_b128 v[212:215], v147 offset:53248
	ds_read_b128 v[216:219], v147 offset:54272
	ds_read_b128 v[220:223], v147 offset:55296
	ds_read_b128 v[224:227], v147 offset:56320
	global_load_lds_dwordx4 v[142:143], off
	s_add_i32 m0, s36, 0x2000
	s_add_u32 s26, s26, 0x20080
	v_lshl_add_u64 v[142:143], v[196:197], 0, s[70:71]
	s_addc_u32 s27, s27, 0
	s_add_i32 s36, s54, s39
	global_load_lds_dwordx4 v[142:143], off
	v_lshl_add_u64 v[142:143], s[26:27], 0, v[114:115]
	s_mov_b32 m0, s36
	s_nop 0
	global_load_lds_dwordx4 v[142:143], off
	v_lshl_add_u64 v[142:143], s[26:27], 0, v[132:133]
	s_add_i32 m0, s36, 0x2000
	s_nop 0
	global_load_lds_dwordx4 v[142:143], off
	v_lshl_add_u64 v[142:143], v[228:229], 0, s[70:71]
	s_mov_b32 m0, s33
	s_nop 0
	global_load_lds_dwordx4 v[142:143], off
	v_lshl_add_u64 v[142:143], v[230:231], 0, s[70:71]
	s_mov_b32 m0, s57
	s_nop 0
	global_load_lds_dwordx4 v[142:143], off
	s_waitcnt vmcnt(8)
	s_waitcnt lgkmcnt(0)
	s_barrier
	s_waitcnt lgkmcnt(0)
	v_mfma_f32_16x16x32_bf16 v[62:65], v[148:151], v[180:183], v[62:65]
	v_mfma_f32_16x16x32_bf16 v[58:61], v[156:159], v[180:183], v[58:61]
	v_mfma_f32_16x16x32_bf16 v[54:57], v[148:151], v[188:191], v[54:57]
	v_mfma_f32_16x16x32_bf16 v[46:49], v[156:159], v[188:191], v[46:49]
	v_mfma_f32_16x16x32_bf16 v[38:41], v[148:151], v[212:215], v[38:41]
	v_mfma_f32_16x16x32_bf16 v[30:33], v[156:159], v[212:215], v[30:33]
	v_mfma_f32_16x16x32_bf16 v[22:25], v[148:151], v[220:223], v[22:25]
	v_mfma_f32_16x16x32_bf16 v[14:17], v[156:159], v[220:223], v[14:17]
	v_mfma_f32_16x16x32_bf16 v[62:65], v[152:155], v[184:187], v[62:65]
	v_mfma_f32_16x16x32_bf16 v[58:61], v[160:163], v[184:187], v[58:61]
	v_mfma_f32_16x16x32_bf16 v[54:57], v[152:155], v[192:195], v[54:57]
	v_mfma_f32_16x16x32_bf16 v[46:49], v[160:163], v[192:195], v[46:49]
	v_mfma_f32_16x16x32_bf16 v[38:41], v[152:155], v[216:219], v[38:41]
	v_mfma_f32_16x16x32_bf16 v[30:33], v[160:163], v[216:219], v[30:33]
	v_mfma_f32_16x16x32_bf16 v[22:25], v[152:155], v[224:227], v[22:25]
	v_mfma_f32_16x16x32_bf16 v[14:17], v[160:163], v[224:227], v[14:17]
	v_mfma_f32_16x16x32_bf16 v[50:53], v[164:167], v[180:183], v[50:53]
	v_mfma_f32_16x16x32_bf16 v[42:45], v[172:175], v[180:183], v[42:45]
	v_mfma_f32_16x16x32_bf16 v[34:37], v[164:167], v[188:191], v[34:37]
	v_mfma_f32_16x16x32_bf16 v[26:29], v[172:175], v[188:191], v[26:29]
	v_mfma_f32_16x16x32_bf16 v[18:21], v[164:167], v[212:215], v[18:21]
	v_mfma_f32_16x16x32_bf16 v[10:13], v[172:175], v[212:215], v[10:13]
	v_mfma_f32_16x16x32_bf16 v[6:9], v[164:167], v[220:223], v[6:9]
	v_mfma_f32_16x16x32_bf16 v[2:5], v[172:175], v[220:223], v[2:5]
	v_mfma_f32_16x16x32_bf16 v[50:53], v[168:171], v[184:187], v[50:53]
	v_mfma_f32_16x16x32_bf16 v[42:45], v[176:179], v[184:187], v[42:45]
	v_mfma_f32_16x16x32_bf16 v[34:37], v[168:171], v[192:195], v[34:37]
	v_mfma_f32_16x16x32_bf16 v[26:29], v[176:179], v[192:195], v[26:29]
	v_mfma_f32_16x16x32_bf16 v[18:21], v[168:171], v[216:219], v[18:21]
	v_mfma_f32_16x16x32_bf16 v[10:13], v[176:179], v[216:219], v[10:13]
	v_mfma_f32_16x16x32_bf16 v[6:9], v[168:171], v[224:227], v[6:9]
	v_mfma_f32_16x16x32_bf16 v[2:5], v[176:179], v[224:227], v[2:5]
	s_barrier
	s_add_i32 s76, s76, 2
	s_add_u32 s24, s24, 0x100
	s_addc_u32 s25, s25, 0
	s_add_u32 s74, s74, 0x100
	s_addc_u32 s75, s75, 0
	s_cmp_gt_u32 s76, 5
	s_cbranch_scc0 .LBB0_619
	s_and_b64 vcc, exec, s[18:19]
	s_cbranch_vccz .LBB0_622
	s_barrier

; #define PG8_STAGE(bufoff, gbase, voff) do { _Pragma("unroll") for (int _i = 0; _i < 2; ++_i) \
;         __builtin_amdgcn_global_load_lds((const unsigned*)((const char*)(gbase) + (voff)[_i]), (LAS unsigned*)(lds + (bufoff) + ldsw + _i * 8192), 16, 0, 0); } while (0)
; #define PG8_LDA(dst, b, h) do { _Pragma("unroll") for (int m = 0; m < 4; ++m) _Pragma("unroll") for (int k = 0; k < 2; ++k) dst[m][k] = *(const LAS bf16x8*)(lds + PG8_SA(b, h) + aoff + m * 2048 + k * 1024); } while (0)
; #define PG8_LDB(dst, b, h) do { _Pragma("unroll") for (int n = 0; n < 2; ++n) _Pragma("unroll") for (int k = 0; k < 2; ++k) dst[n][k] = *(const LAS bf16x8*)(lds + PG8_SB(b, h) + boff + n * 2048 + k * 1024); } while (0)
; #define PG8_MMA(ai, bj, At, Bt) do { __builtin_amdgcn_s_setprio(1); _Pragma("unroll") for (int m = 0; m < 4; ++m) _Pragma("unroll") for (int n = 0; n < 2; ++n) _Pragma("unroll") for (int k = 0; k < 2; ++k) \
;         acc[ai][bj][m][n] = __builtin_amdgcn_mfma_f32_16x16x32_bf16(Bt[n][k], At[m][k], acc[ai][bj][m][n], 0, 0, 0); __builtin_amdgcn_s_setprio(0); } while (0)
; #define PG8_WAIT_V(n) asm volatile("s_waitcnt vmcnt(" #n ")" ::: "memory")
; #define PG8_WAIT_L(n) asm volatile("s_waitcnt lgkmcnt(" #n ")" ::: "memory")
; #define PG8_BAR __builtin_amdgcn_s_barrier()
; #define PG8_SCHED __builtin_amdgcn_sched_barrier(0)
; template <class Epi, class Sched, bool ALIGN_EPI = true, bool SP2 = true>
; __device__ __forceinline__ void gemm_phase(LAS unsigned char* lds, const Sched& S, const Epi& E, const int lda, const int ldb) {
;     ...
;             const bool last = (t == nt - 2);
;             const char* a1 = cA + (size_t)(t + 1) * kstep;
;             const char* a2 = last ? nA : cA + (size_t)(t + 2) * kstep; const char* b2 = last ? nB : cB + (size_t)(t + 2) * kstep;
;             const char* a3 = a2 + kstep; const char* b3 = b2 + kstep;
;             if constexpr (SP2) {
;             PG8_LDB(B0, 0, 0); PG8_LDB(B1, 0, 1); PG8_SCHED; PG8_LDA(At, 0, 0); PG8_STAGE(PG8_SA(1, 1), a1 + hstepA, voffA);
;             PG8_WAIT_V(8); PG8_WAIT_L(0); PG8_BAR; PG8_MMA(0, 0, At, B0); PG8_MMA(0, 1, At, B1); PG8_BAR; PG8_SCHED;
;             PG8_LDA(At, 0, 1); PG8_STAGE(PG8_SB(0, 0), b2, voffB); PG8_STAGE(PG8_SB(0, 1), b2 + hstepB, voffB); PG8_STAGE(PG8_SA(0, 0), a2, voffA);
.LBB0_635:
	s_add_u32 s26, s24, 0x100
	s_addc_u32 s27, s25, 0
	s_add_i32 s54, 0, 0x10000
	s_cmp_eq_u32 s50, 8
	s_cselect_b32 s39, s21, s27
	s_cselect_b32 s38, s20, s26
	s_cselect_b32 s37, s23, vcc_lo
	s_cselect_b32 s36, s22, s87
	s_add_i32 s55, 0, 0x14000
	v_add_u32_e32 v158, s54, v147
	v_add_u32_e32 v174, s55, v147
	ds_read_b128 v[142:145], v158
	ds_read_b128 v[150:153], v158 offset:1024
	ds_read_b128 v[154:157], v158 offset:2048
	ds_read_b128 v[158:161], v158 offset:3072
	ds_read_b128 v[162:165], v174
	ds_read_b128 v[166:169], v174 offset:1024
	ds_read_b128 v[170:173], v174 offset:2048
	ds_read_b128 v[174:177], v174 offset:3072
	v_lshl_add_u64 v[224:225], s[24:25], 0, v[138:139]
	s_add_i32 m0, s75, 0xc000
	ds_read_b128 v[178:181], v149
	ds_read_b128 v[182:185], v149 offset:1024
	ds_read_b128 v[186:189], v149 offset:2048
	ds_read_b128 v[190:193], v149 offset:3072
	ds_read_b128 v[194:197], v149 offset:4096
	ds_read_b128 v[212:215], v149 offset:5120
	ds_read_b128 v[216:219], v149 offset:6144
	ds_read_b128 v[220:223], v149 offset:7168
	global_load_lds_dwordx4 v[224:225], off
	v_lshl_add_u64 v[224:225], s[24:25], 0, v[140:141]
	s_add_i32 m0, s75, 0xe000
	s_nop 0
	global_load_lds_dwordx4 v[224:225], off
	s_waitcnt vmcnt(8)
	s_waitcnt lgkmcnt(0)
	s_barrier
	s_waitcnt lgkmcnt(0)
	v_mfma_f32_16x16x32_bf16 v[128:131], v[142:145], v[178:181], v[128:131]
	v_mfma_f32_16x16x32_bf16 v[124:127], v[154:157], v[178:181], v[124:127]
	v_mfma_f32_16x16x32_bf16 v[120:123], v[142:145], v[186:189], v[120:123]
	v_mfma_f32_16x16x32_bf16 v[110:113], v[154:157], v[186:189], v[110:113]
	v_mfma_f32_16x16x32_bf16 v[102:105], v[142:145], v[194:197], v[102:105]
	v_mfma_f32_16x16x32_bf16 v[94:97], v[154:157], v[194:197], v[94:97]
	v_mfma_f32_16x16x32_bf16 v[86:89], v[142:145], v[216:219], v[86:89]
	v_mfma_f32_16x16x32_bf16 v[78:81], v[154:157], v[216:219], v[78:81]
	v_mfma_f32_16x16x32_bf16 v[128:131], v[150:153], v[182:185], v[128:131]
	v_mfma_f32_16x16x32_bf16 v[124:127], v[158:161], v[182:185], v[124:127]
	v_mfma_f32_16x16x32_bf16 v[120:123], v[150:153], v[190:193], v[120:123]
	v_mfma_f32_16x16x32_bf16 v[110:113], v[158:161], v[190:193], v[110:113]
	v_mfma_f32_16x16x32_bf16 v[102:105], v[150:153], v[212:215], v[102:105]
	v_mfma_f32_16x16x32_bf16 v[94:97], v[158:161], v[212:215], v[94:97]
	v_mfma_f32_16x16x32_bf16 v[86:89], v[150:153], v[220:223], v[86:89]
	v_mfma_f32_16x16x32_bf16 v[78:81], v[158:161], v[220:223], v[78:81]
	v_mfma_f32_16x16x32_bf16 v[116:119], v[162:165], v[178:181], v[116:119]
	v_mfma_f32_16x16x32_bf16 v[106:109], v[170:173], v[178:181], v[106:109]
	v_mfma_f32_16x16x32_bf16 v[98:101], v[162:165], v[186:189], v[98:101]
	v_mfma_f32_16x16x32_bf16 v[90:93], v[170:173], v[186:189], v[90:93]
	v_mfma_f32_16x16x32_bf16 v[82:85], v[162:165], v[194:197], v[82:85]
	v_mfma_f32_16x16x32_bf16 v[74:77], v[170:173], v[194:197], v[74:77]
	v_mfma_f32_16x16x32_bf16 v[70:73], v[162:165], v[216:219], v[70:73]
	v_mfma_f32_16x16x32_bf16 v[66:69], v[170:173], v[216:219], v[66:69]
	v_mfma_f32_16x16x32_bf16 v[116:119], v[166:169], v[182:185], v[116:119]
	v_mfma_f32_16x16x32_bf16 v[106:109], v[174:177], v[182:185], v[106:109]
	v_mfma_f32_16x16x32_bf16 v[98:101], v[166:169], v[190:193], v[98:101]
	v_mfma_f32_16x16x32_bf16 v[90:93], v[174:177], v[190:193], v[90:93]
	v_mfma_f32_16x16x32_bf16 v[82:85], v[166:169], v[212:215], v[82:85]
	v_mfma_f32_16x16x32_bf16 v[74:77], v[174:177], v[212:215], v[74:77]
	v_mfma_f32_16x16x32_bf16 v[70:73], v[166:169], v[220:223], v[70:73]
	v_mfma_f32_16x16x32_bf16 v[66:69], v[174:177], v[220:223], v[66:69]
	s_barrier
	s_add_i32 s24, s54, s57
	v_lshl_add_u64 v[224:225], s[36:37], 0, v[114:115]
	s_mov_b32 m0, s24
	ds_read_b128 v[178:181], v149 offset:16384
	ds_read_b128 v[182:185], v149 offset:17408
	ds_read_b128 v[186:189], v149 offset:18432
	ds_read_b128 v[190:193], v149 offset:19456
	ds_read_b128 v[194:197], v149 offset:20480
	ds_read_b128 v[212:215], v149 offset:21504
	ds_read_b128 v[216:219], v149 offset:22528
	ds_read_b128 v[220:223], v149 offset:23552
	global_load_lds_dwordx4 v[224:225], off
	s_add_i32 m0, s24, 0x2000
	s_add_u32 s24, s36, 0x30000
	v_lshl_add_u64 v[226:227], s[36:37], 0, v[132:133]
	s_addc_u32 s25, s37, 0
	s_add_i32 s54, s55, s57
	global_load_lds_dwordx4 v[226:227], off
	v_lshl_add_u64 v[228:229], s[24:25], 0, v[114:115]
	s_mov_b32 m0, s54
	v_lshl_add_u64 v[230:231], s[38:39], 0, v[134:135]
	global_load_lds_dwordx4 v[228:229], off
	v_lshl_add_u64 v[228:229], s[24:25], 0, v[132:133]
	s_add_i32 m0, s54, 0x2000
	s_nop 0
	global_load_lds_dwordx4 v[228:229], off
	v_lshl_add_u64 v[228:229], s[38:39], 0, v[136:137]
	s_mov_b32 m0, s75
	s_nop 0
	global_load_lds_dwordx4 v[228:229], off
	s_mov_b32 m0, s76
	s_nop 0
	global_load_lds_dwordx4 v[230:231], off
	s_waitcnt vmcnt(8)
	s_waitcnt lgkmcnt(0)
	s_barrier
; #define PG8_STAGE(bufoff, gbase, voff) do { _Pragma("unroll") for (int _i = 0; _i < 2; ++_i) \
;         __builtin_amdgcn_global_load_lds((const unsigned*)((const char*)(gbase) + (voff)[_i]), (LAS unsigned*)(lds + (bufoff) + ldsw + _i * 8192), 16, 0, 0); } while (0)
; #define PG8_LDA(dst, b, h) do { _Pragma("unroll") for (int m = 0; m < 4; ++m) _Pragma("unroll") for (int k = 0; k < 2; ++k) dst[m][k] = *(const LAS bf16x8*)(lds + PG8_SA(b, h) + aoff + m * 2048 + k * 1024); } while (0)
; #define PG8_LDB(dst, b, h) do { _Pragma("unroll") for (int n = 0; n < 2; ++n) _Pragma("unroll") for (int k = 0; k < 2; ++k) dst[n][k] = *(const LAS bf16x8*)(lds + PG8_SB(b, h) + boff + n * 2048 + k * 1024); } while (0)
; #define PG8_MMA(ai, bj, At, Bt) do { __builtin_amdgcn_s_setprio(1); _Pragma("unroll") for (int m = 0; m < 4; ++m) _Pragma("unroll") for (int n = 0; n < 2; ++n) _Pragma("unroll") for (int k = 0; k < 2; ++k) \
;         acc[ai][bj][m][n] = __builtin_amdgcn_mfma_f32_16x16x32_bf16(Bt[n][k], At[m][k], acc[ai][bj][m][n], 0, 0, 0); __builtin_amdgcn_s_setprio(0); } while (0)
; #define PG8_WAIT_V(n) asm volatile("s_waitcnt vmcnt(" #n ")" ::: "memory")
; #define PG8_WAIT_L(n) asm volatile("s_waitcnt lgkmcnt(" #n ")" ::: "memory")
; #define PG8_BAR __builtin_amdgcn_s_barrier()
; #define PG8_SCHED __builtin_amdgcn_sched_barrier(0)
; template <class Epi, class Sched, bool ALIGN_EPI = true, bool SP2 = true>
; __device__ __forceinline__ void gemm_phase(LAS unsigned char* lds, const Sched& S, const Epi& E, const int lda, const int ldb) {
;     ...
;             PG8_WAIT_V(8); PG8_WAIT_L(0); PG8_BAR; PG8_MMA(1, 0, At, B0); PG8_MMA(1, 1, At, B1); PG8_BAR; PG8_SCHED;
;             PG8_LDB(B0, 1, 0); PG8_LDB(B1, 1, 1); PG8_SCHED; PG8_LDA(At, 1, 0); PG8_STAGE(PG8_SA(0, 1), a2 + hstepA, voffA);
;             PG8_WAIT_V(8); PG8_WAIT_L(0); PG8_BAR; PG8_MMA(0, 0, At, B0); PG8_MMA(0, 1, At, B1); PG8_BAR; PG8_SCHED;
	s_waitcnt lgkmcnt(0)
	v_mfma_f32_16x16x32_bf16 v[62:65], v[142:145], v[178:181], v[62:65]
	v_mfma_f32_16x16x32_bf16 v[58:61], v[154:157], v[178:181], v[58:61]
	v_mfma_f32_16x16x32_bf16 v[54:57], v[142:145], v[186:189], v[54:57]
	v_mfma_f32_16x16x32_bf16 v[46:49], v[154:157], v[186:189], v[46:49]
	v_mfma_f32_16x16x32_bf16 v[38:41], v[142:145], v[194:197], v[38:41]
	v_mfma_f32_16x16x32_bf16 v[30:33], v[154:157], v[194:197], v[30:33]
	v_mfma_f32_16x16x32_bf16 v[22:25], v[142:145], v[216:219], v[22:25]
	v_mfma_f32_16x16x32_bf16 v[14:17], v[154:157], v[216:219], v[14:17]
	v_mfma_f32_16x16x32_bf16 v[62:65], v[150:153], v[182:185], v[62:65]
	v_mfma_f32_16x16x32_bf16 v[58:61], v[158:161], v[182:185], v[58:61]
	v_mfma_f32_16x16x32_bf16 v[54:57], v[150:153], v[190:193], v[54:57]
	v_mfma_f32_16x16x32_bf16 v[46:49], v[158:161], v[190:193], v[46:49]
	v_mfma_f32_16x16x32_bf16 v[38:41], v[150:153], v[212:215], v[38:41]
	v_mfma_f32_16x16x32_bf16 v[30:33], v[158:161], v[212:215], v[30:33]
	v_mfma_f32_16x16x32_bf16 v[22:25], v[150:153], v[220:223], v[22:25]
	v_mfma_f32_16x16x32_bf16 v[14:17], v[158:161], v[220:223], v[14:17]
	v_mfma_f32_16x16x32_bf16 v[50:53], v[162:165], v[178:181], v[50:53]
	v_mfma_f32_16x16x32_bf16 v[42:45], v[170:173], v[178:181], v[42:45]
	v_mfma_f32_16x16x32_bf16 v[34:37], v[162:165], v[186:189], v[34:37]
	v_mfma_f32_16x16x32_bf16 v[26:29], v[170:173], v[186:189], v[26:29]
	v_mfma_f32_16x16x32_bf16 v[18:21], v[162:165], v[194:197], v[18:21]
	v_mfma_f32_16x16x32_bf16 v[10:13], v[170:173], v[194:197], v[10:13]
	v_mfma_f32_16x16x32_bf16 v[6:9], v[162:165], v[216:219], v[6:9]
	v_mfma_f32_16x16x32_bf16 v[2:5], v[170:173], v[216:219], v[2:5]
	v_mfma_f32_16x16x32_bf16 v[50:53], v[166:169], v[182:185], v[50:53]
	v_mfma_f32_16x16x32_bf16 v[42:45], v[174:177], v[182:185], v[42:45]
	v_mfma_f32_16x16x32_bf16 v[34:37], v[166:169], v[190:193], v[34:37]
	v_mfma_f32_16x16x32_bf16 v[26:29], v[174:177], v[190:193], v[26:29]
	v_mfma_f32_16x16x32_bf16 v[18:21], v[166:169], v[212:215], v[18:21]
	v_mfma_f32_16x16x32_bf16 v[10:13], v[174:177], v[212:215], v[10:13]
	v_mfma_f32_16x16x32_bf16 v[6:9], v[166:169], v[220:223], v[6:9]
	v_mfma_f32_16x16x32_bf16 v[2:5], v[174:177], v[220:223], v[2:5]
	s_barrier
	s_add_i32 s54, 0, 0x18000
	s_add_i32 s55, 0, 0x1c000
	v_add_u32_e32 v158, s54, v147
	v_add_u32_e32 v174, s55, v147
	ds_read_b128 v[142:145], v158
	ds_read_b128 v[150:153], v158 offset:1024
	ds_read_b128 v[154:157], v158 offset:2048
	ds_read_b128 v[158:161], v158 offset:3072
	ds_read_b128 v[162:165], v174
	ds_read_b128 v[166:169], v174 offset:1024
	ds_read_b128 v[170:173], v174 offset:2048
	ds_read_b128 v[174:177], v174 offset:3072
	s_add_u32 s24, s38, 0x30000
	s_addc_u32 s25, s39, 0
	s_mov_b32 m0, s77
	v_lshl_add_u64 v[232:233], s[24:25], 0, v[136:137]
	ds_read_b128 v[178:181], v149 offset:32768
	ds_read_b128 v[182:185], v149 offset:33792
	ds_read_b128 v[186:189], v149 offset:34816
	ds_read_b128 v[190:193], v149 offset:35840
	ds_read_b128 v[194:197], v149 offset:36864
	ds_read_b128 v[212:215], v149 offset:37888
	ds_read_b128 v[216:219], v149 offset:38912
	ds_read_b128 v[220:223], v149 offset:39936
	global_load_lds_dwordx4 v[232:233], off
	v_lshl_add_u64 v[232:233], s[24:25], 0, v[134:135]
	s_mov_b32 m0, s78
	s_nop 0
	global_load_lds_dwordx4 v[232:233], off
	s_waitcnt vmcnt(8)
	s_waitcnt lgkmcnt(0)
	s_barrier
	s_waitcnt lgkmcnt(0)
	v_mfma_f32_16x16x32_bf16 v[128:131], v[142:145], v[178:181], v[128:131]
	v_mfma_f32_16x16x32_bf16 v[124:127], v[154:157], v[178:181], v[124:127]
	v_mfma_f32_16x16x32_bf16 v[120:123], v[142:145], v[186:189], v[120:123]
	v_mfma_f32_16x16x32_bf16 v[110:113], v[154:157], v[186:189], v[110:113]
	v_mfma_f32_16x16x32_bf16 v[102:105], v[142:145], v[194:197], v[102:105]
	v_mfma_f32_16x16x32_bf16 v[94:97], v[154:157], v[194:197], v[94:97]
	v_mfma_f32_16x16x32_bf16 v[86:89], v[142:145], v[216:219], v[86:89]
	v_mfma_f32_16x16x32_bf16 v[78:81], v[154:157], v[216:219], v[78:81]
	v_mfma_f32_16x16x32_bf16 v[128:131], v[150:153], v[182:185], v[128:131]
	v_mfma_f32_16x16x32_bf16 v[124:127], v[158:161], v[182:185], v[124:127]
	v_mfma_f32_16x16x32_bf16 v[120:123], v[150:153], v[190:193], v[120:123]
	v_mfma_f32_16x16x32_bf16 v[110:113], v[158:161], v[190:193], v[110:113]
	v_mfma_f32_16x16x32_bf16 v[102:105], v[150:153], v[212:215], v[102:105]
	v_mfma_f32_16x16x32_bf16 v[94:97], v[158:161], v[212:215], v[94:97]
	v_mfma_f32_16x16x32_bf16 v[86:89], v[150:153], v[220:223], v[86:89]
	v_mfma_f32_16x16x32_bf16 v[78:81], v[158:161], v[220:223], v[78:81]
	v_mfma_f32_16x16x32_bf16 v[116:119], v[162:165], v[178:181], v[116:119]
	v_mfma_f32_16x16x32_bf16 v[106:109], v[170:173], v[178:181], v[106:109]
	v_mfma_f32_16x16x32_bf16 v[98:101], v[162:165], v[186:189], v[98:101]
	v_mfma_f32_16x16x32_bf16 v[90:93], v[170:173], v[186:189], v[90:93]
	v_mfma_f32_16x16x32_bf16 v[82:85], v[162:165], v[194:197], v[82:85]
	v_mfma_f32_16x16x32_bf16 v[74:77], v[170:173], v[194:197], v[74:77]
	v_mfma_f32_16x16x32_bf16 v[70:73], v[162:165], v[216:219], v[70:73]
	v_mfma_f32_16x16x32_bf16 v[66:69], v[170:173], v[216:219], v[66:69]
	v_mfma_f32_16x16x32_bf16 v[116:119], v[166:169], v[182:185], v[116:119]
	v_mfma_f32_16x16x32_bf16 v[106:109], v[174:177], v[182:185], v[106:109]
	v_mfma_f32_16x16x32_bf16 v[98:101], v[166:169], v[190:193], v[98:101]
	v_mfma_f32_16x16x32_bf16 v[90:93], v[174:177], v[190:193], v[90:93]
	v_mfma_f32_16x16x32_bf16 v[82:85], v[166:169], v[212:215], v[82:85]
	v_mfma_f32_16x16x32_bf16 v[74:77], v[174:177], v[212:215], v[74:77]
	v_mfma_f32_16x16x32_bf16 v[70:73], v[166:169], v[220:223], v[70:73]
	v_mfma_f32_16x16x32_bf16 v[66:69], v[174:177], v[220:223], v[66:69]
	s_barrier
; #define PG8_STAGE(bufoff, gbase, voff) do { _Pragma("unroll") for (int _i = 0; _i < 2; ++_i) \
;         __builtin_amdgcn_global_load_lds((const unsigned*)((const char*)(gbase) + (voff)[_i]), (LAS unsigned*)(lds + (bufoff) + ldsw + _i * 8192), 16, 0, 0); } while (0)
; #define PG8_LDA(dst, b, h) do { _Pragma("unroll") for (int m = 0; m < 4; ++m) _Pragma("unroll") for (int k = 0; k < 2; ++k) dst[m][k] = *(const LAS bf16x8*)(lds + PG8_SA(b, h) + aoff + m * 2048 + k * 1024); } while (0)
; #define PG8_MMA(ai, bj, At, Bt) do { __builtin_amdgcn_s_setprio(1); _Pragma("unroll") for (int m = 0; m < 4; ++m) _Pragma("unroll") for (int n = 0; n < 2; ++n) _Pragma("unroll") for (int k = 0; k < 2; ++k) \
;         acc[ai][bj][m][n] = __builtin_amdgcn_mfma_f32_16x16x32_bf16(Bt[n][k], At[m][k], acc[ai][bj][m][n], 0, 0, 0); __builtin_amdgcn_s_setprio(0); } while (0)
; #define PG8_WAIT_V(n) asm volatile("s_waitcnt vmcnt(" #n ")" ::: "memory")
; #define PG8_WAIT_L(n) asm volatile("s_waitcnt lgkmcnt(" #n ")" ::: "memory")
; #define PG8_BAR __builtin_amdgcn_s_barrier()
; #define PG8_SCHED __builtin_amdgcn_sched_barrier(0)
; template <class Epi, class Sched, bool ALIGN_EPI = true, bool SP2 = true>
; __device__ __forceinline__ void gemm_phase(LAS unsigned char* lds, const Sched& S, const Epi& E, const int lda, const int ldb) {
;     ...
;             PG8_LDA(At, 1, 1); PG8_STAGE(PG8_SB(1, 0), b3, voffB); PG8_STAGE(PG8_SB(1, 1), b3 + hstepB, voffB); PG8_STAGE(PG8_SA(1, 0), a3, voffA);
;             PG8_WAIT_V(8); PG8_WAIT_L(0); PG8_BAR; PG8_MMA(1, 0, At, B0); PG8_MMA(1, 1, At, B1); PG8_BAR; PG8_SCHED;
;     ...
;         if constexpr (ALIGN_EPI) { if (wr == 0) PG8_BAR; }
	s_add_i32 s24, s54, s57
	v_lshl_add_u64 v[224:225], v[224:225], 0, s[70:71]
	s_mov_b32 m0, s24
	ds_read_b128 v[178:181], v149 offset:49152
	ds_read_b128 v[182:185], v149 offset:50176
	ds_read_b128 v[186:189], v149 offset:51200
	ds_read_b128 v[190:193], v149 offset:52224
	ds_read_b128 v[194:197], v149 offset:53248
	ds_read_b128 v[212:215], v149 offset:54272
	ds_read_b128 v[216:219], v149 offset:55296
	ds_read_b128 v[220:223], v149 offset:56320
	global_load_lds_dwordx4 v[224:225], off
	s_add_i32 m0, s24, 0x2000
	s_add_u32 s24, s36, 0x30080
	v_lshl_add_u64 v[224:225], v[226:227], 0, s[70:71]
	s_addc_u32 s25, s37, 0
	s_add_i32 s36, s55, s57
	global_load_lds_dwordx4 v[224:225], off
	v_lshl_add_u64 v[224:225], s[24:25], 0, v[114:115]
	s_mov_b32 m0, s36
	s_nop 0
	global_load_lds_dwordx4 v[224:225], off
	v_lshl_add_u64 v[224:225], s[24:25], 0, v[132:133]
	s_add_i32 m0, s36, 0x2000
	s_nop 0
	global_load_lds_dwordx4 v[224:225], off
	v_lshl_add_u64 v[224:225], v[228:229], 0, s[70:71]
	s_mov_b32 m0, s33
	s_nop 0
	global_load_lds_dwordx4 v[224:225], off
	v_lshl_add_u64 v[224:225], v[230:231], 0, s[70:71]
	s_mov_b32 m0, s79
	s_nop 0
	global_load_lds_dwordx4 v[224:225], off
	s_waitcnt vmcnt(8)
	s_waitcnt lgkmcnt(0)
	s_barrier
	s_waitcnt lgkmcnt(0)
	v_mfma_f32_16x16x32_bf16 v[62:65], v[142:145], v[178:181], v[62:65]
	v_mfma_f32_16x16x32_bf16 v[58:61], v[154:157], v[178:181], v[58:61]
	v_mfma_f32_16x16x32_bf16 v[54:57], v[142:145], v[186:189], v[54:57]
	v_mfma_f32_16x16x32_bf16 v[46:49], v[154:157], v[186:189], v[46:49]
	v_mfma_f32_16x16x32_bf16 v[38:41], v[142:145], v[194:197], v[38:41]
	v_mfma_f32_16x16x32_bf16 v[30:33], v[154:157], v[194:197], v[30:33]
	v_mfma_f32_16x16x32_bf16 v[22:25], v[142:145], v[216:219], v[22:25]
	v_mfma_f32_16x16x32_bf16 v[14:17], v[154:157], v[216:219], v[14:17]
	v_mfma_f32_16x16x32_bf16 v[62:65], v[150:153], v[182:185], v[62:65]
	v_mfma_f32_16x16x32_bf16 v[58:61], v[158:161], v[182:185], v[58:61]
	v_mfma_f32_16x16x32_bf16 v[54:57], v[150:153], v[190:193], v[54:57]
	v_mfma_f32_16x16x32_bf16 v[46:49], v[158:161], v[190:193], v[46:49]
	v_mfma_f32_16x16x32_bf16 v[38:41], v[150:153], v[212:215], v[38:41]
	v_mfma_f32_16x16x32_bf16 v[30:33], v[158:161], v[212:215], v[30:33]
	v_mfma_f32_16x16x32_bf16 v[22:25], v[150:153], v[220:223], v[22:25]
	v_mfma_f32_16x16x32_bf16 v[14:17], v[158:161], v[220:223], v[14:17]
	v_mfma_f32_16x16x32_bf16 v[50:53], v[162:165], v[178:181], v[50:53]
	v_mfma_f32_16x16x32_bf16 v[42:45], v[170:173], v[178:181], v[42:45]
	v_mfma_f32_16x16x32_bf16 v[34:37], v[162:165], v[186:189], v[34:37]
	v_mfma_f32_16x16x32_bf16 v[26:29], v[170:173], v[186:189], v[26:29]
	v_mfma_f32_16x16x32_bf16 v[18:21], v[162:165], v[194:197], v[18:21]
	v_mfma_f32_16x16x32_bf16 v[10:13], v[170:173], v[194:197], v[10:13]
	v_mfma_f32_16x16x32_bf16 v[6:9], v[162:165], v[216:219], v[6:9]
	v_mfma_f32_16x16x32_bf16 v[2:5], v[170:173], v[216:219], v[2:5]
	v_mfma_f32_16x16x32_bf16 v[50:53], v[166:169], v[182:185], v[50:53]
	v_mfma_f32_16x16x32_bf16 v[42:45], v[174:177], v[182:185], v[42:45]
	v_mfma_f32_16x16x32_bf16 v[34:37], v[166:169], v[190:193], v[34:37]
	v_mfma_f32_16x16x32_bf16 v[26:29], v[174:177], v[190:193], v[26:29]
	v_mfma_f32_16x16x32_bf16 v[18:21], v[166:169], v[212:215], v[18:21]
	v_mfma_f32_16x16x32_bf16 v[10:13], v[174:177], v[212:215], v[10:13]
	v_mfma_f32_16x16x32_bf16 v[6:9], v[166:169], v[220:223], v[6:9]
	v_mfma_f32_16x16x32_bf16 v[2:5], v[174:177], v[220:223], v[2:5]
	s_barrier
	s_add_i32 s50, s50, 2
	s_add_u32 s87, s87, 0x100
	s_addc_u32 vcc_lo, vcc_lo, 0
	s_cmp_gt_u32 s50, 9
	s_mov_b64 s[24:25], s[26:27]
	s_cbranch_scc0 .LBB0_635
	s_and_b64 vcc, exec, s[18:19]
	s_cbranch_vccz .LBB0_638
	s_barrier

; #define PG8_STAGE(bufoff, gbase, voff) do { _Pragma("unroll") for (int _i = 0; _i < 2; ++_i) \
;         __builtin_amdgcn_global_load_lds((const unsigned*)((const char*)(gbase) + (voff)[_i]), (LAS unsigned*)(lds + (bufoff) + ldsw + _i * 8192), 16, 0, 0); } while (0)
; #define PG8_LDA(dst, b, h) do { _Pragma("unroll") for (int m = 0; m < 4; ++m) _Pragma("unroll") for (int k = 0; k < 2; ++k) dst[m][k] = *(const LAS bf16x8*)(lds + PG8_SA(b, h) + aoff + m * 2048 + k * 1024); } while (0)
; #define PG8_LDB(dst, b, h) do { _Pragma("unroll") for (int n = 0; n < 2; ++n) _Pragma("unroll") for (int k = 0; k < 2; ++k) dst[n][k] = *(const LAS bf16x8*)(lds + PG8_SB(b, h) + boff + n * 2048 + k * 1024); } while (0)
; #define PG8_MMA(ai, bj, At, Bt) do { __builtin_amdgcn_s_setprio(1); _Pragma("unroll") for (int m = 0; m < 4; ++m) _Pragma("unroll") for (int n = 0; n < 2; ++n) _Pragma("unroll") for (int k = 0; k < 2; ++k) \
;         acc[ai][bj][m][n] = __builtin_amdgcn_mfma_f32_16x16x32_bf16(Bt[n][k], At[m][k], acc[ai][bj][m][n], 0, 0, 0); __builtin_amdgcn_s_setprio(0); } while (0)
; #define PG8_WAIT_V(n) asm volatile("s_waitcnt vmcnt(" #n ")" ::: "memory")
; #define PG8_WAIT_L(n) asm volatile("s_waitcnt lgkmcnt(" #n ")" ::: "memory")
; #define PG8_BAR __builtin_amdgcn_s_barrier()
; #define PG8_SCHED __builtin_amdgcn_sched_barrier(0)
; template <class Epi, class Sched, bool ALIGN_EPI = true, bool SP2 = true>
; __device__ __forceinline__ void gemm_phase(LAS unsigned char* lds, const Sched& S, const Epi& E, const int lda, const int ldb) {
;     ...
;             const bool last = (t == nt - 2);
;             const char* a1 = cA + (size_t)(t + 1) * kstep;
;             const char* a2 = last ? nA : cA + (size_t)(t + 2) * kstep; const char* b2 = last ? nB : cB + (size_t)(t + 2) * kstep;
;             const char* a3 = a2 + kstep; const char* b3 = b2 + kstep;
;             if constexpr (SP2) {
;             PG8_LDB(B0, 0, 0); PG8_LDB(B1, 0, 1); PG8_SCHED; PG8_LDA(At, 0, 0); PG8_STAGE(PG8_SA(1, 1), a1 + hstepA, voffA);
;             PG8_WAIT_V(8); PG8_WAIT_L(0); PG8_BAR; PG8_MMA(0, 0, At, B0); PG8_MMA(0, 1, At, B1); PG8_BAR; PG8_SCHED;
;             PG8_LDA(At, 0, 1); PG8_STAGE(PG8_SB(0, 0), b2, voffB); PG8_STAGE(PG8_SB(0, 1), b2 + hstepB, voffB); PG8_STAGE(PG8_SA(0, 0), a2, voffA);
.LBB0_651:
	s_add_u32 s36, s26, 0xfffc0080
	s_addc_u32 s37, s27, -1
	s_add_i32 s54, 0, 0x10000
	s_cmp_eq_u32 s50, 12
	s_cselect_b32 s39, s23, s37
	s_cselect_b32 s38, s22, s36
	s_cselect_b32 s37, s25, vcc_hi
	s_cselect_b32 s36, s24, vcc_lo
	s_add_i32 s29, 0, 0x14000
	v_add_u32_e32 v144, s54, v189
	v_add_u32_e32 v160, s29, v189
	ds_read_b128 v[132:135], v144
	ds_read_b128 v[136:139], v144 offset:1024
	ds_read_b128 v[140:143], v144 offset:2048
	ds_read_b128 v[144:147], v144 offset:3072
	ds_read_b128 v[148:151], v160
	ds_read_b128 v[152:155], v160 offset:1024
	ds_read_b128 v[156:159], v160 offset:2048
	ds_read_b128 v[160:163], v160 offset:3072
	v_lshl_add_u64 v[186:187], s[26:27], 0, v[174:175]
	s_add_i32 m0, s76, 0xc000
	ds_read_b128 v[164:167], v191
	ds_read_b128 v[178:181], v191 offset:1024
	ds_read_b128 v[182:185], v191 offset:2048
	ds_read_b128 v[192:195], v191 offset:3072
	ds_read_b128 v[212:215], v191 offset:4096
	ds_read_b128 v[216:219], v191 offset:5120
	ds_read_b128 v[220:223], v191 offset:6144
	ds_read_b128 v[224:227], v191 offset:7168
	global_load_lds_dwordx4 v[186:187], off
	v_lshl_add_u64 v[186:187], s[26:27], 0, v[176:177]
	s_add_i32 m0, s76, 0xe000
	s_nop 0
	global_load_lds_dwordx4 v[186:187], off
	s_waitcnt vmcnt(8)
	s_waitcnt lgkmcnt(0)
	s_barrier
	s_waitcnt lgkmcnt(0)
	v_mfma_f32_16x16x32_bf16 v[128:131], v[132:135], v[164:167], v[128:131]
	v_mfma_f32_16x16x32_bf16 v[124:127], v[140:143], v[164:167], v[124:127]
	v_mfma_f32_16x16x32_bf16 v[116:119], v[132:135], v[182:185], v[116:119]
	v_mfma_f32_16x16x32_bf16 v[106:109], v[140:143], v[182:185], v[106:109]
	v_mfma_f32_16x16x32_bf16 v[98:101], v[132:135], v[212:215], v[98:101]
	v_mfma_f32_16x16x32_bf16 v[90:93], v[140:143], v[212:215], v[90:93]
	v_mfma_f32_16x16x32_bf16 v[82:85], v[132:135], v[220:223], v[82:85]
	v_mfma_f32_16x16x32_bf16 v[74:77], v[140:143], v[220:223], v[74:77]
	v_mfma_f32_16x16x32_bf16 v[128:131], v[136:139], v[178:181], v[128:131]
	v_mfma_f32_16x16x32_bf16 v[124:127], v[144:147], v[178:181], v[124:127]
	v_mfma_f32_16x16x32_bf16 v[116:119], v[136:139], v[192:195], v[116:119]
	v_mfma_f32_16x16x32_bf16 v[106:109], v[144:147], v[192:195], v[106:109]
	v_mfma_f32_16x16x32_bf16 v[98:101], v[136:139], v[216:219], v[98:101]
	v_mfma_f32_16x16x32_bf16 v[90:93], v[144:147], v[216:219], v[90:93]
	v_mfma_f32_16x16x32_bf16 v[82:85], v[136:139], v[224:227], v[82:85]
	v_mfma_f32_16x16x32_bf16 v[74:77], v[144:147], v[224:227], v[74:77]
	v_mfma_f32_16x16x32_bf16 v[120:123], v[148:151], v[164:167], v[120:123]
	v_mfma_f32_16x16x32_bf16 v[110:113], v[156:159], v[164:167], v[110:113]
	v_mfma_f32_16x16x32_bf16 v[102:105], v[148:151], v[182:185], v[102:105]
	v_mfma_f32_16x16x32_bf16 v[94:97], v[156:159], v[182:185], v[94:97]
	v_mfma_f32_16x16x32_bf16 v[86:89], v[148:151], v[212:215], v[86:89]
	v_mfma_f32_16x16x32_bf16 v[78:81], v[156:159], v[212:215], v[78:81]
	v_mfma_f32_16x16x32_bf16 v[70:73], v[148:151], v[220:223], v[70:73]
	v_mfma_f32_16x16x32_bf16 v[66:69], v[156:159], v[220:223], v[66:69]
	v_mfma_f32_16x16x32_bf16 v[120:123], v[152:155], v[178:181], v[120:123]
	v_mfma_f32_16x16x32_bf16 v[110:113], v[160:163], v[178:181], v[110:113]
	v_mfma_f32_16x16x32_bf16 v[102:105], v[152:155], v[192:195], v[102:105]
	v_mfma_f32_16x16x32_bf16 v[94:97], v[160:163], v[192:195], v[94:97]
	v_mfma_f32_16x16x32_bf16 v[86:89], v[152:155], v[216:219], v[86:89]
	v_mfma_f32_16x16x32_bf16 v[78:81], v[160:163], v[216:219], v[78:81]
	v_mfma_f32_16x16x32_bf16 v[70:73], v[152:155], v[224:227], v[70:73]
	v_mfma_f32_16x16x32_bf16 v[66:69], v[160:163], v[224:227], v[66:69]
	s_barrier
	s_add_i32 s54, s54, s62
	v_lshl_add_u64 v[186:187], s[36:37], 0, v[114:115]
	s_mov_b32 m0, s54
	ds_read_b128 v[164:167], v191 offset:16384
	ds_read_b128 v[178:181], v191 offset:17408
	ds_read_b128 v[182:185], v191 offset:18432
	ds_read_b128 v[192:195], v191 offset:19456
	ds_read_b128 v[212:215], v191 offset:20480
	ds_read_b128 v[216:219], v191 offset:21504
	ds_read_b128 v[220:223], v191 offset:22528
	ds_read_b128 v[224:227], v191 offset:23552
	global_load_lds_dwordx4 v[186:187], off
	s_add_i32 m0, s54, 0x2000
	s_add_u32 s54, s36, 0x40000
	v_lshl_add_u64 v[196:197], s[36:37], 0, v[168:169]
	s_addc_u32 s55, s37, 0
	s_add_i32 s29, s29, s62
	global_load_lds_dwordx4 v[196:197], off
	v_lshl_add_u64 v[228:229], s[54:55], 0, v[114:115]
	s_mov_b32 m0, s29
	v_lshl_add_u64 v[230:231], s[38:39], 0, v[170:171]
	global_load_lds_dwordx4 v[228:229], off
	v_lshl_add_u64 v[228:229], s[54:55], 0, v[168:169]
	s_add_i32 m0, s29, 0x2000
	s_nop 0
	global_load_lds_dwordx4 v[228:229], off
	v_lshl_add_u64 v[228:229], s[38:39], 0, v[172:173]
	s_mov_b32 m0, s76
	s_nop 0
	global_load_lds_dwordx4 v[228:229], off
	s_mov_b32 m0, s77
	s_nop 0
	global_load_lds_dwordx4 v[230:231], off
	s_waitcnt vmcnt(8)
	s_waitcnt lgkmcnt(0)
	s_barrier
; #define PG8_STAGE(bufoff, gbase, voff) do { _Pragma("unroll") for (int _i = 0; _i < 2; ++_i) \
;         __builtin_amdgcn_global_load_lds((const unsigned*)((const char*)(gbase) + (voff)[_i]), (LAS unsigned*)(lds + (bufoff) + ldsw + _i * 8192), 16, 0, 0); } while (0)
; #define PG8_LDA(dst, b, h) do { _Pragma("unroll") for (int m = 0; m < 4; ++m) _Pragma("unroll") for (int k = 0; k < 2; ++k) dst[m][k] = *(const LAS bf16x8*)(lds + PG8_SA(b, h) + aoff + m * 2048 + k * 1024); } while (0)
; #define PG8_LDB(dst, b, h) do { _Pragma("unroll") for (int n = 0; n < 2; ++n) _Pragma("unroll") for (int k = 0; k < 2; ++k) dst[n][k] = *(const LAS bf16x8*)(lds + PG8_SB(b, h) + boff + n * 2048 + k * 1024); } while (0)
; #define PG8_MMA(ai, bj, At, Bt) do { __builtin_amdgcn_s_setprio(1); _Pragma("unroll") for (int m = 0; m < 4; ++m) _Pragma("unroll") for (int n = 0; n < 2; ++n) _Pragma("unroll") for (int k = 0; k < 2; ++k) \
;         acc[ai][bj][m][n] = __builtin_amdgcn_mfma_f32_16x16x32_bf16(Bt[n][k], At[m][k], acc[ai][bj][m][n], 0, 0, 0); __builtin_amdgcn_s_setprio(0); } while (0)
; #define PG8_WAIT_V(n) asm volatile("s_waitcnt vmcnt(" #n ")" ::: "memory")
; #define PG8_WAIT_L(n) asm volatile("s_waitcnt lgkmcnt(" #n ")" ::: "memory")
; #define PG8_BAR __builtin_amdgcn_s_barrier()
; #define PG8_SCHED __builtin_amdgcn_sched_barrier(0)
; template <class Epi, class Sched, bool ALIGN_EPI = true, bool SP2 = true>
; __device__ __forceinline__ void gemm_phase(LAS unsigned char* lds, const Sched& S, const Epi& E, const int lda, const int ldb) {
;     ...
;             PG8_WAIT_V(8); PG8_WAIT_L(0); PG8_BAR; PG8_MMA(1, 0, At, B0); PG8_MMA(1, 1, At, B1); PG8_BAR; PG8_SCHED;
;             PG8_LDB(B0, 1, 0); PG8_LDB(B1, 1, 1); PG8_SCHED; PG8_LDA(At, 1, 0); PG8_STAGE(PG8_SA(0, 1), a2 + hstepA, voffA);
;             PG8_WAIT_V(8); PG8_WAIT_L(0); PG8_BAR; PG8_MMA(0, 0, At, B0); PG8_MMA(0, 1, At, B1); PG8_BAR; PG8_SCHED;
	s_waitcnt lgkmcnt(0)
	v_mfma_f32_16x16x32_bf16 v[62:65], v[132:135], v[164:167], v[62:65]
	v_mfma_f32_16x16x32_bf16 v[58:61], v[140:143], v[164:167], v[58:61]
	v_mfma_f32_16x16x32_bf16 v[50:53], v[132:135], v[182:185], v[50:53]
	v_mfma_f32_16x16x32_bf16 v[42:45], v[140:143], v[182:185], v[42:45]
	v_mfma_f32_16x16x32_bf16 v[34:37], v[132:135], v[212:215], v[34:37]
	v_mfma_f32_16x16x32_bf16 v[26:29], v[140:143], v[212:215], v[26:29]
	v_mfma_f32_16x16x32_bf16 v[18:21], v[132:135], v[220:223], v[18:21]
	v_mfma_f32_16x16x32_bf16 v[10:13], v[140:143], v[220:223], v[10:13]
	v_mfma_f32_16x16x32_bf16 v[62:65], v[136:139], v[178:181], v[62:65]
	v_mfma_f32_16x16x32_bf16 v[58:61], v[144:147], v[178:181], v[58:61]
	v_mfma_f32_16x16x32_bf16 v[50:53], v[136:139], v[192:195], v[50:53]
	v_mfma_f32_16x16x32_bf16 v[42:45], v[144:147], v[192:195], v[42:45]
	v_mfma_f32_16x16x32_bf16 v[34:37], v[136:139], v[216:219], v[34:37]
	v_mfma_f32_16x16x32_bf16 v[26:29], v[144:147], v[216:219], v[26:29]
	v_mfma_f32_16x16x32_bf16 v[18:21], v[136:139], v[224:227], v[18:21]
	v_mfma_f32_16x16x32_bf16 v[10:13], v[144:147], v[224:227], v[10:13]
	v_mfma_f32_16x16x32_bf16 v[54:57], v[148:151], v[164:167], v[54:57]
	v_mfma_f32_16x16x32_bf16 v[46:49], v[156:159], v[164:167], v[46:49]
	v_mfma_f32_16x16x32_bf16 v[38:41], v[148:151], v[182:185], v[38:41]
	v_mfma_f32_16x16x32_bf16 v[30:33], v[156:159], v[182:185], v[30:33]
	v_mfma_f32_16x16x32_bf16 v[22:25], v[148:151], v[212:215], v[22:25]
	v_mfma_f32_16x16x32_bf16 v[14:17], v[156:159], v[212:215], v[14:17]
	v_mfma_f32_16x16x32_bf16 v[6:9], v[148:151], v[220:223], v[6:9]
	v_mfma_f32_16x16x32_bf16 v[2:5], v[156:159], v[220:223], v[2:5]
	v_mfma_f32_16x16x32_bf16 v[54:57], v[152:155], v[178:181], v[54:57]
	v_mfma_f32_16x16x32_bf16 v[46:49], v[160:163], v[178:181], v[46:49]
	v_mfma_f32_16x16x32_bf16 v[38:41], v[152:155], v[192:195], v[38:41]
	v_mfma_f32_16x16x32_bf16 v[30:33], v[160:163], v[192:195], v[30:33]
	v_mfma_f32_16x16x32_bf16 v[22:25], v[152:155], v[216:219], v[22:25]
	v_mfma_f32_16x16x32_bf16 v[14:17], v[160:163], v[216:219], v[14:17]
	v_mfma_f32_16x16x32_bf16 v[6:9], v[152:155], v[224:227], v[6:9]
	v_mfma_f32_16x16x32_bf16 v[2:5], v[160:163], v[224:227], v[2:5]
	s_barrier
	s_add_i32 s29, 0, 0x18000
	s_add_i32 s54, 0, 0x1c000
	v_add_u32_e32 v144, s29, v189
	v_add_u32_e32 v160, s54, v189
	ds_read_b128 v[132:135], v144
	ds_read_b128 v[136:139], v144 offset:1024
	ds_read_b128 v[140:143], v144 offset:2048
	ds_read_b128 v[144:147], v144 offset:3072
	ds_read_b128 v[148:151], v160
	ds_read_b128 v[152:155], v160 offset:1024
	ds_read_b128 v[156:159], v160 offset:2048
	ds_read_b128 v[160:163], v160 offset:3072
	s_add_u32 s38, s38, 0x40000
	s_addc_u32 s39, s39, 0
	s_mov_b32 m0, s78
	v_lshl_add_u64 v[232:233], s[38:39], 0, v[172:173]
	ds_read_b128 v[164:167], v191 offset:32768
	ds_read_b128 v[178:181], v191 offset:33792
	ds_read_b128 v[182:185], v191 offset:34816
	ds_read_b128 v[192:195], v191 offset:35840
	ds_read_b128 v[212:215], v191 offset:36864
	ds_read_b128 v[216:219], v191 offset:37888
	ds_read_b128 v[220:223], v191 offset:38912
	ds_read_b128 v[224:227], v191 offset:39936
	global_load_lds_dwordx4 v[232:233], off
	v_lshl_add_u64 v[232:233], s[38:39], 0, v[170:171]
	s_mov_b32 m0, s79
	s_nop 0
	global_load_lds_dwordx4 v[232:233], off
	s_waitcnt vmcnt(8)
	s_waitcnt lgkmcnt(0)
	s_barrier
	s_waitcnt lgkmcnt(0)
	v_mfma_f32_16x16x32_bf16 v[128:131], v[132:135], v[164:167], v[128:131]
	v_mfma_f32_16x16x32_bf16 v[124:127], v[140:143], v[164:167], v[124:127]
	v_mfma_f32_16x16x32_bf16 v[116:119], v[132:135], v[182:185], v[116:119]
	v_mfma_f32_16x16x32_bf16 v[106:109], v[140:143], v[182:185], v[106:109]
	v_mfma_f32_16x16x32_bf16 v[98:101], v[132:135], v[212:215], v[98:101]
	v_mfma_f32_16x16x32_bf16 v[90:93], v[140:143], v[212:215], v[90:93]
	v_mfma_f32_16x16x32_bf16 v[82:85], v[132:135], v[220:223], v[82:85]
	v_mfma_f32_16x16x32_bf16 v[74:77], v[140:143], v[220:223], v[74:77]
	v_mfma_f32_16x16x32_bf16 v[128:131], v[136:139], v[178:181], v[128:131]
	v_mfma_f32_16x16x32_bf16 v[124:127], v[144:147], v[178:181], v[124:127]
	v_mfma_f32_16x16x32_bf16 v[116:119], v[136:139], v[192:195], v[116:119]
	v_mfma_f32_16x16x32_bf16 v[106:109], v[144:147], v[192:195], v[106:109]
	v_mfma_f32_16x16x32_bf16 v[98:101], v[136:139], v[216:219], v[98:101]
	v_mfma_f32_16x16x32_bf16 v[90:93], v[144:147], v[216:219], v[90:93]
	v_mfma_f32_16x16x32_bf16 v[82:85], v[136:139], v[224:227], v[82:85]
	v_mfma_f32_16x16x32_bf16 v[74:77], v[144:147], v[224:227], v[74:77]
	v_mfma_f32_16x16x32_bf16 v[120:123], v[148:151], v[164:167], v[120:123]
	v_mfma_f32_16x16x32_bf16 v[110:113], v[156:159], v[164:167], v[110:113]
	v_mfma_f32_16x16x32_bf16 v[102:105], v[148:151], v[182:185], v[102:105]
	v_mfma_f32_16x16x32_bf16 v[94:97], v[156:159], v[182:185], v[94:97]
	v_mfma_f32_16x16x32_bf16 v[86:89], v[148:151], v[212:215], v[86:89]
	v_mfma_f32_16x16x32_bf16 v[78:81], v[156:159], v[212:215], v[78:81]
	v_mfma_f32_16x16x32_bf16 v[70:73], v[148:151], v[220:223], v[70:73]
	v_mfma_f32_16x16x32_bf16 v[66:69], v[156:159], v[220:223], v[66:69]
	v_mfma_f32_16x16x32_bf16 v[120:123], v[152:155], v[178:181], v[120:123]
	v_mfma_f32_16x16x32_bf16 v[110:113], v[160:163], v[178:181], v[110:113]
	v_mfma_f32_16x16x32_bf16 v[102:105], v[152:155], v[192:195], v[102:105]
	v_mfma_f32_16x16x32_bf16 v[94:97], v[160:163], v[192:195], v[94:97]
	v_mfma_f32_16x16x32_bf16 v[86:89], v[152:155], v[216:219], v[86:89]
	v_mfma_f32_16x16x32_bf16 v[78:81], v[160:163], v[216:219], v[78:81]
	v_mfma_f32_16x16x32_bf16 v[70:73], v[152:155], v[224:227], v[70:73]
	v_mfma_f32_16x16x32_bf16 v[66:69], v[160:163], v[224:227], v[66:69]
	s_barrier
; #define PG8_STAGE(bufoff, gbase, voff) do { _Pragma("unroll") for (int _i = 0; _i < 2; ++_i) \
;         __builtin_amdgcn_global_load_lds((const unsigned*)((const char*)(gbase) + (voff)[_i]), (LAS unsigned*)(lds + (bufoff) + ldsw + _i * 8192), 16, 0, 0); } while (0)
; #define PG8_LDA(dst, b, h) do { _Pragma("unroll") for (int m = 0; m < 4; ++m) _Pragma("unroll") for (int k = 0; k < 2; ++k) dst[m][k] = *(const LAS bf16x8*)(lds + PG8_SA(b, h) + aoff + m * 2048 + k * 1024); } while (0)
; #define PG8_MMA(ai, bj, At, Bt) do { __builtin_amdgcn_s_setprio(1); _Pragma("unroll") for (int m = 0; m < 4; ++m) _Pragma("unroll") for (int n = 0; n < 2; ++n) _Pragma("unroll") for (int k = 0; k < 2; ++k) \
;         acc[ai][bj][m][n] = __builtin_amdgcn_mfma_f32_16x16x32_bf16(Bt[n][k], At[m][k], acc[ai][bj][m][n], 0, 0, 0); __builtin_amdgcn_s_setprio(0); } while (0)
; #define PG8_WAIT_V(n) asm volatile("s_waitcnt vmcnt(" #n ")" ::: "memory")
; #define PG8_WAIT_L(n) asm volatile("s_waitcnt lgkmcnt(" #n ")" ::: "memory")
; #define PG8_BAR __builtin_amdgcn_s_barrier()
; #define PG8_SCHED __builtin_amdgcn_sched_barrier(0)
; template <class Epi, class Sched, bool ALIGN_EPI = true, bool SP2 = true>
; __device__ __forceinline__ void gemm_phase(LAS unsigned char* lds, const Sched& S, const Epi& E, const int lda, const int ldb) {
;     ...
;             PG8_LDA(At, 1, 1); PG8_STAGE(PG8_SB(1, 0), b3, voffB); PG8_STAGE(PG8_SB(1, 1), b3 + hstepB, voffB); PG8_STAGE(PG8_SA(1, 0), a3, voffA);
;             PG8_WAIT_V(8); PG8_WAIT_L(0); PG8_BAR; PG8_MMA(1, 0, At, B0); PG8_MMA(1, 1, At, B1); PG8_BAR; PG8_SCHED;
;     ...
;         if constexpr (ALIGN_EPI) { if (wr == 0) PG8_BAR; }
	s_add_i32 s29, s29, s62
	v_lshl_add_u64 v[186:187], v[186:187], 0, s[70:71]
	s_mov_b32 m0, s29
	ds_read_b128 v[164:167], v191 offset:49152
	ds_read_b128 v[178:181], v191 offset:50176
	ds_read_b128 v[182:185], v191 offset:51200
	ds_read_b128 v[192:195], v191 offset:52224
	ds_read_b128 v[212:215], v191 offset:53248
	ds_read_b128 v[216:219], v191 offset:54272
	ds_read_b128 v[220:223], v191 offset:55296
	ds_read_b128 v[224:227], v191 offset:56320
	global_load_lds_dwordx4 v[186:187], off
	s_add_i32 m0, s29, 0x2000
	s_add_u32 s36, s36, 0x40080
	v_lshl_add_u64 v[186:187], v[196:197], 0, s[70:71]
	s_addc_u32 s37, s37, 0
	s_add_i32 s29, s54, s62
	global_load_lds_dwordx4 v[186:187], off
	v_lshl_add_u64 v[186:187], s[36:37], 0, v[114:115]
	s_mov_b32 m0, s29
	s_nop 0
	global_load_lds_dwordx4 v[186:187], off
	v_lshl_add_u64 v[186:187], s[36:37], 0, v[168:169]
	s_add_i32 m0, s29, 0x2000
	s_nop 0
	global_load_lds_dwordx4 v[186:187], off
	v_lshl_add_u64 v[186:187], v[228:229], 0, s[70:71]
	s_mov_b32 m0, s82
	s_nop 0
	global_load_lds_dwordx4 v[186:187], off
	v_lshl_add_u64 v[186:187], v[230:231], 0, s[70:71]
	s_mov_b32 m0, s86
	s_nop 0
	global_load_lds_dwordx4 v[186:187], off
	s_waitcnt vmcnt(8)
	s_waitcnt lgkmcnt(0)
	s_barrier
	s_waitcnt lgkmcnt(0)
	v_mfma_f32_16x16x32_bf16 v[62:65], v[132:135], v[164:167], v[62:65]
	v_mfma_f32_16x16x32_bf16 v[58:61], v[140:143], v[164:167], v[58:61]
	v_mfma_f32_16x16x32_bf16 v[50:53], v[132:135], v[182:185], v[50:53]
	v_mfma_f32_16x16x32_bf16 v[42:45], v[140:143], v[182:185], v[42:45]
	v_mfma_f32_16x16x32_bf16 v[34:37], v[132:135], v[212:215], v[34:37]
	v_mfma_f32_16x16x32_bf16 v[26:29], v[140:143], v[212:215], v[26:29]
	v_mfma_f32_16x16x32_bf16 v[18:21], v[132:135], v[220:223], v[18:21]
	v_mfma_f32_16x16x32_bf16 v[10:13], v[140:143], v[220:223], v[10:13]
	v_mfma_f32_16x16x32_bf16 v[62:65], v[136:139], v[178:181], v[62:65]
	v_mfma_f32_16x16x32_bf16 v[58:61], v[144:147], v[178:181], v[58:61]
	v_mfma_f32_16x16x32_bf16 v[50:53], v[136:139], v[192:195], v[50:53]
	v_mfma_f32_16x16x32_bf16 v[42:45], v[144:147], v[192:195], v[42:45]
	v_mfma_f32_16x16x32_bf16 v[34:37], v[136:139], v[216:219], v[34:37]
	v_mfma_f32_16x16x32_bf16 v[26:29], v[144:147], v[216:219], v[26:29]
	v_mfma_f32_16x16x32_bf16 v[18:21], v[136:139], v[224:227], v[18:21]
	v_mfma_f32_16x16x32_bf16 v[10:13], v[144:147], v[224:227], v[10:13]
	v_mfma_f32_16x16x32_bf16 v[54:57], v[148:151], v[164:167], v[54:57]
	v_mfma_f32_16x16x32_bf16 v[46:49], v[156:159], v[164:167], v[46:49]
	v_mfma_f32_16x16x32_bf16 v[38:41], v[148:151], v[182:185], v[38:41]
	v_mfma_f32_16x16x32_bf16 v[30:33], v[156:159], v[182:185], v[30:33]
	v_mfma_f32_16x16x32_bf16 v[22:25], v[148:151], v[212:215], v[22:25]
	v_mfma_f32_16x16x32_bf16 v[14:17], v[156:159], v[212:215], v[14:17]
	v_mfma_f32_16x16x32_bf16 v[6:9], v[148:151], v[220:223], v[6:9]
	v_mfma_f32_16x16x32_bf16 v[2:5], v[156:159], v[220:223], v[2:5]
	v_mfma_f32_16x16x32_bf16 v[54:57], v[152:155], v[178:181], v[54:57]
	v_mfma_f32_16x16x32_bf16 v[46:49], v[160:163], v[178:181], v[46:49]
	v_mfma_f32_16x16x32_bf16 v[38:41], v[152:155], v[192:195], v[38:41]
	v_mfma_f32_16x16x32_bf16 v[30:33], v[160:163], v[192:195], v[30:33]
	v_mfma_f32_16x16x32_bf16 v[22:25], v[152:155], v[216:219], v[22:25]
	v_mfma_f32_16x16x32_bf16 v[14:17], v[160:163], v[216:219], v[14:17]
	v_mfma_f32_16x16x32_bf16 v[6:9], v[152:155], v[224:227], v[6:9]
	v_mfma_f32_16x16x32_bf16 v[2:5], v[160:163], v[224:227], v[2:5]
	s_barrier
	s_add_i32 s50, s50, 2
	s_add_u32 s26, s26, 0x100
	s_addc_u32 s27, s27, 0
	s_add_u32 vcc_lo, vcc_lo, 0x100
	s_addc_u32 vcc_hi, vcc_hi, 0
	s_cmp_gt_u32 s50, 13
	s_cbranch_scc0 .LBB0_651
	s_and_b64 vcc, exec, s[18:19]
	s_cbranch_vccz .LBB0_654
	s_barrier

; #define PG8_STAGE(bufoff, gbase, voff) do { _Pragma("unroll") for (int _i = 0; _i < 2; ++_i) \
;         __builtin_amdgcn_global_load_lds((const unsigned*)((const char*)(gbase) + (voff)[_i]), (LAS unsigned*)(lds + (bufoff) + ldsw + _i * 8192), 16, 0, 0); } while (0)
; #define PG8_LDA(dst, b, h) do { _Pragma("unroll") for (int m = 0; m < 4; ++m) _Pragma("unroll") for (int k = 0; k < 2; ++k) dst[m][k] = *(const LAS bf16x8*)(lds + PG8_SA(b, h) + aoff + m * 2048 + k * 1024); } while (0)
; #define PG8_LDB(dst, b, h) do { _Pragma("unroll") for (int n = 0; n < 2; ++n) _Pragma("unroll") for (int k = 0; k < 2; ++k) dst[n][k] = *(const LAS bf16x8*)(lds + PG8_SB(b, h) + boff + n * 2048 + k * 1024); } while (0)
; #define PG8_MMA(ai, bj, At, Bt) do { __builtin_amdgcn_s_setprio(1); _Pragma("unroll") for (int m = 0; m < 4; ++m) _Pragma("unroll") for (int n = 0; n < 2; ++n) _Pragma("unroll") for (int k = 0; k < 2; ++k) \
;         acc[ai][bj][m][n] = __builtin_amdgcn_mfma_f32_16x16x32_bf16(Bt[n][k], At[m][k], acc[ai][bj][m][n], 0, 0, 0); __builtin_amdgcn_s_setprio(0); } while (0)
; #define PG8_WAIT_V(n) asm volatile("s_waitcnt vmcnt(" #n ")" ::: "memory")
; #define PG8_WAIT_L(n) asm volatile("s_waitcnt lgkmcnt(" #n ")" ::: "memory")
; #define PG8_BAR __builtin_amdgcn_s_barrier()
; #define PG8_SCHED __builtin_amdgcn_sched_barrier(0)
; template <class Epi, class Sched, bool ALIGN_EPI = true, bool SP2 = true>
; __device__ __forceinline__ void gemm_phase(LAS unsigned char* lds, const Sched& S, const Epi& E, const int lda, const int ldb) {
;     ...
;             const bool last = (t == nt - 2);
;             const char* a1 = cA + (size_t)(t + 1) * kstep;
;             const char* a2 = last ? nA : cA + (size_t)(t + 2) * kstep; const char* b2 = last ? nB : cB + (size_t)(t + 2) * kstep;
;             const char* a3 = a2 + kstep; const char* b3 = b2 + kstep;
;             if constexpr (SP2) {
;             PG8_LDB(B0, 0, 0); PG8_LDB(B1, 0, 1); PG8_SCHED; PG8_LDA(At, 0, 0); PG8_STAGE(PG8_SA(1, 1), a1 + hstepA, voffA);
;             PG8_WAIT_V(8); PG8_WAIT_L(0); PG8_BAR; PG8_MMA(0, 0, At, B0); PG8_MMA(0, 1, At, B1); PG8_BAR; PG8_SCHED;
;             PG8_LDA(At, 0, 1); PG8_STAGE(PG8_SB(0, 0), b2, voffB); PG8_STAGE(PG8_SB(0, 1), b2 + hstepB, voffB); PG8_STAGE(PG8_SA(0, 0), a2, voffA);
.LBB0_667:
	s_add_u32 s29, s36, 0xfffc0080
	s_addc_u32 s38, s37, -1
	s_add_i32 s50, 0, 0x10000
	s_cmp_eq_u32 s30, 12
	s_cselect_b32 s41, s21, s38
	s_cselect_b32 s40, s20, s29
	v_add_u32_e32 v142, s50, v145
	s_cselect_b32 s39, s25, s28
	s_cselect_b32 s38, s24, s23
	s_add_i32 s29, 0, 0x14000
	ds_read_b128 v[148:151], v142
	ds_read_b128 v[152:155], v142 offset:1024
	ds_read_b128 v[156:159], v142 offset:2048
	ds_read_b128 v[160:163], v142 offset:3072
	v_add_u32_e32 v142, s29, v145
	ds_read_b128 v[164:167], v142
	ds_read_b128 v[168:171], v142 offset:1024
	ds_read_b128 v[172:175], v142 offset:2048
	ds_read_b128 v[176:179], v142 offset:3072
	v_lshl_add_u64 v[142:143], s[36:37], 0, v[138:139]
	s_add_i32 m0, s27, 0xc000
	ds_read_b128 v[180:183], v147
	ds_read_b128 v[184:187], v147 offset:1024
	ds_read_b128 v[188:191], v147 offset:2048
	ds_read_b128 v[192:195], v147 offset:3072
	ds_read_b128 v[212:215], v147 offset:4096
	ds_read_b128 v[216:219], v147 offset:5120
	ds_read_b128 v[220:223], v147 offset:6144
	ds_read_b128 v[224:227], v147 offset:7168
	global_load_lds_dwordx4 v[142:143], off
	v_lshl_add_u64 v[142:143], s[36:37], 0, v[140:141]
	s_add_i32 m0, s27, 0xe000
	s_nop 0
	global_load_lds_dwordx4 v[142:143], off
	s_waitcnt vmcnt(8)
	s_waitcnt lgkmcnt(0)
	s_barrier
	s_waitcnt lgkmcnt(0)
	v_mfma_f32_16x16x32_bf16 v[128:131], v[148:151], v[180:183], v[128:131]
	v_mfma_f32_16x16x32_bf16 v[124:127], v[156:159], v[180:183], v[124:127]
	v_mfma_f32_16x16x32_bf16 v[120:123], v[148:151], v[188:191], v[120:123]
	v_mfma_f32_16x16x32_bf16 v[110:113], v[156:159], v[188:191], v[110:113]
	v_mfma_f32_16x16x32_bf16 v[102:105], v[148:151], v[212:215], v[102:105]
	v_mfma_f32_16x16x32_bf16 v[94:97], v[156:159], v[212:215], v[94:97]
	v_mfma_f32_16x16x32_bf16 v[86:89], v[148:151], v[220:223], v[86:89]
	v_mfma_f32_16x16x32_bf16 v[78:81], v[156:159], v[220:223], v[78:81]
	v_mfma_f32_16x16x32_bf16 v[128:131], v[152:155], v[184:187], v[128:131]
	v_mfma_f32_16x16x32_bf16 v[124:127], v[160:163], v[184:187], v[124:127]
	v_mfma_f32_16x16x32_bf16 v[120:123], v[152:155], v[192:195], v[120:123]
	v_mfma_f32_16x16x32_bf16 v[110:113], v[160:163], v[192:195], v[110:113]
	v_mfma_f32_16x16x32_bf16 v[102:105], v[152:155], v[216:219], v[102:105]
	v_mfma_f32_16x16x32_bf16 v[94:97], v[160:163], v[216:219], v[94:97]
	v_mfma_f32_16x16x32_bf16 v[86:89], v[152:155], v[224:227], v[86:89]
	v_mfma_f32_16x16x32_bf16 v[78:81], v[160:163], v[224:227], v[78:81]
	v_mfma_f32_16x16x32_bf16 v[116:119], v[164:167], v[180:183], v[116:119]
	v_mfma_f32_16x16x32_bf16 v[106:109], v[172:175], v[180:183], v[106:109]
	v_mfma_f32_16x16x32_bf16 v[98:101], v[164:167], v[188:191], v[98:101]
	v_mfma_f32_16x16x32_bf16 v[90:93], v[172:175], v[188:191], v[90:93]
	v_mfma_f32_16x16x32_bf16 v[82:85], v[164:167], v[212:215], v[82:85]
	v_mfma_f32_16x16x32_bf16 v[74:77], v[172:175], v[212:215], v[74:77]
	v_mfma_f32_16x16x32_bf16 v[70:73], v[164:167], v[220:223], v[70:73]
	v_mfma_f32_16x16x32_bf16 v[66:69], v[172:175], v[220:223], v[66:69]
	v_mfma_f32_16x16x32_bf16 v[116:119], v[168:171], v[184:187], v[116:119]
	v_mfma_f32_16x16x32_bf16 v[106:109], v[176:179], v[184:187], v[106:109]
	v_mfma_f32_16x16x32_bf16 v[98:101], v[168:171], v[192:195], v[98:101]
	v_mfma_f32_16x16x32_bf16 v[90:93], v[176:179], v[192:195], v[90:93]
	v_mfma_f32_16x16x32_bf16 v[82:85], v[168:171], v[216:219], v[82:85]
	v_mfma_f32_16x16x32_bf16 v[74:77], v[176:179], v[216:219], v[74:77]
	v_mfma_f32_16x16x32_bf16 v[70:73], v[168:171], v[224:227], v[70:73]
	v_mfma_f32_16x16x32_bf16 v[66:69], v[176:179], v[224:227], v[66:69]
	s_barrier
	s_add_i32 s50, s50, s63
	v_lshl_add_u64 v[142:143], s[38:39], 0, v[114:115]
	s_mov_b32 m0, s50
	ds_read_b128 v[180:183], v147 offset:16384
	ds_read_b128 v[184:187], v147 offset:17408
	ds_read_b128 v[188:191], v147 offset:18432
	ds_read_b128 v[192:195], v147 offset:19456
	ds_read_b128 v[212:215], v147 offset:20480
	ds_read_b128 v[216:219], v147 offset:21504
	ds_read_b128 v[220:223], v147 offset:22528
	ds_read_b128 v[224:227], v147 offset:23552
	global_load_lds_dwordx4 v[142:143], off
	s_add_i32 m0, s50, 0x2000
	s_add_u32 s54, s38, 0x40000
	v_lshl_add_u64 v[196:197], s[38:39], 0, v[132:133]
	s_addc_u32 s55, s39, 0
	s_add_i32 s29, s29, s63
	global_load_lds_dwordx4 v[196:197], off
	v_lshl_add_u64 v[228:229], s[54:55], 0, v[114:115]
	s_mov_b32 m0, s29
	v_lshl_add_u64 v[230:231], s[40:41], 0, v[134:135]
	global_load_lds_dwordx4 v[228:229], off
	v_lshl_add_u64 v[228:229], s[54:55], 0, v[132:133]
	s_add_i32 m0, s29, 0x2000
	s_nop 0
	global_load_lds_dwordx4 v[228:229], off
	v_lshl_add_u64 v[228:229], s[40:41], 0, v[136:137]
	s_mov_b32 m0, s27
	s_nop 0
	global_load_lds_dwordx4 v[228:229], off
	s_mov_b32 m0, s72
	s_nop 0
	global_load_lds_dwordx4 v[230:231], off
	s_waitcnt vmcnt(8)
	s_waitcnt lgkmcnt(0)
	s_barrier
; #define PG8_STAGE(bufoff, gbase, voff) do { _Pragma("unroll") for (int _i = 0; _i < 2; ++_i) \
;         __builtin_amdgcn_global_load_lds((const unsigned*)((const char*)(gbase) + (voff)[_i]), (LAS unsigned*)(lds + (bufoff) + ldsw + _i * 8192), 16, 0, 0); } while (0)
; #define PG8_LDA(dst, b, h) do { _Pragma("unroll") for (int m = 0; m < 4; ++m) _Pragma("unroll") for (int k = 0; k < 2; ++k) dst[m][k] = *(const LAS bf16x8*)(lds + PG8_SA(b, h) + aoff + m * 2048 + k * 1024); } while (0)
; #define PG8_LDB(dst, b, h) do { _Pragma("unroll") for (int n = 0; n < 2; ++n) _Pragma("unroll") for (int k = 0; k < 2; ++k) dst[n][k] = *(const LAS bf16x8*)(lds + PG8_SB(b, h) + boff + n * 2048 + k * 1024); } while (0)
; #define PG8_MMA(ai, bj, At, Bt) do { __builtin_amdgcn_s_setprio(1); _Pragma("unroll") for (int m = 0; m < 4; ++m) _Pragma("unroll") for (int n = 0; n < 2; ++n) _Pragma("unroll") for (int k = 0; k < 2; ++k) \
;         acc[ai][bj][m][n] = __builtin_amdgcn_mfma_f32_16x16x32_bf16(Bt[n][k], At[m][k], acc[ai][bj][m][n], 0, 0, 0); __builtin_amdgcn_s_setprio(0); } while (0)
; #define PG8_WAIT_V(n) asm volatile("s_waitcnt vmcnt(" #n ")" ::: "memory")
; #define PG8_WAIT_L(n) asm volatile("s_waitcnt lgkmcnt(" #n ")" ::: "memory")
; #define PG8_BAR __builtin_amdgcn_s_barrier()
; #define PG8_SCHED __builtin_amdgcn_sched_barrier(0)
; template <class Epi, class Sched, bool ALIGN_EPI = true, bool SP2 = true>
; __device__ __forceinline__ void gemm_phase(LAS unsigned char* lds, const Sched& S, const Epi& E, const int lda, const int ldb) {
;     ...
;             PG8_WAIT_V(8); PG8_WAIT_L(0); PG8_BAR; PG8_MMA(1, 0, At, B0); PG8_MMA(1, 1, At, B1); PG8_BAR; PG8_SCHED;
;             PG8_LDB(B0, 1, 0); PG8_LDB(B1, 1, 1); PG8_SCHED; PG8_LDA(At, 1, 0); PG8_STAGE(PG8_SA(0, 1), a2 + hstepA, voffA);
;             PG8_WAIT_V(8); PG8_WAIT_L(0); PG8_BAR; PG8_MMA(0, 0, At, B0); PG8_MMA(0, 1, At, B1); PG8_BAR; PG8_SCHED;
	s_waitcnt lgkmcnt(0)
	v_mfma_f32_16x16x32_bf16 v[62:65], v[148:151], v[180:183], v[62:65]
	v_mfma_f32_16x16x32_bf16 v[58:61], v[156:159], v[180:183], v[58:61]
	v_mfma_f32_16x16x32_bf16 v[54:57], v[148:151], v[188:191], v[54:57]
	v_mfma_f32_16x16x32_bf16 v[46:49], v[156:159], v[188:191], v[46:49]
	v_mfma_f32_16x16x32_bf16 v[38:41], v[148:151], v[212:215], v[38:41]
	v_mfma_f32_16x16x32_bf16 v[30:33], v[156:159], v[212:215], v[30:33]
	v_mfma_f32_16x16x32_bf16 v[22:25], v[148:151], v[220:223], v[22:25]
	v_mfma_f32_16x16x32_bf16 v[14:17], v[156:159], v[220:223], v[14:17]
	v_mfma_f32_16x16x32_bf16 v[62:65], v[152:155], v[184:187], v[62:65]
	v_mfma_f32_16x16x32_bf16 v[58:61], v[160:163], v[184:187], v[58:61]
	v_mfma_f32_16x16x32_bf16 v[54:57], v[152:155], v[192:195], v[54:57]
	v_mfma_f32_16x16x32_bf16 v[46:49], v[160:163], v[192:195], v[46:49]
	v_mfma_f32_16x16x32_bf16 v[38:41], v[152:155], v[216:219], v[38:41]
	v_mfma_f32_16x16x32_bf16 v[30:33], v[160:163], v[216:219], v[30:33]
	v_mfma_f32_16x16x32_bf16 v[22:25], v[152:155], v[224:227], v[22:25]
	v_mfma_f32_16x16x32_bf16 v[14:17], v[160:163], v[224:227], v[14:17]
	v_mfma_f32_16x16x32_bf16 v[50:53], v[164:167], v[180:183], v[50:53]
	v_mfma_f32_16x16x32_bf16 v[42:45], v[172:175], v[180:183], v[42:45]
	v_mfma_f32_16x16x32_bf16 v[34:37], v[164:167], v[188:191], v[34:37]
	v_mfma_f32_16x16x32_bf16 v[26:29], v[172:175], v[188:191], v[26:29]
	v_mfma_f32_16x16x32_bf16 v[18:21], v[164:167], v[212:215], v[18:21]
	v_mfma_f32_16x16x32_bf16 v[10:13], v[172:175], v[212:215], v[10:13]
	v_mfma_f32_16x16x32_bf16 v[6:9], v[164:167], v[220:223], v[6:9]
	v_mfma_f32_16x16x32_bf16 v[2:5], v[172:175], v[220:223], v[2:5]
	v_mfma_f32_16x16x32_bf16 v[50:53], v[168:171], v[184:187], v[50:53]
	v_mfma_f32_16x16x32_bf16 v[42:45], v[176:179], v[184:187], v[42:45]
	v_mfma_f32_16x16x32_bf16 v[34:37], v[168:171], v[192:195], v[34:37]
	v_mfma_f32_16x16x32_bf16 v[26:29], v[176:179], v[192:195], v[26:29]
	v_mfma_f32_16x16x32_bf16 v[18:21], v[168:171], v[216:219], v[18:21]
	v_mfma_f32_16x16x32_bf16 v[10:13], v[176:179], v[216:219], v[10:13]
	v_mfma_f32_16x16x32_bf16 v[6:9], v[168:171], v[224:227], v[6:9]
	v_mfma_f32_16x16x32_bf16 v[2:5], v[176:179], v[224:227], v[2:5]
	s_barrier
	s_add_i32 s29, 0, 0x18000
	s_add_i32 s50, 0, 0x1c000
	v_add_u32_e32 v160, s29, v145
	v_add_u32_e32 v176, s50, v145
	ds_read_b128 v[148:151], v160
	ds_read_b128 v[152:155], v160 offset:1024
	ds_read_b128 v[156:159], v160 offset:2048
	ds_read_b128 v[160:163], v160 offset:3072
	ds_read_b128 v[164:167], v176
	ds_read_b128 v[168:171], v176 offset:1024
	ds_read_b128 v[172:175], v176 offset:2048
	ds_read_b128 v[176:179], v176 offset:3072
	s_add_u32 s40, s40, 0x40000
	s_addc_u32 s41, s41, 0
	s_mov_b32 m0, s33
	v_lshl_add_u64 v[232:233], s[40:41], 0, v[136:137]
	ds_read_b128 v[180:183], v147 offset:32768
	ds_read_b128 v[184:187], v147 offset:33792
	ds_read_b128 v[188:191], v147 offset:34816
	ds_read_b128 v[192:195], v147 offset:35840
	ds_read_b128 v[212:215], v147 offset:36864
	ds_read_b128 v[216:219], v147 offset:37888
	ds_read_b128 v[220:223], v147 offset:38912
	ds_read_b128 v[224:227], v147 offset:39936
	global_load_lds_dwordx4 v[232:233], off
	v_lshl_add_u64 v[232:233], s[40:41], 0, v[134:135]
	s_mov_b32 m0, s73
	s_nop 0
	global_load_lds_dwordx4 v[232:233], off
	s_waitcnt vmcnt(8)
	s_waitcnt lgkmcnt(0)
	s_barrier
	s_waitcnt lgkmcnt(0)
	v_mfma_f32_16x16x32_bf16 v[128:131], v[148:151], v[180:183], v[128:131]
	v_mfma_f32_16x16x32_bf16 v[124:127], v[156:159], v[180:183], v[124:127]
	v_mfma_f32_16x16x32_bf16 v[120:123], v[148:151], v[188:191], v[120:123]
	v_mfma_f32_16x16x32_bf16 v[110:113], v[156:159], v[188:191], v[110:113]
	v_mfma_f32_16x16x32_bf16 v[102:105], v[148:151], v[212:215], v[102:105]
	v_mfma_f32_16x16x32_bf16 v[94:97], v[156:159], v[212:215], v[94:97]
	v_mfma_f32_16x16x32_bf16 v[86:89], v[148:151], v[220:223], v[86:89]
	v_mfma_f32_16x16x32_bf16 v[78:81], v[156:159], v[220:223], v[78:81]
	v_mfma_f32_16x16x32_bf16 v[128:131], v[152:155], v[184:187], v[128:131]
	v_mfma_f32_16x16x32_bf16 v[124:127], v[160:163], v[184:187], v[124:127]
	v_mfma_f32_16x16x32_bf16 v[120:123], v[152:155], v[192:195], v[120:123]
	v_mfma_f32_16x16x32_bf16 v[110:113], v[160:163], v[192:195], v[110:113]
	v_mfma_f32_16x16x32_bf16 v[102:105], v[152:155], v[216:219], v[102:105]
	v_mfma_f32_16x16x32_bf16 v[94:97], v[160:163], v[216:219], v[94:97]
	v_mfma_f32_16x16x32_bf16 v[86:89], v[152:155], v[224:227], v[86:89]
	v_mfma_f32_16x16x32_bf16 v[78:81], v[160:163], v[224:227], v[78:81]
	v_mfma_f32_16x16x32_bf16 v[116:119], v[164:167], v[180:183], v[116:119]
	v_mfma_f32_16x16x32_bf16 v[106:109], v[172:175], v[180:183], v[106:109]
	v_mfma_f32_16x16x32_bf16 v[98:101], v[164:167], v[188:191], v[98:101]
	v_mfma_f32_16x16x32_bf16 v[90:93], v[172:175], v[188:191], v[90:93]
	v_mfma_f32_16x16x32_bf16 v[82:85], v[164:167], v[212:215], v[82:85]
	v_mfma_f32_16x16x32_bf16 v[74:77], v[172:175], v[212:215], v[74:77]
	v_mfma_f32_16x16x32_bf16 v[70:73], v[164:167], v[220:223], v[70:73]
	v_mfma_f32_16x16x32_bf16 v[66:69], v[172:175], v[220:223], v[66:69]
	v_mfma_f32_16x16x32_bf16 v[116:119], v[168:171], v[184:187], v[116:119]
	v_mfma_f32_16x16x32_bf16 v[106:109], v[176:179], v[184:187], v[106:109]
	v_mfma_f32_16x16x32_bf16 v[98:101], v[168:171], v[192:195], v[98:101]
	v_mfma_f32_16x16x32_bf16 v[90:93], v[176:179], v[192:195], v[90:93]
	v_mfma_f32_16x16x32_bf16 v[82:85], v[168:171], v[216:219], v[82:85]
	v_mfma_f32_16x16x32_bf16 v[74:77], v[176:179], v[216:219], v[74:77]
	v_mfma_f32_16x16x32_bf16 v[70:73], v[168:171], v[224:227], v[70:73]
	v_mfma_f32_16x16x32_bf16 v[66:69], v[176:179], v[224:227], v[66:69]
	s_barrier
; #define PG8_STAGE(bufoff, gbase, voff) do { _Pragma("unroll") for (int _i = 0; _i < 2; ++_i) \
;         __builtin_amdgcn_global_load_lds((const unsigned*)((const char*)(gbase) + (voff)[_i]), (LAS unsigned*)(lds + (bufoff) + ldsw + _i * 8192), 16, 0, 0); } while (0)
; #define PG8_LDA(dst, b, h) do { _Pragma("unroll") for (int m = 0; m < 4; ++m) _Pragma("unroll") for (int k = 0; k < 2; ++k) dst[m][k] = *(const LAS bf16x8*)(lds + PG8_SA(b, h) + aoff + m * 2048 + k * 1024); } while (0)
; #define PG8_MMA(ai, bj, At, Bt) do { __builtin_amdgcn_s_setprio(1); _Pragma("unroll") for (int m = 0; m < 4; ++m) _Pragma("unroll") for (int n = 0; n < 2; ++n) _Pragma("unroll") for (int k = 0; k < 2; ++k) \
;         acc[ai][bj][m][n] = __builtin_amdgcn_mfma_f32_16x16x32_bf16(Bt[n][k], At[m][k], acc[ai][bj][m][n], 0, 0, 0); __builtin_amdgcn_s_setprio(0); } while (0)
; #define PG8_WAIT_V(n) asm volatile("s_waitcnt vmcnt(" #n ")" ::: "memory")
; #define PG8_WAIT_L(n) asm volatile("s_waitcnt lgkmcnt(" #n ")" ::: "memory")
; #define PG8_BAR __builtin_amdgcn_s_barrier()
; #define PG8_SCHED __builtin_amdgcn_sched_barrier(0)
; template <class Epi, class Sched, bool ALIGN_EPI = true, bool SP2 = true>
; __device__ __forceinline__ void gemm_phase(LAS unsigned char* lds, const Sched& S, const Epi& E, const int lda, const int ldb) {
;     ...
;             PG8_LDA(At, 1, 1); PG8_STAGE(PG8_SB(1, 0), b3, voffB); PG8_STAGE(PG8_SB(1, 1), b3 + hstepB, voffB); PG8_STAGE(PG8_SA(1, 0), a3, voffA);
;             PG8_WAIT_V(8); PG8_WAIT_L(0); PG8_BAR; PG8_MMA(1, 0, At, B0); PG8_MMA(1, 1, At, B1); PG8_BAR; PG8_SCHED;
;     ...
;         if constexpr (ALIGN_EPI) { if (wr == 0) PG8_BAR; }
	s_add_i32 s29, s29, s63
	v_lshl_add_u64 v[142:143], v[142:143], 0, s[70:71]
	s_mov_b32 m0, s29
	ds_read_b128 v[180:183], v147 offset:49152
	ds_read_b128 v[184:187], v147 offset:50176
	ds_read_b128 v[188:191], v147 offset:51200
	ds_read_b128 v[192:195], v147 offset:52224
	ds_read_b128 v[212:215], v147 offset:53248
	ds_read_b128 v[216:219], v147 offset:54272
	ds_read_b128 v[220:223], v147 offset:55296
	ds_read_b128 v[224:227], v147 offset:56320
	global_load_lds_dwordx4 v[142:143], off
	s_add_i32 m0, s29, 0x2000
	s_add_u32 s38, s38, 0x40080
	v_lshl_add_u64 v[142:143], v[196:197], 0, s[70:71]
	s_addc_u32 s39, s39, 0
	s_add_i32 s29, s50, s63
	global_load_lds_dwordx4 v[142:143], off
	v_lshl_add_u64 v[142:143], s[38:39], 0, v[114:115]
	s_mov_b32 m0, s29
	s_nop 0
	global_load_lds_dwordx4 v[142:143], off
	v_lshl_add_u64 v[142:143], s[38:39], 0, v[132:133]
	s_add_i32 m0, s29, 0x2000
	s_nop 0
	global_load_lds_dwordx4 v[142:143], off
	v_lshl_add_u64 v[142:143], v[228:229], 0, s[70:71]
	s_mov_b32 m0, s74
	s_nop 0
	global_load_lds_dwordx4 v[142:143], off
	v_lshl_add_u64 v[142:143], v[230:231], 0, s[70:71]
	s_mov_b32 m0, s75
	s_nop 0
	global_load_lds_dwordx4 v[142:143], off
	s_waitcnt vmcnt(8)
	s_waitcnt lgkmcnt(0)
	s_barrier
	s_waitcnt lgkmcnt(0)
	v_mfma_f32_16x16x32_bf16 v[62:65], v[148:151], v[180:183], v[62:65]
	v_mfma_f32_16x16x32_bf16 v[58:61], v[156:159], v[180:183], v[58:61]
	v_mfma_f32_16x16x32_bf16 v[54:57], v[148:151], v[188:191], v[54:57]
	v_mfma_f32_16x16x32_bf16 v[46:49], v[156:159], v[188:191], v[46:49]
	v_mfma_f32_16x16x32_bf16 v[38:41], v[148:151], v[212:215], v[38:41]
	v_mfma_f32_16x16x32_bf16 v[30:33], v[156:159], v[212:215], v[30:33]
	v_mfma_f32_16x16x32_bf16 v[22:25], v[148:151], v[220:223], v[22:25]
	v_mfma_f32_16x16x32_bf16 v[14:17], v[156:159], v[220:223], v[14:17]
	v_mfma_f32_16x16x32_bf16 v[62:65], v[152:155], v[184:187], v[62:65]
	v_mfma_f32_16x16x32_bf16 v[58:61], v[160:163], v[184:187], v[58:61]
	v_mfma_f32_16x16x32_bf16 v[54:57], v[152:155], v[192:195], v[54:57]
	v_mfma_f32_16x16x32_bf16 v[46:49], v[160:163], v[192:195], v[46:49]
	v_mfma_f32_16x16x32_bf16 v[38:41], v[152:155], v[216:219], v[38:41]
	v_mfma_f32_16x16x32_bf16 v[30:33], v[160:163], v[216:219], v[30:33]
	v_mfma_f32_16x16x32_bf16 v[22:25], v[152:155], v[224:227], v[22:25]
	v_mfma_f32_16x16x32_bf16 v[14:17], v[160:163], v[224:227], v[14:17]
	v_mfma_f32_16x16x32_bf16 v[50:53], v[164:167], v[180:183], v[50:53]
	v_mfma_f32_16x16x32_bf16 v[42:45], v[172:175], v[180:183], v[42:45]
	v_mfma_f32_16x16x32_bf16 v[34:37], v[164:167], v[188:191], v[34:37]
	v_mfma_f32_16x16x32_bf16 v[26:29], v[172:175], v[188:191], v[26:29]
	v_mfma_f32_16x16x32_bf16 v[18:21], v[164:167], v[212:215], v[18:21]
	v_mfma_f32_16x16x32_bf16 v[10:13], v[172:175], v[212:215], v[10:13]
	v_mfma_f32_16x16x32_bf16 v[6:9], v[164:167], v[220:223], v[6:9]
	v_mfma_f32_16x16x32_bf16 v[2:5], v[172:175], v[220:223], v[2:5]
	v_mfma_f32_16x16x32_bf16 v[50:53], v[168:171], v[184:187], v[50:53]
	v_mfma_f32_16x16x32_bf16 v[42:45], v[176:179], v[184:187], v[42:45]
	v_mfma_f32_16x16x32_bf16 v[34:37], v[168:171], v[192:195], v[34:37]
	v_mfma_f32_16x16x32_bf16 v[26:29], v[176:179], v[192:195], v[26:29]
	v_mfma_f32_16x16x32_bf16 v[18:21], v[168:171], v[216:219], v[18:21]
	v_mfma_f32_16x16x32_bf16 v[10:13], v[176:179], v[216:219], v[10:13]
	v_mfma_f32_16x16x32_bf16 v[6:9], v[168:171], v[224:227], v[6:9]
	v_mfma_f32_16x16x32_bf16 v[2:5], v[176:179], v[224:227], v[2:5]
	s_barrier
	s_add_i32 s30, s30, 2
	s_add_u32 s36, s36, 0x100
	s_addc_u32 s37, s37, 0
	s_add_u32 s23, s23, 0x100
	s_addc_u32 s28, s28, 0
	s_cmp_gt_u32 s30, 13
	s_cbranch_scc0 .LBB0_667
	s_and_b64 vcc, exec, s[18:19]
	s_cbranch_vccz .LBB0_670
	s_barrier

; #define PG8_STAGE(bufoff, gbase, voff) do { _Pragma("unroll") for (int _i = 0; _i < 2; ++_i) \
;         __builtin_amdgcn_global_load_lds((const unsigned*)((const char*)(gbase) + (voff)[_i]), (LAS unsigned*)(lds + (bufoff) + ldsw + _i * 8192), 16, 0, 0); } while (0)
; #define PG8_LDA(dst, b, h) do { _Pragma("unroll") for (int m = 0; m < 4; ++m) _Pragma("unroll") for (int k = 0; k < 2; ++k) dst[m][k] = *(const LAS bf16x8*)(lds + PG8_SA(b, h) + aoff + m * 2048 + k * 1024); } while (0)
; #define PG8_LDB(dst, b, h) do { _Pragma("unroll") for (int n = 0; n < 2; ++n) _Pragma("unroll") for (int k = 0; k < 2; ++k) dst[n][k] = *(const LAS bf16x8*)(lds + PG8_SB(b, h) + boff + n * 2048 + k * 1024); } while (0)
; #define PG8_MMA(ai, bj, At, Bt) do { __builtin_amdgcn_s_setprio(1); _Pragma("unroll") for (int m = 0; m < 4; ++m) _Pragma("unroll") for (int n = 0; n < 2; ++n) _Pragma("unroll") for (int k = 0; k < 2; ++k) \
;         acc[ai][bj][m][n] = __builtin_amdgcn_mfma_f32_16x16x32_bf16(Bt[n][k], At[m][k], acc[ai][bj][m][n], 0, 0, 0); __builtin_amdgcn_s_setprio(0); } while (0)
; #define PG8_WAIT_V(n) asm volatile("s_waitcnt vmcnt(" #n ")" ::: "memory")
; #define PG8_WAIT_L(n) asm volatile("s_waitcnt lgkmcnt(" #n ")" ::: "memory")
; #define PG8_BAR __builtin_amdgcn_s_barrier()
; #define PG8_SCHED __builtin_amdgcn_sched_barrier(0)
; template <class Epi, class Sched, bool ALIGN_EPI = true, bool SP2 = true>
; __device__ __forceinline__ void gemm_phase(LAS unsigned char* lds, const Sched& S, const Epi& E, const int lda, const int ldb) {
;     ...
;             const bool last = (t == nt - 2);
;             const char* a1 = cA + (size_t)(t + 1) * kstep;
;             const char* a2 = last ? nA : cA + (size_t)(t + 2) * kstep; const char* b2 = last ? nB : cB + (size_t)(t + 2) * kstep;
;             const char* a3 = a2 + kstep; const char* b3 = b2 + kstep;
;             if constexpr (SP2) {
;             PG8_LDB(B0, 0, 0); PG8_LDB(B1, 0, 1); PG8_SCHED; PG8_LDA(At, 0, 0); PG8_STAGE(PG8_SA(1, 1), a1 + hstepA, voffA);
;             PG8_WAIT_V(8); PG8_WAIT_L(0); PG8_BAR; PG8_MMA(0, 0, At, B0); PG8_MMA(0, 1, At, B1); PG8_BAR; PG8_SCHED;
;             PG8_LDA(At, 0, 1); PG8_STAGE(PG8_SB(0, 0), b2, voffB); PG8_STAGE(PG8_SB(0, 1), b2 + hstepB, voffB); PG8_STAGE(PG8_SA(0, 0), a2, voffA);
.LBB0_684:
	s_add_u32 s26, s24, 0xfffc0080
	s_addc_u32 s27, s25, -1
	s_add_i32 s29, 0, 0x10000
	s_cmp_eq_u32 s50, 12
	s_cselect_b32 s37, s19, s27
	s_cselect_b32 s36, s18, s26
	v_add_u32_e32 v142, s29, v145
	s_cselect_b32 s27, s21, s73
	s_cselect_b32 s26, s20, s72
	s_add_i32 s74, 0, 0x14000
	ds_read_b128 v[148:151], v142
	ds_read_b128 v[152:155], v142 offset:1024
	ds_read_b128 v[156:159], v142 offset:2048
	ds_read_b128 v[160:163], v142 offset:3072
	v_add_u32_e32 v142, s74, v145
	ds_read_b128 v[164:167], v142
	ds_read_b128 v[168:171], v142 offset:1024
	ds_read_b128 v[172:175], v142 offset:2048
	ds_read_b128 v[176:179], v142 offset:3072
	v_lshl_add_u64 v[142:143], s[24:25], 0, v[138:139]
	s_add_i32 m0, s41, 0xc000
	ds_read_b128 v[180:183], v147
	ds_read_b128 v[184:187], v147 offset:1024
	ds_read_b128 v[188:191], v147 offset:2048
	ds_read_b128 v[192:195], v147 offset:3072
	ds_read_b128 v[212:215], v147 offset:4096
	ds_read_b128 v[216:219], v147 offset:5120
	ds_read_b128 v[220:223], v147 offset:6144
	ds_read_b128 v[224:227], v147 offset:7168
	global_load_lds_dwordx4 v[142:143], off
	v_lshl_add_u64 v[142:143], s[24:25], 0, v[140:141]
	s_add_i32 m0, s41, 0xe000
	s_nop 0
	global_load_lds_dwordx4 v[142:143], off
	s_waitcnt vmcnt(8)
	s_waitcnt lgkmcnt(0)
	s_barrier
	s_waitcnt lgkmcnt(0)
	v_mfma_f32_16x16x32_bf16 v[128:131], v[148:151], v[180:183], v[128:131]
	v_mfma_f32_16x16x32_bf16 v[124:127], v[156:159], v[180:183], v[124:127]
	v_mfma_f32_16x16x32_bf16 v[120:123], v[148:151], v[188:191], v[120:123]
	v_mfma_f32_16x16x32_bf16 v[110:113], v[156:159], v[188:191], v[110:113]
	v_mfma_f32_16x16x32_bf16 v[102:105], v[148:151], v[212:215], v[102:105]
	v_mfma_f32_16x16x32_bf16 v[94:97], v[156:159], v[212:215], v[94:97]
	v_mfma_f32_16x16x32_bf16 v[86:89], v[148:151], v[220:223], v[86:89]
	v_mfma_f32_16x16x32_bf16 v[78:81], v[156:159], v[220:223], v[78:81]
	v_mfma_f32_16x16x32_bf16 v[128:131], v[152:155], v[184:187], v[128:131]
	v_mfma_f32_16x16x32_bf16 v[124:127], v[160:163], v[184:187], v[124:127]
	v_mfma_f32_16x16x32_bf16 v[120:123], v[152:155], v[192:195], v[120:123]
	v_mfma_f32_16x16x32_bf16 v[110:113], v[160:163], v[192:195], v[110:113]
	v_mfma_f32_16x16x32_bf16 v[102:105], v[152:155], v[216:219], v[102:105]
	v_mfma_f32_16x16x32_bf16 v[94:97], v[160:163], v[216:219], v[94:97]
	v_mfma_f32_16x16x32_bf16 v[86:89], v[152:155], v[224:227], v[86:89]
	v_mfma_f32_16x16x32_bf16 v[78:81], v[160:163], v[224:227], v[78:81]
	v_mfma_f32_16x16x32_bf16 v[116:119], v[164:167], v[180:183], v[116:119]
	v_mfma_f32_16x16x32_bf16 v[106:109], v[172:175], v[180:183], v[106:109]
	v_mfma_f32_16x16x32_bf16 v[98:101], v[164:167], v[188:191], v[98:101]
	v_mfma_f32_16x16x32_bf16 v[90:93], v[172:175], v[188:191], v[90:93]
	v_mfma_f32_16x16x32_bf16 v[82:85], v[164:167], v[212:215], v[82:85]
	v_mfma_f32_16x16x32_bf16 v[74:77], v[172:175], v[212:215], v[74:77]
	v_mfma_f32_16x16x32_bf16 v[70:73], v[164:167], v[220:223], v[70:73]
	v_mfma_f32_16x16x32_bf16 v[66:69], v[172:175], v[220:223], v[66:69]
	v_mfma_f32_16x16x32_bf16 v[116:119], v[168:171], v[184:187], v[116:119]
	v_mfma_f32_16x16x32_bf16 v[106:109], v[176:179], v[184:187], v[106:109]
	v_mfma_f32_16x16x32_bf16 v[98:101], v[168:171], v[192:195], v[98:101]
	v_mfma_f32_16x16x32_bf16 v[90:93], v[176:179], v[192:195], v[90:93]
	v_mfma_f32_16x16x32_bf16 v[82:85], v[168:171], v[216:219], v[82:85]
	v_mfma_f32_16x16x32_bf16 v[74:77], v[176:179], v[216:219], v[74:77]
	v_mfma_f32_16x16x32_bf16 v[70:73], v[168:171], v[224:227], v[70:73]
	v_mfma_f32_16x16x32_bf16 v[66:69], v[176:179], v[224:227], v[66:69]
	s_barrier
	s_add_i32 s29, s29, s39
	v_lshl_add_u64 v[142:143], s[26:27], 0, v[114:115]
	s_mov_b32 m0, s29
	ds_read_b128 v[180:183], v147 offset:16384
	ds_read_b128 v[184:187], v147 offset:17408
	ds_read_b128 v[188:191], v147 offset:18432
	ds_read_b128 v[192:195], v147 offset:19456
	ds_read_b128 v[212:215], v147 offset:20480
	ds_read_b128 v[216:219], v147 offset:21504
	ds_read_b128 v[220:223], v147 offset:22528
	ds_read_b128 v[224:227], v147 offset:23552
	global_load_lds_dwordx4 v[142:143], off
	s_add_i32 m0, s29, 0x2000
	s_add_u32 s54, s26, 0x520000
	v_lshl_add_u64 v[196:197], s[26:27], 0, v[132:133]
	s_addc_u32 s55, s27, 0
	s_add_i32 s29, s74, s39
	global_load_lds_dwordx4 v[196:197], off
	v_lshl_add_u64 v[228:229], s[54:55], 0, v[114:115]
	s_mov_b32 m0, s29
	v_lshl_add_u64 v[230:231], s[36:37], 0, v[134:135]
	global_load_lds_dwordx4 v[228:229], off
	v_lshl_add_u64 v[228:229], s[54:55], 0, v[132:133]
	s_add_i32 m0, s29, 0x2000
	s_nop 0
	global_load_lds_dwordx4 v[228:229], off
	v_lshl_add_u64 v[228:229], s[36:37], 0, v[136:137]
	s_mov_b32 m0, s41
	s_nop 0
	global_load_lds_dwordx4 v[228:229], off
	s_mov_b32 m0, s43
	s_nop 0
	global_load_lds_dwordx4 v[230:231], off
	s_waitcnt vmcnt(8)
	s_waitcnt lgkmcnt(0)
	s_barrier
; #define PG8_STAGE(bufoff, gbase, voff) do { _Pragma("unroll") for (int _i = 0; _i < 2; ++_i) \
;         __builtin_amdgcn_global_load_lds((const unsigned*)((const char*)(gbase) + (voff)[_i]), (LAS unsigned*)(lds + (bufoff) + ldsw + _i * 8192), 16, 0, 0); } while (0)
; #define PG8_LDA(dst, b, h) do { _Pragma("unroll") for (int m = 0; m < 4; ++m) _Pragma("unroll") for (int k = 0; k < 2; ++k) dst[m][k] = *(const LAS bf16x8*)(lds + PG8_SA(b, h) + aoff + m * 2048 + k * 1024); } while (0)
; #define PG8_LDB(dst, b, h) do { _Pragma("unroll") for (int n = 0; n < 2; ++n) _Pragma("unroll") for (int k = 0; k < 2; ++k) dst[n][k] = *(const LAS bf16x8*)(lds + PG8_SB(b, h) + boff + n * 2048 + k * 1024); } while (0)
; #define PG8_MMA(ai, bj, At, Bt) do { __builtin_amdgcn_s_setprio(1); _Pragma("unroll") for (int m = 0; m < 4; ++m) _Pragma("unroll") for (int n = 0; n < 2; ++n) _Pragma("unroll") for (int k = 0; k < 2; ++k) \
;         acc[ai][bj][m][n] = __builtin_amdgcn_mfma_f32_16x16x32_bf16(Bt[n][k], At[m][k], acc[ai][bj][m][n], 0, 0, 0); __builtin_amdgcn_s_setprio(0); } while (0)
; #define PG8_WAIT_V(n) asm volatile("s_waitcnt vmcnt(" #n ")" ::: "memory")
; #define PG8_WAIT_L(n) asm volatile("s_waitcnt lgkmcnt(" #n ")" ::: "memory")
; #define PG8_BAR __builtin_amdgcn_s_barrier()
; #define PG8_SCHED __builtin_amdgcn_sched_barrier(0)
; template <class Epi, class Sched, bool ALIGN_EPI = true, bool SP2 = true>
; __device__ __forceinline__ void gemm_phase(LAS unsigned char* lds, const Sched& S, const Epi& E, const int lda, const int ldb) {
;     ...
;             PG8_WAIT_V(8); PG8_WAIT_L(0); PG8_BAR; PG8_MMA(1, 0, At, B0); PG8_MMA(1, 1, At, B1); PG8_BAR; PG8_SCHED;
;             PG8_LDB(B0, 1, 0); PG8_LDB(B1, 1, 1); PG8_SCHED; PG8_LDA(At, 1, 0); PG8_STAGE(PG8_SA(0, 1), a2 + hstepA, voffA);
;             PG8_WAIT_V(8); PG8_WAIT_L(0); PG8_BAR; PG8_MMA(0, 0, At, B0); PG8_MMA(0, 1, At, B1); PG8_BAR; PG8_SCHED;
	s_waitcnt lgkmcnt(0)
	v_mfma_f32_16x16x32_bf16 v[62:65], v[148:151], v[180:183], v[62:65]
	v_mfma_f32_16x16x32_bf16 v[58:61], v[156:159], v[180:183], v[58:61]
	v_mfma_f32_16x16x32_bf16 v[54:57], v[148:151], v[188:191], v[54:57]
	v_mfma_f32_16x16x32_bf16 v[46:49], v[156:159], v[188:191], v[46:49]
	v_mfma_f32_16x16x32_bf16 v[38:41], v[148:151], v[212:215], v[38:41]
	v_mfma_f32_16x16x32_bf16 v[30:33], v[156:159], v[212:215], v[30:33]
	v_mfma_f32_16x16x32_bf16 v[22:25], v[148:151], v[220:223], v[22:25]
	v_mfma_f32_16x16x32_bf16 v[14:17], v[156:159], v[220:223], v[14:17]
	v_mfma_f32_16x16x32_bf16 v[62:65], v[152:155], v[184:187], v[62:65]
	v_mfma_f32_16x16x32_bf16 v[58:61], v[160:163], v[184:187], v[58:61]
	v_mfma_f32_16x16x32_bf16 v[54:57], v[152:155], v[192:195], v[54:57]
	v_mfma_f32_16x16x32_bf16 v[46:49], v[160:163], v[192:195], v[46:49]
	v_mfma_f32_16x16x32_bf16 v[38:41], v[152:155], v[216:219], v[38:41]
	v_mfma_f32_16x16x32_bf16 v[30:33], v[160:163], v[216:219], v[30:33]
	v_mfma_f32_16x16x32_bf16 v[22:25], v[152:155], v[224:227], v[22:25]
	v_mfma_f32_16x16x32_bf16 v[14:17], v[160:163], v[224:227], v[14:17]
	v_mfma_f32_16x16x32_bf16 v[50:53], v[164:167], v[180:183], v[50:53]
	v_mfma_f32_16x16x32_bf16 v[42:45], v[172:175], v[180:183], v[42:45]
	v_mfma_f32_16x16x32_bf16 v[34:37], v[164:167], v[188:191], v[34:37]
	v_mfma_f32_16x16x32_bf16 v[26:29], v[172:175], v[188:191], v[26:29]
	v_mfma_f32_16x16x32_bf16 v[18:21], v[164:167], v[212:215], v[18:21]
	v_mfma_f32_16x16x32_bf16 v[10:13], v[172:175], v[212:215], v[10:13]
	v_mfma_f32_16x16x32_bf16 v[6:9], v[164:167], v[220:223], v[6:9]
	v_mfma_f32_16x16x32_bf16 v[2:5], v[172:175], v[220:223], v[2:5]
	v_mfma_f32_16x16x32_bf16 v[50:53], v[168:171], v[184:187], v[50:53]
	v_mfma_f32_16x16x32_bf16 v[42:45], v[176:179], v[184:187], v[42:45]
	v_mfma_f32_16x16x32_bf16 v[34:37], v[168:171], v[192:195], v[34:37]
	v_mfma_f32_16x16x32_bf16 v[26:29], v[176:179], v[192:195], v[26:29]
	v_mfma_f32_16x16x32_bf16 v[18:21], v[168:171], v[216:219], v[18:21]
	v_mfma_f32_16x16x32_bf16 v[10:13], v[176:179], v[216:219], v[10:13]
	v_mfma_f32_16x16x32_bf16 v[6:9], v[168:171], v[224:227], v[6:9]
	v_mfma_f32_16x16x32_bf16 v[2:5], v[176:179], v[224:227], v[2:5]
	s_barrier
	s_add_i32 s29, 0, 0x18000
	s_add_i32 s54, 0, 0x1c000
	v_add_u32_e32 v160, s29, v145
	v_add_u32_e32 v176, s54, v145
	ds_read_b128 v[148:151], v160
	ds_read_b128 v[152:155], v160 offset:1024
	ds_read_b128 v[156:159], v160 offset:2048
	ds_read_b128 v[160:163], v160 offset:3072
	ds_read_b128 v[164:167], v176
	ds_read_b128 v[168:171], v176 offset:1024
	ds_read_b128 v[172:175], v176 offset:2048
	ds_read_b128 v[176:179], v176 offset:3072
	s_add_u32 s36, s36, 0x40000
	s_addc_u32 s37, s37, 0
	s_mov_b32 m0, s33
	v_lshl_add_u64 v[232:233], s[36:37], 0, v[136:137]
	ds_read_b128 v[180:183], v147 offset:32768
	ds_read_b128 v[184:187], v147 offset:33792
	ds_read_b128 v[188:191], v147 offset:34816
	ds_read_b128 v[192:195], v147 offset:35840
	ds_read_b128 v[212:215], v147 offset:36864
	ds_read_b128 v[216:219], v147 offset:37888
	ds_read_b128 v[220:223], v147 offset:38912
	ds_read_b128 v[224:227], v147 offset:39936
	global_load_lds_dwordx4 v[232:233], off
	v_lshl_add_u64 v[232:233], s[36:37], 0, v[134:135]
	s_mov_b32 m0, s48
	s_nop 0
	global_load_lds_dwordx4 v[232:233], off
	s_waitcnt vmcnt(8)
	s_waitcnt lgkmcnt(0)
	s_barrier
	s_waitcnt lgkmcnt(0)
	v_mfma_f32_16x16x32_bf16 v[128:131], v[148:151], v[180:183], v[128:131]
	v_mfma_f32_16x16x32_bf16 v[124:127], v[156:159], v[180:183], v[124:127]
	v_mfma_f32_16x16x32_bf16 v[120:123], v[148:151], v[188:191], v[120:123]
	v_mfma_f32_16x16x32_bf16 v[110:113], v[156:159], v[188:191], v[110:113]
	v_mfma_f32_16x16x32_bf16 v[102:105], v[148:151], v[212:215], v[102:105]
	v_mfma_f32_16x16x32_bf16 v[94:97], v[156:159], v[212:215], v[94:97]
	v_mfma_f32_16x16x32_bf16 v[86:89], v[148:151], v[220:223], v[86:89]
	v_mfma_f32_16x16x32_bf16 v[78:81], v[156:159], v[220:223], v[78:81]
	v_mfma_f32_16x16x32_bf16 v[128:131], v[152:155], v[184:187], v[128:131]
	v_mfma_f32_16x16x32_bf16 v[124:127], v[160:163], v[184:187], v[124:127]
	v_mfma_f32_16x16x32_bf16 v[120:123], v[152:155], v[192:195], v[120:123]
	v_mfma_f32_16x16x32_bf16 v[110:113], v[160:163], v[192:195], v[110:113]
	v_mfma_f32_16x16x32_bf16 v[102:105], v[152:155], v[216:219], v[102:105]
	v_mfma_f32_16x16x32_bf16 v[94:97], v[160:163], v[216:219], v[94:97]
	v_mfma_f32_16x16x32_bf16 v[86:89], v[152:155], v[224:227], v[86:89]
	v_mfma_f32_16x16x32_bf16 v[78:81], v[160:163], v[224:227], v[78:81]
	v_mfma_f32_16x16x32_bf16 v[116:119], v[164:167], v[180:183], v[116:119]
	v_mfma_f32_16x16x32_bf16 v[106:109], v[172:175], v[180:183], v[106:109]
	v_mfma_f32_16x16x32_bf16 v[98:101], v[164:167], v[188:191], v[98:101]
	v_mfma_f32_16x16x32_bf16 v[90:93], v[172:175], v[188:191], v[90:93]
	v_mfma_f32_16x16x32_bf16 v[82:85], v[164:167], v[212:215], v[82:85]
	v_mfma_f32_16x16x32_bf16 v[74:77], v[172:175], v[212:215], v[74:77]
	v_mfma_f32_16x16x32_bf16 v[70:73], v[164:167], v[220:223], v[70:73]
	v_mfma_f32_16x16x32_bf16 v[66:69], v[172:175], v[220:223], v[66:69]
	v_mfma_f32_16x16x32_bf16 v[116:119], v[168:171], v[184:187], v[116:119]
	v_mfma_f32_16x16x32_bf16 v[106:109], v[176:179], v[184:187], v[106:109]
	v_mfma_f32_16x16x32_bf16 v[98:101], v[168:171], v[192:195], v[98:101]
	v_mfma_f32_16x16x32_bf16 v[90:93], v[176:179], v[192:195], v[90:93]
	v_mfma_f32_16x16x32_bf16 v[82:85], v[168:171], v[216:219], v[82:85]
	v_mfma_f32_16x16x32_bf16 v[74:77], v[176:179], v[216:219], v[74:77]
	v_mfma_f32_16x16x32_bf16 v[70:73], v[168:171], v[224:227], v[70:73]
	v_mfma_f32_16x16x32_bf16 v[66:69], v[176:179], v[224:227], v[66:69]
	s_barrier
; #define PG8_STAGE(bufoff, gbase, voff) do { _Pragma("unroll") for (int _i = 0; _i < 2; ++_i) \
;         __builtin_amdgcn_global_load_lds((const unsigned*)((const char*)(gbase) + (voff)[_i]), (LAS unsigned*)(lds + (bufoff) + ldsw + _i * 8192), 16, 0, 0); } while (0)
; #define PG8_LDA(dst, b, h) do { _Pragma("unroll") for (int m = 0; m < 4; ++m) _Pragma("unroll") for (int k = 0; k < 2; ++k) dst[m][k] = *(const LAS bf16x8*)(lds + PG8_SA(b, h) + aoff + m * 2048 + k * 1024); } while (0)
; #define PG8_MMA(ai, bj, At, Bt) do { __builtin_amdgcn_s_setprio(1); _Pragma("unroll") for (int m = 0; m < 4; ++m) _Pragma("unroll") for (int n = 0; n < 2; ++n) _Pragma("unroll") for (int k = 0; k < 2; ++k) \
;         acc[ai][bj][m][n] = __builtin_amdgcn_mfma_f32_16x16x32_bf16(Bt[n][k], At[m][k], acc[ai][bj][m][n], 0, 0, 0); __builtin_amdgcn_s_setprio(0); } while (0)
; #define PG8_WAIT_V(n) asm volatile("s_waitcnt vmcnt(" #n ")" ::: "memory")
; #define PG8_WAIT_L(n) asm volatile("s_waitcnt lgkmcnt(" #n ")" ::: "memory")
; #define PG8_BAR __builtin_amdgcn_s_barrier()
; #define PG8_SCHED __builtin_amdgcn_sched_barrier(0)
; template <class Epi, class Sched, bool ALIGN_EPI = true, bool SP2 = true>
; __device__ __forceinline__ void gemm_phase(LAS unsigned char* lds, const Sched& S, const Epi& E, const int lda, const int ldb) {
;     ...
;             PG8_LDA(At, 1, 1); PG8_STAGE(PG8_SB(1, 0), b3, voffB); PG8_STAGE(PG8_SB(1, 1), b3 + hstepB, voffB); PG8_STAGE(PG8_SA(1, 0), a3, voffA);
;             PG8_WAIT_V(8); PG8_WAIT_L(0); PG8_BAR; PG8_MMA(1, 0, At, B0); PG8_MMA(1, 1, At, B1); PG8_BAR; PG8_SCHED;
;     ...
;         if constexpr (ALIGN_EPI) { if (wr == 0) PG8_BAR; }
	s_add_i32 s29, s29, s39
	v_lshl_add_u64 v[142:143], v[142:143], 0, s[70:71]
	s_mov_b32 m0, s29
	ds_read_b128 v[180:183], v147 offset:49152
	ds_read_b128 v[184:187], v147 offset:50176
	ds_read_b128 v[188:191], v147 offset:51200
	ds_read_b128 v[192:195], v147 offset:52224
	ds_read_b128 v[212:215], v147 offset:53248
	ds_read_b128 v[216:219], v147 offset:54272
	ds_read_b128 v[220:223], v147 offset:55296
	ds_read_b128 v[224:227], v147 offset:56320
	global_load_lds_dwordx4 v[142:143], off
	s_add_i32 m0, s29, 0x2000
	s_add_u32 s26, s26, 0x520080
	v_lshl_add_u64 v[142:143], v[196:197], 0, s[70:71]
	s_addc_u32 s27, s27, 0
	s_add_i32 s29, s54, s39
	global_load_lds_dwordx4 v[142:143], off
	v_lshl_add_u64 v[142:143], s[26:27], 0, v[114:115]
	s_mov_b32 m0, s29
	s_nop 0
	global_load_lds_dwordx4 v[142:143], off
	v_lshl_add_u64 v[142:143], s[26:27], 0, v[132:133]
	s_add_i32 m0, s29, 0x2000
	s_nop 0
	global_load_lds_dwordx4 v[142:143], off
	v_lshl_add_u64 v[142:143], v[228:229], 0, s[70:71]
	s_mov_b32 m0, s49
	s_nop 0
	global_load_lds_dwordx4 v[142:143], off
	v_lshl_add_u64 v[142:143], v[230:231], 0, s[70:71]
	s_mov_b32 m0, s51
	s_nop 0
	global_load_lds_dwordx4 v[142:143], off
	s_waitcnt vmcnt(8)
	s_waitcnt lgkmcnt(0)
	s_barrier
	s_waitcnt lgkmcnt(0)
	v_mfma_f32_16x16x32_bf16 v[62:65], v[148:151], v[180:183], v[62:65]
	v_mfma_f32_16x16x32_bf16 v[58:61], v[156:159], v[180:183], v[58:61]
	v_mfma_f32_16x16x32_bf16 v[54:57], v[148:151], v[188:191], v[54:57]
	v_mfma_f32_16x16x32_bf16 v[46:49], v[156:159], v[188:191], v[46:49]
	v_mfma_f32_16x16x32_bf16 v[38:41], v[148:151], v[212:215], v[38:41]
	v_mfma_f32_16x16x32_bf16 v[30:33], v[156:159], v[212:215], v[30:33]
	v_mfma_f32_16x16x32_bf16 v[22:25], v[148:151], v[220:223], v[22:25]
	v_mfma_f32_16x16x32_bf16 v[14:17], v[156:159], v[220:223], v[14:17]
	v_mfma_f32_16x16x32_bf16 v[62:65], v[152:155], v[184:187], v[62:65]
	v_mfma_f32_16x16x32_bf16 v[58:61], v[160:163], v[184:187], v[58:61]
	v_mfma_f32_16x16x32_bf16 v[54:57], v[152:155], v[192:195], v[54:57]
	v_mfma_f32_16x16x32_bf16 v[46:49], v[160:163], v[192:195], v[46:49]
	v_mfma_f32_16x16x32_bf16 v[38:41], v[152:155], v[216:219], v[38:41]
	v_mfma_f32_16x16x32_bf16 v[30:33], v[160:163], v[216:219], v[30:33]
	v_mfma_f32_16x16x32_bf16 v[22:25], v[152:155], v[224:227], v[22:25]
	v_mfma_f32_16x16x32_bf16 v[14:17], v[160:163], v[224:227], v[14:17]
	v_mfma_f32_16x16x32_bf16 v[50:53], v[164:167], v[180:183], v[50:53]
	v_mfma_f32_16x16x32_bf16 v[42:45], v[172:175], v[180:183], v[42:45]
	v_mfma_f32_16x16x32_bf16 v[34:37], v[164:167], v[188:191], v[34:37]
	v_mfma_f32_16x16x32_bf16 v[26:29], v[172:175], v[188:191], v[26:29]
	v_mfma_f32_16x16x32_bf16 v[18:21], v[164:167], v[212:215], v[18:21]
	v_mfma_f32_16x16x32_bf16 v[10:13], v[172:175], v[212:215], v[10:13]
	v_mfma_f32_16x16x32_bf16 v[6:9], v[164:167], v[220:223], v[6:9]
	v_mfma_f32_16x16x32_bf16 v[2:5], v[172:175], v[220:223], v[2:5]
	v_mfma_f32_16x16x32_bf16 v[50:53], v[168:171], v[184:187], v[50:53]
	v_mfma_f32_16x16x32_bf16 v[42:45], v[176:179], v[184:187], v[42:45]
	v_mfma_f32_16x16x32_bf16 v[34:37], v[168:171], v[192:195], v[34:37]
	v_mfma_f32_16x16x32_bf16 v[26:29], v[176:179], v[192:195], v[26:29]
	v_mfma_f32_16x16x32_bf16 v[18:21], v[168:171], v[216:219], v[18:21]
	v_mfma_f32_16x16x32_bf16 v[10:13], v[176:179], v[216:219], v[10:13]
	v_mfma_f32_16x16x32_bf16 v[6:9], v[168:171], v[224:227], v[6:9]
	v_mfma_f32_16x16x32_bf16 v[2:5], v[176:179], v[224:227], v[2:5]
	s_barrier
	s_add_i32 s50, s50, 2
	s_add_u32 s24, s24, 0x100
	s_addc_u32 s25, s25, 0
	s_add_u32 s72, s72, 0x100
	s_addc_u32 s73, s73, 0
	s_cmp_gt_u32 s50, 13
	s_cbranch_scc0 .LBB0_684
	s_and_b64 vcc, exec, s[10:11]
	s_cbranch_vccz .LBB0_687
	s_barrier

; #define PG8_STAGE(bufoff, gbase, voff) do { _Pragma("unroll") for (int _i = 0; _i < 2; ++_i) \
;         __builtin_amdgcn_global_load_lds((const unsigned*)((const char*)(gbase) + (voff)[_i]), (LAS unsigned*)(lds + (bufoff) + ldsw + _i * 8192), 16, 0, 0); } while (0)
; #define PG8_LDA(dst, b, h) do { _Pragma("unroll") for (int m = 0; m < 4; ++m) _Pragma("unroll") for (int k = 0; k < 2; ++k) dst[m][k] = *(const LAS bf16x8*)(lds + PG8_SA(b, h) + aoff + m * 2048 + k * 1024); } while (0)
; #define PG8_LDB(dst, b, h) do { _Pragma("unroll") for (int n = 0; n < 2; ++n) _Pragma("unroll") for (int k = 0; k < 2; ++k) dst[n][k] = *(const LAS bf16x8*)(lds + PG8_SB(b, h) + boff + n * 2048 + k * 1024); } while (0)
; #define PG8_MMA(ai, bj, At, Bt) do { __builtin_amdgcn_s_setprio(1); _Pragma("unroll") for (int m = 0; m < 4; ++m) _Pragma("unroll") for (int n = 0; n < 2; ++n) _Pragma("unroll") for (int k = 0; k < 2; ++k) \
;         acc[ai][bj][m][n] = __builtin_amdgcn_mfma_f32_16x16x32_bf16(Bt[n][k], At[m][k], acc[ai][bj][m][n], 0, 0, 0); __builtin_amdgcn_s_setprio(0); } while (0)
; #define PG8_WAIT_V(n) asm volatile("s_waitcnt vmcnt(" #n ")" ::: "memory")
; #define PG8_WAIT_L(n) asm volatile("s_waitcnt lgkmcnt(" #n ")" ::: "memory")
; #define PG8_BAR __builtin_amdgcn_s_barrier()
; #define PG8_SCHED __builtin_amdgcn_sched_barrier(0)
; template <class Epi, class Sched, bool ALIGN_EPI = true, bool SP2 = true>
; __device__ __forceinline__ void gemm_phase(LAS unsigned char* lds, const Sched& S, const Epi& E, const int lda, const int ldb) {
;     ...
;             const bool last = (t == nt - 2);
;             const char* a1 = cA + (size_t)(t + 1) * kstep;
;             const char* a2 = last ? nA : cA + (size_t)(t + 2) * kstep; const char* b2 = last ? nB : cB + (size_t)(t + 2) * kstep;
;             const char* a3 = a2 + kstep; const char* b3 = b2 + kstep;
;             if constexpr (SP2) {
;             PG8_LDB(B0, 0, 0); PG8_LDB(B1, 0, 1); PG8_SCHED; PG8_LDA(At, 0, 0); PG8_STAGE(PG8_SA(1, 1), a1 + hstepA, voffA);
;             PG8_WAIT_V(8); PG8_WAIT_L(0); PG8_BAR; PG8_MMA(0, 0, At, B0); PG8_MMA(0, 1, At, B1); PG8_BAR; PG8_SCHED;
;             PG8_LDA(At, 0, 1); PG8_STAGE(PG8_SB(0, 0), b2, voffB); PG8_STAGE(PG8_SB(0, 1), b2 + hstepB, voffB); PG8_STAGE(PG8_SA(0, 0), a2, voffA);
.LBB0_905:
	s_add_u32 s22, s20, 0xfff80080
	s_addc_u32 s23, s21, -1
	s_add_i32 s29, 0, 0x10000
	s_cmp_eq_u32 s50, 28
	s_cselect_b32 s25, s17, s23
	s_cselect_b32 s24, s16, s22
	s_cselect_b32 s23, s19, s73
	s_cselect_b32 s22, s18, s72
	s_add_i32 s74, 0, 0x14000
	v_add_u32_e32 v158, s29, v143
	v_add_u32_e32 v174, s74, v143
	ds_read_b128 v[146:149], v158
	ds_read_b128 v[150:153], v158 offset:1024
	ds_read_b128 v[154:157], v158 offset:2048
	ds_read_b128 v[158:161], v158 offset:3072
	ds_read_b128 v[162:165], v174
	ds_read_b128 v[166:169], v174 offset:1024
	ds_read_b128 v[170:173], v174 offset:2048
	ds_read_b128 v[174:177], v174 offset:3072
	v_lshl_add_u64 v[224:225], s[20:21], 0, v[138:139]
	s_add_i32 m0, s37, 0xc000
	ds_read_b128 v[178:181], v145
	ds_read_b128 v[182:185], v145 offset:1024
	ds_read_b128 v[186:189], v145 offset:2048
	ds_read_b128 v[190:193], v145 offset:3072
	ds_read_b128 v[194:197], v145 offset:4096
	ds_read_b128 v[212:215], v145 offset:5120
	ds_read_b128 v[216:219], v145 offset:6144
	ds_read_b128 v[220:223], v145 offset:7168
	global_load_lds_dwordx4 v[224:225], off
	v_lshl_add_u64 v[224:225], s[20:21], 0, v[140:141]
	s_add_i32 m0, s37, 0xe000
	s_nop 0
	global_load_lds_dwordx4 v[224:225], off
	s_waitcnt vmcnt(8)
	s_waitcnt lgkmcnt(0)
	s_barrier
	s_waitcnt lgkmcnt(0)
	v_mfma_f32_16x16x32_bf16 v[128:131], v[146:149], v[178:181], v[128:131]
	v_mfma_f32_16x16x32_bf16 v[124:127], v[154:157], v[178:181], v[124:127]
	v_mfma_f32_16x16x32_bf16 v[120:123], v[146:149], v[186:189], v[120:123]
	v_mfma_f32_16x16x32_bf16 v[116:119], v[154:157], v[186:189], v[116:119]
	v_mfma_f32_16x16x32_bf16 v[102:105], v[146:149], v[194:197], v[102:105]
	v_mfma_f32_16x16x32_bf16 v[98:101], v[154:157], v[194:197], v[98:101]
	v_mfma_f32_16x16x32_bf16 v[86:89], v[146:149], v[216:219], v[86:89]
	v_mfma_f32_16x16x32_bf16 v[82:85], v[154:157], v[216:219], v[82:85]
	v_mfma_f32_16x16x32_bf16 v[128:131], v[150:153], v[182:185], v[128:131]
	v_mfma_f32_16x16x32_bf16 v[124:127], v[158:161], v[182:185], v[124:127]
	v_mfma_f32_16x16x32_bf16 v[120:123], v[150:153], v[190:193], v[120:123]
	v_mfma_f32_16x16x32_bf16 v[116:119], v[158:161], v[190:193], v[116:119]
	v_mfma_f32_16x16x32_bf16 v[102:105], v[150:153], v[212:215], v[102:105]
	v_mfma_f32_16x16x32_bf16 v[98:101], v[158:161], v[212:215], v[98:101]
	v_mfma_f32_16x16x32_bf16 v[86:89], v[150:153], v[220:223], v[86:89]
	v_mfma_f32_16x16x32_bf16 v[82:85], v[158:161], v[220:223], v[82:85]
	v_mfma_f32_16x16x32_bf16 v[110:113], v[162:165], v[178:181], v[110:113]
	v_mfma_f32_16x16x32_bf16 v[106:109], v[170:173], v[178:181], v[106:109]
	v_mfma_f32_16x16x32_bf16 v[94:97], v[162:165], v[186:189], v[94:97]
	v_mfma_f32_16x16x32_bf16 v[90:93], v[170:173], v[186:189], v[90:93]
	v_mfma_f32_16x16x32_bf16 v[78:81], v[162:165], v[194:197], v[78:81]
	v_mfma_f32_16x16x32_bf16 v[74:77], v[170:173], v[194:197], v[74:77]
	v_mfma_f32_16x16x32_bf16 v[70:73], v[162:165], v[216:219], v[70:73]
	v_mfma_f32_16x16x32_bf16 v[66:69], v[170:173], v[216:219], v[66:69]
	v_mfma_f32_16x16x32_bf16 v[110:113], v[166:169], v[182:185], v[110:113]
	v_mfma_f32_16x16x32_bf16 v[106:109], v[174:177], v[182:185], v[106:109]
	v_mfma_f32_16x16x32_bf16 v[94:97], v[166:169], v[190:193], v[94:97]
	v_mfma_f32_16x16x32_bf16 v[90:93], v[174:177], v[190:193], v[90:93]
	v_mfma_f32_16x16x32_bf16 v[78:81], v[166:169], v[212:215], v[78:81]
	v_mfma_f32_16x16x32_bf16 v[74:77], v[174:177], v[212:215], v[74:77]
	v_mfma_f32_16x16x32_bf16 v[70:73], v[166:169], v[220:223], v[70:73]
	v_mfma_f32_16x16x32_bf16 v[66:69], v[174:177], v[220:223], v[66:69]
	s_barrier
	s_add_i32 s29, s29, s12
	v_lshl_add_u64 v[224:225], s[22:23], 0, v[114:115]
	s_mov_b32 m0, s29
	ds_read_b128 v[178:181], v145 offset:16384
	ds_read_b128 v[182:185], v145 offset:17408
	ds_read_b128 v[186:189], v145 offset:18432
	ds_read_b128 v[190:193], v145 offset:19456
	ds_read_b128 v[194:197], v145 offset:20480
	ds_read_b128 v[212:215], v145 offset:21504
	ds_read_b128 v[216:219], v145 offset:22528
	ds_read_b128 v[220:223], v145 offset:23552
	global_load_lds_dwordx4 v[224:225], off
	s_add_i32 m0, s29, 0x2000
	s_add_u32 s54, s22, 0x400000
	v_lshl_add_u64 v[226:227], s[22:23], 0, v[132:133]
	s_addc_u32 s55, s23, 0
	s_add_i32 s29, s74, s12
	global_load_lds_dwordx4 v[226:227], off
	v_lshl_add_u64 v[228:229], s[54:55], 0, v[114:115]
	s_mov_b32 m0, s29
	v_lshl_add_u64 v[230:231], s[24:25], 0, v[134:135]
	global_load_lds_dwordx4 v[228:229], off
	v_lshl_add_u64 v[228:229], s[54:55], 0, v[132:133]
	s_add_i32 m0, s29, 0x2000
	s_nop 0
	global_load_lds_dwordx4 v[228:229], off
	v_lshl_add_u64 v[228:229], s[24:25], 0, v[136:137]
	s_mov_b32 m0, s37
	s_nop 0
	global_load_lds_dwordx4 v[228:229], off
	s_mov_b32 m0, s38
	s_nop 0
	global_load_lds_dwordx4 v[230:231], off
	s_waitcnt vmcnt(8)
	s_waitcnt lgkmcnt(0)
	s_barrier
; #define PG8_STAGE(bufoff, gbase, voff) do { _Pragma("unroll") for (int _i = 0; _i < 2; ++_i) \
;         __builtin_amdgcn_global_load_lds((const unsigned*)((const char*)(gbase) + (voff)[_i]), (LAS unsigned*)(lds + (bufoff) + ldsw + _i * 8192), 16, 0, 0); } while (0)
; #define PG8_LDA(dst, b, h) do { _Pragma("unroll") for (int m = 0; m < 4; ++m) _Pragma("unroll") for (int k = 0; k < 2; ++k) dst[m][k] = *(const LAS bf16x8*)(lds + PG8_SA(b, h) + aoff + m * 2048 + k * 1024); } while (0)
; #define PG8_LDB(dst, b, h) do { _Pragma("unroll") for (int n = 0; n < 2; ++n) _Pragma("unroll") for (int k = 0; k < 2; ++k) dst[n][k] = *(const LAS bf16x8*)(lds + PG8_SB(b, h) + boff + n * 2048 + k * 1024); } while (0)
; #define PG8_MMA(ai, bj, At, Bt) do { __builtin_amdgcn_s_setprio(1); _Pragma("unroll") for (int m = 0; m < 4; ++m) _Pragma("unroll") for (int n = 0; n < 2; ++n) _Pragma("unroll") for (int k = 0; k < 2; ++k) \
;         acc[ai][bj][m][n] = __builtin_amdgcn_mfma_f32_16x16x32_bf16(Bt[n][k], At[m][k], acc[ai][bj][m][n], 0, 0, 0); __builtin_amdgcn_s_setprio(0); } while (0)
; #define PG8_WAIT_V(n) asm volatile("s_waitcnt vmcnt(" #n ")" ::: "memory")
; #define PG8_WAIT_L(n) asm volatile("s_waitcnt lgkmcnt(" #n ")" ::: "memory")
; #define PG8_BAR __builtin_amdgcn_s_barrier()
; #define PG8_SCHED __builtin_amdgcn_sched_barrier(0)
; template <class Epi, class Sched, bool ALIGN_EPI = true, bool SP2 = true>
; __device__ __forceinline__ void gemm_phase(LAS unsigned char* lds, const Sched& S, const Epi& E, const int lda, const int ldb) {
;     ...
;             PG8_WAIT_V(8); PG8_WAIT_L(0); PG8_BAR; PG8_MMA(1, 0, At, B0); PG8_MMA(1, 1, At, B1); PG8_BAR; PG8_SCHED;
;             PG8_LDB(B0, 1, 0); PG8_LDB(B1, 1, 1); PG8_SCHED; PG8_LDA(At, 1, 0); PG8_STAGE(PG8_SA(0, 1), a2 + hstepA, voffA);
;             PG8_WAIT_V(8); PG8_WAIT_L(0); PG8_BAR; PG8_MMA(0, 0, At, B0); PG8_MMA(0, 1, At, B1); PG8_BAR; PG8_SCHED;
	s_waitcnt lgkmcnt(0)
	v_mfma_f32_16x16x32_bf16 v[62:65], v[146:149], v[178:181], v[62:65]
	v_mfma_f32_16x16x32_bf16 v[58:61], v[154:157], v[178:181], v[58:61]
	v_mfma_f32_16x16x32_bf16 v[54:57], v[146:149], v[186:189], v[54:57]
	v_mfma_f32_16x16x32_bf16 v[50:53], v[154:157], v[186:189], v[50:53]
	v_mfma_f32_16x16x32_bf16 v[38:41], v[146:149], v[194:197], v[38:41]
	v_mfma_f32_16x16x32_bf16 v[34:37], v[154:157], v[194:197], v[34:37]
	v_mfma_f32_16x16x32_bf16 v[22:25], v[146:149], v[216:219], v[22:25]
	v_mfma_f32_16x16x32_bf16 v[18:21], v[154:157], v[216:219], v[18:21]
	v_mfma_f32_16x16x32_bf16 v[62:65], v[150:153], v[182:185], v[62:65]
	v_mfma_f32_16x16x32_bf16 v[58:61], v[158:161], v[182:185], v[58:61]
	v_mfma_f32_16x16x32_bf16 v[54:57], v[150:153], v[190:193], v[54:57]
	v_mfma_f32_16x16x32_bf16 v[50:53], v[158:161], v[190:193], v[50:53]
	v_mfma_f32_16x16x32_bf16 v[38:41], v[150:153], v[212:215], v[38:41]
	v_mfma_f32_16x16x32_bf16 v[34:37], v[158:161], v[212:215], v[34:37]
	v_mfma_f32_16x16x32_bf16 v[22:25], v[150:153], v[220:223], v[22:25]
	v_mfma_f32_16x16x32_bf16 v[18:21], v[158:161], v[220:223], v[18:21]
	v_mfma_f32_16x16x32_bf16 v[46:49], v[162:165], v[178:181], v[46:49]
	v_mfma_f32_16x16x32_bf16 v[42:45], v[170:173], v[178:181], v[42:45]
	v_mfma_f32_16x16x32_bf16 v[30:33], v[162:165], v[186:189], v[30:33]
	v_mfma_f32_16x16x32_bf16 v[26:29], v[170:173], v[186:189], v[26:29]
	v_mfma_f32_16x16x32_bf16 v[14:17], v[162:165], v[194:197], v[14:17]
	v_mfma_f32_16x16x32_bf16 v[10:13], v[170:173], v[194:197], v[10:13]
	v_mfma_f32_16x16x32_bf16 v[6:9], v[162:165], v[216:219], v[6:9]
	v_mfma_f32_16x16x32_bf16 v[2:5], v[170:173], v[216:219], v[2:5]
	v_mfma_f32_16x16x32_bf16 v[46:49], v[166:169], v[182:185], v[46:49]
	v_mfma_f32_16x16x32_bf16 v[42:45], v[174:177], v[182:185], v[42:45]
	v_mfma_f32_16x16x32_bf16 v[30:33], v[166:169], v[190:193], v[30:33]
	v_mfma_f32_16x16x32_bf16 v[26:29], v[174:177], v[190:193], v[26:29]
	v_mfma_f32_16x16x32_bf16 v[14:17], v[166:169], v[212:215], v[14:17]
	v_mfma_f32_16x16x32_bf16 v[10:13], v[174:177], v[212:215], v[10:13]
	v_mfma_f32_16x16x32_bf16 v[6:9], v[166:169], v[220:223], v[6:9]
	v_mfma_f32_16x16x32_bf16 v[2:5], v[174:177], v[220:223], v[2:5]
	s_barrier
	s_add_i32 s29, 0, 0x18000
	s_add_i32 s54, 0, 0x1c000
	v_add_u32_e32 v158, s29, v143
	v_add_u32_e32 v174, s54, v143
	ds_read_b128 v[146:149], v158
	ds_read_b128 v[150:153], v158 offset:1024
	ds_read_b128 v[154:157], v158 offset:2048
	ds_read_b128 v[158:161], v158 offset:3072
	ds_read_b128 v[162:165], v174
	ds_read_b128 v[166:169], v174 offset:1024
	ds_read_b128 v[170:173], v174 offset:2048
	ds_read_b128 v[174:177], v174 offset:3072
	s_add_u32 s24, s24, 0x80000
	s_addc_u32 s25, s25, 0
	s_mov_b32 m0, s39
	v_lshl_add_u64 v[232:233], s[24:25], 0, v[136:137]
	ds_read_b128 v[178:181], v145 offset:32768
	ds_read_b128 v[182:185], v145 offset:33792
	ds_read_b128 v[186:189], v145 offset:34816
	ds_read_b128 v[190:193], v145 offset:35840
	ds_read_b128 v[194:197], v145 offset:36864
	ds_read_b128 v[212:215], v145 offset:37888
	ds_read_b128 v[216:219], v145 offset:38912
	ds_read_b128 v[220:223], v145 offset:39936
	global_load_lds_dwordx4 v[232:233], off
	v_lshl_add_u64 v[232:233], s[24:25], 0, v[134:135]
	s_mov_b32 m0, s40
	s_nop 0
	global_load_lds_dwordx4 v[232:233], off
	s_waitcnt vmcnt(8)
	s_waitcnt lgkmcnt(0)
	s_barrier
	s_waitcnt lgkmcnt(0)
	v_mfma_f32_16x16x32_bf16 v[128:131], v[146:149], v[178:181], v[128:131]
	v_mfma_f32_16x16x32_bf16 v[124:127], v[154:157], v[178:181], v[124:127]
	v_mfma_f32_16x16x32_bf16 v[120:123], v[146:149], v[186:189], v[120:123]
	v_mfma_f32_16x16x32_bf16 v[116:119], v[154:157], v[186:189], v[116:119]
	v_mfma_f32_16x16x32_bf16 v[102:105], v[146:149], v[194:197], v[102:105]
	v_mfma_f32_16x16x32_bf16 v[98:101], v[154:157], v[194:197], v[98:101]
	v_mfma_f32_16x16x32_bf16 v[86:89], v[146:149], v[216:219], v[86:89]
	v_mfma_f32_16x16x32_bf16 v[82:85], v[154:157], v[216:219], v[82:85]
	v_mfma_f32_16x16x32_bf16 v[128:131], v[150:153], v[182:185], v[128:131]
	v_mfma_f32_16x16x32_bf16 v[124:127], v[158:161], v[182:185], v[124:127]
	v_mfma_f32_16x16x32_bf16 v[120:123], v[150:153], v[190:193], v[120:123]
	v_mfma_f32_16x16x32_bf16 v[116:119], v[158:161], v[190:193], v[116:119]
	v_mfma_f32_16x16x32_bf16 v[102:105], v[150:153], v[212:215], v[102:105]
	v_mfma_f32_16x16x32_bf16 v[98:101], v[158:161], v[212:215], v[98:101]
	v_mfma_f32_16x16x32_bf16 v[86:89], v[150:153], v[220:223], v[86:89]
	v_mfma_f32_16x16x32_bf16 v[82:85], v[158:161], v[220:223], v[82:85]
	v_mfma_f32_16x16x32_bf16 v[110:113], v[162:165], v[178:181], v[110:113]
	v_mfma_f32_16x16x32_bf16 v[106:109], v[170:173], v[178:181], v[106:109]
	v_mfma_f32_16x16x32_bf16 v[94:97], v[162:165], v[186:189], v[94:97]
	v_mfma_f32_16x16x32_bf16 v[90:93], v[170:173], v[186:189], v[90:93]
	v_mfma_f32_16x16x32_bf16 v[78:81], v[162:165], v[194:197], v[78:81]
	v_mfma_f32_16x16x32_bf16 v[74:77], v[170:173], v[194:197], v[74:77]
	v_mfma_f32_16x16x32_bf16 v[70:73], v[162:165], v[216:219], v[70:73]
	v_mfma_f32_16x16x32_bf16 v[66:69], v[170:173], v[216:219], v[66:69]
	v_mfma_f32_16x16x32_bf16 v[110:113], v[166:169], v[182:185], v[110:113]
	v_mfma_f32_16x16x32_bf16 v[106:109], v[174:177], v[182:185], v[106:109]
	v_mfma_f32_16x16x32_bf16 v[94:97], v[166:169], v[190:193], v[94:97]
	v_mfma_f32_16x16x32_bf16 v[90:93], v[174:177], v[190:193], v[90:93]
	v_mfma_f32_16x16x32_bf16 v[78:81], v[166:169], v[212:215], v[78:81]
	v_mfma_f32_16x16x32_bf16 v[74:77], v[174:177], v[212:215], v[74:77]
	v_mfma_f32_16x16x32_bf16 v[70:73], v[166:169], v[220:223], v[70:73]
	v_mfma_f32_16x16x32_bf16 v[66:69], v[174:177], v[220:223], v[66:69]
	s_barrier
; #define PG8_STAGE(bufoff, gbase, voff) do { _Pragma("unroll") for (int _i = 0; _i < 2; ++_i) \
;         __builtin_amdgcn_global_load_lds((const unsigned*)((const char*)(gbase) + (voff)[_i]), (LAS unsigned*)(lds + (bufoff) + ldsw + _i * 8192), 16, 0, 0); } while (0)
; #define PG8_LDA(dst, b, h) do { _Pragma("unroll") for (int m = 0; m < 4; ++m) _Pragma("unroll") for (int k = 0; k < 2; ++k) dst[m][k] = *(const LAS bf16x8*)(lds + PG8_SA(b, h) + aoff + m * 2048 + k * 1024); } while (0)
; #define PG8_MMA(ai, bj, At, Bt) do { __builtin_amdgcn_s_setprio(1); _Pragma("unroll") for (int m = 0; m < 4; ++m) _Pragma("unroll") for (int n = 0; n < 2; ++n) _Pragma("unroll") for (int k = 0; k < 2; ++k) \
;         acc[ai][bj][m][n] = __builtin_amdgcn_mfma_f32_16x16x32_bf16(Bt[n][k], At[m][k], acc[ai][bj][m][n], 0, 0, 0); __builtin_amdgcn_s_setprio(0); } while (0)
; #define PG8_WAIT_V(n) asm volatile("s_waitcnt vmcnt(" #n ")" ::: "memory")
; #define PG8_WAIT_L(n) asm volatile("s_waitcnt lgkmcnt(" #n ")" ::: "memory")
; #define PG8_BAR __builtin_amdgcn_s_barrier()
; #define PG8_SCHED __builtin_amdgcn_sched_barrier(0)
; template <class Epi, class Sched, bool ALIGN_EPI = true, bool SP2 = true>
; __device__ __forceinline__ void gemm_phase(LAS unsigned char* lds, const Sched& S, const Epi& E, const int lda, const int ldb) {
;     ...
;             PG8_LDA(At, 1, 1); PG8_STAGE(PG8_SB(1, 0), b3, voffB); PG8_STAGE(PG8_SB(1, 1), b3 + hstepB, voffB); PG8_STAGE(PG8_SA(1, 0), a3, voffA);
;             PG8_WAIT_V(8); PG8_WAIT_L(0); PG8_BAR; PG8_MMA(1, 0, At, B0); PG8_MMA(1, 1, At, B1); PG8_BAR; PG8_SCHED;
;     ...
;         if constexpr (ALIGN_EPI) { if (wr == 0) PG8_BAR; }
	s_add_i32 s24, s29, s12
	v_lshl_add_u64 v[224:225], v[224:225], 0, s[70:71]
	s_mov_b32 m0, s24
	ds_read_b128 v[178:181], v145 offset:49152
	ds_read_b128 v[182:185], v145 offset:50176
	ds_read_b128 v[186:189], v145 offset:51200
	ds_read_b128 v[190:193], v145 offset:52224
	ds_read_b128 v[194:197], v145 offset:53248
	ds_read_b128 v[212:215], v145 offset:54272
	ds_read_b128 v[216:219], v145 offset:55296
	ds_read_b128 v[220:223], v145 offset:56320
	global_load_lds_dwordx4 v[224:225], off
	s_add_i32 m0, s24, 0x2000
	s_add_u32 s22, s22, 0x400080
	v_lshl_add_u64 v[224:225], v[226:227], 0, s[70:71]
	s_addc_u32 s23, s23, 0
	s_add_i32 s24, s54, s12
	global_load_lds_dwordx4 v[224:225], off
	v_lshl_add_u64 v[224:225], s[22:23], 0, v[114:115]
	s_mov_b32 m0, s24
	s_nop 0
	global_load_lds_dwordx4 v[224:225], off
	v_lshl_add_u64 v[224:225], s[22:23], 0, v[132:133]
	s_add_i32 m0, s24, 0x2000
	s_nop 0
	global_load_lds_dwordx4 v[224:225], off
	v_lshl_add_u64 v[224:225], v[228:229], 0, s[70:71]
	s_mov_b32 m0, s28
	s_nop 0
	global_load_lds_dwordx4 v[224:225], off
	v_lshl_add_u64 v[224:225], v[230:231], 0, s[70:71]
	s_mov_b32 m0, s30
	s_nop 0
	global_load_lds_dwordx4 v[224:225], off
	s_waitcnt vmcnt(8)
	s_waitcnt lgkmcnt(0)
	s_barrier
	s_waitcnt lgkmcnt(0)
	v_mfma_f32_16x16x32_bf16 v[62:65], v[146:149], v[178:181], v[62:65]
	v_mfma_f32_16x16x32_bf16 v[58:61], v[154:157], v[178:181], v[58:61]
	v_mfma_f32_16x16x32_bf16 v[54:57], v[146:149], v[186:189], v[54:57]
	v_mfma_f32_16x16x32_bf16 v[50:53], v[154:157], v[186:189], v[50:53]
	v_mfma_f32_16x16x32_bf16 v[38:41], v[146:149], v[194:197], v[38:41]
	v_mfma_f32_16x16x32_bf16 v[34:37], v[154:157], v[194:197], v[34:37]
	v_mfma_f32_16x16x32_bf16 v[22:25], v[146:149], v[216:219], v[22:25]
	v_mfma_f32_16x16x32_bf16 v[18:21], v[154:157], v[216:219], v[18:21]
	v_mfma_f32_16x16x32_bf16 v[62:65], v[150:153], v[182:185], v[62:65]
	v_mfma_f32_16x16x32_bf16 v[58:61], v[158:161], v[182:185], v[58:61]
	v_mfma_f32_16x16x32_bf16 v[54:57], v[150:153], v[190:193], v[54:57]
	v_mfma_f32_16x16x32_bf16 v[50:53], v[158:161], v[190:193], v[50:53]
	v_mfma_f32_16x16x32_bf16 v[38:41], v[150:153], v[212:215], v[38:41]
	v_mfma_f32_16x16x32_bf16 v[34:37], v[158:161], v[212:215], v[34:37]
	v_mfma_f32_16x16x32_bf16 v[22:25], v[150:153], v[220:223], v[22:25]
	v_mfma_f32_16x16x32_bf16 v[18:21], v[158:161], v[220:223], v[18:21]
	v_mfma_f32_16x16x32_bf16 v[46:49], v[162:165], v[178:181], v[46:49]
	v_mfma_f32_16x16x32_bf16 v[42:45], v[170:173], v[178:181], v[42:45]
	v_mfma_f32_16x16x32_bf16 v[30:33], v[162:165], v[186:189], v[30:33]
	v_mfma_f32_16x16x32_bf16 v[26:29], v[170:173], v[186:189], v[26:29]
	v_mfma_f32_16x16x32_bf16 v[14:17], v[162:165], v[194:197], v[14:17]
	v_mfma_f32_16x16x32_bf16 v[10:13], v[170:173], v[194:197], v[10:13]
	v_mfma_f32_16x16x32_bf16 v[6:9], v[162:165], v[216:219], v[6:9]
	v_mfma_f32_16x16x32_bf16 v[2:5], v[170:173], v[216:219], v[2:5]
	v_mfma_f32_16x16x32_bf16 v[46:49], v[166:169], v[182:185], v[46:49]
	v_mfma_f32_16x16x32_bf16 v[42:45], v[174:177], v[182:185], v[42:45]
	v_mfma_f32_16x16x32_bf16 v[30:33], v[166:169], v[190:193], v[30:33]
	v_mfma_f32_16x16x32_bf16 v[26:29], v[174:177], v[190:193], v[26:29]
	v_mfma_f32_16x16x32_bf16 v[14:17], v[166:169], v[212:215], v[14:17]
	v_mfma_f32_16x16x32_bf16 v[10:13], v[174:177], v[212:215], v[10:13]
	v_mfma_f32_16x16x32_bf16 v[6:9], v[166:169], v[220:223], v[6:9]
	v_mfma_f32_16x16x32_bf16 v[2:5], v[174:177], v[220:223], v[2:5]
	s_barrier
	s_add_i32 s50, s50, 2
	s_add_u32 s20, s20, 0x100
	s_addc_u32 s21, s21, 0
	s_add_u32 s72, s72, 0x100
	s_addc_u32 s73, s73, 0
	s_cmp_gt_u32 s50, 29
	s_cbranch_scc0 .LBB0_905
	s_and_b64 vcc, exec, s[14:15]
	s_cbranch_vccz .LBB0_908
	s_barrier

; #define PG8_STAGE(bufoff, gbase, voff) do { _Pragma("unroll") for (int _i = 0; _i < 2; ++_i) \
;         __builtin_amdgcn_global_load_lds((const unsigned*)((const char*)(gbase) + (voff)[_i]), (LAS unsigned*)(lds + (bufoff) + ldsw + _i * 8192), 16, 0, 0); } while (0)
; #define PG8_LDA(dst, b, h) do { _Pragma("unroll") for (int m = 0; m < 4; ++m) _Pragma("unroll") for (int k = 0; k < 2; ++k) dst[m][k] = *(const LAS bf16x8*)(lds + PG8_SA(b, h) + aoff + m * 2048 + k * 1024); } while (0)
; #define PG8_LDB(dst, b, h) do { _Pragma("unroll") for (int n = 0; n < 2; ++n) _Pragma("unroll") for (int k = 0; k < 2; ++k) dst[n][k] = *(const LAS bf16x8*)(lds + PG8_SB(b, h) + boff + n * 2048 + k * 1024); } while (0)
; #define PG8_MMA(ai, bj, At, Bt) do { __builtin_amdgcn_s_setprio(1); _Pragma("unroll") for (int m = 0; m < 4; ++m) _Pragma("unroll") for (int n = 0; n < 2; ++n) _Pragma("unroll") for (int k = 0; k < 2; ++k) \
;         acc[ai][bj][m][n] = __builtin_amdgcn_mfma_f32_16x16x32_bf16(Bt[n][k], At[m][k], acc[ai][bj][m][n], 0, 0, 0); __builtin_amdgcn_s_setprio(0); } while (0)
; #define PG8_WAIT_V(n) asm volatile("s_waitcnt vmcnt(" #n ")" ::: "memory")
; #define PG8_WAIT_L(n) asm volatile("s_waitcnt lgkmcnt(" #n ")" ::: "memory")
; #define PG8_BAR __builtin_amdgcn_s_barrier()
; #define PG8_SCHED __builtin_amdgcn_sched_barrier(0)
; template <class Epi, class Sched, bool ALIGN_EPI = true, bool SP2 = true>
; __device__ __forceinline__ void gemm_phase(LAS unsigned char* lds, const Sched& S, const Epi& E, const int lda, const int ldb) {
;     ...
;             const bool last = (t == nt - 2);
;             const char* a1 = cA + (size_t)(t + 1) * kstep;
;             const char* a2 = last ? nA : cA + (size_t)(t + 2) * kstep; const char* b2 = last ? nB : cB + (size_t)(t + 2) * kstep;
;             const char* a3 = a2 + kstep; const char* b3 = b2 + kstep;
;             if constexpr (SP2) {
;             PG8_LDB(B0, 0, 0); PG8_LDB(B1, 0, 1); PG8_SCHED; PG8_LDA(At, 0, 0); PG8_STAGE(PG8_SA(1, 1), a1 + hstepA, voffA);
;             PG8_WAIT_V(8); PG8_WAIT_L(0); PG8_BAR; PG8_MMA(0, 0, At, B0); PG8_MMA(0, 1, At, B1); PG8_BAR; PG8_SCHED;
;             PG8_LDA(At, 0, 1); PG8_STAGE(PG8_SB(0, 0), b2, voffB); PG8_STAGE(PG8_SB(0, 1), b2 + hstepB, voffB); PG8_STAGE(PG8_SA(0, 0), a2, voffA);
.LBB0_922:
	s_add_u32 s22, s20, 0x100
	s_addc_u32 s23, s21, 0
	s_add_u32 s24, s33, s20
	s_addc_u32 s25, s50, s21
	s_cmp_eq_u32 s72, 4
	s_cselect_b32 s26, 0, s22
	s_cselect_b32 s27, 0, s23
	s_cselect_b32 s24, s16, s24
	s_cselect_b32 s25, s17, s25
	s_add_u32 s26, s0, s26
	s_addc_u32 s27, s1, s27
	s_add_i32 s29, 0, 0x10000
	s_add_i32 s54, 0, 0x14000
	v_add_u32_e32 v144, s29, v193
	v_add_u32_e32 v160, s54, v193
	ds_read_b128 v[132:135], v144
	ds_read_b128 v[136:139], v144 offset:1024
	ds_read_b128 v[140:143], v144 offset:2048
	ds_read_b128 v[144:147], v144 offset:3072
	ds_read_b128 v[148:151], v160
	ds_read_b128 v[152:155], v160 offset:1024
	ds_read_b128 v[156:159], v160 offset:2048
	ds_read_b128 v[160:163], v160 offset:3072
	v_lshl_add_u64 v[190:191], v[178:179], 0, s[20:21]
	s_add_i32 m0, s39, 0xc000
	ds_read_b128 v[164:167], v195
	ds_read_b128 v[168:171], v195 offset:1024
	ds_read_b128 v[182:185], v195 offset:2048
	ds_read_b128 v[186:189], v195 offset:3072
	ds_read_b128 v[212:215], v195 offset:4096
	ds_read_b128 v[216:219], v195 offset:5120
	ds_read_b128 v[220:223], v195 offset:6144
	ds_read_b128 v[224:227], v195 offset:7168
	global_load_lds_dwordx4 v[190:191], off
	v_lshl_add_u64 v[190:191], v[180:181], 0, s[20:21]
	s_add_i32 m0, s39, 0xe000
	s_nop 0
	global_load_lds_dwordx4 v[190:191], off
	s_waitcnt vmcnt(8)
	s_waitcnt lgkmcnt(0)
	s_barrier
	s_waitcnt lgkmcnt(0)
	v_mfma_f32_16x16x32_bf16 v[128:131], v[132:135], v[164:167], v[128:131]
	v_mfma_f32_16x16x32_bf16 v[124:127], v[140:143], v[164:167], v[124:127]
	v_mfma_f32_16x16x32_bf16 v[110:113], v[132:135], v[182:185], v[110:113]
	v_mfma_f32_16x16x32_bf16 v[106:109], v[140:143], v[182:185], v[106:109]
	v_mfma_f32_16x16x32_bf16 v[94:97], v[132:135], v[212:215], v[94:97]
	v_mfma_f32_16x16x32_bf16 v[90:93], v[140:143], v[212:215], v[90:93]
	v_mfma_f32_16x16x32_bf16 v[78:81], v[132:135], v[220:223], v[78:81]
	v_mfma_f32_16x16x32_bf16 v[74:77], v[140:143], v[220:223], v[74:77]
	v_mfma_f32_16x16x32_bf16 v[128:131], v[136:139], v[168:171], v[128:131]
	v_mfma_f32_16x16x32_bf16 v[124:127], v[144:147], v[168:171], v[124:127]
	v_mfma_f32_16x16x32_bf16 v[110:113], v[136:139], v[186:189], v[110:113]
	v_mfma_f32_16x16x32_bf16 v[106:109], v[144:147], v[186:189], v[106:109]
	v_mfma_f32_16x16x32_bf16 v[94:97], v[136:139], v[216:219], v[94:97]
	v_mfma_f32_16x16x32_bf16 v[90:93], v[144:147], v[216:219], v[90:93]
	v_mfma_f32_16x16x32_bf16 v[78:81], v[136:139], v[224:227], v[78:81]
	v_mfma_f32_16x16x32_bf16 v[74:77], v[144:147], v[224:227], v[74:77]
	v_mfma_f32_16x16x32_bf16 v[120:123], v[148:151], v[164:167], v[120:123]
	v_mfma_f32_16x16x32_bf16 v[116:119], v[156:159], v[164:167], v[116:119]
	v_mfma_f32_16x16x32_bf16 v[102:105], v[148:151], v[182:185], v[102:105]
	v_mfma_f32_16x16x32_bf16 v[98:101], v[156:159], v[182:185], v[98:101]
	v_mfma_f32_16x16x32_bf16 v[86:89], v[148:151], v[212:215], v[86:89]
	v_mfma_f32_16x16x32_bf16 v[82:85], v[156:159], v[212:215], v[82:85]
	v_mfma_f32_16x16x32_bf16 v[70:73], v[148:151], v[220:223], v[70:73]
	v_mfma_f32_16x16x32_bf16 v[66:69], v[156:159], v[220:223], v[66:69]
	v_mfma_f32_16x16x32_bf16 v[120:123], v[152:155], v[168:171], v[120:123]
	v_mfma_f32_16x16x32_bf16 v[116:119], v[160:163], v[168:171], v[116:119]
	v_mfma_f32_16x16x32_bf16 v[102:105], v[152:155], v[186:189], v[102:105]
	v_mfma_f32_16x16x32_bf16 v[98:101], v[160:163], v[186:189], v[98:101]
	v_mfma_f32_16x16x32_bf16 v[86:89], v[152:155], v[216:219], v[86:89]
	v_mfma_f32_16x16x32_bf16 v[82:85], v[160:163], v[216:219], v[82:85]
	v_mfma_f32_16x16x32_bf16 v[70:73], v[152:155], v[224:227], v[70:73]
	v_mfma_f32_16x16x32_bf16 v[66:69], v[160:163], v[224:227], v[66:69]
	s_barrier
	s_add_i32 s20, s29, s38
	v_lshl_add_u64 v[190:191], s[24:25], 0, v[114:115]
	s_mov_b32 m0, s20
	ds_read_b128 v[164:167], v195 offset:16384
	ds_read_b128 v[168:171], v195 offset:17408
	ds_read_b128 v[182:185], v195 offset:18432
	ds_read_b128 v[186:189], v195 offset:19456
	ds_read_b128 v[212:215], v195 offset:20480
	ds_read_b128 v[216:219], v195 offset:21504
	ds_read_b128 v[220:223], v195 offset:22528
	ds_read_b128 v[224:227], v195 offset:23552
	global_load_lds_dwordx4 v[190:191], off
	s_add_i32 m0, s20, 0x2000
	s_add_u32 s20, s24, 0x20000
	v_lshl_add_u64 v[196:197], s[24:25], 0, v[172:173]
	s_addc_u32 s21, s25, 0
	s_add_i32 s29, s54, s38
	global_load_lds_dwordx4 v[196:197], off
	v_lshl_add_u64 v[228:229], s[20:21], 0, v[114:115]
	s_mov_b32 m0, s29
	v_lshl_add_u64 v[230:231], s[26:27], 0, v[174:175]
	global_load_lds_dwordx4 v[228:229], off
	v_lshl_add_u64 v[228:229], s[20:21], 0, v[172:173]
	s_add_i32 m0, s29, 0x2000
	s_nop 0
	global_load_lds_dwordx4 v[228:229], off
	v_lshl_add_u64 v[228:229], s[26:27], 0, v[176:177]
	s_mov_b32 m0, s39
	s_nop 0
	global_load_lds_dwordx4 v[228:229], off
	s_mov_b32 m0, s40
	s_nop 0
	global_load_lds_dwordx4 v[230:231], off
	s_waitcnt vmcnt(8)
	s_waitcnt lgkmcnt(0)
	s_barrier
; #define PG8_STAGE(bufoff, gbase, voff) do { _Pragma("unroll") for (int _i = 0; _i < 2; ++_i) \
;         __builtin_amdgcn_global_load_lds((const unsigned*)((const char*)(gbase) + (voff)[_i]), (LAS unsigned*)(lds + (bufoff) + ldsw + _i * 8192), 16, 0, 0); } while (0)
; #define PG8_LDA(dst, b, h) do { _Pragma("unroll") for (int m = 0; m < 4; ++m) _Pragma("unroll") for (int k = 0; k < 2; ++k) dst[m][k] = *(const LAS bf16x8*)(lds + PG8_SA(b, h) + aoff + m * 2048 + k * 1024); } while (0)
; #define PG8_LDB(dst, b, h) do { _Pragma("unroll") for (int n = 0; n < 2; ++n) _Pragma("unroll") for (int k = 0; k < 2; ++k) dst[n][k] = *(const LAS bf16x8*)(lds + PG8_SB(b, h) + boff + n * 2048 + k * 1024); } while (0)
; #define PG8_MMA(ai, bj, At, Bt) do { __builtin_amdgcn_s_setprio(1); _Pragma("unroll") for (int m = 0; m < 4; ++m) _Pragma("unroll") for (int n = 0; n < 2; ++n) _Pragma("unroll") for (int k = 0; k < 2; ++k) \
;         acc[ai][bj][m][n] = __builtin_amdgcn_mfma_f32_16x16x32_bf16(Bt[n][k], At[m][k], acc[ai][bj][m][n], 0, 0, 0); __builtin_amdgcn_s_setprio(0); } while (0)
; #define PG8_WAIT_V(n) asm volatile("s_waitcnt vmcnt(" #n ")" ::: "memory")
; #define PG8_WAIT_L(n) asm volatile("s_waitcnt lgkmcnt(" #n ")" ::: "memory")
; #define PG8_BAR __builtin_amdgcn_s_barrier()
; #define PG8_SCHED __builtin_amdgcn_sched_barrier(0)
; template <class Epi, class Sched, bool ALIGN_EPI = true, bool SP2 = true>
; __device__ __forceinline__ void gemm_phase(LAS unsigned char* lds, const Sched& S, const Epi& E, const int lda, const int ldb) {
;     ...
;             PG8_WAIT_V(8); PG8_WAIT_L(0); PG8_BAR; PG8_MMA(1, 0, At, B0); PG8_MMA(1, 1, At, B1); PG8_BAR; PG8_SCHED;
;             PG8_LDB(B0, 1, 0); PG8_LDB(B1, 1, 1); PG8_SCHED; PG8_LDA(At, 1, 0); PG8_STAGE(PG8_SA(0, 1), a2 + hstepA, voffA);
;             PG8_WAIT_V(8); PG8_WAIT_L(0); PG8_BAR; PG8_MMA(0, 0, At, B0); PG8_MMA(0, 1, At, B1); PG8_BAR; PG8_SCHED;
	s_waitcnt lgkmcnt(0)
	v_mfma_f32_16x16x32_bf16 v[62:65], v[132:135], v[164:167], v[62:65]
	v_mfma_f32_16x16x32_bf16 v[58:61], v[140:143], v[164:167], v[58:61]
	v_mfma_f32_16x16x32_bf16 v[46:49], v[132:135], v[182:185], v[46:49]
	v_mfma_f32_16x16x32_bf16 v[42:45], v[140:143], v[182:185], v[42:45]
	v_mfma_f32_16x16x32_bf16 v[30:33], v[132:135], v[212:215], v[30:33]
	v_mfma_f32_16x16x32_bf16 v[26:29], v[140:143], v[212:215], v[26:29]
	v_mfma_f32_16x16x32_bf16 v[14:17], v[132:135], v[220:223], v[14:17]
	v_mfma_f32_16x16x32_bf16 v[10:13], v[140:143], v[220:223], v[10:13]
	v_mfma_f32_16x16x32_bf16 v[62:65], v[136:139], v[168:171], v[62:65]
	v_mfma_f32_16x16x32_bf16 v[58:61], v[144:147], v[168:171], v[58:61]
	v_mfma_f32_16x16x32_bf16 v[46:49], v[136:139], v[186:189], v[46:49]
	v_mfma_f32_16x16x32_bf16 v[42:45], v[144:147], v[186:189], v[42:45]
	v_mfma_f32_16x16x32_bf16 v[30:33], v[136:139], v[216:219], v[30:33]
	v_mfma_f32_16x16x32_bf16 v[26:29], v[144:147], v[216:219], v[26:29]
	v_mfma_f32_16x16x32_bf16 v[14:17], v[136:139], v[224:227], v[14:17]
	v_mfma_f32_16x16x32_bf16 v[10:13], v[144:147], v[224:227], v[10:13]
	v_mfma_f32_16x16x32_bf16 v[54:57], v[148:151], v[164:167], v[54:57]
	v_mfma_f32_16x16x32_bf16 v[50:53], v[156:159], v[164:167], v[50:53]
	v_mfma_f32_16x16x32_bf16 v[38:41], v[148:151], v[182:185], v[38:41]
	v_mfma_f32_16x16x32_bf16 v[34:37], v[156:159], v[182:185], v[34:37]
	v_mfma_f32_16x16x32_bf16 v[22:25], v[148:151], v[212:215], v[22:25]
	v_mfma_f32_16x16x32_bf16 v[18:21], v[156:159], v[212:215], v[18:21]
	v_mfma_f32_16x16x32_bf16 v[6:9], v[148:151], v[220:223], v[6:9]
	v_mfma_f32_16x16x32_bf16 v[2:5], v[156:159], v[220:223], v[2:5]
	v_mfma_f32_16x16x32_bf16 v[54:57], v[152:155], v[168:171], v[54:57]
	v_mfma_f32_16x16x32_bf16 v[50:53], v[160:163], v[168:171], v[50:53]
	v_mfma_f32_16x16x32_bf16 v[38:41], v[152:155], v[186:189], v[38:41]
	v_mfma_f32_16x16x32_bf16 v[34:37], v[160:163], v[186:189], v[34:37]
	v_mfma_f32_16x16x32_bf16 v[22:25], v[152:155], v[216:219], v[22:25]
	v_mfma_f32_16x16x32_bf16 v[18:21], v[160:163], v[216:219], v[18:21]
	v_mfma_f32_16x16x32_bf16 v[6:9], v[152:155], v[224:227], v[6:9]
	v_mfma_f32_16x16x32_bf16 v[2:5], v[160:163], v[224:227], v[2:5]
	s_barrier
	s_add_i32 s29, 0, 0x18000
	s_add_i32 s54, 0, 0x1c000
	v_add_u32_e32 v144, s29, v193
	v_add_u32_e32 v160, s54, v193
	ds_read_b128 v[132:135], v144
	ds_read_b128 v[136:139], v144 offset:1024
	ds_read_b128 v[140:143], v144 offset:2048
	ds_read_b128 v[144:147], v144 offset:3072
	ds_read_b128 v[148:151], v160
	ds_read_b128 v[152:155], v160 offset:1024
	ds_read_b128 v[156:159], v160 offset:2048
	ds_read_b128 v[160:163], v160 offset:3072
	s_add_u32 s20, s26, 0x20000
	s_addc_u32 s21, s27, 0
	s_mov_b32 m0, s41
	v_lshl_add_u64 v[232:233], s[20:21], 0, v[176:177]
	ds_read_b128 v[164:167], v195 offset:32768
	ds_read_b128 v[168:171], v195 offset:33792
	ds_read_b128 v[182:185], v195 offset:34816
	ds_read_b128 v[186:189], v195 offset:35840
	ds_read_b128 v[212:215], v195 offset:36864
	ds_read_b128 v[216:219], v195 offset:37888
	ds_read_b128 v[220:223], v195 offset:38912
	ds_read_b128 v[224:227], v195 offset:39936
	global_load_lds_dwordx4 v[232:233], off
	v_lshl_add_u64 v[232:233], s[20:21], 0, v[174:175]
	s_mov_b32 m0, s43
	s_nop 0
	global_load_lds_dwordx4 v[232:233], off
	s_waitcnt vmcnt(8)
	s_waitcnt lgkmcnt(0)
	s_barrier
	s_waitcnt lgkmcnt(0)
	v_mfma_f32_16x16x32_bf16 v[128:131], v[132:135], v[164:167], v[128:131]
	v_mfma_f32_16x16x32_bf16 v[124:127], v[140:143], v[164:167], v[124:127]
	v_mfma_f32_16x16x32_bf16 v[110:113], v[132:135], v[182:185], v[110:113]
	v_mfma_f32_16x16x32_bf16 v[106:109], v[140:143], v[182:185], v[106:109]
	v_mfma_f32_16x16x32_bf16 v[94:97], v[132:135], v[212:215], v[94:97]
	v_mfma_f32_16x16x32_bf16 v[90:93], v[140:143], v[212:215], v[90:93]
	v_mfma_f32_16x16x32_bf16 v[78:81], v[132:135], v[220:223], v[78:81]
	v_mfma_f32_16x16x32_bf16 v[74:77], v[140:143], v[220:223], v[74:77]
	v_mfma_f32_16x16x32_bf16 v[128:131], v[136:139], v[168:171], v[128:131]
	v_mfma_f32_16x16x32_bf16 v[124:127], v[144:147], v[168:171], v[124:127]
	v_mfma_f32_16x16x32_bf16 v[110:113], v[136:139], v[186:189], v[110:113]
	v_mfma_f32_16x16x32_bf16 v[106:109], v[144:147], v[186:189], v[106:109]
	v_mfma_f32_16x16x32_bf16 v[94:97], v[136:139], v[216:219], v[94:97]
	v_mfma_f32_16x16x32_bf16 v[90:93], v[144:147], v[216:219], v[90:93]
	v_mfma_f32_16x16x32_bf16 v[78:81], v[136:139], v[224:227], v[78:81]
	v_mfma_f32_16x16x32_bf16 v[74:77], v[144:147], v[224:227], v[74:77]
	v_mfma_f32_16x16x32_bf16 v[120:123], v[148:151], v[164:167], v[120:123]
	v_mfma_f32_16x16x32_bf16 v[116:119], v[156:159], v[164:167], v[116:119]
	v_mfma_f32_16x16x32_bf16 v[102:105], v[148:151], v[182:185], v[102:105]
	v_mfma_f32_16x16x32_bf16 v[98:101], v[156:159], v[182:185], v[98:101]
	v_mfma_f32_16x16x32_bf16 v[86:89], v[148:151], v[212:215], v[86:89]
	v_mfma_f32_16x16x32_bf16 v[82:85], v[156:159], v[212:215], v[82:85]
	v_mfma_f32_16x16x32_bf16 v[70:73], v[148:151], v[220:223], v[70:73]
	v_mfma_f32_16x16x32_bf16 v[66:69], v[156:159], v[220:223], v[66:69]
	v_mfma_f32_16x16x32_bf16 v[120:123], v[152:155], v[168:171], v[120:123]
	v_mfma_f32_16x16x32_bf16 v[116:119], v[160:163], v[168:171], v[116:119]
	v_mfma_f32_16x16x32_bf16 v[102:105], v[152:155], v[186:189], v[102:105]
	v_mfma_f32_16x16x32_bf16 v[98:101], v[160:163], v[186:189], v[98:101]
	v_mfma_f32_16x16x32_bf16 v[86:89], v[152:155], v[216:219], v[86:89]
	v_mfma_f32_16x16x32_bf16 v[82:85], v[160:163], v[216:219], v[82:85]
	v_mfma_f32_16x16x32_bf16 v[70:73], v[152:155], v[224:227], v[70:73]
	v_mfma_f32_16x16x32_bf16 v[66:69], v[160:163], v[224:227], v[66:69]
	s_barrier
; #define PG8_STAGE(bufoff, gbase, voff) do { _Pragma("unroll") for (int _i = 0; _i < 2; ++_i) \
;         __builtin_amdgcn_global_load_lds((const unsigned*)((const char*)(gbase) + (voff)[_i]), (LAS unsigned*)(lds + (bufoff) + ldsw + _i * 8192), 16, 0, 0); } while (0)
; #define PG8_LDA(dst, b, h) do { _Pragma("unroll") for (int m = 0; m < 4; ++m) _Pragma("unroll") for (int k = 0; k < 2; ++k) dst[m][k] = *(const LAS bf16x8*)(lds + PG8_SA(b, h) + aoff + m * 2048 + k * 1024); } while (0)
; #define PG8_MMA(ai, bj, At, Bt) do { __builtin_amdgcn_s_setprio(1); _Pragma("unroll") for (int m = 0; m < 4; ++m) _Pragma("unroll") for (int n = 0; n < 2; ++n) _Pragma("unroll") for (int k = 0; k < 2; ++k) \
;         acc[ai][bj][m][n] = __builtin_amdgcn_mfma_f32_16x16x32_bf16(Bt[n][k], At[m][k], acc[ai][bj][m][n], 0, 0, 0); __builtin_amdgcn_s_setprio(0); } while (0)
; #define PG8_WAIT_V(n) asm volatile("s_waitcnt vmcnt(" #n ")" ::: "memory")
; #define PG8_WAIT_L(n) asm volatile("s_waitcnt lgkmcnt(" #n ")" ::: "memory")
; #define PG8_BAR __builtin_amdgcn_s_barrier()
; #define PG8_SCHED __builtin_amdgcn_sched_barrier(0)
; template <class Epi, class Sched, bool ALIGN_EPI = true, bool SP2 = true>
; __device__ __forceinline__ void gemm_phase(LAS unsigned char* lds, const Sched& S, const Epi& E, const int lda, const int ldb) {
;     ...
;             PG8_LDA(At, 1, 1); PG8_STAGE(PG8_SB(1, 0), b3, voffB); PG8_STAGE(PG8_SB(1, 1), b3 + hstepB, voffB); PG8_STAGE(PG8_SA(1, 0), a3, voffA);
;             PG8_WAIT_V(8); PG8_WAIT_L(0); PG8_BAR; PG8_MMA(1, 0, At, B0); PG8_MMA(1, 1, At, B1); PG8_BAR; PG8_SCHED;
;     ...
;         if constexpr (ALIGN_EPI) { if (wr == 0) PG8_BAR; }
	s_add_i32 s20, s29, s38
	v_lshl_add_u64 v[190:191], v[190:191], 0, s[70:71]
	s_mov_b32 m0, s20
	ds_read_b128 v[164:167], v195 offset:49152
	ds_read_b128 v[168:171], v195 offset:50176
	ds_read_b128 v[182:185], v195 offset:51200
	ds_read_b128 v[186:189], v195 offset:52224
	ds_read_b128 v[212:215], v195 offset:53248
	ds_read_b128 v[216:219], v195 offset:54272
	ds_read_b128 v[220:223], v195 offset:55296
	ds_read_b128 v[224:227], v195 offset:56320
	global_load_lds_dwordx4 v[190:191], off
	s_add_i32 m0, s20, 0x2000
	s_add_u32 s20, s24, 0x20080
	v_lshl_add_u64 v[190:191], v[196:197], 0, s[70:71]
	s_addc_u32 s21, s25, 0
	s_add_i32 s24, s54, s38
	global_load_lds_dwordx4 v[190:191], off
	v_lshl_add_u64 v[190:191], s[20:21], 0, v[114:115]
	s_mov_b32 m0, s24
	s_nop 0
	global_load_lds_dwordx4 v[190:191], off
	v_lshl_add_u64 v[190:191], s[20:21], 0, v[172:173]
	s_add_i32 m0, s24, 0x2000
	s_nop 0
	global_load_lds_dwordx4 v[190:191], off
	v_lshl_add_u64 v[190:191], v[228:229], 0, s[70:71]
	s_mov_b32 m0, s51
	s_nop 0
	global_load_lds_dwordx4 v[190:191], off
	v_lshl_add_u64 v[190:191], v[230:231], 0, s[70:71]
	s_mov_b32 m0, s52
	s_nop 0
	global_load_lds_dwordx4 v[190:191], off
	s_waitcnt vmcnt(8)
	s_waitcnt lgkmcnt(0)
	s_barrier
	s_waitcnt lgkmcnt(0)
	v_mfma_f32_16x16x32_bf16 v[62:65], v[132:135], v[164:167], v[62:65]
	v_mfma_f32_16x16x32_bf16 v[58:61], v[140:143], v[164:167], v[58:61]
	v_mfma_f32_16x16x32_bf16 v[46:49], v[132:135], v[182:185], v[46:49]
	v_mfma_f32_16x16x32_bf16 v[42:45], v[140:143], v[182:185], v[42:45]
	v_mfma_f32_16x16x32_bf16 v[30:33], v[132:135], v[212:215], v[30:33]
	v_mfma_f32_16x16x32_bf16 v[26:29], v[140:143], v[212:215], v[26:29]
	v_mfma_f32_16x16x32_bf16 v[14:17], v[132:135], v[220:223], v[14:17]
	v_mfma_f32_16x16x32_bf16 v[10:13], v[140:143], v[220:223], v[10:13]
	v_mfma_f32_16x16x32_bf16 v[62:65], v[136:139], v[168:171], v[62:65]
	v_mfma_f32_16x16x32_bf16 v[58:61], v[144:147], v[168:171], v[58:61]
	v_mfma_f32_16x16x32_bf16 v[46:49], v[136:139], v[186:189], v[46:49]
	v_mfma_f32_16x16x32_bf16 v[42:45], v[144:147], v[186:189], v[42:45]
	v_mfma_f32_16x16x32_bf16 v[30:33], v[136:139], v[216:219], v[30:33]
	v_mfma_f32_16x16x32_bf16 v[26:29], v[144:147], v[216:219], v[26:29]
	v_mfma_f32_16x16x32_bf16 v[14:17], v[136:139], v[224:227], v[14:17]
	v_mfma_f32_16x16x32_bf16 v[10:13], v[144:147], v[224:227], v[10:13]
	v_mfma_f32_16x16x32_bf16 v[54:57], v[148:151], v[164:167], v[54:57]
	v_mfma_f32_16x16x32_bf16 v[50:53], v[156:159], v[164:167], v[50:53]
	v_mfma_f32_16x16x32_bf16 v[38:41], v[148:151], v[182:185], v[38:41]
	v_mfma_f32_16x16x32_bf16 v[34:37], v[156:159], v[182:185], v[34:37]
	v_mfma_f32_16x16x32_bf16 v[22:25], v[148:151], v[212:215], v[22:25]
	v_mfma_f32_16x16x32_bf16 v[18:21], v[156:159], v[212:215], v[18:21]
	v_mfma_f32_16x16x32_bf16 v[6:9], v[148:151], v[220:223], v[6:9]
	v_mfma_f32_16x16x32_bf16 v[2:5], v[156:159], v[220:223], v[2:5]
	v_mfma_f32_16x16x32_bf16 v[54:57], v[152:155], v[168:171], v[54:57]
	v_mfma_f32_16x16x32_bf16 v[50:53], v[160:163], v[168:171], v[50:53]
	v_mfma_f32_16x16x32_bf16 v[38:41], v[152:155], v[186:189], v[38:41]
	v_mfma_f32_16x16x32_bf16 v[34:37], v[160:163], v[186:189], v[34:37]
	v_mfma_f32_16x16x32_bf16 v[22:25], v[152:155], v[216:219], v[22:25]
	v_mfma_f32_16x16x32_bf16 v[18:21], v[160:163], v[216:219], v[18:21]
	v_mfma_f32_16x16x32_bf16 v[6:9], v[152:155], v[224:227], v[6:9]
	v_mfma_f32_16x16x32_bf16 v[2:5], v[160:163], v[224:227], v[2:5]
	s_barrier
	s_add_i32 s72, s72, 2
	s_cmp_gt_u32 s72, 5
	s_mov_b64 s[20:21], s[22:23]
	s_cbranch_scc0 .LBB0_922
	s_and_b64 vcc, exec, s[10:11]
	s_cbranch_vccz .LBB0_925
	s_barrier

; #define PG8_STAGE(bufoff, gbase, voff) do { _Pragma("unroll") for (int _i = 0; _i < 2; ++_i) \
;         __builtin_amdgcn_global_load_lds((const unsigned*)((const char*)(gbase) + (voff)[_i]), (LAS unsigned*)(lds + (bufoff) + ldsw + _i * 8192), 16, 0, 0); } while (0)
; #define PG8_LDA(dst, b, h) do { _Pragma("unroll") for (int m = 0; m < 4; ++m) _Pragma("unroll") for (int k = 0; k < 2; ++k) dst[m][k] = *(const LAS bf16x8*)(lds + PG8_SA(b, h) + aoff + m * 2048 + k * 1024); } while (0)
; #define PG8_LDB(dst, b, h) do { _Pragma("unroll") for (int n = 0; n < 2; ++n) _Pragma("unroll") for (int k = 0; k < 2; ++k) dst[n][k] = *(const LAS bf16x8*)(lds + PG8_SB(b, h) + boff + n * 2048 + k * 1024); } while (0)
; #define PG8_MMA(ai, bj, At, Bt) do { __builtin_amdgcn_s_setprio(1); _Pragma("unroll") for (int m = 0; m < 4; ++m) _Pragma("unroll") for (int n = 0; n < 2; ++n) _Pragma("unroll") for (int k = 0; k < 2; ++k) \
;         acc[ai][bj][m][n] = __builtin_amdgcn_mfma_f32_16x16x32_bf16(Bt[n][k], At[m][k], acc[ai][bj][m][n], 0, 0, 0); __builtin_amdgcn_s_setprio(0); } while (0)
; #define PG8_WAIT_V(n) asm volatile("s_waitcnt vmcnt(" #n ")" ::: "memory")
; #define PG8_WAIT_L(n) asm volatile("s_waitcnt lgkmcnt(" #n ")" ::: "memory")
; #define PG8_BAR __builtin_amdgcn_s_barrier()
; #define PG8_SCHED __builtin_amdgcn_sched_barrier(0)
; template <class Epi, class Sched, bool ALIGN_EPI = true, bool SP2 = true>
; __device__ __forceinline__ void gemm_phase(LAS unsigned char* lds, const Sched& S, const Epi& E, const int lda, const int ldb) {
;     ...
;             const bool last = (t == nt - 2);
;             const char* a1 = cA + (size_t)(t + 1) * kstep;
;             const char* a2 = last ? nA : cA + (size_t)(t + 2) * kstep; const char* b2 = last ? nB : cB + (size_t)(t + 2) * kstep;
;             const char* a3 = a2 + kstep; const char* b3 = b2 + kstep;
;             if constexpr (SP2) {
;             PG8_LDB(B0, 0, 0); PG8_LDB(B1, 0, 1); PG8_SCHED; PG8_LDA(At, 0, 0); PG8_STAGE(PG8_SA(1, 1), a1 + hstepA, voffA);
;             PG8_WAIT_V(8); PG8_WAIT_L(0); PG8_BAR; PG8_MMA(0, 0, At, B0); PG8_MMA(0, 1, At, B1); PG8_BAR; PG8_SCHED;
;             PG8_LDA(At, 0, 1); PG8_STAGE(PG8_SB(0, 0), b2, voffB); PG8_STAGE(PG8_SB(0, 1), b2 + hstepB, voffB); PG8_STAGE(PG8_SA(0, 0), a2, voffA);
.LBB0_1060:
	s_add_i32 s39, s24, 2
	s_add_u32 s25, s6, 0xfff00080
	s_addc_u32 s26, s7, -1
	s_add_i32 s29, 0, 0x10000
	s_cmp_eq_u32 s36, s24
	s_cselect_b32 s27, s21, s26
	s_cselect_b32 s26, s20, s25
	s_cselect_b32 s25, s23, s38
	s_cselect_b32 s24, s22, s37
	s_add_i32 s50, 0, 0x14000
	v_add_u32_e32 v70, s29, v246
	v_add_u32_e32 v114, s50, v246
	ds_read_b128 v[34:37], v70
	ds_read_b128 v[38:41], v70 offset:1024
	ds_read_b128 v[66:69], v70 offset:2048
	ds_read_b128 v[70:73], v70 offset:3072
	ds_read_b128 v[98:101], v114
	ds_read_b128 v[102:105], v114 offset:1024
	ds_read_b128 v[126:129], v114 offset:2048
	ds_read_b128 v[130:133], v114 offset:3072
	v_lshl_add_u64 v[116:117], s[6:7], 0, v[220:221]
	s_add_i32 m0, s57, 0xc000
	ds_read_b128 v[158:161], v248
	ds_read_b128 v[162:165], v248 offset:1024
	ds_read_b128 v[174:177], v248 offset:2048
	ds_read_b128 v[178:181], v248 offset:3072
	ds_read_b128 v[182:185], v248 offset:4096
	ds_read_b128 v[186:189], v248 offset:5120
	ds_read_b128 v[190:193], v248 offset:6144
	ds_read_b128 v[194:197], v248 offset:7168
	global_load_lds_dwordx4 v[116:117], off
	v_lshl_add_u64 v[116:117], s[6:7], 0, v[222:223]
	s_add_i32 m0, s57, 0xe000
	s_nop 0
	global_load_lds_dwordx4 v[116:117], off
	s_waitcnt vmcnt(8)
	s_waitcnt lgkmcnt(0)
	s_barrier
	s_waitcnt lgkmcnt(0)
	v_mfma_f32_16x16x32_bf16 v[54:57], v[34:37], v[158:161], v[54:57]
	v_mfma_f32_16x16x32_bf16 v[50:53], v[66:69], v[158:161], v[50:53]
	v_mfma_f32_16x16x32_bf16 v[86:89], v[34:37], v[174:177], v[86:89]
	v_mfma_f32_16x16x32_bf16 v[82:85], v[66:69], v[174:177], v[82:85]
	v_mfma_f32_16x16x32_bf16 v[110:113], v[34:37], v[182:185], v[110:113]
	v_mfma_f32_16x16x32_bf16 v[106:109], v[66:69], v[182:185], v[106:109]
	v_mfma_f32_16x16x32_bf16 v[138:141], v[34:37], v[190:193], v[138:141]
	v_mfma_f32_16x16x32_bf16 v[134:137], v[66:69], v[190:193], v[134:137]
	v_mfma_f32_16x16x32_bf16 v[54:57], v[38:41], v[162:165], v[54:57]
	v_mfma_f32_16x16x32_bf16 v[50:53], v[70:73], v[162:165], v[50:53]
	v_mfma_f32_16x16x32_bf16 v[86:89], v[38:41], v[178:181], v[86:89]
	v_mfma_f32_16x16x32_bf16 v[82:85], v[70:73], v[178:181], v[82:85]
	v_mfma_f32_16x16x32_bf16 v[110:113], v[38:41], v[186:189], v[110:113]
	v_mfma_f32_16x16x32_bf16 v[106:109], v[70:73], v[186:189], v[106:109]
	v_mfma_f32_16x16x32_bf16 v[138:141], v[38:41], v[194:197], v[138:141]
	v_mfma_f32_16x16x32_bf16 v[134:137], v[70:73], v[194:197], v[134:137]
	v_mfma_f32_16x16x32_bf16 v[170:173], v[98:101], v[158:161], v[170:173]
	v_mfma_f32_16x16x32_bf16 v[154:157], v[98:101], v[174:177], v[154:157]
	v_mfma_f32_16x16x32_bf16 v[150:153], v[126:129], v[174:177], v[150:153]
	v_mfma_f32_16x16x32_bf16 v[146:149], v[98:101], v[182:185], v[146:149]
	v_mfma_f32_16x16x32_bf16 v[142:145], v[126:129], v[182:185], v[142:145]
	v_mfma_f32_16x16x32_bf16 v[122:125], v[98:101], v[190:193], v[122:125]
	v_mfma_f32_16x16x32_bf16 v[116:119], v[126:129], v[190:193], v[118:121]
	v_mfma_f32_16x16x32_bf16 v[170:173], v[102:105], v[162:165], v[170:173]
	v_mfma_f32_16x16x32_bf16 v[158:161], v[126:129], v[158:161], v[166:169]
	v_mfma_f32_16x16x32_bf16 v[154:157], v[102:105], v[178:181], v[154:157]
	v_mfma_f32_16x16x32_bf16 v[150:153], v[130:133], v[178:181], v[150:153]
	v_mfma_f32_16x16x32_bf16 v[146:149], v[102:105], v[186:189], v[146:149]
	v_mfma_f32_16x16x32_bf16 v[142:145], v[130:133], v[186:189], v[142:145]
	v_mfma_f32_16x16x32_bf16 v[122:125], v[102:105], v[194:197], v[122:125]
	v_mfma_f32_16x16x32_bf16 v[116:119], v[130:133], v[194:197], v[116:119]
	v_mfma_f32_16x16x32_bf16 v[158:161], v[130:133], v[162:165], v[158:161]
	s_barrier
	s_add_i32 s29, s29, s51
	v_lshl_add_u64 v[224:225], s[24:25], 0, v[214:215]
	s_mov_b32 m0, s29
	ds_read_b128 v[162:165], v248 offset:16384
	ds_read_b128 v[166:169], v248 offset:17408
	ds_read_b128 v[174:177], v248 offset:18432
	ds_read_b128 v[178:181], v248 offset:19456
	ds_read_b128 v[182:185], v248 offset:20480
	ds_read_b128 v[186:189], v248 offset:21504
	ds_read_b128 v[190:193], v248 offset:22528
	ds_read_b128 v[194:197], v248 offset:23552
	global_load_lds_dwordx4 v[224:225], off
	s_add_i32 m0, s29, 0x2000
	s_add_u32 s54, s24, 0x100000
	v_lshl_add_u64 v[226:227], s[24:25], 0, v[218:219]
	s_addc_u32 s55, s25, 0
	s_add_i32 s29, s50, s51
	global_load_lds_dwordx4 v[226:227], off
	v_lshl_add_u64 v[120:121], s[54:55], 0, v[214:215]
	s_mov_b32 m0, s29
	v_lshl_add_u64 v[228:229], s[26:27], 0, v[212:213]
	global_load_lds_dwordx4 v[120:121], off
	v_lshl_add_u64 v[120:121], s[54:55], 0, v[218:219]
	s_add_i32 m0, s29, 0x2000
	v_lshl_add_u64 v[230:231], s[26:27], 0, v[216:217]
	global_load_lds_dwordx4 v[120:121], off
	s_mov_b32 m0, s57
	s_nop 0
	global_load_lds_dwordx4 v[228:229], off
	s_mov_b32 m0, s62
	s_nop 0
	global_load_lds_dwordx4 v[230:231], off
	s_waitcnt vmcnt(8)
	s_waitcnt lgkmcnt(0)
	s_barrier
; #define PG8_STAGE(bufoff, gbase, voff) do { _Pragma("unroll") for (int _i = 0; _i < 2; ++_i) \
;         __builtin_amdgcn_global_load_lds((const unsigned*)((const char*)(gbase) + (voff)[_i]), (LAS unsigned*)(lds + (bufoff) + ldsw + _i * 8192), 16, 0, 0); } while (0)
; #define PG8_LDA(dst, b, h) do { _Pragma("unroll") for (int m = 0; m < 4; ++m) _Pragma("unroll") for (int k = 0; k < 2; ++k) dst[m][k] = *(const LAS bf16x8*)(lds + PG8_SA(b, h) + aoff + m * 2048 + k * 1024); } while (0)
; #define PG8_LDB(dst, b, h) do { _Pragma("unroll") for (int n = 0; n < 2; ++n) _Pragma("unroll") for (int k = 0; k < 2; ++k) dst[n][k] = *(const LAS bf16x8*)(lds + PG8_SB(b, h) + boff + n * 2048 + k * 1024); } while (0)
; #define PG8_MMA(ai, bj, At, Bt) do { __builtin_amdgcn_s_setprio(1); _Pragma("unroll") for (int m = 0; m < 4; ++m) _Pragma("unroll") for (int n = 0; n < 2; ++n) _Pragma("unroll") for (int k = 0; k < 2; ++k) \
;         acc[ai][bj][m][n] = __builtin_amdgcn_mfma_f32_16x16x32_bf16(Bt[n][k], At[m][k], acc[ai][bj][m][n], 0, 0, 0); __builtin_amdgcn_s_setprio(0); } while (0)
; #define PG8_WAIT_V(n) asm volatile("s_waitcnt vmcnt(" #n ")" ::: "memory")
; #define PG8_WAIT_L(n) asm volatile("s_waitcnt lgkmcnt(" #n ")" ::: "memory")
; #define PG8_BAR __builtin_amdgcn_s_barrier()
; #define PG8_SCHED __builtin_amdgcn_sched_barrier(0)
; template <class Epi, class Sched, bool ALIGN_EPI = true, bool SP2 = true>
; __device__ __forceinline__ void gemm_phase(LAS unsigned char* lds, const Sched& S, const Epi& E, const int lda, const int ldb) {
;     ...
;             PG8_WAIT_V(8); PG8_WAIT_L(0); PG8_BAR; PG8_MMA(1, 0, At, B0); PG8_MMA(1, 1, At, B1); PG8_BAR; PG8_SCHED;
;             PG8_LDB(B0, 1, 0); PG8_LDB(B1, 1, 1); PG8_SCHED; PG8_LDA(At, 1, 0); PG8_STAGE(PG8_SA(0, 1), a2 + hstepA, voffA);
;             PG8_WAIT_V(8); PG8_WAIT_L(0); PG8_BAR; PG8_MMA(0, 0, At, B0); PG8_MMA(0, 1, At, B1); PG8_BAR; PG8_SCHED;
	s_waitcnt lgkmcnt(0)
	v_mfma_f32_16x16x32_bf16 v[94:97], v[34:37], v[162:165], v[94:97]
	v_mfma_f32_16x16x32_bf16 v[90:93], v[66:69], v[162:165], v[90:93]
	v_mfma_f32_16x16x32_bf16 v[62:65], v[34:37], v[174:177], v[62:65]
	v_mfma_f32_16x16x32_bf16 v[58:61], v[66:69], v[174:177], v[58:61]
	v_mfma_f32_16x16x32_bf16 v[30:33], v[34:37], v[182:185], v[30:33]
	v_mfma_f32_16x16x32_bf16 v[26:29], v[66:69], v[182:185], v[26:29]
	v_mfma_f32_16x16x32_bf16 v[14:17], v[34:37], v[190:193], v[14:17]
	v_mfma_f32_16x16x32_bf16 v[10:13], v[66:69], v[190:193], v[10:13]
	v_mfma_f32_16x16x32_bf16 v[94:97], v[38:41], v[166:169], v[94:97]
	v_mfma_f32_16x16x32_bf16 v[90:93], v[70:73], v[166:169], v[90:93]
	v_mfma_f32_16x16x32_bf16 v[62:65], v[38:41], v[178:181], v[62:65]
	v_mfma_f32_16x16x32_bf16 v[58:61], v[70:73], v[178:181], v[58:61]
	v_mfma_f32_16x16x32_bf16 v[30:33], v[38:41], v[186:189], v[30:33]
	v_mfma_f32_16x16x32_bf16 v[26:29], v[70:73], v[186:189], v[26:29]
	v_mfma_f32_16x16x32_bf16 v[14:17], v[38:41], v[194:197], v[14:17]
	v_mfma_f32_16x16x32_bf16 v[10:13], v[70:73], v[194:197], v[10:13]
	v_mfma_f32_16x16x32_bf16 v[46:49], v[98:101], v[174:177], v[46:49]
	v_mfma_f32_16x16x32_bf16 v[42:45], v[126:129], v[174:177], v[42:45]
	v_mfma_f32_16x16x32_bf16 v[22:25], v[98:101], v[182:185], v[22:25]
	v_mfma_f32_16x16x32_bf16 v[18:21], v[126:129], v[182:185], v[18:21]
	v_mfma_f32_16x16x32_bf16 v[6:9], v[98:101], v[190:193], v[6:9]
	v_mfma_f32_16x16x32_bf16 v[2:5], v[126:129], v[190:193], v[2:5]
	v_mfma_f32_16x16x32_bf16 v[34:37], v[98:101], v[162:165], v[78:81]
	v_mfma_f32_16x16x32_bf16 v[38:41], v[126:129], v[162:165], v[74:77]
	v_mfma_f32_16x16x32_bf16 v[46:49], v[102:105], v[178:181], v[46:49]
	v_mfma_f32_16x16x32_bf16 v[42:45], v[130:133], v[178:181], v[42:45]
	v_mfma_f32_16x16x32_bf16 v[22:25], v[102:105], v[186:189], v[22:25]
	v_mfma_f32_16x16x32_bf16 v[18:21], v[130:133], v[186:189], v[18:21]
	v_mfma_f32_16x16x32_bf16 v[6:9], v[102:105], v[194:197], v[6:9]
	v_mfma_f32_16x16x32_bf16 v[2:5], v[130:133], v[194:197], v[2:5]
	v_mfma_f32_16x16x32_bf16 v[34:37], v[102:105], v[166:169], v[34:37]
	v_mfma_f32_16x16x32_bf16 v[38:41], v[130:133], v[166:169], v[38:41]
	s_barrier
	s_add_i32 s29, 0, 0x18000
	s_add_i32 s50, 0, 0x1c000
	v_add_u32_e32 v78, s29, v246
	v_add_u32_e32 v114, s50, v246
	ds_read_b128 v[66:69], v78
	ds_read_b128 v[70:73], v78 offset:1024
	ds_read_b128 v[74:77], v78 offset:2048
	ds_read_b128 v[78:81], v78 offset:3072
	ds_read_b128 v[98:101], v114
	ds_read_b128 v[102:105], v114 offset:1024
	ds_read_b128 v[126:129], v114 offset:2048
	ds_read_b128 v[130:133], v114 offset:3072
	s_add_u32 s26, s26, 0x100000
	s_addc_u32 s27, s27, 0
	s_mov_b32 m0, s63
	v_lshl_add_u64 v[120:121], s[26:27], 0, v[212:213]
	ds_read_b128 v[162:165], v248 offset:32768
	ds_read_b128 v[166:169], v248 offset:33792
	ds_read_b128 v[174:177], v248 offset:34816
	ds_read_b128 v[178:181], v248 offset:35840
	ds_read_b128 v[182:185], v248 offset:36864
	ds_read_b128 v[186:189], v248 offset:37888
	ds_read_b128 v[190:193], v248 offset:38912
	ds_read_b128 v[194:197], v248 offset:39936
	global_load_lds_dwordx4 v[120:121], off
	v_lshl_add_u64 v[120:121], s[26:27], 0, v[216:217]
	s_mov_b32 m0, s72
	s_nop 0
	global_load_lds_dwordx4 v[120:121], off
	s_waitcnt vmcnt(8)
	s_waitcnt lgkmcnt(0)
	s_barrier
	s_waitcnt lgkmcnt(0)
	v_mfma_f32_16x16x32_bf16 v[54:57], v[66:69], v[162:165], v[54:57]
	v_mfma_f32_16x16x32_bf16 v[50:53], v[74:77], v[162:165], v[50:53]
	v_mfma_f32_16x16x32_bf16 v[86:89], v[66:69], v[174:177], v[86:89]
	v_mfma_f32_16x16x32_bf16 v[82:85], v[74:77], v[174:177], v[82:85]
	v_mfma_f32_16x16x32_bf16 v[110:113], v[66:69], v[182:185], v[110:113]
	v_mfma_f32_16x16x32_bf16 v[106:109], v[74:77], v[182:185], v[106:109]
	v_mfma_f32_16x16x32_bf16 v[138:141], v[66:69], v[190:193], v[138:141]
	v_mfma_f32_16x16x32_bf16 v[134:137], v[74:77], v[190:193], v[134:137]
	v_mfma_f32_16x16x32_bf16 v[54:57], v[70:73], v[166:169], v[54:57]
	v_mfma_f32_16x16x32_bf16 v[50:53], v[78:81], v[166:169], v[50:53]
	v_mfma_f32_16x16x32_bf16 v[86:89], v[70:73], v[178:181], v[86:89]
	v_mfma_f32_16x16x32_bf16 v[82:85], v[78:81], v[178:181], v[82:85]
	v_mfma_f32_16x16x32_bf16 v[110:113], v[70:73], v[186:189], v[110:113]
	v_mfma_f32_16x16x32_bf16 v[106:109], v[78:81], v[186:189], v[106:109]
	v_mfma_f32_16x16x32_bf16 v[138:141], v[70:73], v[194:197], v[138:141]
	v_mfma_f32_16x16x32_bf16 v[134:137], v[78:81], v[194:197], v[134:137]
	v_mfma_f32_16x16x32_bf16 v[170:173], v[98:101], v[162:165], v[170:173]
	v_mfma_f32_16x16x32_bf16 v[158:161], v[126:129], v[162:165], v[158:161]
	v_mfma_f32_16x16x32_bf16 v[154:157], v[98:101], v[174:177], v[154:157]
	v_mfma_f32_16x16x32_bf16 v[150:153], v[126:129], v[174:177], v[150:153]
	v_mfma_f32_16x16x32_bf16 v[146:149], v[98:101], v[182:185], v[146:149]
	v_mfma_f32_16x16x32_bf16 v[142:145], v[126:129], v[182:185], v[142:145]
	v_mfma_f32_16x16x32_bf16 v[120:123], v[98:101], v[190:193], v[122:125]
	v_mfma_f32_16x16x32_bf16 v[116:119], v[126:129], v[190:193], v[116:119]
	v_mfma_f32_16x16x32_bf16 v[170:173], v[102:105], v[166:169], v[170:173]
	v_mfma_f32_16x16x32_bf16 v[166:169], v[130:133], v[166:169], v[158:161]
	v_mfma_f32_16x16x32_bf16 v[154:157], v[102:105], v[178:181], v[154:157]
	v_mfma_f32_16x16x32_bf16 v[150:153], v[130:133], v[178:181], v[150:153]
	v_mfma_f32_16x16x32_bf16 v[146:149], v[102:105], v[186:189], v[146:149]
	v_mfma_f32_16x16x32_bf16 v[142:145], v[130:133], v[186:189], v[142:145]
	v_mfma_f32_16x16x32_bf16 v[122:125], v[102:105], v[194:197], v[120:123]
	v_mfma_f32_16x16x32_bf16 v[118:121], v[130:133], v[194:197], v[116:119]
	s_barrier
; #define PG8_STAGE(bufoff, gbase, voff) do { _Pragma("unroll") for (int _i = 0; _i < 2; ++_i) \
;         __builtin_amdgcn_global_load_lds((const unsigned*)((const char*)(gbase) + (voff)[_i]), (LAS unsigned*)(lds + (bufoff) + ldsw + _i * 8192), 16, 0, 0); } while (0)
; #define PG8_LDA(dst, b, h) do { _Pragma("unroll") for (int m = 0; m < 4; ++m) _Pragma("unroll") for (int k = 0; k < 2; ++k) dst[m][k] = *(const LAS bf16x8*)(lds + PG8_SA(b, h) + aoff + m * 2048 + k * 1024); } while (0)
; #define PG8_MMA(ai, bj, At, Bt) do { __builtin_amdgcn_s_setprio(1); _Pragma("unroll") for (int m = 0; m < 4; ++m) _Pragma("unroll") for (int n = 0; n < 2; ++n) _Pragma("unroll") for (int k = 0; k < 2; ++k) \
;         acc[ai][bj][m][n] = __builtin_amdgcn_mfma_f32_16x16x32_bf16(Bt[n][k], At[m][k], acc[ai][bj][m][n], 0, 0, 0); __builtin_amdgcn_s_setprio(0); } while (0)
; #define PG8_WAIT_V(n) asm volatile("s_waitcnt vmcnt(" #n ")" ::: "memory")
; #define PG8_WAIT_L(n) asm volatile("s_waitcnt lgkmcnt(" #n ")" ::: "memory")
; #define PG8_BAR __builtin_amdgcn_s_barrier()
; #define PG8_SCHED __builtin_amdgcn_sched_barrier(0)
; template <class Epi, class Sched, bool ALIGN_EPI = true, bool SP2 = true>
; __device__ __forceinline__ void gemm_phase(LAS unsigned char* lds, const Sched& S, const Epi& E, const int lda, const int ldb) {
;     ...
;             PG8_LDA(At, 1, 1); PG8_STAGE(PG8_SB(1, 0), b3, voffB); PG8_STAGE(PG8_SB(1, 1), b3 + hstepB, voffB); PG8_STAGE(PG8_SA(1, 0), a3, voffA);
;             PG8_WAIT_V(8); PG8_WAIT_L(0); PG8_BAR; PG8_MMA(1, 0, At, B0); PG8_MMA(1, 1, At, B1); PG8_BAR; PG8_SCHED;
;     ...
;         if constexpr (ALIGN_EPI) { if (wr == 0) PG8_BAR; }
	s_add_i32 s26, s29, s51
	v_lshl_add_u64 v[116:117], v[224:225], 0, s[70:71]
	s_mov_b32 m0, s26
	ds_read_b128 v[158:161], v248 offset:49152
	ds_read_b128 v[162:165], v248 offset:50176
	ds_read_b128 v[174:177], v248 offset:51200
	ds_read_b128 v[178:181], v248 offset:52224
	ds_read_b128 v[182:185], v248 offset:53248
	ds_read_b128 v[186:189], v248 offset:54272
	ds_read_b128 v[190:193], v248 offset:55296
	ds_read_b128 v[194:197], v248 offset:56320
	global_load_lds_dwordx4 v[116:117], off
	s_add_i32 m0, s26, 0x2000
	s_add_u32 s24, s24, 0x100080
	v_lshl_add_u64 v[116:117], v[226:227], 0, s[70:71]
	s_addc_u32 s25, s25, 0
	s_add_i32 s26, s50, s51
	global_load_lds_dwordx4 v[116:117], off
	v_lshl_add_u64 v[116:117], s[24:25], 0, v[214:215]
	s_mov_b32 m0, s26
	s_nop 0
	global_load_lds_dwordx4 v[116:117], off
	v_lshl_add_u64 v[116:117], s[24:25], 0, v[218:219]
	s_add_i32 m0, s26, 0x2000
	s_nop 0
	global_load_lds_dwordx4 v[116:117], off
	v_lshl_add_u64 v[116:117], v[228:229], 0, s[70:71]
	s_mov_b32 m0, s73
	s_nop 0
	global_load_lds_dwordx4 v[116:117], off
	v_lshl_add_u64 v[116:117], v[230:231], 0, s[70:71]
	s_mov_b32 m0, s76
	s_nop 0
	global_load_lds_dwordx4 v[116:117], off
	s_waitcnt vmcnt(8)
	s_waitcnt lgkmcnt(0)
	s_barrier
	s_waitcnt lgkmcnt(0)
	v_mfma_f32_16x16x32_bf16 v[94:97], v[66:69], v[158:161], v[94:97]
	v_mfma_f32_16x16x32_bf16 v[90:93], v[74:77], v[158:161], v[90:93]
	v_mfma_f32_16x16x32_bf16 v[62:65], v[66:69], v[174:177], v[62:65]
	v_mfma_f32_16x16x32_bf16 v[58:61], v[74:77], v[174:177], v[58:61]
	v_mfma_f32_16x16x32_bf16 v[30:33], v[66:69], v[182:185], v[30:33]
	v_mfma_f32_16x16x32_bf16 v[26:29], v[74:77], v[182:185], v[26:29]
	v_mfma_f32_16x16x32_bf16 v[14:17], v[66:69], v[190:193], v[14:17]
	v_mfma_f32_16x16x32_bf16 v[10:13], v[74:77], v[190:193], v[10:13]
	v_mfma_f32_16x16x32_bf16 v[94:97], v[70:73], v[162:165], v[94:97]
	v_mfma_f32_16x16x32_bf16 v[90:93], v[78:81], v[162:165], v[90:93]
	v_mfma_f32_16x16x32_bf16 v[62:65], v[70:73], v[178:181], v[62:65]
	v_mfma_f32_16x16x32_bf16 v[58:61], v[78:81], v[178:181], v[58:61]
	v_mfma_f32_16x16x32_bf16 v[30:33], v[70:73], v[186:189], v[30:33]
	v_mfma_f32_16x16x32_bf16 v[26:29], v[78:81], v[186:189], v[26:29]
	v_mfma_f32_16x16x32_bf16 v[14:17], v[70:73], v[194:197], v[14:17]
	v_mfma_f32_16x16x32_bf16 v[10:13], v[78:81], v[194:197], v[10:13]
	v_mfma_f32_16x16x32_bf16 v[34:37], v[98:101], v[158:161], v[34:37]
	v_mfma_f32_16x16x32_bf16 v[78:81], v[102:105], v[162:165], v[34:37]
	v_mfma_f32_16x16x32_bf16 v[34:37], v[126:129], v[158:161], v[38:41]
	v_mfma_f32_16x16x32_bf16 v[74:77], v[130:133], v[162:165], v[34:37]
	v_mfma_f32_16x16x32_bf16 v[34:37], v[98:101], v[174:177], v[46:49]
	v_mfma_f32_16x16x32_bf16 v[46:49], v[102:105], v[178:181], v[34:37]
	v_mfma_f32_16x16x32_bf16 v[34:37], v[126:129], v[174:177], v[42:45]
	v_mfma_f32_16x16x32_bf16 v[22:25], v[98:101], v[182:185], v[22:25]
	v_mfma_f32_16x16x32_bf16 v[18:21], v[126:129], v[182:185], v[18:21]
	v_mfma_f32_16x16x32_bf16 v[6:9], v[98:101], v[190:193], v[6:9]
	v_mfma_f32_16x16x32_bf16 v[2:5], v[126:129], v[190:193], v[2:5]
	v_mfma_f32_16x16x32_bf16 v[42:45], v[130:133], v[178:181], v[34:37]
	v_mfma_f32_16x16x32_bf16 v[22:25], v[102:105], v[186:189], v[22:25]
	v_mfma_f32_16x16x32_bf16 v[18:21], v[130:133], v[186:189], v[18:21]
	v_mfma_f32_16x16x32_bf16 v[6:9], v[102:105], v[194:197], v[6:9]
	v_mfma_f32_16x16x32_bf16 v[2:5], v[130:133], v[194:197], v[2:5]
	s_barrier
	s_add_u32 s6, s6, 0x100
	s_addc_u32 s7, s7, 0
	s_add_u32 s37, s37, 0x100
	s_addc_u32 s38, s38, 0
	s_cmp_ge_i32 s39, s33
	s_mov_b32 s24, s39
	s_cbranch_scc0 .LBB0_1060
	s_and_b64 vcc, exec, s[18:19]
	s_cbranch_vccz .LBB0_1063
	s_barrier

; #define PG8_STAGE(bufoff, gbase, voff) do { _Pragma("unroll") for (int _i = 0; _i < 2; ++_i) \
;         __builtin_amdgcn_global_load_lds((const unsigned*)((const char*)(gbase) + (voff)[_i]), (LAS unsigned*)(lds + (bufoff) + ldsw + _i * 8192), 16, 0, 0); } while (0)
; #define PG8_LDA(dst, b, h) do { _Pragma("unroll") for (int m = 0; m < 4; ++m) _Pragma("unroll") for (int k = 0; k < 2; ++k) dst[m][k] = *(const LAS bf16x8*)(lds + PG8_SA(b, h) + aoff + m * 2048 + k * 1024); } while (0)
; #define PG8_LDB(dst, b, h) do { _Pragma("unroll") for (int n = 0; n < 2; ++n) _Pragma("unroll") for (int k = 0; k < 2; ++k) dst[n][k] = *(const LAS bf16x8*)(lds + PG8_SB(b, h) + boff + n * 2048 + k * 1024); } while (0)
; #define PG8_MMA(ai, bj, At, Bt) do { __builtin_amdgcn_s_setprio(1); _Pragma("unroll") for (int m = 0; m < 4; ++m) _Pragma("unroll") for (int n = 0; n < 2; ++n) _Pragma("unroll") for (int k = 0; k < 2; ++k) \
;         acc[ai][bj][m][n] = __builtin_amdgcn_mfma_f32_16x16x32_bf16(Bt[n][k], At[m][k], acc[ai][bj][m][n], 0, 0, 0); __builtin_amdgcn_s_setprio(0); } while (0)
; #define PG8_WAIT_V(n) asm volatile("s_waitcnt vmcnt(" #n ")" ::: "memory")
; #define PG8_WAIT_L(n) asm volatile("s_waitcnt lgkmcnt(" #n ")" ::: "memory")
; #define PG8_BAR __builtin_amdgcn_s_barrier()
; #define PG8_SCHED __builtin_amdgcn_sched_barrier(0)
; template <class Epi, class Sched, bool ALIGN_EPI = true, bool SP2 = true>
; __device__ __forceinline__ void gemm_phase(LAS unsigned char* lds, const Sched& S, const Epi& E, const int lda, const int ldb) {
;     ...
;             const bool last = (t == nt - 2);
;             const char* a1 = cA + (size_t)(t + 1) * kstep;
;             const char* a2 = last ? nA : cA + (size_t)(t + 2) * kstep; const char* b2 = last ? nB : cB + (size_t)(t + 2) * kstep;
;             const char* a3 = a2 + kstep; const char* b3 = b2 + kstep;
;             if constexpr (SP2) {
;             PG8_LDB(B0, 0, 0); PG8_LDB(B1, 0, 1); PG8_SCHED; PG8_LDA(At, 0, 0); PG8_STAGE(PG8_SA(1, 1), a1 + hstepA, voffA);
;             PG8_WAIT_V(8); PG8_WAIT_L(0); PG8_BAR; PG8_MMA(0, 0, At, B0); PG8_MMA(0, 1, At, B1); PG8_BAR; PG8_SCHED;
;             PG8_LDA(At, 0, 1); PG8_STAGE(PG8_SB(0, 0), b2, voffB); PG8_STAGE(PG8_SB(0, 1), b2 + hstepB, voffB); PG8_STAGE(PG8_SA(0, 0), a2, voffA);
.LBB0_1206:
	s_add_u32 s24, s22, 0xfff00080
	s_addc_u32 s25, s23, -1
	s_add_i32 s29, 0, 0x10000
	s_cmp_eq_u32 s50, 4
	s_cselect_b32 s27, s17, s25
	s_cselect_b32 s26, s16, s24
	s_cselect_b32 s25, s19, s33
	s_cselect_b32 s24, s18, s30
	s_add_i32 s76, 0, 0x14000
	v_add_u32_e32 v144, s29, v216
	v_add_u32_e32 v160, s76, v216
	ds_read_b128 v[132:135], v144
	ds_read_b128 v[136:139], v144 offset:1024
	ds_read_b128 v[140:143], v144 offset:2048
	ds_read_b128 v[144:147], v144 offset:3072
	ds_read_b128 v[148:151], v160
	ds_read_b128 v[152:155], v160 offset:1024
	ds_read_b128 v[156:159], v160 offset:2048
	ds_read_b128 v[160:163], v160 offset:3072
	v_lshl_add_u64 v[214:215], s[22:23], 0, v[196:197]
	s_add_i32 m0, s36, 0xc000
	ds_read_b128 v[164:167], v218
	ds_read_b128 v[168:171], v218 offset:1024
	ds_read_b128 v[220:223], v218 offset:2048
	ds_read_b128 v[224:227], v218 offset:3072
	ds_read_b128 v[228:231], v218 offset:4096
	ds_read_b128 v[232:235], v218 offset:5120
	ds_read_b128 v[236:239], v218 offset:6144
	ds_read_b128 v[240:243], v218 offset:7168
	global_load_lds_dwordx4 v[214:215], off
	v_lshl_add_u64 v[214:215], s[22:23], 0, v[212:213]
	s_add_i32 m0, s36, 0xe000
	s_nop 0
	global_load_lds_dwordx4 v[214:215], off
	s_waitcnt vmcnt(8)
	s_waitcnt lgkmcnt(0)
	s_barrier
	s_waitcnt lgkmcnt(0)
	v_mfma_f32_16x16x32_bf16 v[128:131], v[132:135], v[164:167], v[128:131]
	v_mfma_f32_16x16x32_bf16 v[124:127], v[140:143], v[164:167], v[124:127]
	v_mfma_f32_16x16x32_bf16 v[116:119], v[132:135], v[220:223], v[116:119]
	v_mfma_f32_16x16x32_bf16 v[106:109], v[140:143], v[220:223], v[106:109]
	v_mfma_f32_16x16x32_bf16 v[98:101], v[132:135], v[228:231], v[98:101]
	v_mfma_f32_16x16x32_bf16 v[90:93], v[140:143], v[228:231], v[90:93]
	v_mfma_f32_16x16x32_bf16 v[82:85], v[132:135], v[236:239], v[82:85]
	v_mfma_f32_16x16x32_bf16 v[74:77], v[140:143], v[236:239], v[74:77]
	v_mfma_f32_16x16x32_bf16 v[128:131], v[136:139], v[168:171], v[128:131]
	v_mfma_f32_16x16x32_bf16 v[124:127], v[144:147], v[168:171], v[124:127]
	v_mfma_f32_16x16x32_bf16 v[116:119], v[136:139], v[224:227], v[116:119]
	v_mfma_f32_16x16x32_bf16 v[106:109], v[144:147], v[224:227], v[106:109]
	v_mfma_f32_16x16x32_bf16 v[98:101], v[136:139], v[232:235], v[98:101]
	v_mfma_f32_16x16x32_bf16 v[90:93], v[144:147], v[232:235], v[90:93]
	v_mfma_f32_16x16x32_bf16 v[82:85], v[136:139], v[240:243], v[82:85]
	v_mfma_f32_16x16x32_bf16 v[74:77], v[144:147], v[240:243], v[74:77]
	v_mfma_f32_16x16x32_bf16 v[120:123], v[148:151], v[164:167], v[120:123]
	v_mfma_f32_16x16x32_bf16 v[110:113], v[156:159], v[164:167], v[110:113]
	v_mfma_f32_16x16x32_bf16 v[102:105], v[148:151], v[220:223], v[102:105]
	v_mfma_f32_16x16x32_bf16 v[94:97], v[156:159], v[220:223], v[94:97]
	v_mfma_f32_16x16x32_bf16 v[86:89], v[148:151], v[228:231], v[86:89]
	v_mfma_f32_16x16x32_bf16 v[78:81], v[156:159], v[228:231], v[78:81]
	v_mfma_f32_16x16x32_bf16 v[70:73], v[148:151], v[236:239], v[70:73]
	v_mfma_f32_16x16x32_bf16 v[66:69], v[156:159], v[236:239], v[66:69]
	v_mfma_f32_16x16x32_bf16 v[120:123], v[152:155], v[168:171], v[120:123]
	v_mfma_f32_16x16x32_bf16 v[110:113], v[160:163], v[168:171], v[110:113]
	v_mfma_f32_16x16x32_bf16 v[102:105], v[152:155], v[224:227], v[102:105]
	v_mfma_f32_16x16x32_bf16 v[94:97], v[160:163], v[224:227], v[94:97]
	v_mfma_f32_16x16x32_bf16 v[86:89], v[152:155], v[232:235], v[86:89]
	v_mfma_f32_16x16x32_bf16 v[78:81], v[160:163], v[232:235], v[78:81]
	v_mfma_f32_16x16x32_bf16 v[70:73], v[152:155], v[240:243], v[70:73]
	v_mfma_f32_16x16x32_bf16 v[66:69], v[160:163], v[240:243], v[66:69]
	s_barrier
	s_add_i32 s29, s29, s12
	v_lshl_add_u64 v[214:215], s[24:25], 0, v[114:115]
	s_mov_b32 m0, s29
	ds_read_b128 v[164:167], v218 offset:16384
	ds_read_b128 v[168:171], v218 offset:17408
	ds_read_b128 v[220:223], v218 offset:18432
	ds_read_b128 v[224:227], v218 offset:19456
	ds_read_b128 v[228:231], v218 offset:20480
	ds_read_b128 v[232:235], v218 offset:21504
	ds_read_b128 v[236:239], v218 offset:22528
	ds_read_b128 v[240:243], v218 offset:23552
	global_load_lds_dwordx4 v[214:215], off
	s_add_i32 m0, s29, 0x2000
	s_add_u32 s54, s24, 0x100000
	v_lshl_add_u64 v[246:247], s[24:25], 0, v[172:173]
	s_addc_u32 s55, s25, 0
	s_add_i32 s29, s76, s12
	global_load_lds_dwordx4 v[246:247], off
	v_lshl_add_u64 v[248:249], s[54:55], 0, v[114:115]
	s_mov_b32 m0, s29
	v_lshl_add_u64 v[250:251], s[26:27], 0, v[174:175]
	global_load_lds_dwordx4 v[248:249], off
	v_lshl_add_u64 v[248:249], s[54:55], 0, v[172:173]
	s_add_i32 m0, s29, 0x2000
	s_nop 0
	global_load_lds_dwordx4 v[248:249], off
	v_lshl_add_u64 v[248:249], s[26:27], 0, v[176:177]
	s_mov_b32 m0, s36
	s_nop 0
	global_load_lds_dwordx4 v[248:249], off
	s_mov_b32 m0, s37
	s_nop 0
	global_load_lds_dwordx4 v[250:251], off
	s_waitcnt vmcnt(8)
	s_waitcnt lgkmcnt(0)
	s_barrier
; #define PG8_STAGE(bufoff, gbase, voff) do { _Pragma("unroll") for (int _i = 0; _i < 2; ++_i) \
;         __builtin_amdgcn_global_load_lds((const unsigned*)((const char*)(gbase) + (voff)[_i]), (LAS unsigned*)(lds + (bufoff) + ldsw + _i * 8192), 16, 0, 0); } while (0)
; #define PG8_LDA(dst, b, h) do { _Pragma("unroll") for (int m = 0; m < 4; ++m) _Pragma("unroll") for (int k = 0; k < 2; ++k) dst[m][k] = *(const LAS bf16x8*)(lds + PG8_SA(b, h) + aoff + m * 2048 + k * 1024); } while (0)
; #define PG8_LDB(dst, b, h) do { _Pragma("unroll") for (int n = 0; n < 2; ++n) _Pragma("unroll") for (int k = 0; k < 2; ++k) dst[n][k] = *(const LAS bf16x8*)(lds + PG8_SB(b, h) + boff + n * 2048 + k * 1024); } while (0)
; #define PG8_MMA(ai, bj, At, Bt) do { __builtin_amdgcn_s_setprio(1); _Pragma("unroll") for (int m = 0; m < 4; ++m) _Pragma("unroll") for (int n = 0; n < 2; ++n) _Pragma("unroll") for (int k = 0; k < 2; ++k) \
;         acc[ai][bj][m][n] = __builtin_amdgcn_mfma_f32_16x16x32_bf16(Bt[n][k], At[m][k], acc[ai][bj][m][n], 0, 0, 0); __builtin_amdgcn_s_setprio(0); } while (0)
; #define PG8_WAIT_V(n) asm volatile("s_waitcnt vmcnt(" #n ")" ::: "memory")
; #define PG8_WAIT_L(n) asm volatile("s_waitcnt lgkmcnt(" #n ")" ::: "memory")
; #define PG8_BAR __builtin_amdgcn_s_barrier()
; #define PG8_SCHED __builtin_amdgcn_sched_barrier(0)
; template <class Epi, class Sched, bool ALIGN_EPI = true, bool SP2 = true>
; __device__ __forceinline__ void gemm_phase(LAS unsigned char* lds, const Sched& S, const Epi& E, const int lda, const int ldb) {
;     ...
;             PG8_WAIT_V(8); PG8_WAIT_L(0); PG8_BAR; PG8_MMA(1, 0, At, B0); PG8_MMA(1, 1, At, B1); PG8_BAR; PG8_SCHED;
;             PG8_LDB(B0, 1, 0); PG8_LDB(B1, 1, 1); PG8_SCHED; PG8_LDA(At, 1, 0); PG8_STAGE(PG8_SA(0, 1), a2 + hstepA, voffA);
;             PG8_WAIT_V(8); PG8_WAIT_L(0); PG8_BAR; PG8_MMA(0, 0, At, B0); PG8_MMA(0, 1, At, B1); PG8_BAR; PG8_SCHED;
	s_waitcnt lgkmcnt(0)
	v_mfma_f32_16x16x32_bf16 v[62:65], v[132:135], v[164:167], v[62:65]
	v_mfma_f32_16x16x32_bf16 v[58:61], v[140:143], v[164:167], v[58:61]
	v_mfma_f32_16x16x32_bf16 v[50:53], v[132:135], v[220:223], v[50:53]
	v_mfma_f32_16x16x32_bf16 v[42:45], v[140:143], v[220:223], v[42:45]
	v_mfma_f32_16x16x32_bf16 v[34:37], v[132:135], v[228:231], v[34:37]
	v_mfma_f32_16x16x32_bf16 v[26:29], v[140:143], v[228:231], v[26:29]
	v_mfma_f32_16x16x32_bf16 v[18:21], v[132:135], v[236:239], v[18:21]
	v_mfma_f32_16x16x32_bf16 v[10:13], v[140:143], v[236:239], v[10:13]
	v_mfma_f32_16x16x32_bf16 v[62:65], v[136:139], v[168:171], v[62:65]
	v_mfma_f32_16x16x32_bf16 v[58:61], v[144:147], v[168:171], v[58:61]
	v_mfma_f32_16x16x32_bf16 v[50:53], v[136:139], v[224:227], v[50:53]
	v_mfma_f32_16x16x32_bf16 v[42:45], v[144:147], v[224:227], v[42:45]
	v_mfma_f32_16x16x32_bf16 v[34:37], v[136:139], v[232:235], v[34:37]
	v_mfma_f32_16x16x32_bf16 v[26:29], v[144:147], v[232:235], v[26:29]
	v_mfma_f32_16x16x32_bf16 v[18:21], v[136:139], v[240:243], v[18:21]
	v_mfma_f32_16x16x32_bf16 v[10:13], v[144:147], v[240:243], v[10:13]
	v_mfma_f32_16x16x32_bf16 v[54:57], v[148:151], v[164:167], v[54:57]
	v_mfma_f32_16x16x32_bf16 v[46:49], v[156:159], v[164:167], v[46:49]
	v_mfma_f32_16x16x32_bf16 v[38:41], v[148:151], v[220:223], v[38:41]
	v_mfma_f32_16x16x32_bf16 v[30:33], v[156:159], v[220:223], v[30:33]
	v_mfma_f32_16x16x32_bf16 v[22:25], v[148:151], v[228:231], v[22:25]
	v_mfma_f32_16x16x32_bf16 v[14:17], v[156:159], v[228:231], v[14:17]
	v_mfma_f32_16x16x32_bf16 v[6:9], v[148:151], v[236:239], v[6:9]
	v_mfma_f32_16x16x32_bf16 v[2:5], v[156:159], v[236:239], v[2:5]
	v_mfma_f32_16x16x32_bf16 v[54:57], v[152:155], v[168:171], v[54:57]
	v_mfma_f32_16x16x32_bf16 v[46:49], v[160:163], v[168:171], v[46:49]
	v_mfma_f32_16x16x32_bf16 v[38:41], v[152:155], v[224:227], v[38:41]
	v_mfma_f32_16x16x32_bf16 v[30:33], v[160:163], v[224:227], v[30:33]
	v_mfma_f32_16x16x32_bf16 v[22:25], v[152:155], v[232:235], v[22:25]
	v_mfma_f32_16x16x32_bf16 v[14:17], v[160:163], v[232:235], v[14:17]
	v_mfma_f32_16x16x32_bf16 v[6:9], v[152:155], v[240:243], v[6:9]
	v_mfma_f32_16x16x32_bf16 v[2:5], v[160:163], v[240:243], v[2:5]
	s_barrier
	s_add_i32 s29, 0, 0x18000
	s_add_i32 s54, 0, 0x1c000
	v_add_u32_e32 v144, s29, v216
	v_add_u32_e32 v160, s54, v216
	ds_read_b128 v[132:135], v144
	ds_read_b128 v[136:139], v144 offset:1024
	ds_read_b128 v[140:143], v144 offset:2048
	ds_read_b128 v[144:147], v144 offset:3072
	ds_read_b128 v[148:151], v160
	ds_read_b128 v[152:155], v160 offset:1024
	ds_read_b128 v[156:159], v160 offset:2048
	ds_read_b128 v[160:163], v160 offset:3072
	s_add_u32 s26, s26, 0x100000
	s_addc_u32 s27, s27, 0
	s_mov_b32 m0, s38
	v_lshl_add_u64 v[252:253], s[26:27], 0, v[176:177]
	ds_read_b128 v[164:167], v218 offset:32768
	ds_read_b128 v[168:171], v218 offset:33792
	ds_read_b128 v[220:223], v218 offset:34816
	ds_read_b128 v[224:227], v218 offset:35840
	ds_read_b128 v[228:231], v218 offset:36864
	ds_read_b128 v[232:235], v218 offset:37888
	ds_read_b128 v[236:239], v218 offset:38912
	ds_read_b128 v[240:243], v218 offset:39936
	global_load_lds_dwordx4 v[252:253], off
	v_lshl_add_u64 v[252:253], s[26:27], 0, v[174:175]
	s_mov_b32 m0, s39
	s_nop 0
	global_load_lds_dwordx4 v[252:253], off
	s_waitcnt vmcnt(8)
	s_waitcnt lgkmcnt(0)
	s_barrier
	s_waitcnt lgkmcnt(0)
	v_mfma_f32_16x16x32_bf16 v[128:131], v[132:135], v[164:167], v[128:131]
	v_mfma_f32_16x16x32_bf16 v[124:127], v[140:143], v[164:167], v[124:127]
	v_mfma_f32_16x16x32_bf16 v[116:119], v[132:135], v[220:223], v[116:119]
	v_mfma_f32_16x16x32_bf16 v[106:109], v[140:143], v[220:223], v[106:109]
	v_mfma_f32_16x16x32_bf16 v[98:101], v[132:135], v[228:231], v[98:101]
	v_mfma_f32_16x16x32_bf16 v[90:93], v[140:143], v[228:231], v[90:93]
	v_mfma_f32_16x16x32_bf16 v[82:85], v[132:135], v[236:239], v[82:85]
	v_mfma_f32_16x16x32_bf16 v[74:77], v[140:143], v[236:239], v[74:77]
	v_mfma_f32_16x16x32_bf16 v[128:131], v[136:139], v[168:171], v[128:131]
	v_mfma_f32_16x16x32_bf16 v[124:127], v[144:147], v[168:171], v[124:127]
	v_mfma_f32_16x16x32_bf16 v[116:119], v[136:139], v[224:227], v[116:119]
	v_mfma_f32_16x16x32_bf16 v[106:109], v[144:147], v[224:227], v[106:109]
	v_mfma_f32_16x16x32_bf16 v[98:101], v[136:139], v[232:235], v[98:101]
	v_mfma_f32_16x16x32_bf16 v[90:93], v[144:147], v[232:235], v[90:93]
	v_mfma_f32_16x16x32_bf16 v[82:85], v[136:139], v[240:243], v[82:85]
	v_mfma_f32_16x16x32_bf16 v[74:77], v[144:147], v[240:243], v[74:77]
	v_mfma_f32_16x16x32_bf16 v[120:123], v[148:151], v[164:167], v[120:123]
	v_mfma_f32_16x16x32_bf16 v[110:113], v[156:159], v[164:167], v[110:113]
	v_mfma_f32_16x16x32_bf16 v[102:105], v[148:151], v[220:223], v[102:105]
	v_mfma_f32_16x16x32_bf16 v[94:97], v[156:159], v[220:223], v[94:97]
	v_mfma_f32_16x16x32_bf16 v[86:89], v[148:151], v[228:231], v[86:89]
	v_mfma_f32_16x16x32_bf16 v[78:81], v[156:159], v[228:231], v[78:81]
	v_mfma_f32_16x16x32_bf16 v[70:73], v[148:151], v[236:239], v[70:73]
	v_mfma_f32_16x16x32_bf16 v[66:69], v[156:159], v[236:239], v[66:69]
	v_mfma_f32_16x16x32_bf16 v[120:123], v[152:155], v[168:171], v[120:123]
	v_mfma_f32_16x16x32_bf16 v[110:113], v[160:163], v[168:171], v[110:113]
	v_mfma_f32_16x16x32_bf16 v[102:105], v[152:155], v[224:227], v[102:105]
	v_mfma_f32_16x16x32_bf16 v[94:97], v[160:163], v[224:227], v[94:97]
	v_mfma_f32_16x16x32_bf16 v[86:89], v[152:155], v[232:235], v[86:89]
	v_mfma_f32_16x16x32_bf16 v[78:81], v[160:163], v[232:235], v[78:81]
	v_mfma_f32_16x16x32_bf16 v[70:73], v[152:155], v[240:243], v[70:73]
	v_mfma_f32_16x16x32_bf16 v[66:69], v[160:163], v[240:243], v[66:69]
	s_barrier
; #define PG8_STAGE(bufoff, gbase, voff) do { _Pragma("unroll") for (int _i = 0; _i < 2; ++_i) \
;         __builtin_amdgcn_global_load_lds((const unsigned*)((const char*)(gbase) + (voff)[_i]), (LAS unsigned*)(lds + (bufoff) + ldsw + _i * 8192), 16, 0, 0); } while (0)
; #define PG8_LDA(dst, b, h) do { _Pragma("unroll") for (int m = 0; m < 4; ++m) _Pragma("unroll") for (int k = 0; k < 2; ++k) dst[m][k] = *(const LAS bf16x8*)(lds + PG8_SA(b, h) + aoff + m * 2048 + k * 1024); } while (0)
; #define PG8_MMA(ai, bj, At, Bt) do { __builtin_amdgcn_s_setprio(1); _Pragma("unroll") for (int m = 0; m < 4; ++m) _Pragma("unroll") for (int n = 0; n < 2; ++n) _Pragma("unroll") for (int k = 0; k < 2; ++k) \
;         acc[ai][bj][m][n] = __builtin_amdgcn_mfma_f32_16x16x32_bf16(Bt[n][k], At[m][k], acc[ai][bj][m][n], 0, 0, 0); __builtin_amdgcn_s_setprio(0); } while (0)
; #define PG8_WAIT_V(n) asm volatile("s_waitcnt vmcnt(" #n ")" ::: "memory")
; #define PG8_WAIT_L(n) asm volatile("s_waitcnt lgkmcnt(" #n ")" ::: "memory")
; #define PG8_BAR __builtin_amdgcn_s_barrier()
; #define PG8_SCHED __builtin_amdgcn_sched_barrier(0)
; template <class Epi, class Sched, bool ALIGN_EPI = true, bool SP2 = true>
; __device__ __forceinline__ void gemm_phase(LAS unsigned char* lds, const Sched& S, const Epi& E, const int lda, const int ldb) {
;     ...
;             PG8_LDA(At, 1, 1); PG8_STAGE(PG8_SB(1, 0), b3, voffB); PG8_STAGE(PG8_SB(1, 1), b3 + hstepB, voffB); PG8_STAGE(PG8_SA(1, 0), a3, voffA);
;             PG8_WAIT_V(8); PG8_WAIT_L(0); PG8_BAR; PG8_MMA(1, 0, At, B0); PG8_MMA(1, 1, At, B1); PG8_BAR; PG8_SCHED;
;     ...
;         }
;         if constexpr (ALIGN_EPI) { if (wr == 0) PG8_BAR; }
	s_add_i32 s26, s29, s12
	v_lshl_add_u64 v[214:215], v[214:215], 0, s[70:71]
	s_mov_b32 m0, s26
	ds_read_b128 v[164:167], v218 offset:49152
	ds_read_b128 v[168:171], v218 offset:50176
	ds_read_b128 v[220:223], v218 offset:51200
	ds_read_b128 v[224:227], v218 offset:52224
	ds_read_b128 v[228:231], v218 offset:53248
	ds_read_b128 v[232:235], v218 offset:54272
	ds_read_b128 v[236:239], v218 offset:55296
	ds_read_b128 v[240:243], v218 offset:56320
	global_load_lds_dwordx4 v[214:215], off
	s_add_i32 m0, s26, 0x2000
	s_add_u32 s24, s24, 0x100080
	v_lshl_add_u64 v[214:215], v[246:247], 0, s[70:71]
	s_addc_u32 s25, s25, 0
	s_add_i32 s26, s54, s12
	global_load_lds_dwordx4 v[214:215], off
	v_lshl_add_u64 v[214:215], s[24:25], 0, v[114:115]
	s_mov_b32 m0, s26
	s_nop 0
	global_load_lds_dwordx4 v[214:215], off
	v_lshl_add_u64 v[214:215], s[24:25], 0, v[172:173]
	s_add_i32 m0, s26, 0x2000
	s_nop 0
	global_load_lds_dwordx4 v[214:215], off
	v_lshl_add_u64 v[214:215], v[248:249], 0, s[70:71]
	s_mov_b32 m0, s52
	s_nop 0
	global_load_lds_dwordx4 v[214:215], off
	v_lshl_add_u64 v[214:215], v[250:251], 0, s[70:71]
	s_mov_b32 m0, s57
	s_nop 0
	global_load_lds_dwordx4 v[214:215], off
	s_waitcnt vmcnt(8)
	s_waitcnt lgkmcnt(0)
	s_barrier
	s_waitcnt lgkmcnt(0)
	v_mfma_f32_16x16x32_bf16 v[62:65], v[132:135], v[164:167], v[62:65]
	v_mfma_f32_16x16x32_bf16 v[58:61], v[140:143], v[164:167], v[58:61]
	v_mfma_f32_16x16x32_bf16 v[50:53], v[132:135], v[220:223], v[50:53]
	v_mfma_f32_16x16x32_bf16 v[42:45], v[140:143], v[220:223], v[42:45]
	v_mfma_f32_16x16x32_bf16 v[34:37], v[132:135], v[228:231], v[34:37]
	v_mfma_f32_16x16x32_bf16 v[26:29], v[140:143], v[228:231], v[26:29]
	v_mfma_f32_16x16x32_bf16 v[18:21], v[132:135], v[236:239], v[18:21]
	v_mfma_f32_16x16x32_bf16 v[10:13], v[140:143], v[236:239], v[10:13]
	v_mfma_f32_16x16x32_bf16 v[62:65], v[136:139], v[168:171], v[62:65]
	v_mfma_f32_16x16x32_bf16 v[58:61], v[144:147], v[168:171], v[58:61]
	v_mfma_f32_16x16x32_bf16 v[50:53], v[136:139], v[224:227], v[50:53]
	v_mfma_f32_16x16x32_bf16 v[42:45], v[144:147], v[224:227], v[42:45]
	v_mfma_f32_16x16x32_bf16 v[34:37], v[136:139], v[232:235], v[34:37]
	v_mfma_f32_16x16x32_bf16 v[26:29], v[144:147], v[232:235], v[26:29]
	v_mfma_f32_16x16x32_bf16 v[18:21], v[136:139], v[240:243], v[18:21]
	v_mfma_f32_16x16x32_bf16 v[10:13], v[144:147], v[240:243], v[10:13]
	v_mfma_f32_16x16x32_bf16 v[54:57], v[148:151], v[164:167], v[54:57]
	v_mfma_f32_16x16x32_bf16 v[46:49], v[156:159], v[164:167], v[46:49]
	v_mfma_f32_16x16x32_bf16 v[38:41], v[148:151], v[220:223], v[38:41]
	v_mfma_f32_16x16x32_bf16 v[30:33], v[156:159], v[220:223], v[30:33]
	v_mfma_f32_16x16x32_bf16 v[22:25], v[148:151], v[228:231], v[22:25]
	v_mfma_f32_16x16x32_bf16 v[14:17], v[156:159], v[228:231], v[14:17]
	v_mfma_f32_16x16x32_bf16 v[6:9], v[148:151], v[236:239], v[6:9]
	v_mfma_f32_16x16x32_bf16 v[2:5], v[156:159], v[236:239], v[2:5]
	v_mfma_f32_16x16x32_bf16 v[54:57], v[152:155], v[168:171], v[54:57]
	v_mfma_f32_16x16x32_bf16 v[46:49], v[160:163], v[168:171], v[46:49]
	v_mfma_f32_16x16x32_bf16 v[38:41], v[152:155], v[224:227], v[38:41]
	v_mfma_f32_16x16x32_bf16 v[30:33], v[160:163], v[224:227], v[30:33]
	v_mfma_f32_16x16x32_bf16 v[22:25], v[152:155], v[232:235], v[22:25]
	v_mfma_f32_16x16x32_bf16 v[14:17], v[160:163], v[232:235], v[14:17]
	v_mfma_f32_16x16x32_bf16 v[6:9], v[152:155], v[240:243], v[6:9]
	v_mfma_f32_16x16x32_bf16 v[2:5], v[160:163], v[240:243], v[2:5]
	s_barrier
	s_add_i32 s50, s50, 2
	s_add_u32 s22, s22, 0x100
	s_addc_u32 s23, s23, 0
	s_add_u32 s30, s30, 0x100
	s_addc_u32 s33, s33, 0
	s_cmp_gt_u32 s50, 5
	s_cbranch_scc0 .LBB0_1206
	s_and_b64 vcc, exec, s[10:11]
	s_cbranch_vccz .LBB0_1209
	s_barrier

; #define PG8_STAGE(bufoff, gbase, voff) do { _Pragma("unroll") for (int _i = 0; _i < 2; ++_i) \
;         __builtin_amdgcn_global_load_lds((const unsigned*)((const char*)(gbase) + (voff)[_i]), (LAS unsigned*)(lds + (bufoff) + ldsw + _i * 8192), 16, 0, 0); } while (0)
; #define PG8_LDA(dst, b, h) do { _Pragma("unroll") for (int m = 0; m < 4; ++m) _Pragma("unroll") for (int k = 0; k < 2; ++k) dst[m][k] = *(const LAS bf16x8*)(lds + PG8_SA(b, h) + aoff + m * 2048 + k * 1024); } while (0)
; #define PG8_LDB(dst, b, h) do { _Pragma("unroll") for (int n = 0; n < 2; ++n) _Pragma("unroll") for (int k = 0; k < 2; ++k) dst[n][k] = *(const LAS bf16x8*)(lds + PG8_SB(b, h) + boff + n * 2048 + k * 1024); } while (0)
; #define PG8_MMA(ai, bj, At, Bt) do { __builtin_amdgcn_s_setprio(1); _Pragma("unroll") for (int m = 0; m < 4; ++m) _Pragma("unroll") for (int n = 0; n < 2; ++n) _Pragma("unroll") for (int k = 0; k < 2; ++k) \
;         acc[ai][bj][m][n] = __builtin_amdgcn_mfma_f32_16x16x32_bf16(Bt[n][k], At[m][k], acc[ai][bj][m][n], 0, 0, 0); __builtin_amdgcn_s_setprio(0); } while (0)
; #define PG8_WAIT_V(n) asm volatile("s_waitcnt vmcnt(" #n ")" ::: "memory")
; #define PG8_WAIT_L(n) asm volatile("s_waitcnt lgkmcnt(" #n ")" ::: "memory")
; template <class Epi, class Sched, bool ALIGN_EPI = true, bool SP2 = true>
; __device__ __forceinline__ void gemm_phase(LAS unsigned char* lds, const Sched& S, const Epi& E, const int lda, const int ldb) {
;     ...
;         const char* nA = has_next ? nxt.A : cA; const char* nB = has_next ? nxt.B : cB;
;         const int nt = cur.nt;
;         for (int t = 0; t < nt; t += 2) {
;             const bool last = (t == nt - 2);
;             const char* a1 = cA + (size_t)(t + 1) * kstep;
;             const char* a2 = last ? nA : cA + (size_t)(t + 2) * kstep; const char* b2 = last ? nB : cB + (size_t)(t + 2) * kstep;
;             const char* a3 = a2 + kstep; const char* b3 = b2 + kstep;
;             if constexpr (SP2) {
;             PG8_LDB(B0, 0, 0); PG8_LDB(B1, 0, 1); PG8_SCHED; PG8_LDA(At, 0, 0); PG8_STAGE(PG8_SA(1, 1), a1 + hstepA, voffA);
;             PG8_WAIT_V(8); PG8_WAIT_L(0); PG8_BAR; PG8_MMA(0, 0, At, B0); PG8_MMA(0, 1, At, B1); PG8_BAR; PG8_SCHED;
;             PG8_LDA(At, 0, 1); PG8_STAGE(PG8_SB(0, 0), b2, voffB); PG8_STAGE(PG8_SB(0, 1), b2 + hstepB, voffB); PG8_STAGE(PG8_SA(0, 0), a2, voffA);
.LBB0_1347:
	s_add_u32 s26, s24, 0xfff00080
	s_addc_u32 s27, s25, -1
	s_add_i32 s29, 0, 0x10000
	s_cmp_eq_u32 s50, 60
	s_cselect_b32 s37, s21, s27
	s_cselect_b32 s36, s20, s26
	v_add_u32_e32 v114, s29, v196
	s_cselect_b32 s27, s23, s30
	s_cselect_b32 s26, s22, s28
	s_add_i32 s72, 0, 0x14000
	ds_read_b128 v[132:135], v114
	ds_read_b128 v[136:139], v114 offset:1024
	ds_read_b128 v[140:143], v114 offset:2048
	ds_read_b128 v[144:147], v114 offset:3072
	v_add_u32_e32 v114, s72, v196
	ds_read_b128 v[156:159], v114
	ds_read_b128 v[160:163], v114 offset:1024
	ds_read_b128 v[164:167], v114 offset:2048
	ds_read_b128 v[168:171], v114 offset:3072
	v_lshl_add_u64 v[222:223], s[24:25], 0, v[152:153]
	s_add_i32 m0, s48, 0xc000
	ds_read_b128 v[172:175], v213
	ds_read_b128 v[176:179], v213 offset:1024
	ds_read_b128 v[180:183], v213 offset:2048
	ds_read_b128 v[184:187], v213 offset:3072
	ds_read_b128 v[188:191], v213 offset:4096
	ds_read_b128 v[192:195], v213 offset:5120
	ds_read_b128 v[214:217], v213 offset:6144
	ds_read_b128 v[218:221], v213 offset:7168
	global_load_lds_dwordx4 v[222:223], off
	v_lshl_add_u64 v[222:223], s[24:25], 0, v[154:155]
	s_add_i32 m0, s48, 0xe000
	s_nop 0
	global_load_lds_dwordx4 v[222:223], off
	s_waitcnt vmcnt(8)
	s_waitcnt lgkmcnt(0)
	s_barrier
	s_waitcnt lgkmcnt(0)
	v_mfma_f32_16x16x32_bf16 v[128:131], v[132:135], v[172:175], v[128:131]
	v_mfma_f32_16x16x32_bf16 v[124:127], v[140:143], v[172:175], v[124:127]
	v_mfma_f32_16x16x32_bf16 v[116:119], v[132:135], v[180:183], v[116:119]
	v_mfma_f32_16x16x32_bf16 v[110:113], v[140:143], v[180:183], v[110:113]
	v_mfma_f32_16x16x32_bf16 v[102:105], v[132:135], v[188:191], v[102:105]
	v_mfma_f32_16x16x32_bf16 v[94:97], v[140:143], v[188:191], v[94:97]
	v_mfma_f32_16x16x32_bf16 v[86:89], v[132:135], v[214:217], v[86:89]
	v_mfma_f32_16x16x32_bf16 v[78:81], v[140:143], v[214:217], v[78:81]
	v_mfma_f32_16x16x32_bf16 v[128:131], v[136:139], v[176:179], v[128:131]
	v_mfma_f32_16x16x32_bf16 v[124:127], v[144:147], v[176:179], v[124:127]
	v_mfma_f32_16x16x32_bf16 v[116:119], v[136:139], v[184:187], v[116:119]
	v_mfma_f32_16x16x32_bf16 v[110:113], v[144:147], v[184:187], v[110:113]
	v_mfma_f32_16x16x32_bf16 v[102:105], v[136:139], v[192:195], v[102:105]
	v_mfma_f32_16x16x32_bf16 v[94:97], v[144:147], v[192:195], v[94:97]
	v_mfma_f32_16x16x32_bf16 v[86:89], v[136:139], v[218:221], v[86:89]
	v_mfma_f32_16x16x32_bf16 v[78:81], v[144:147], v[218:221], v[78:81]
	v_mfma_f32_16x16x32_bf16 v[120:123], v[156:159], v[172:175], v[120:123]
	v_mfma_f32_16x16x32_bf16 v[106:109], v[164:167], v[172:175], v[106:109]
	v_mfma_f32_16x16x32_bf16 v[98:101], v[156:159], v[180:183], v[98:101]
	v_mfma_f32_16x16x32_bf16 v[90:93], v[164:167], v[180:183], v[90:93]
	v_mfma_f32_16x16x32_bf16 v[82:85], v[156:159], v[188:191], v[82:85]
	v_mfma_f32_16x16x32_bf16 v[74:77], v[164:167], v[188:191], v[74:77]
	v_mfma_f32_16x16x32_bf16 v[70:73], v[156:159], v[214:217], v[70:73]
	v_mfma_f32_16x16x32_bf16 v[66:69], v[164:167], v[214:217], v[66:69]
	v_mfma_f32_16x16x32_bf16 v[120:123], v[160:163], v[176:179], v[120:123]
	v_mfma_f32_16x16x32_bf16 v[106:109], v[168:171], v[176:179], v[106:109]
	v_mfma_f32_16x16x32_bf16 v[98:101], v[160:163], v[184:187], v[98:101]
	v_mfma_f32_16x16x32_bf16 v[90:93], v[168:171], v[184:187], v[90:93]
	v_mfma_f32_16x16x32_bf16 v[82:85], v[160:163], v[192:195], v[82:85]
	v_mfma_f32_16x16x32_bf16 v[74:77], v[168:171], v[192:195], v[74:77]
	v_mfma_f32_16x16x32_bf16 v[70:73], v[160:163], v[218:221], v[70:73]
	v_mfma_f32_16x16x32_bf16 v[66:69], v[168:171], v[218:221], v[66:69]
	s_barrier
	s_add_i32 s29, s29, s47
	v_lshl_add_u64 v[222:223], s[26:27], 0, v[148:149]
	s_mov_b32 m0, s29
	ds_read_b128 v[172:175], v213 offset:16384
	ds_read_b128 v[176:179], v213 offset:17408
	ds_read_b128 v[180:183], v213 offset:18432
	ds_read_b128 v[184:187], v213 offset:19456
	ds_read_b128 v[188:191], v213 offset:20480
	ds_read_b128 v[192:195], v213 offset:21504
	ds_read_b128 v[214:217], v213 offset:22528
	ds_read_b128 v[218:221], v213 offset:23552
	global_load_lds_dwordx4 v[222:223], off
	s_add_i32 m0, s29, 0x2000
	s_add_u32 s54, s26, 0x100000
	v_lshl_add_u64 v[224:225], s[26:27], 0, v[150:151]
	s_addc_u32 s55, s27, 0
	s_add_i32 s29, s72, s47
	global_load_lds_dwordx4 v[224:225], off
	v_lshl_add_u64 v[226:227], s[54:55], 0, v[148:149]
	s_mov_b32 m0, s29
	v_lshl_add_u64 v[228:229], s[36:37], 0, v[150:151]
	global_load_lds_dwordx4 v[226:227], off
	v_lshl_add_u64 v[226:227], s[54:55], 0, v[150:151]
	s_add_i32 m0, s29, 0x2000
	s_nop 0
	global_load_lds_dwordx4 v[226:227], off
	v_lshl_add_u64 v[226:227], s[36:37], 0, v[148:149]
	s_mov_b32 m0, s48
	s_nop 0
	global_load_lds_dwordx4 v[226:227], off
	s_mov_b32 m0, s49
	s_nop 0
	global_load_lds_dwordx4 v[228:229], off
	s_waitcnt vmcnt(8)
	s_waitcnt lgkmcnt(0)
	s_barrier
; #define PG8_STAGE(bufoff, gbase, voff) do { _Pragma("unroll") for (int _i = 0; _i < 2; ++_i) \
;         __builtin_amdgcn_global_load_lds((const unsigned*)((const char*)(gbase) + (voff)[_i]), (LAS unsigned*)(lds + (bufoff) + ldsw + _i * 8192), 16, 0, 0); } while (0)
; #define PG8_LDA(dst, b, h) do { _Pragma("unroll") for (int m = 0; m < 4; ++m) _Pragma("unroll") for (int k = 0; k < 2; ++k) dst[m][k] = *(const LAS bf16x8*)(lds + PG8_SA(b, h) + aoff + m * 2048 + k * 1024); } while (0)
; #define PG8_LDB(dst, b, h) do { _Pragma("unroll") for (int n = 0; n < 2; ++n) _Pragma("unroll") for (int k = 0; k < 2; ++k) dst[n][k] = *(const LAS bf16x8*)(lds + PG8_SB(b, h) + boff + n * 2048 + k * 1024); } while (0)
; #define PG8_MMA(ai, bj, At, Bt) do { __builtin_amdgcn_s_setprio(1); _Pragma("unroll") for (int m = 0; m < 4; ++m) _Pragma("unroll") for (int n = 0; n < 2; ++n) _Pragma("unroll") for (int k = 0; k < 2; ++k) \
;         acc[ai][bj][m][n] = __builtin_amdgcn_mfma_f32_16x16x32_bf16(Bt[n][k], At[m][k], acc[ai][bj][m][n], 0, 0, 0); __builtin_amdgcn_s_setprio(0); } while (0)
; #define PG8_WAIT_V(n) asm volatile("s_waitcnt vmcnt(" #n ")" ::: "memory")
; #define PG8_WAIT_L(n) asm volatile("s_waitcnt lgkmcnt(" #n ")" ::: "memory")
; #define PG8_BAR __builtin_amdgcn_s_barrier()
; #define PG8_SCHED __builtin_amdgcn_sched_barrier(0)
; template <class Epi, class Sched, bool ALIGN_EPI = true, bool SP2 = true>
; __device__ __forceinline__ void gemm_phase(LAS unsigned char* lds, const Sched& S, const Epi& E, const int lda, const int ldb) {
;     ...
;             PG8_WAIT_V(8); PG8_WAIT_L(0); PG8_BAR; PG8_MMA(1, 0, At, B0); PG8_MMA(1, 1, At, B1); PG8_BAR; PG8_SCHED;
;             PG8_LDB(B0, 1, 0); PG8_LDB(B1, 1, 1); PG8_SCHED; PG8_LDA(At, 1, 0); PG8_STAGE(PG8_SA(0, 1), a2 + hstepA, voffA);
;             PG8_WAIT_V(8); PG8_WAIT_L(0); PG8_BAR; PG8_MMA(0, 0, At, B0); PG8_MMA(0, 1, At, B1); PG8_BAR; PG8_SCHED;
	s_waitcnt lgkmcnt(0)
	v_mfma_f32_16x16x32_bf16 v[62:65], v[132:135], v[172:175], v[62:65]
	v_mfma_f32_16x16x32_bf16 v[58:61], v[140:143], v[172:175], v[58:61]
	v_mfma_f32_16x16x32_bf16 v[54:57], v[132:135], v[180:183], v[54:57]
	v_mfma_f32_16x16x32_bf16 v[46:49], v[140:143], v[180:183], v[46:49]
	v_mfma_f32_16x16x32_bf16 v[38:41], v[132:135], v[188:191], v[38:41]
	v_mfma_f32_16x16x32_bf16 v[30:33], v[140:143], v[188:191], v[30:33]
	v_mfma_f32_16x16x32_bf16 v[22:25], v[132:135], v[214:217], v[22:25]
	v_mfma_f32_16x16x32_bf16 v[14:17], v[140:143], v[214:217], v[14:17]
	v_mfma_f32_16x16x32_bf16 v[62:65], v[136:139], v[176:179], v[62:65]
	v_mfma_f32_16x16x32_bf16 v[58:61], v[144:147], v[176:179], v[58:61]
	v_mfma_f32_16x16x32_bf16 v[54:57], v[136:139], v[184:187], v[54:57]
	v_mfma_f32_16x16x32_bf16 v[46:49], v[144:147], v[184:187], v[46:49]
	v_mfma_f32_16x16x32_bf16 v[38:41], v[136:139], v[192:195], v[38:41]
	v_mfma_f32_16x16x32_bf16 v[30:33], v[144:147], v[192:195], v[30:33]
	v_mfma_f32_16x16x32_bf16 v[22:25], v[136:139], v[218:221], v[22:25]
	v_mfma_f32_16x16x32_bf16 v[14:17], v[144:147], v[218:221], v[14:17]
	v_mfma_f32_16x16x32_bf16 v[50:53], v[156:159], v[172:175], v[50:53]
	v_mfma_f32_16x16x32_bf16 v[42:45], v[164:167], v[172:175], v[42:45]
	v_mfma_f32_16x16x32_bf16 v[34:37], v[156:159], v[180:183], v[34:37]
	v_mfma_f32_16x16x32_bf16 v[26:29], v[164:167], v[180:183], v[26:29]
	v_mfma_f32_16x16x32_bf16 v[18:21], v[156:159], v[188:191], v[18:21]
	v_mfma_f32_16x16x32_bf16 v[10:13], v[164:167], v[188:191], v[10:13]
	v_mfma_f32_16x16x32_bf16 v[6:9], v[156:159], v[214:217], v[6:9]
	v_mfma_f32_16x16x32_bf16 v[2:5], v[164:167], v[214:217], v[2:5]
	v_mfma_f32_16x16x32_bf16 v[50:53], v[160:163], v[176:179], v[50:53]
	v_mfma_f32_16x16x32_bf16 v[42:45], v[168:171], v[176:179], v[42:45]
	v_mfma_f32_16x16x32_bf16 v[34:37], v[160:163], v[184:187], v[34:37]
	v_mfma_f32_16x16x32_bf16 v[26:29], v[168:171], v[184:187], v[26:29]
	v_mfma_f32_16x16x32_bf16 v[18:21], v[160:163], v[192:195], v[18:21]
	v_mfma_f32_16x16x32_bf16 v[10:13], v[168:171], v[192:195], v[10:13]
	v_mfma_f32_16x16x32_bf16 v[6:9], v[160:163], v[218:221], v[6:9]
	v_mfma_f32_16x16x32_bf16 v[2:5], v[168:171], v[218:221], v[2:5]
	s_barrier
	s_add_i32 s29, 0, 0x18000
	v_add_u32_e32 v114, s29, v196
	s_add_i32 s54, 0, 0x1c000
	ds_read_b128 v[132:135], v114
	ds_read_b128 v[136:139], v114 offset:1024
	ds_read_b128 v[140:143], v114 offset:2048
	ds_read_b128 v[144:147], v114 offset:3072
	v_add_u32_e32 v114, s54, v196
	ds_read_b128 v[156:159], v114
	ds_read_b128 v[160:163], v114 offset:1024
	ds_read_b128 v[164:167], v114 offset:2048
	ds_read_b128 v[168:171], v114 offset:3072
	s_add_u32 s36, s36, 0x100000
	s_addc_u32 s37, s37, 0
	s_mov_b32 m0, s51
	v_lshl_add_u64 v[230:231], s[36:37], 0, v[148:149]
	ds_read_b128 v[172:175], v213 offset:32768
	ds_read_b128 v[176:179], v213 offset:33792
	ds_read_b128 v[180:183], v213 offset:34816
	ds_read_b128 v[184:187], v213 offset:35840
	ds_read_b128 v[188:191], v213 offset:36864
	ds_read_b128 v[192:195], v213 offset:37888
	ds_read_b128 v[214:217], v213 offset:38912
	ds_read_b128 v[218:221], v213 offset:39936
	global_load_lds_dwordx4 v[230:231], off
	v_lshl_add_u64 v[230:231], s[36:37], 0, v[150:151]
	s_mov_b32 m0, s52
	s_nop 0
	global_load_lds_dwordx4 v[230:231], off
	s_waitcnt vmcnt(8)
	s_waitcnt lgkmcnt(0)
	s_barrier
	s_waitcnt lgkmcnt(0)
	v_mfma_f32_16x16x32_bf16 v[128:131], v[132:135], v[172:175], v[128:131]
	v_mfma_f32_16x16x32_bf16 v[124:127], v[140:143], v[172:175], v[124:127]
	v_mfma_f32_16x16x32_bf16 v[116:119], v[132:135], v[180:183], v[116:119]
	v_mfma_f32_16x16x32_bf16 v[110:113], v[140:143], v[180:183], v[110:113]
	v_mfma_f32_16x16x32_bf16 v[102:105], v[132:135], v[188:191], v[102:105]
	v_mfma_f32_16x16x32_bf16 v[94:97], v[140:143], v[188:191], v[94:97]
	v_mfma_f32_16x16x32_bf16 v[86:89], v[132:135], v[214:217], v[86:89]
	v_mfma_f32_16x16x32_bf16 v[78:81], v[140:143], v[214:217], v[78:81]
	v_mfma_f32_16x16x32_bf16 v[128:131], v[136:139], v[176:179], v[128:131]
	v_mfma_f32_16x16x32_bf16 v[124:127], v[144:147], v[176:179], v[124:127]
	v_mfma_f32_16x16x32_bf16 v[116:119], v[136:139], v[184:187], v[116:119]
	v_mfma_f32_16x16x32_bf16 v[110:113], v[144:147], v[184:187], v[110:113]
	v_mfma_f32_16x16x32_bf16 v[102:105], v[136:139], v[192:195], v[102:105]
	v_mfma_f32_16x16x32_bf16 v[94:97], v[144:147], v[192:195], v[94:97]
	v_mfma_f32_16x16x32_bf16 v[86:89], v[136:139], v[218:221], v[86:89]
	v_mfma_f32_16x16x32_bf16 v[78:81], v[144:147], v[218:221], v[78:81]
	v_mfma_f32_16x16x32_bf16 v[120:123], v[156:159], v[172:175], v[120:123]
	v_mfma_f32_16x16x32_bf16 v[106:109], v[164:167], v[172:175], v[106:109]
	v_mfma_f32_16x16x32_bf16 v[98:101], v[156:159], v[180:183], v[98:101]
	v_mfma_f32_16x16x32_bf16 v[90:93], v[164:167], v[180:183], v[90:93]
	v_mfma_f32_16x16x32_bf16 v[82:85], v[156:159], v[188:191], v[82:85]
	v_mfma_f32_16x16x32_bf16 v[74:77], v[164:167], v[188:191], v[74:77]
	v_mfma_f32_16x16x32_bf16 v[70:73], v[156:159], v[214:217], v[70:73]
	v_mfma_f32_16x16x32_bf16 v[66:69], v[164:167], v[214:217], v[66:69]
	v_mfma_f32_16x16x32_bf16 v[120:123], v[160:163], v[176:179], v[120:123]
	v_mfma_f32_16x16x32_bf16 v[106:109], v[168:171], v[176:179], v[106:109]
	v_mfma_f32_16x16x32_bf16 v[98:101], v[160:163], v[184:187], v[98:101]
	v_mfma_f32_16x16x32_bf16 v[90:93], v[168:171], v[184:187], v[90:93]
	v_mfma_f32_16x16x32_bf16 v[82:85], v[160:163], v[192:195], v[82:85]
	v_mfma_f32_16x16x32_bf16 v[74:77], v[168:171], v[192:195], v[74:77]
	v_mfma_f32_16x16x32_bf16 v[70:73], v[160:163], v[218:221], v[70:73]
	v_mfma_f32_16x16x32_bf16 v[66:69], v[168:171], v[218:221], v[66:69]
	s_barrier
; #define PG8_STAGE(bufoff, gbase, voff) do { _Pragma("unroll") for (int _i = 0; _i < 2; ++_i) \
;         __builtin_amdgcn_global_load_lds((const unsigned*)((const char*)(gbase) + (voff)[_i]), (LAS unsigned*)(lds + (bufoff) + ldsw + _i * 8192), 16, 0, 0); } while (0)
; #define PG8_LDA(dst, b, h) do { _Pragma("unroll") for (int m = 0; m < 4; ++m) _Pragma("unroll") for (int k = 0; k < 2; ++k) dst[m][k] = *(const LAS bf16x8*)(lds + PG8_SA(b, h) + aoff + m * 2048 + k * 1024); } while (0)
; #define PG8_MMA(ai, bj, At, Bt) do { __builtin_amdgcn_s_setprio(1); _Pragma("unroll") for (int m = 0; m < 4; ++m) _Pragma("unroll") for (int n = 0; n < 2; ++n) _Pragma("unroll") for (int k = 0; k < 2; ++k) \
;         acc[ai][bj][m][n] = __builtin_amdgcn_mfma_f32_16x16x32_bf16(Bt[n][k], At[m][k], acc[ai][bj][m][n], 0, 0, 0); __builtin_amdgcn_s_setprio(0); } while (0)
; #define PG8_WAIT_V(n) asm volatile("s_waitcnt vmcnt(" #n ")" ::: "memory")
; #define PG8_WAIT_L(n) asm volatile("s_waitcnt lgkmcnt(" #n ")" ::: "memory")
; #define PG8_BAR __builtin_amdgcn_s_barrier()
; #define PG8_SCHED __builtin_amdgcn_sched_barrier(0)
; template <class Epi, class Sched, bool ALIGN_EPI = true, bool SP2 = true>
; __device__ __forceinline__ void gemm_phase(LAS unsigned char* lds, const Sched& S, const Epi& E, const int lda, const int ldb) {
;     ...
;             PG8_LDA(At, 1, 1); PG8_STAGE(PG8_SB(1, 0), b3, voffB); PG8_STAGE(PG8_SB(1, 1), b3 + hstepB, voffB); PG8_STAGE(PG8_SA(1, 0), a3, voffA);
;             PG8_WAIT_V(8); PG8_WAIT_L(0); PG8_BAR; PG8_MMA(1, 0, At, B0); PG8_MMA(1, 1, At, B1); PG8_BAR; PG8_SCHED;
;     ...
;         }
;         if constexpr (ALIGN_EPI) { if (wr == 0) PG8_BAR; }
	s_add_i32 s29, s29, s47
	v_lshl_add_u64 v[222:223], v[222:223], 0, s[70:71]
	s_mov_b32 m0, s29
	ds_read_b128 v[172:175], v213 offset:49152
	ds_read_b128 v[176:179], v213 offset:50176
	ds_read_b128 v[180:183], v213 offset:51200
	ds_read_b128 v[184:187], v213 offset:52224
	ds_read_b128 v[188:191], v213 offset:53248
	ds_read_b128 v[192:195], v213 offset:54272
	ds_read_b128 v[214:217], v213 offset:55296
	ds_read_b128 v[218:221], v213 offset:56320
	global_load_lds_dwordx4 v[222:223], off
	s_add_i32 m0, s29, 0x2000
	s_add_u32 s26, s26, 0x100080
	v_lshl_add_u64 v[222:223], v[224:225], 0, s[70:71]
	s_addc_u32 s27, s27, 0
	s_add_i32 s29, s54, s47
	global_load_lds_dwordx4 v[222:223], off
	v_lshl_add_u64 v[222:223], s[26:27], 0, v[148:149]
	s_mov_b32 m0, s29
	s_nop 0
	global_load_lds_dwordx4 v[222:223], off
	v_lshl_add_u64 v[222:223], s[26:27], 0, v[150:151]
	s_add_i32 m0, s29, 0x2000
	s_nop 0
	global_load_lds_dwordx4 v[222:223], off
	v_lshl_add_u64 v[222:223], v[226:227], 0, s[70:71]
	s_mov_b32 m0, s57
	s_nop 0
	global_load_lds_dwordx4 v[222:223], off
	v_lshl_add_u64 v[222:223], v[228:229], 0, s[70:71]
	s_mov_b32 m0, s62
	s_nop 0
	global_load_lds_dwordx4 v[222:223], off
	s_waitcnt vmcnt(8)
	s_waitcnt lgkmcnt(0)
	s_barrier
	s_waitcnt lgkmcnt(0)
	v_mfma_f32_16x16x32_bf16 v[62:65], v[132:135], v[172:175], v[62:65]
	v_mfma_f32_16x16x32_bf16 v[58:61], v[140:143], v[172:175], v[58:61]
	v_mfma_f32_16x16x32_bf16 v[54:57], v[132:135], v[180:183], v[54:57]
	v_mfma_f32_16x16x32_bf16 v[46:49], v[140:143], v[180:183], v[46:49]
	v_mfma_f32_16x16x32_bf16 v[38:41], v[132:135], v[188:191], v[38:41]
	v_mfma_f32_16x16x32_bf16 v[30:33], v[140:143], v[188:191], v[30:33]
	v_mfma_f32_16x16x32_bf16 v[22:25], v[132:135], v[214:217], v[22:25]
	v_mfma_f32_16x16x32_bf16 v[14:17], v[140:143], v[214:217], v[14:17]
	v_mfma_f32_16x16x32_bf16 v[62:65], v[136:139], v[176:179], v[62:65]
	v_mfma_f32_16x16x32_bf16 v[58:61], v[144:147], v[176:179], v[58:61]
	v_mfma_f32_16x16x32_bf16 v[54:57], v[136:139], v[184:187], v[54:57]
	v_mfma_f32_16x16x32_bf16 v[46:49], v[144:147], v[184:187], v[46:49]
	v_mfma_f32_16x16x32_bf16 v[38:41], v[136:139], v[192:195], v[38:41]
	v_mfma_f32_16x16x32_bf16 v[30:33], v[144:147], v[192:195], v[30:33]
	v_mfma_f32_16x16x32_bf16 v[22:25], v[136:139], v[218:221], v[22:25]
	v_mfma_f32_16x16x32_bf16 v[14:17], v[144:147], v[218:221], v[14:17]
	v_mfma_f32_16x16x32_bf16 v[50:53], v[156:159], v[172:175], v[50:53]
	v_mfma_f32_16x16x32_bf16 v[42:45], v[164:167], v[172:175], v[42:45]
	v_mfma_f32_16x16x32_bf16 v[34:37], v[156:159], v[180:183], v[34:37]
	v_mfma_f32_16x16x32_bf16 v[26:29], v[164:167], v[180:183], v[26:29]
	v_mfma_f32_16x16x32_bf16 v[18:21], v[156:159], v[188:191], v[18:21]
	v_mfma_f32_16x16x32_bf16 v[10:13], v[164:167], v[188:191], v[10:13]
	v_mfma_f32_16x16x32_bf16 v[6:9], v[156:159], v[214:217], v[6:9]
	v_mfma_f32_16x16x32_bf16 v[2:5], v[164:167], v[214:217], v[2:5]
	v_mfma_f32_16x16x32_bf16 v[50:53], v[160:163], v[176:179], v[50:53]
	v_mfma_f32_16x16x32_bf16 v[42:45], v[168:171], v[176:179], v[42:45]
	v_mfma_f32_16x16x32_bf16 v[34:37], v[160:163], v[184:187], v[34:37]
	v_mfma_f32_16x16x32_bf16 v[26:29], v[168:171], v[184:187], v[26:29]
	v_mfma_f32_16x16x32_bf16 v[18:21], v[160:163], v[192:195], v[18:21]
	v_mfma_f32_16x16x32_bf16 v[10:13], v[168:171], v[192:195], v[10:13]
	v_mfma_f32_16x16x32_bf16 v[6:9], v[160:163], v[218:221], v[6:9]
	v_mfma_f32_16x16x32_bf16 v[2:5], v[168:171], v[218:221], v[2:5]
	s_barrier
	s_add_i32 s50, s50, 2
	s_add_u32 s24, s24, 0x100
	s_addc_u32 s25, s25, 0
	s_add_u32 s28, s28, 0x100
	s_addc_u32 s30, s30, 0
	s_cmp_gt_u32 s50, 61
	s_cbranch_scc0 .LBB0_1347
	s_and_b64 vcc, exec, s[18:19]
	s_cbranch_vccz .LBB0_1350
	s_barrier

; #define PG8_STAGE(bufoff, gbase, voff) do { _Pragma("unroll") for (int _i = 0; _i < 2; ++_i) \
;         __builtin_amdgcn_global_load_lds((const unsigned*)((const char*)(gbase) + (voff)[_i]), (LAS unsigned*)(lds + (bufoff) + ldsw + _i * 8192), 16, 0, 0); } while (0)
; #define PG8_LDA(dst, b, h) do { _Pragma("unroll") for (int m = 0; m < 4; ++m) _Pragma("unroll") for (int k = 0; k < 2; ++k) dst[m][k] = *(const LAS bf16x8*)(lds + PG8_SA(b, h) + aoff + m * 2048 + k * 1024); } while (0)
; #define PG8_LDB(dst, b, h) do { _Pragma("unroll") for (int n = 0; n < 2; ++n) _Pragma("unroll") for (int k = 0; k < 2; ++k) dst[n][k] = *(const LAS bf16x8*)(lds + PG8_SB(b, h) + boff + n * 2048 + k * 1024); } while (0)
; #define PG8_MMA(ai, bj, At, Bt) do { __builtin_amdgcn_s_setprio(1); _Pragma("unroll") for (int m = 0; m < 4; ++m) _Pragma("unroll") for (int n = 0; n < 2; ++n) _Pragma("unroll") for (int k = 0; k < 2; ++k) \
;         acc[ai][bj][m][n] = __builtin_amdgcn_mfma_f32_16x16x32_bf16(Bt[n][k], At[m][k], acc[ai][bj][m][n], 0, 0, 0); __builtin_amdgcn_s_setprio(0); } while (0)
; #define PG8_WAIT_V(n) asm volatile("s_waitcnt vmcnt(" #n ")" ::: "memory")
; #define PG8_WAIT_L(n) asm volatile("s_waitcnt lgkmcnt(" #n ")" ::: "memory")
; template <class Epi, class Sched, bool ALIGN_EPI = true, bool SP2 = true>
; __device__ __forceinline__ void gemm_phase(LAS unsigned char* lds, const Sched& S, const Epi& E, const int lda, const int ldb) {
;     ...
;         const char* nA = has_next ? nxt.A : cA; const char* nB = has_next ? nxt.B : cB;
;         const int nt = cur.nt;
;         for (int t = 0; t < nt; t += 2) {
;             const bool last = (t == nt - 2);
;             const char* a1 = cA + (size_t)(t + 1) * kstep;
;             const char* a2 = last ? nA : cA + (size_t)(t + 2) * kstep; const char* b2 = last ? nB : cB + (size_t)(t + 2) * kstep;
;             const char* a3 = a2 + kstep; const char* b3 = b2 + kstep;
;             if constexpr (SP2) {
;             PG8_LDB(B0, 0, 0); PG8_LDB(B1, 0, 1); PG8_SCHED; PG8_LDA(At, 0, 0); PG8_STAGE(PG8_SA(1, 1), a1 + hstepA, voffA);
;             PG8_WAIT_V(8); PG8_WAIT_L(0); PG8_BAR; PG8_MMA(0, 0, At, B0); PG8_MMA(0, 1, At, B1); PG8_BAR; PG8_SCHED;
;             PG8_LDA(At, 0, 1); PG8_STAGE(PG8_SB(0, 0), b2, voffB); PG8_STAGE(PG8_SB(0, 1), b2 + hstepB, voffB); PG8_STAGE(PG8_SA(0, 0), a2, voffA);
.LBB0_1373:
	s_add_u32 s26, s24, 0xfff00080
	s_addc_u32 s27, s25, -1
	s_add_i32 s29, 0, 0x10000
	s_cmp_eq_u32 s50, 60
	s_cselect_b32 s37, s21, s27
	s_cselect_b32 s36, s20, s26
	v_add_u32_e32 v114, s29, v194
	s_cselect_b32 s27, s23, s30
	s_cselect_b32 s26, s22, s28
	s_add_i32 s72, 0, 0x14000
	ds_read_b128 v[132:135], v114
	ds_read_b128 v[136:139], v114 offset:1024
	ds_read_b128 v[140:143], v114 offset:2048
	ds_read_b128 v[144:147], v114 offset:3072
	v_add_u32_e32 v114, s72, v194
	ds_read_b128 v[148:151], v114
	ds_read_b128 v[152:155], v114 offset:1024
	ds_read_b128 v[156:159], v114 offset:2048
	ds_read_b128 v[160:163], v114 offset:3072
	v_lshl_add_u64 v[192:193], s[24:25], 0, v[188:189]
	s_add_i32 m0, s48, 0xc000
	ds_read_b128 v[164:167], v197
	ds_read_b128 v[168:171], v197 offset:1024
	ds_read_b128 v[172:175], v197 offset:2048
	ds_read_b128 v[176:179], v197 offset:3072
	ds_read_b128 v[180:183], v197 offset:4096
	ds_read_b128 v[212:215], v197 offset:5120
	ds_read_b128 v[216:219], v197 offset:6144
	ds_read_b128 v[220:223], v197 offset:7168
	global_load_lds_dwordx4 v[192:193], off
	v_lshl_add_u64 v[192:193], s[24:25], 0, v[190:191]
	s_add_i32 m0, s48, 0xe000
	s_nop 0
	global_load_lds_dwordx4 v[192:193], off
	s_waitcnt vmcnt(8)
	s_waitcnt lgkmcnt(0)
	s_barrier
	s_waitcnt lgkmcnt(0)
	v_mfma_f32_16x16x32_bf16 v[128:131], v[132:135], v[164:167], v[128:131]
	v_mfma_f32_16x16x32_bf16 v[124:127], v[140:143], v[164:167], v[124:127]
	v_mfma_f32_16x16x32_bf16 v[120:123], v[132:135], v[172:175], v[120:123]
	v_mfma_f32_16x16x32_bf16 v[116:119], v[140:143], v[172:175], v[116:119]
	v_mfma_f32_16x16x32_bf16 v[102:105], v[132:135], v[180:183], v[102:105]
	v_mfma_f32_16x16x32_bf16 v[98:101], v[140:143], v[180:183], v[98:101]
	v_mfma_f32_16x16x32_bf16 v[94:97], v[132:135], v[216:219], v[94:97]
	v_mfma_f32_16x16x32_bf16 v[86:89], v[140:143], v[216:219], v[86:89]
	v_mfma_f32_16x16x32_bf16 v[128:131], v[136:139], v[168:171], v[128:131]
	v_mfma_f32_16x16x32_bf16 v[124:127], v[144:147], v[168:171], v[124:127]
	v_mfma_f32_16x16x32_bf16 v[120:123], v[136:139], v[176:179], v[120:123]
	v_mfma_f32_16x16x32_bf16 v[116:119], v[144:147], v[176:179], v[116:119]
	v_mfma_f32_16x16x32_bf16 v[102:105], v[136:139], v[212:215], v[102:105]
	v_mfma_f32_16x16x32_bf16 v[98:101], v[144:147], v[212:215], v[98:101]
	v_mfma_f32_16x16x32_bf16 v[94:97], v[136:139], v[220:223], v[94:97]
	v_mfma_f32_16x16x32_bf16 v[86:89], v[144:147], v[220:223], v[86:89]
	v_mfma_f32_16x16x32_bf16 v[110:113], v[148:151], v[164:167], v[110:113]
	v_mfma_f32_16x16x32_bf16 v[106:109], v[156:159], v[164:167], v[106:109]
	v_mfma_f32_16x16x32_bf16 v[90:93], v[148:151], v[172:175], v[90:93]
	v_mfma_f32_16x16x32_bf16 v[82:85], v[156:159], v[172:175], v[82:85]
	v_mfma_f32_16x16x32_bf16 v[78:81], v[148:151], v[180:183], v[78:81]
	v_mfma_f32_16x16x32_bf16 v[74:77], v[156:159], v[180:183], v[74:77]
	v_mfma_f32_16x16x32_bf16 v[70:73], v[148:151], v[216:219], v[70:73]
	v_mfma_f32_16x16x32_bf16 v[66:69], v[156:159], v[216:219], v[66:69]
	v_mfma_f32_16x16x32_bf16 v[110:113], v[152:155], v[168:171], v[110:113]
	v_mfma_f32_16x16x32_bf16 v[106:109], v[160:163], v[168:171], v[106:109]
	v_mfma_f32_16x16x32_bf16 v[90:93], v[152:155], v[176:179], v[90:93]
	v_mfma_f32_16x16x32_bf16 v[82:85], v[160:163], v[176:179], v[82:85]
	v_mfma_f32_16x16x32_bf16 v[78:81], v[152:155], v[212:215], v[78:81]
	v_mfma_f32_16x16x32_bf16 v[74:77], v[160:163], v[212:215], v[74:77]
	v_mfma_f32_16x16x32_bf16 v[70:73], v[152:155], v[220:223], v[70:73]
	v_mfma_f32_16x16x32_bf16 v[66:69], v[160:163], v[220:223], v[66:69]
	s_barrier
	s_add_i32 s29, s29, s47
	v_lshl_add_u64 v[192:193], s[26:27], 0, v[184:185]
	s_mov_b32 m0, s29
	ds_read_b128 v[164:167], v197 offset:16384
	ds_read_b128 v[168:171], v197 offset:17408
	ds_read_b128 v[172:175], v197 offset:18432
	ds_read_b128 v[176:179], v197 offset:19456
	ds_read_b128 v[180:183], v197 offset:20480
	ds_read_b128 v[212:215], v197 offset:21504
	ds_read_b128 v[216:219], v197 offset:22528
	ds_read_b128 v[220:223], v197 offset:23552
	global_load_lds_dwordx4 v[192:193], off
	s_add_i32 m0, s29, 0x2000
	s_add_u32 s54, s26, 0x100000
	v_lshl_add_u64 v[224:225], s[26:27], 0, v[186:187]
	s_addc_u32 s55, s27, 0
	s_add_i32 s29, s72, s47
	global_load_lds_dwordx4 v[224:225], off
	v_lshl_add_u64 v[226:227], s[54:55], 0, v[184:185]
	s_mov_b32 m0, s29
	v_lshl_add_u64 v[228:229], s[36:37], 0, v[186:187]
	global_load_lds_dwordx4 v[226:227], off
	v_lshl_add_u64 v[226:227], s[54:55], 0, v[186:187]
	s_add_i32 m0, s29, 0x2000
	s_nop 0
	global_load_lds_dwordx4 v[226:227], off
	v_lshl_add_u64 v[226:227], s[36:37], 0, v[184:185]
	s_mov_b32 m0, s48
	s_nop 0
	global_load_lds_dwordx4 v[226:227], off
	s_mov_b32 m0, s49
	s_nop 0
	global_load_lds_dwordx4 v[228:229], off
	s_waitcnt vmcnt(8)
	s_waitcnt lgkmcnt(0)
	s_barrier
; #define PG8_STAGE(bufoff, gbase, voff) do { _Pragma("unroll") for (int _i = 0; _i < 2; ++_i) \
;         __builtin_amdgcn_global_load_lds((const unsigned*)((const char*)(gbase) + (voff)[_i]), (LAS unsigned*)(lds + (bufoff) + ldsw + _i * 8192), 16, 0, 0); } while (0)
; #define PG8_LDA(dst, b, h) do { _Pragma("unroll") for (int m = 0; m < 4; ++m) _Pragma("unroll") for (int k = 0; k < 2; ++k) dst[m][k] = *(const LAS bf16x8*)(lds + PG8_SA(b, h) + aoff + m * 2048 + k * 1024); } while (0)
; #define PG8_LDB(dst, b, h) do { _Pragma("unroll") for (int n = 0; n < 2; ++n) _Pragma("unroll") for (int k = 0; k < 2; ++k) dst[n][k] = *(const LAS bf16x8*)(lds + PG8_SB(b, h) + boff + n * 2048 + k * 1024); } while (0)
; #define PG8_MMA(ai, bj, At, Bt) do { __builtin_amdgcn_s_setprio(1); _Pragma("unroll") for (int m = 0; m < 4; ++m) _Pragma("unroll") for (int n = 0; n < 2; ++n) _Pragma("unroll") for (int k = 0; k < 2; ++k) \
;         acc[ai][bj][m][n] = __builtin_amdgcn_mfma_f32_16x16x32_bf16(Bt[n][k], At[m][k], acc[ai][bj][m][n], 0, 0, 0); __builtin_amdgcn_s_setprio(0); } while (0)
; #define PG8_WAIT_V(n) asm volatile("s_waitcnt vmcnt(" #n ")" ::: "memory")
; #define PG8_WAIT_L(n) asm volatile("s_waitcnt lgkmcnt(" #n ")" ::: "memory")
; #define PG8_BAR __builtin_amdgcn_s_barrier()
; #define PG8_SCHED __builtin_amdgcn_sched_barrier(0)
; template <class Epi, class Sched, bool ALIGN_EPI = true, bool SP2 = true>
; __device__ __forceinline__ void gemm_phase(LAS unsigned char* lds, const Sched& S, const Epi& E, const int lda, const int ldb) {
;     ...
;             PG8_WAIT_V(8); PG8_WAIT_L(0); PG8_BAR; PG8_MMA(1, 0, At, B0); PG8_MMA(1, 1, At, B1); PG8_BAR; PG8_SCHED;
;             PG8_LDB(B0, 1, 0); PG8_LDB(B1, 1, 1); PG8_SCHED; PG8_LDA(At, 1, 0); PG8_STAGE(PG8_SA(0, 1), a2 + hstepA, voffA);
;             PG8_WAIT_V(8); PG8_WAIT_L(0); PG8_BAR; PG8_MMA(0, 0, At, B0); PG8_MMA(0, 1, At, B1); PG8_BAR; PG8_SCHED;
	s_waitcnt lgkmcnt(0)
	v_mfma_f32_16x16x32_bf16 v[62:65], v[132:135], v[164:167], v[62:65]
	v_mfma_f32_16x16x32_bf16 v[58:61], v[140:143], v[164:167], v[58:61]
	v_mfma_f32_16x16x32_bf16 v[54:57], v[132:135], v[172:175], v[54:57]
	v_mfma_f32_16x16x32_bf16 v[50:53], v[140:143], v[172:175], v[50:53]
	v_mfma_f32_16x16x32_bf16 v[38:41], v[132:135], v[180:183], v[38:41]
	v_mfma_f32_16x16x32_bf16 v[34:37], v[140:143], v[180:183], v[34:37]
	v_mfma_f32_16x16x32_bf16 v[22:25], v[132:135], v[216:219], v[22:25]
	v_mfma_f32_16x16x32_bf16 v[18:21], v[140:143], v[216:219], v[18:21]
	v_mfma_f32_16x16x32_bf16 v[62:65], v[136:139], v[168:171], v[62:65]
	v_mfma_f32_16x16x32_bf16 v[58:61], v[144:147], v[168:171], v[58:61]
	v_mfma_f32_16x16x32_bf16 v[54:57], v[136:139], v[176:179], v[54:57]
	v_mfma_f32_16x16x32_bf16 v[50:53], v[144:147], v[176:179], v[50:53]
	v_mfma_f32_16x16x32_bf16 v[38:41], v[136:139], v[212:215], v[38:41]
	v_mfma_f32_16x16x32_bf16 v[34:37], v[144:147], v[212:215], v[34:37]
	v_mfma_f32_16x16x32_bf16 v[22:25], v[136:139], v[220:223], v[22:25]
	v_mfma_f32_16x16x32_bf16 v[18:21], v[144:147], v[220:223], v[18:21]
	v_mfma_f32_16x16x32_bf16 v[46:49], v[148:151], v[164:167], v[46:49]
	v_mfma_f32_16x16x32_bf16 v[42:45], v[156:159], v[164:167], v[42:45]
	v_mfma_f32_16x16x32_bf16 v[30:33], v[148:151], v[172:175], v[30:33]
	v_mfma_f32_16x16x32_bf16 v[26:29], v[156:159], v[172:175], v[26:29]
	v_mfma_f32_16x16x32_bf16 v[14:17], v[148:151], v[180:183], v[14:17]
	v_mfma_f32_16x16x32_bf16 v[10:13], v[156:159], v[180:183], v[10:13]
	v_mfma_f32_16x16x32_bf16 v[6:9], v[148:151], v[216:219], v[6:9]
	v_mfma_f32_16x16x32_bf16 v[2:5], v[156:159], v[216:219], v[2:5]
	v_mfma_f32_16x16x32_bf16 v[46:49], v[152:155], v[168:171], v[46:49]
	v_mfma_f32_16x16x32_bf16 v[42:45], v[160:163], v[168:171], v[42:45]
	v_mfma_f32_16x16x32_bf16 v[30:33], v[152:155], v[176:179], v[30:33]
	v_mfma_f32_16x16x32_bf16 v[26:29], v[160:163], v[176:179], v[26:29]
	v_mfma_f32_16x16x32_bf16 v[14:17], v[152:155], v[212:215], v[14:17]
	v_mfma_f32_16x16x32_bf16 v[10:13], v[160:163], v[212:215], v[10:13]
	v_mfma_f32_16x16x32_bf16 v[6:9], v[152:155], v[220:223], v[6:9]
	v_mfma_f32_16x16x32_bf16 v[2:5], v[160:163], v[220:223], v[2:5]
	s_barrier
	s_add_i32 s29, 0, 0x18000
	v_add_u32_e32 v114, s29, v194
	s_add_i32 s54, 0, 0x1c000
	ds_read_b128 v[132:135], v114
	ds_read_b128 v[136:139], v114 offset:1024
	ds_read_b128 v[140:143], v114 offset:2048
	ds_read_b128 v[144:147], v114 offset:3072
	v_add_u32_e32 v114, s54, v194
	ds_read_b128 v[148:151], v114
	ds_read_b128 v[152:155], v114 offset:1024
	ds_read_b128 v[156:159], v114 offset:2048
	ds_read_b128 v[160:163], v114 offset:3072
	s_add_u32 s36, s36, 0x100000
	s_addc_u32 s37, s37, 0
	s_mov_b32 m0, s51
	v_lshl_add_u64 v[230:231], s[36:37], 0, v[184:185]
	ds_read_b128 v[164:167], v197 offset:32768
	ds_read_b128 v[168:171], v197 offset:33792
	ds_read_b128 v[172:175], v197 offset:34816
	ds_read_b128 v[176:179], v197 offset:35840
	ds_read_b128 v[180:183], v197 offset:36864
	ds_read_b128 v[212:215], v197 offset:37888
	ds_read_b128 v[216:219], v197 offset:38912
	ds_read_b128 v[220:223], v197 offset:39936
	global_load_lds_dwordx4 v[230:231], off
	v_lshl_add_u64 v[230:231], s[36:37], 0, v[186:187]
	s_mov_b32 m0, s52
	s_nop 0
	global_load_lds_dwordx4 v[230:231], off
	s_waitcnt vmcnt(8)
	s_waitcnt lgkmcnt(0)
	s_barrier
	s_waitcnt lgkmcnt(0)
	v_mfma_f32_16x16x32_bf16 v[128:131], v[132:135], v[164:167], v[128:131]
	v_mfma_f32_16x16x32_bf16 v[124:127], v[140:143], v[164:167], v[124:127]
	v_mfma_f32_16x16x32_bf16 v[120:123], v[132:135], v[172:175], v[120:123]
	v_mfma_f32_16x16x32_bf16 v[116:119], v[140:143], v[172:175], v[116:119]
	v_mfma_f32_16x16x32_bf16 v[102:105], v[132:135], v[180:183], v[102:105]
	v_mfma_f32_16x16x32_bf16 v[98:101], v[140:143], v[180:183], v[98:101]
	v_mfma_f32_16x16x32_bf16 v[94:97], v[132:135], v[216:219], v[94:97]
	v_mfma_f32_16x16x32_bf16 v[86:89], v[140:143], v[216:219], v[86:89]
	v_mfma_f32_16x16x32_bf16 v[128:131], v[136:139], v[168:171], v[128:131]
	v_mfma_f32_16x16x32_bf16 v[124:127], v[144:147], v[168:171], v[124:127]
	v_mfma_f32_16x16x32_bf16 v[120:123], v[136:139], v[176:179], v[120:123]
	v_mfma_f32_16x16x32_bf16 v[116:119], v[144:147], v[176:179], v[116:119]
	v_mfma_f32_16x16x32_bf16 v[102:105], v[136:139], v[212:215], v[102:105]
	v_mfma_f32_16x16x32_bf16 v[98:101], v[144:147], v[212:215], v[98:101]
	v_mfma_f32_16x16x32_bf16 v[94:97], v[136:139], v[220:223], v[94:97]
	v_mfma_f32_16x16x32_bf16 v[86:89], v[144:147], v[220:223], v[86:89]
	v_mfma_f32_16x16x32_bf16 v[110:113], v[148:151], v[164:167], v[110:113]
	v_mfma_f32_16x16x32_bf16 v[106:109], v[156:159], v[164:167], v[106:109]
	v_mfma_f32_16x16x32_bf16 v[90:93], v[148:151], v[172:175], v[90:93]
	v_mfma_f32_16x16x32_bf16 v[82:85], v[156:159], v[172:175], v[82:85]
	v_mfma_f32_16x16x32_bf16 v[78:81], v[148:151], v[180:183], v[78:81]
	v_mfma_f32_16x16x32_bf16 v[74:77], v[156:159], v[180:183], v[74:77]
	v_mfma_f32_16x16x32_bf16 v[70:73], v[148:151], v[216:219], v[70:73]
	v_mfma_f32_16x16x32_bf16 v[66:69], v[156:159], v[216:219], v[66:69]
	v_mfma_f32_16x16x32_bf16 v[110:113], v[152:155], v[168:171], v[110:113]
	v_mfma_f32_16x16x32_bf16 v[106:109], v[160:163], v[168:171], v[106:109]
	v_mfma_f32_16x16x32_bf16 v[90:93], v[152:155], v[176:179], v[90:93]
	v_mfma_f32_16x16x32_bf16 v[82:85], v[160:163], v[176:179], v[82:85]
	v_mfma_f32_16x16x32_bf16 v[78:81], v[152:155], v[212:215], v[78:81]
	v_mfma_f32_16x16x32_bf16 v[74:77], v[160:163], v[212:215], v[74:77]
	v_mfma_f32_16x16x32_bf16 v[70:73], v[152:155], v[220:223], v[70:73]
	v_mfma_f32_16x16x32_bf16 v[66:69], v[160:163], v[220:223], v[66:69]
	s_barrier
; #define PG8_STAGE(bufoff, gbase, voff) do { _Pragma("unroll") for (int _i = 0; _i < 2; ++_i) \
;         __builtin_amdgcn_global_load_lds((const unsigned*)((const char*)(gbase) + (voff)[_i]), (LAS unsigned*)(lds + (bufoff) + ldsw + _i * 8192), 16, 0, 0); } while (0)
; #define PG8_LDA(dst, b, h) do { _Pragma("unroll") for (int m = 0; m < 4; ++m) _Pragma("unroll") for (int k = 0; k < 2; ++k) dst[m][k] = *(const LAS bf16x8*)(lds + PG8_SA(b, h) + aoff + m * 2048 + k * 1024); } while (0)
; #define PG8_MMA(ai, bj, At, Bt) do { __builtin_amdgcn_s_setprio(1); _Pragma("unroll") for (int m = 0; m < 4; ++m) _Pragma("unroll") for (int n = 0; n < 2; ++n) _Pragma("unroll") for (int k = 0; k < 2; ++k) \
;         acc[ai][bj][m][n] = __builtin_amdgcn_mfma_f32_16x16x32_bf16(Bt[n][k], At[m][k], acc[ai][bj][m][n], 0, 0, 0); __builtin_amdgcn_s_setprio(0); } while (0)
; #define PG8_WAIT_V(n) asm volatile("s_waitcnt vmcnt(" #n ")" ::: "memory")
; #define PG8_WAIT_L(n) asm volatile("s_waitcnt lgkmcnt(" #n ")" ::: "memory")
; #define PG8_BAR __builtin_amdgcn_s_barrier()
; #define PG8_SCHED __builtin_amdgcn_sched_barrier(0)
; template <class Epi, class Sched, bool ALIGN_EPI = true, bool SP2 = true>
; __device__ __forceinline__ void gemm_phase(LAS unsigned char* lds, const Sched& S, const Epi& E, const int lda, const int ldb) {
;     ...
;             PG8_LDA(At, 1, 1); PG8_STAGE(PG8_SB(1, 0), b3, voffB); PG8_STAGE(PG8_SB(1, 1), b3 + hstepB, voffB); PG8_STAGE(PG8_SA(1, 0), a3, voffA);
;             PG8_WAIT_V(8); PG8_WAIT_L(0); PG8_BAR; PG8_MMA(1, 0, At, B0); PG8_MMA(1, 1, At, B1); PG8_BAR; PG8_SCHED;
;     ...
;         }
;         if constexpr (ALIGN_EPI) { if (wr == 0) PG8_BAR; }
	s_add_i32 s29, s29, s47
	v_lshl_add_u64 v[192:193], v[192:193], 0, s[70:71]
	s_mov_b32 m0, s29
	ds_read_b128 v[164:167], v197 offset:49152
	ds_read_b128 v[168:171], v197 offset:50176
	ds_read_b128 v[172:175], v197 offset:51200
	ds_read_b128 v[176:179], v197 offset:52224
	ds_read_b128 v[180:183], v197 offset:53248
	ds_read_b128 v[212:215], v197 offset:54272
	ds_read_b128 v[216:219], v197 offset:55296
	ds_read_b128 v[220:223], v197 offset:56320
	global_load_lds_dwordx4 v[192:193], off
	s_add_i32 m0, s29, 0x2000
	s_add_u32 s26, s26, 0x100080
	v_lshl_add_u64 v[192:193], v[224:225], 0, s[70:71]
	s_addc_u32 s27, s27, 0
	s_add_i32 s29, s54, s47
	global_load_lds_dwordx4 v[192:193], off
	v_lshl_add_u64 v[192:193], s[26:27], 0, v[184:185]
	s_mov_b32 m0, s29
	s_nop 0
	global_load_lds_dwordx4 v[192:193], off
	v_lshl_add_u64 v[192:193], s[26:27], 0, v[186:187]
	s_add_i32 m0, s29, 0x2000
	s_nop 0
	global_load_lds_dwordx4 v[192:193], off
	v_lshl_add_u64 v[192:193], v[226:227], 0, s[70:71]
	s_mov_b32 m0, s57
	s_nop 0
	global_load_lds_dwordx4 v[192:193], off
	v_lshl_add_u64 v[192:193], v[228:229], 0, s[70:71]
	s_mov_b32 m0, s62
	s_nop 0
	global_load_lds_dwordx4 v[192:193], off
	s_waitcnt vmcnt(8)
	s_waitcnt lgkmcnt(0)
	s_barrier
	s_waitcnt lgkmcnt(0)
	v_mfma_f32_16x16x32_bf16 v[62:65], v[132:135], v[164:167], v[62:65]
	v_mfma_f32_16x16x32_bf16 v[58:61], v[140:143], v[164:167], v[58:61]
	v_mfma_f32_16x16x32_bf16 v[54:57], v[132:135], v[172:175], v[54:57]
	v_mfma_f32_16x16x32_bf16 v[50:53], v[140:143], v[172:175], v[50:53]
	v_mfma_f32_16x16x32_bf16 v[38:41], v[132:135], v[180:183], v[38:41]
	v_mfma_f32_16x16x32_bf16 v[34:37], v[140:143], v[180:183], v[34:37]
	v_mfma_f32_16x16x32_bf16 v[22:25], v[132:135], v[216:219], v[22:25]
	v_mfma_f32_16x16x32_bf16 v[18:21], v[140:143], v[216:219], v[18:21]
	v_mfma_f32_16x16x32_bf16 v[62:65], v[136:139], v[168:171], v[62:65]
	v_mfma_f32_16x16x32_bf16 v[58:61], v[144:147], v[168:171], v[58:61]
	v_mfma_f32_16x16x32_bf16 v[54:57], v[136:139], v[176:179], v[54:57]
	v_mfma_f32_16x16x32_bf16 v[50:53], v[144:147], v[176:179], v[50:53]
	v_mfma_f32_16x16x32_bf16 v[38:41], v[136:139], v[212:215], v[38:41]
	v_mfma_f32_16x16x32_bf16 v[34:37], v[144:147], v[212:215], v[34:37]
	v_mfma_f32_16x16x32_bf16 v[22:25], v[136:139], v[220:223], v[22:25]
	v_mfma_f32_16x16x32_bf16 v[18:21], v[144:147], v[220:223], v[18:21]
	v_mfma_f32_16x16x32_bf16 v[46:49], v[148:151], v[164:167], v[46:49]
	v_mfma_f32_16x16x32_bf16 v[42:45], v[156:159], v[164:167], v[42:45]
	v_mfma_f32_16x16x32_bf16 v[30:33], v[148:151], v[172:175], v[30:33]
	v_mfma_f32_16x16x32_bf16 v[26:29], v[156:159], v[172:175], v[26:29]
	v_mfma_f32_16x16x32_bf16 v[14:17], v[148:151], v[180:183], v[14:17]
	v_mfma_f32_16x16x32_bf16 v[10:13], v[156:159], v[180:183], v[10:13]
	v_mfma_f32_16x16x32_bf16 v[6:9], v[148:151], v[216:219], v[6:9]
	v_mfma_f32_16x16x32_bf16 v[2:5], v[156:159], v[216:219], v[2:5]
	v_mfma_f32_16x16x32_bf16 v[46:49], v[152:155], v[168:171], v[46:49]
	v_mfma_f32_16x16x32_bf16 v[42:45], v[160:163], v[168:171], v[42:45]
	v_mfma_f32_16x16x32_bf16 v[30:33], v[152:155], v[176:179], v[30:33]
	v_mfma_f32_16x16x32_bf16 v[26:29], v[160:163], v[176:179], v[26:29]
	v_mfma_f32_16x16x32_bf16 v[14:17], v[152:155], v[212:215], v[14:17]
	v_mfma_f32_16x16x32_bf16 v[10:13], v[160:163], v[212:215], v[10:13]
	v_mfma_f32_16x16x32_bf16 v[6:9], v[152:155], v[220:223], v[6:9]
	v_mfma_f32_16x16x32_bf16 v[2:5], v[160:163], v[220:223], v[2:5]
	s_barrier
	s_add_i32 s50, s50, 2
	s_add_u32 s24, s24, 0x100
	s_addc_u32 s25, s25, 0
	s_add_u32 s28, s28, 0x100
	s_addc_u32 s30, s30, 0
	s_cmp_gt_u32 s50, 61
	s_cbranch_scc0 .LBB0_1373
	s_and_b64 vcc, exec, s[18:19]
	s_cbranch_vccz .LBB0_1376
	s_barrier

; #define PG8_STAGE(bufoff, gbase, voff) do { _Pragma("unroll") for (int _i = 0; _i < 2; ++_i) \
;         __builtin_amdgcn_global_load_lds((const unsigned*)((const char*)(gbase) + (voff)[_i]), (LAS unsigned*)(lds + (bufoff) + ldsw + _i * 8192), 16, 0, 0); } while (0)
; #define PG8_LDA(dst, b, h) do { _Pragma("unroll") for (int m = 0; m < 4; ++m) _Pragma("unroll") for (int k = 0; k < 2; ++k) dst[m][k] = *(const LAS bf16x8*)(lds + PG8_SA(b, h) + aoff + m * 2048 + k * 1024); } while (0)
; #define PG8_LDB(dst, b, h) do { _Pragma("unroll") for (int n = 0; n < 2; ++n) _Pragma("unroll") for (int k = 0; k < 2; ++k) dst[n][k] = *(const LAS bf16x8*)(lds + PG8_SB(b, h) + boff + n * 2048 + k * 1024); } while (0)
; #define PG8_MMA(ai, bj, At, Bt) do { __builtin_amdgcn_s_setprio(1); _Pragma("unroll") for (int m = 0; m < 4; ++m) _Pragma("unroll") for (int n = 0; n < 2; ++n) _Pragma("unroll") for (int k = 0; k < 2; ++k) \
;         acc[ai][bj][m][n] = __builtin_amdgcn_mfma_f32_16x16x32_bf16(Bt[n][k], At[m][k], acc[ai][bj][m][n], 0, 0, 0); __builtin_amdgcn_s_setprio(0); } while (0)
; #define PG8_WAIT_V(n) asm volatile("s_waitcnt vmcnt(" #n ")" ::: "memory")
; #define PG8_WAIT_L(n) asm volatile("s_waitcnt lgkmcnt(" #n ")" ::: "memory")
; template <class Epi, class Sched, bool ALIGN_EPI = true, bool SP2 = true>
; __device__ __forceinline__ void gemm_phase(LAS unsigned char* lds, const Sched& S, const Epi& E, const int lda, const int ldb) {
;     ...
;         const char* nA = has_next ? nxt.A : cA; const char* nB = has_next ? nxt.B : cB;
;         const int nt = cur.nt;
;         for (int t = 0; t < nt; t += 2) {
;             const bool last = (t == nt - 2);
;             const char* a1 = cA + (size_t)(t + 1) * kstep;
;             const char* a2 = last ? nA : cA + (size_t)(t + 2) * kstep; const char* b2 = last ? nB : cB + (size_t)(t + 2) * kstep;
;             const char* a3 = a2 + kstep; const char* b3 = b2 + kstep;
;             if constexpr (SP2) {
;             PG8_LDB(B0, 0, 0); PG8_LDB(B1, 0, 1); PG8_SCHED; PG8_LDA(At, 0, 0); PG8_STAGE(PG8_SA(1, 1), a1 + hstepA, voffA);
;             PG8_WAIT_V(8); PG8_WAIT_L(0); PG8_BAR; PG8_MMA(0, 0, At, B0); PG8_MMA(0, 1, At, B1); PG8_BAR; PG8_SCHED;
;             PG8_LDA(At, 0, 1); PG8_STAGE(PG8_SB(0, 0), b2, voffB); PG8_STAGE(PG8_SB(0, 1), b2 + hstepB, voffB); PG8_STAGE(PG8_SA(0, 0), a2, voffA);
.LBB0_1390:
	s_add_u32 s26, s24, 0xfff00080
	s_addc_u32 s27, s25, -1
	s_add_i32 s29, 0, 0x10000
	s_cmp_eq_u32 s50, 4
	s_cselect_b32 s37, s19, s27
	s_cselect_b32 s36, s18, s26
	v_add_u32_e32 v154, s29, v156
	s_cselect_b32 s27, s21, s33
	s_cselect_b32 s26, s20, s30
	s_add_i32 s72, 0, 0x14000
	ds_read_b128 v[160:163], v154
	ds_read_b128 v[164:167], v154 offset:1024
	ds_read_b128 v[168:171], v154 offset:2048
	ds_read_b128 v[172:175], v154 offset:3072
	v_add_u32_e32 v154, s72, v156
	ds_read_b128 v[176:179], v154
	ds_read_b128 v[180:183], v154 offset:1024
	ds_read_b128 v[184:187], v154 offset:2048
	ds_read_b128 v[188:191], v154 offset:3072
	v_lshl_add_u64 v[154:155], s[24:25], 0, v[150:151]
	s_add_i32 m0, s47, 0xc000
	ds_read_b128 v[192:195], v158
	ds_read_b128 v[212:215], v158 offset:1024
	ds_read_b128 v[216:219], v158 offset:2048
	ds_read_b128 v[220:223], v158 offset:3072
	ds_read_b128 v[224:227], v158 offset:4096
	ds_read_b128 v[228:231], v158 offset:5120
	ds_read_b128 v[232:235], v158 offset:6144
	ds_read_b128 v[236:239], v158 offset:7168
	global_load_lds_dwordx4 v[154:155], off
	v_lshl_add_u64 v[154:155], s[24:25], 0, v[152:153]
	s_add_i32 m0, s47, 0xe000
	s_nop 0
	global_load_lds_dwordx4 v[154:155], off
	s_waitcnt vmcnt(8)
	s_waitcnt lgkmcnt(0)
	s_barrier
	s_waitcnt lgkmcnt(0)
	v_mfma_f32_16x16x32_bf16 v[128:131], v[160:163], v[192:195], v[128:131]
	v_mfma_f32_16x16x32_bf16 v[94:97], v[168:171], v[192:195], v[94:97]
	v_mfma_f32_16x16x32_bf16 v[124:127], v[160:163], v[216:219], v[124:127]
	v_mfma_f32_16x16x32_bf16 v[90:93], v[168:171], v[216:219], v[90:93]
	v_mfma_f32_16x16x32_bf16 v[120:123], v[160:163], v[224:227], v[120:123]
	v_mfma_f32_16x16x32_bf16 v[86:89], v[168:171], v[224:227], v[86:89]
	v_mfma_f32_16x16x32_bf16 v[116:119], v[160:163], v[232:235], v[116:119]
	v_mfma_f32_16x16x32_bf16 v[82:85], v[168:171], v[232:235], v[82:85]
	v_mfma_f32_16x16x32_bf16 v[128:131], v[164:167], v[212:215], v[128:131]
	v_mfma_f32_16x16x32_bf16 v[94:97], v[172:175], v[212:215], v[94:97]
	v_mfma_f32_16x16x32_bf16 v[124:127], v[164:167], v[220:223], v[124:127]
	v_mfma_f32_16x16x32_bf16 v[90:93], v[172:175], v[220:223], v[90:93]
	v_mfma_f32_16x16x32_bf16 v[120:123], v[164:167], v[228:231], v[120:123]
	v_mfma_f32_16x16x32_bf16 v[86:89], v[172:175], v[228:231], v[86:89]
	v_mfma_f32_16x16x32_bf16 v[116:119], v[164:167], v[236:239], v[116:119]
	v_mfma_f32_16x16x32_bf16 v[82:85], v[172:175], v[236:239], v[82:85]
	v_mfma_f32_16x16x32_bf16 v[66:69], v[176:179], v[192:195], v[66:69]
	v_mfma_f32_16x16x32_bf16 v[42:45], v[184:187], v[192:195], v[42:45]
	v_mfma_f32_16x16x32_bf16 v[58:61], v[176:179], v[216:219], v[58:61]
	v_mfma_f32_16x16x32_bf16 v[34:37], v[184:187], v[216:219], v[34:37]
	v_mfma_f32_16x16x32_bf16 v[54:57], v[176:179], v[224:227], v[54:57]
	v_mfma_f32_16x16x32_bf16 v[30:33], v[184:187], v[224:227], v[30:33]
	v_mfma_f32_16x16x32_bf16 v[50:53], v[176:179], v[232:235], v[50:53]
	v_mfma_f32_16x16x32_bf16 v[22:25], v[184:187], v[232:235], v[22:25]
	v_mfma_f32_16x16x32_bf16 v[66:69], v[180:183], v[212:215], v[66:69]
	v_mfma_f32_16x16x32_bf16 v[42:45], v[188:191], v[212:215], v[42:45]
	v_mfma_f32_16x16x32_bf16 v[58:61], v[180:183], v[220:223], v[58:61]
	v_mfma_f32_16x16x32_bf16 v[34:37], v[188:191], v[220:223], v[34:37]
	v_mfma_f32_16x16x32_bf16 v[54:57], v[180:183], v[228:231], v[54:57]
	v_mfma_f32_16x16x32_bf16 v[30:33], v[188:191], v[228:231], v[30:33]
	v_mfma_f32_16x16x32_bf16 v[50:53], v[180:183], v[236:239], v[50:53]
	v_mfma_f32_16x16x32_bf16 v[22:25], v[188:191], v[236:239], v[22:25]
	s_barrier
	s_add_i32 s29, s29, s43
	v_lshl_add_u64 v[154:155], s[26:27], 0, v[114:115]
	s_mov_b32 m0, s29
	ds_read_b128 v[192:195], v158 offset:16384
	ds_read_b128 v[212:215], v158 offset:17408
	ds_read_b128 v[216:219], v158 offset:18432
	ds_read_b128 v[220:223], v158 offset:19456
	ds_read_b128 v[224:227], v158 offset:20480
	ds_read_b128 v[228:231], v158 offset:21504
	ds_read_b128 v[232:235], v158 offset:22528
	ds_read_b128 v[236:239], v158 offset:23552
	global_load_lds_dwordx4 v[154:155], off
	s_add_i32 m0, s29, 0x2000
	s_add_u32 s54, s26, 0x100000
	v_lshl_add_u64 v[196:197], s[26:27], 0, v[132:133]
	s_addc_u32 s55, s27, 0
	s_add_i32 s29, s72, s43
	global_load_lds_dwordx4 v[196:197], off
	v_lshl_add_u64 v[240:241], s[54:55], 0, v[114:115]
	s_mov_b32 m0, s29
	v_lshl_add_u64 v[242:243], s[36:37], 0, v[132:133]
	global_load_lds_dwordx4 v[240:241], off
	v_lshl_add_u64 v[240:241], s[54:55], 0, v[132:133]
	s_add_i32 m0, s29, 0x2000
	s_nop 0
	global_load_lds_dwordx4 v[240:241], off
	v_lshl_add_u64 v[240:241], s[36:37], 0, v[114:115]
	s_mov_b32 m0, s47
	s_nop 0
	global_load_lds_dwordx4 v[240:241], off
	s_mov_b32 m0, s48
	s_nop 0
	global_load_lds_dwordx4 v[242:243], off
	s_waitcnt vmcnt(8)
	s_waitcnt lgkmcnt(0)
	s_barrier
; #define PG8_STAGE(bufoff, gbase, voff) do { _Pragma("unroll") for (int _i = 0; _i < 2; ++_i) \
;         __builtin_amdgcn_global_load_lds((const unsigned*)((const char*)(gbase) + (voff)[_i]), (LAS unsigned*)(lds + (bufoff) + ldsw + _i * 8192), 16, 0, 0); } while (0)
; #define PG8_LDA(dst, b, h) do { _Pragma("unroll") for (int m = 0; m < 4; ++m) _Pragma("unroll") for (int k = 0; k < 2; ++k) dst[m][k] = *(const LAS bf16x8*)(lds + PG8_SA(b, h) + aoff + m * 2048 + k * 1024); } while (0)
; #define PG8_LDB(dst, b, h) do { _Pragma("unroll") for (int n = 0; n < 2; ++n) _Pragma("unroll") for (int k = 0; k < 2; ++k) dst[n][k] = *(const LAS bf16x8*)(lds + PG8_SB(b, h) + boff + n * 2048 + k * 1024); } while (0)
; #define PG8_MMA(ai, bj, At, Bt) do { __builtin_amdgcn_s_setprio(1); _Pragma("unroll") for (int m = 0; m < 4; ++m) _Pragma("unroll") for (int n = 0; n < 2; ++n) _Pragma("unroll") for (int k = 0; k < 2; ++k) \
;         acc[ai][bj][m][n] = __builtin_amdgcn_mfma_f32_16x16x32_bf16(Bt[n][k], At[m][k], acc[ai][bj][m][n], 0, 0, 0); __builtin_amdgcn_s_setprio(0); } while (0)
; #define PG8_WAIT_V(n) asm volatile("s_waitcnt vmcnt(" #n ")" ::: "memory")
; #define PG8_WAIT_L(n) asm volatile("s_waitcnt lgkmcnt(" #n ")" ::: "memory")
; #define PG8_BAR __builtin_amdgcn_s_barrier()
; #define PG8_SCHED __builtin_amdgcn_sched_barrier(0)
; template <class Epi, class Sched, bool ALIGN_EPI = true, bool SP2 = true>
; __device__ __forceinline__ void gemm_phase(LAS unsigned char* lds, const Sched& S, const Epi& E, const int lda, const int ldb) {
;     ...
;             PG8_WAIT_V(8); PG8_WAIT_L(0); PG8_BAR; PG8_MMA(1, 0, At, B0); PG8_MMA(1, 1, At, B1); PG8_BAR; PG8_SCHED;
;             PG8_LDB(B0, 1, 0); PG8_LDB(B1, 1, 1); PG8_SCHED; PG8_LDA(At, 1, 0); PG8_STAGE(PG8_SA(0, 1), a2 + hstepA, voffA);
;             PG8_WAIT_V(8); PG8_WAIT_L(0); PG8_BAR; PG8_MMA(0, 0, At, B0); PG8_MMA(0, 1, At, B1); PG8_BAR; PG8_SCHED;
	s_waitcnt lgkmcnt(0)
	v_mfma_f32_16x16x32_bf16 v[110:113], v[160:163], v[192:195], v[110:113]
	v_mfma_f32_16x16x32_bf16 v[78:81], v[168:171], v[192:195], v[78:81]
	v_mfma_f32_16x16x32_bf16 v[106:109], v[160:163], v[216:219], v[106:109]
	v_mfma_f32_16x16x32_bf16 v[74:77], v[168:171], v[216:219], v[74:77]
	v_mfma_f32_16x16x32_bf16 v[102:105], v[160:163], v[224:227], v[102:105]
	v_mfma_f32_16x16x32_bf16 v[70:73], v[168:171], v[224:227], v[70:73]
	v_mfma_f32_16x16x32_bf16 v[98:101], v[160:163], v[232:235], v[98:101]
	v_mfma_f32_16x16x32_bf16 v[62:65], v[168:171], v[232:235], v[62:65]
	v_mfma_f32_16x16x32_bf16 v[110:113], v[164:167], v[212:215], v[110:113]
	v_mfma_f32_16x16x32_bf16 v[78:81], v[172:175], v[212:215], v[78:81]
	v_mfma_f32_16x16x32_bf16 v[106:109], v[164:167], v[220:223], v[106:109]
	v_mfma_f32_16x16x32_bf16 v[74:77], v[172:175], v[220:223], v[74:77]
	v_mfma_f32_16x16x32_bf16 v[102:105], v[164:167], v[228:231], v[102:105]
	v_mfma_f32_16x16x32_bf16 v[70:73], v[172:175], v[228:231], v[70:73]
	v_mfma_f32_16x16x32_bf16 v[98:101], v[164:167], v[236:239], v[98:101]
	v_mfma_f32_16x16x32_bf16 v[62:65], v[172:175], v[236:239], v[62:65]
	v_mfma_f32_16x16x32_bf16 v[46:49], v[176:179], v[192:195], v[46:49]
	v_mfma_f32_16x16x32_bf16 v[14:17], v[184:187], v[192:195], v[14:17]
	v_mfma_f32_16x16x32_bf16 v[38:41], v[176:179], v[216:219], v[38:41]
	v_mfma_f32_16x16x32_bf16 v[10:13], v[184:187], v[216:219], v[10:13]
	v_mfma_f32_16x16x32_bf16 v[26:29], v[176:179], v[224:227], v[26:29]
	v_mfma_f32_16x16x32_bf16 v[6:9], v[184:187], v[224:227], v[6:9]
	v_mfma_f32_16x16x32_bf16 v[18:21], v[176:179], v[232:235], v[18:21]
	v_mfma_f32_16x16x32_bf16 v[2:5], v[184:187], v[232:235], v[2:5]
	v_mfma_f32_16x16x32_bf16 v[46:49], v[180:183], v[212:215], v[46:49]
	v_mfma_f32_16x16x32_bf16 v[14:17], v[188:191], v[212:215], v[14:17]
	v_mfma_f32_16x16x32_bf16 v[38:41], v[180:183], v[220:223], v[38:41]
	v_mfma_f32_16x16x32_bf16 v[10:13], v[188:191], v[220:223], v[10:13]
	v_mfma_f32_16x16x32_bf16 v[26:29], v[180:183], v[228:231], v[26:29]
	v_mfma_f32_16x16x32_bf16 v[6:9], v[188:191], v[228:231], v[6:9]
	v_mfma_f32_16x16x32_bf16 v[18:21], v[180:183], v[236:239], v[18:21]
	v_mfma_f32_16x16x32_bf16 v[2:5], v[188:191], v[236:239], v[2:5]
	s_barrier
	s_add_i32 s29, 0, 0x18000
	v_add_u32_e32 v159, s29, v156
	s_add_i32 s54, 0, 0x1c000
	ds_read_b128 v[160:163], v159
	ds_read_b128 v[164:167], v159 offset:1024
	ds_read_b128 v[168:171], v159 offset:2048
	ds_read_b128 v[172:175], v159 offset:3072
	v_add_u32_e32 v159, s54, v156
	ds_read_b128 v[176:179], v159
	ds_read_b128 v[180:183], v159 offset:1024
	ds_read_b128 v[184:187], v159 offset:2048
	ds_read_b128 v[188:191], v159 offset:3072
	s_add_u32 s36, s36, 0x100000
	s_addc_u32 s37, s37, 0
	s_mov_b32 m0, s49
	v_lshl_add_u64 v[246:247], s[36:37], 0, v[114:115]
	ds_read_b128 v[192:195], v158 offset:32768
	ds_read_b128 v[212:215], v158 offset:33792
	ds_read_b128 v[216:219], v158 offset:34816
	ds_read_b128 v[220:223], v158 offset:35840
	ds_read_b128 v[224:227], v158 offset:36864
	ds_read_b128 v[228:231], v158 offset:37888
	ds_read_b128 v[232:235], v158 offset:38912
	ds_read_b128 v[236:239], v158 offset:39936
	global_load_lds_dwordx4 v[246:247], off
	v_lshl_add_u64 v[246:247], s[36:37], 0, v[132:133]
	s_mov_b32 m0, s51
	s_nop 0
	global_load_lds_dwordx4 v[246:247], off
	s_waitcnt vmcnt(8)
	s_waitcnt lgkmcnt(0)
	s_barrier
	s_waitcnt lgkmcnt(0)
	v_mfma_f32_16x16x32_bf16 v[128:131], v[160:163], v[192:195], v[128:131]
	v_mfma_f32_16x16x32_bf16 v[94:97], v[168:171], v[192:195], v[94:97]
	v_mfma_f32_16x16x32_bf16 v[124:127], v[160:163], v[216:219], v[124:127]
	v_mfma_f32_16x16x32_bf16 v[90:93], v[168:171], v[216:219], v[90:93]
	v_mfma_f32_16x16x32_bf16 v[120:123], v[160:163], v[224:227], v[120:123]
	v_mfma_f32_16x16x32_bf16 v[86:89], v[168:171], v[224:227], v[86:89]
	v_mfma_f32_16x16x32_bf16 v[116:119], v[160:163], v[232:235], v[116:119]
	v_mfma_f32_16x16x32_bf16 v[82:85], v[168:171], v[232:235], v[82:85]
	v_mfma_f32_16x16x32_bf16 v[128:131], v[164:167], v[212:215], v[128:131]
	v_mfma_f32_16x16x32_bf16 v[94:97], v[172:175], v[212:215], v[94:97]
	v_mfma_f32_16x16x32_bf16 v[124:127], v[164:167], v[220:223], v[124:127]
	v_mfma_f32_16x16x32_bf16 v[90:93], v[172:175], v[220:223], v[90:93]
	v_mfma_f32_16x16x32_bf16 v[120:123], v[164:167], v[228:231], v[120:123]
	v_mfma_f32_16x16x32_bf16 v[86:89], v[172:175], v[228:231], v[86:89]
	v_mfma_f32_16x16x32_bf16 v[116:119], v[164:167], v[236:239], v[116:119]
	v_mfma_f32_16x16x32_bf16 v[82:85], v[172:175], v[236:239], v[82:85]
	v_mfma_f32_16x16x32_bf16 v[66:69], v[176:179], v[192:195], v[66:69]
	v_mfma_f32_16x16x32_bf16 v[42:45], v[184:187], v[192:195], v[42:45]
	v_mfma_f32_16x16x32_bf16 v[58:61], v[176:179], v[216:219], v[58:61]
	v_mfma_f32_16x16x32_bf16 v[34:37], v[184:187], v[216:219], v[34:37]
	v_mfma_f32_16x16x32_bf16 v[54:57], v[176:179], v[224:227], v[54:57]
	v_mfma_f32_16x16x32_bf16 v[30:33], v[184:187], v[224:227], v[30:33]
	v_mfma_f32_16x16x32_bf16 v[50:53], v[176:179], v[232:235], v[50:53]
	v_mfma_f32_16x16x32_bf16 v[22:25], v[184:187], v[232:235], v[22:25]
	v_mfma_f32_16x16x32_bf16 v[66:69], v[180:183], v[212:215], v[66:69]
	v_mfma_f32_16x16x32_bf16 v[42:45], v[188:191], v[212:215], v[42:45]
	v_mfma_f32_16x16x32_bf16 v[58:61], v[180:183], v[220:223], v[58:61]
	v_mfma_f32_16x16x32_bf16 v[34:37], v[188:191], v[220:223], v[34:37]
	v_mfma_f32_16x16x32_bf16 v[54:57], v[180:183], v[228:231], v[54:57]
	v_mfma_f32_16x16x32_bf16 v[30:33], v[188:191], v[228:231], v[30:33]
	v_mfma_f32_16x16x32_bf16 v[50:53], v[180:183], v[236:239], v[50:53]
	v_mfma_f32_16x16x32_bf16 v[22:25], v[188:191], v[236:239], v[22:25]
	s_barrier
; #define PG8_STAGE(bufoff, gbase, voff) do { _Pragma("unroll") for (int _i = 0; _i < 2; ++_i) \
;         __builtin_amdgcn_global_load_lds((const unsigned*)((const char*)(gbase) + (voff)[_i]), (LAS unsigned*)(lds + (bufoff) + ldsw + _i * 8192), 16, 0, 0); } while (0)
; #define PG8_LDA(dst, b, h) do { _Pragma("unroll") for (int m = 0; m < 4; ++m) _Pragma("unroll") for (int k = 0; k < 2; ++k) dst[m][k] = *(const LAS bf16x8*)(lds + PG8_SA(b, h) + aoff + m * 2048 + k * 1024); } while (0)
; #define PG8_MMA(ai, bj, At, Bt) do { __builtin_amdgcn_s_setprio(1); _Pragma("unroll") for (int m = 0; m < 4; ++m) _Pragma("unroll") for (int n = 0; n < 2; ++n) _Pragma("unroll") for (int k = 0; k < 2; ++k) \
;         acc[ai][bj][m][n] = __builtin_amdgcn_mfma_f32_16x16x32_bf16(Bt[n][k], At[m][k], acc[ai][bj][m][n], 0, 0, 0); __builtin_amdgcn_s_setprio(0); } while (0)
; #define PG8_WAIT_V(n) asm volatile("s_waitcnt vmcnt(" #n ")" ::: "memory")
; #define PG8_WAIT_L(n) asm volatile("s_waitcnt lgkmcnt(" #n ")" ::: "memory")
; #define PG8_BAR __builtin_amdgcn_s_barrier()
; #define PG8_SCHED __builtin_amdgcn_sched_barrier(0)
; template <class Epi, class Sched, bool ALIGN_EPI = true, bool SP2 = true>
; __device__ __forceinline__ void gemm_phase(LAS unsigned char* lds, const Sched& S, const Epi& E, const int lda, const int ldb) {
;     ...
;             PG8_LDA(At, 1, 1); PG8_STAGE(PG8_SB(1, 0), b3, voffB); PG8_STAGE(PG8_SB(1, 1), b3 + hstepB, voffB); PG8_STAGE(PG8_SA(1, 0), a3, voffA);
;             PG8_WAIT_V(8); PG8_WAIT_L(0); PG8_BAR; PG8_MMA(1, 0, At, B0); PG8_MMA(1, 1, At, B1); PG8_BAR; PG8_SCHED;
;     ...
;         }
;         if constexpr (ALIGN_EPI) { if (wr == 0) PG8_BAR; }
	s_add_i32 s29, s29, s43
	v_lshl_add_u64 v[154:155], v[154:155], 0, s[70:71]
	s_mov_b32 m0, s29
	ds_read_b128 v[192:195], v158 offset:49152
	ds_read_b128 v[212:215], v158 offset:50176
	ds_read_b128 v[216:219], v158 offset:51200
	ds_read_b128 v[220:223], v158 offset:52224
	ds_read_b128 v[224:227], v158 offset:53248
	ds_read_b128 v[228:231], v158 offset:54272
	ds_read_b128 v[232:235], v158 offset:55296
	ds_read_b128 v[236:239], v158 offset:56320
	global_load_lds_dwordx4 v[154:155], off
	s_add_i32 m0, s29, 0x2000
	s_add_u32 s26, s26, 0x100080
	v_lshl_add_u64 v[154:155], v[196:197], 0, s[70:71]
	s_addc_u32 s27, s27, 0
	s_add_i32 s29, s54, s43
	global_load_lds_dwordx4 v[154:155], off
	v_lshl_add_u64 v[154:155], s[26:27], 0, v[114:115]
	s_mov_b32 m0, s29
	s_nop 0
	global_load_lds_dwordx4 v[154:155], off
	v_lshl_add_u64 v[154:155], s[26:27], 0, v[132:133]
	s_add_i32 m0, s29, 0x2000
	s_nop 0
	global_load_lds_dwordx4 v[154:155], off
	v_lshl_add_u64 v[154:155], v[240:241], 0, s[70:71]
	s_mov_b32 m0, s62
	s_nop 0
	global_load_lds_dwordx4 v[154:155], off
	v_lshl_add_u64 v[154:155], v[242:243], 0, s[70:71]
	s_mov_b32 m0, s63
	s_nop 0
	global_load_lds_dwordx4 v[154:155], off
	s_waitcnt vmcnt(8)
	s_waitcnt lgkmcnt(0)
	s_barrier
	s_waitcnt lgkmcnt(0)
	v_mfma_f32_16x16x32_bf16 v[110:113], v[160:163], v[192:195], v[110:113]
	v_mfma_f32_16x16x32_bf16 v[78:81], v[168:171], v[192:195], v[78:81]
	v_mfma_f32_16x16x32_bf16 v[106:109], v[160:163], v[216:219], v[106:109]
	v_mfma_f32_16x16x32_bf16 v[74:77], v[168:171], v[216:219], v[74:77]
	v_mfma_f32_16x16x32_bf16 v[102:105], v[160:163], v[224:227], v[102:105]
	v_mfma_f32_16x16x32_bf16 v[70:73], v[168:171], v[224:227], v[70:73]
	v_mfma_f32_16x16x32_bf16 v[98:101], v[160:163], v[232:235], v[98:101]
	v_mfma_f32_16x16x32_bf16 v[62:65], v[168:171], v[232:235], v[62:65]
	v_mfma_f32_16x16x32_bf16 v[110:113], v[164:167], v[212:215], v[110:113]
	v_mfma_f32_16x16x32_bf16 v[78:81], v[172:175], v[212:215], v[78:81]
	v_mfma_f32_16x16x32_bf16 v[106:109], v[164:167], v[220:223], v[106:109]
	v_mfma_f32_16x16x32_bf16 v[74:77], v[172:175], v[220:223], v[74:77]
	v_mfma_f32_16x16x32_bf16 v[102:105], v[164:167], v[228:231], v[102:105]
	v_mfma_f32_16x16x32_bf16 v[70:73], v[172:175], v[228:231], v[70:73]
	v_mfma_f32_16x16x32_bf16 v[98:101], v[164:167], v[236:239], v[98:101]
	v_mfma_f32_16x16x32_bf16 v[62:65], v[172:175], v[236:239], v[62:65]
	v_mfma_f32_16x16x32_bf16 v[46:49], v[176:179], v[192:195], v[46:49]
	v_mfma_f32_16x16x32_bf16 v[14:17], v[184:187], v[192:195], v[14:17]
	v_mfma_f32_16x16x32_bf16 v[38:41], v[176:179], v[216:219], v[38:41]
	v_mfma_f32_16x16x32_bf16 v[10:13], v[184:187], v[216:219], v[10:13]
	v_mfma_f32_16x16x32_bf16 v[26:29], v[176:179], v[224:227], v[26:29]
	v_mfma_f32_16x16x32_bf16 v[6:9], v[184:187], v[224:227], v[6:9]
	v_mfma_f32_16x16x32_bf16 v[18:21], v[176:179], v[232:235], v[18:21]
	v_mfma_f32_16x16x32_bf16 v[2:5], v[184:187], v[232:235], v[2:5]
	v_mfma_f32_16x16x32_bf16 v[46:49], v[180:183], v[212:215], v[46:49]
	v_mfma_f32_16x16x32_bf16 v[14:17], v[188:191], v[212:215], v[14:17]
	v_mfma_f32_16x16x32_bf16 v[38:41], v[180:183], v[220:223], v[38:41]
	v_mfma_f32_16x16x32_bf16 v[10:13], v[188:191], v[220:223], v[10:13]
	v_mfma_f32_16x16x32_bf16 v[26:29], v[180:183], v[228:231], v[26:29]
	v_mfma_f32_16x16x32_bf16 v[6:9], v[188:191], v[228:231], v[6:9]
	v_mfma_f32_16x16x32_bf16 v[18:21], v[180:183], v[236:239], v[18:21]
	v_mfma_f32_16x16x32_bf16 v[2:5], v[188:191], v[236:239], v[2:5]
	s_barrier
	s_add_i32 s50, s50, 2
	s_add_u32 s24, s24, 0x100
	s_addc_u32 s25, s25, 0
	s_add_u32 s30, s30, 0x100
	s_addc_u32 s33, s33, 0
	s_cmp_gt_u32 s50, 5
	s_cbranch_scc0 .LBB0_1390
	s_and_b64 vcc, exec, s[10:11]
	s_cbranch_vccz .LBB0_1393
	s_barrier
